# all s_setprio flips around the GEMM MFMA blocks removed (priority stays 0)
# baseline (speedup 1.0000x reference)
; #define PG8_STAGE(bufoff, gbase, voff) do { _Pragma("unroll") for (int _i = 0; _i < 2; ++_i) \
;         __builtin_amdgcn_global_load_lds((const unsigned*)((const char*)(gbase) + (voff)[_i]), (PG8_LAS unsigned*)(lds + (bufoff) + ldsw + _i * 8192), 16, 0, 0); } while (0)
; #define PG8_LDA(dst, b, h) do { _Pragma("unroll") for (int m = 0; m < 4; ++m) _Pragma("unroll") for (int k = 0; k < 2; ++k) dst[m][k] = *(const PG8_LAS bf16x8*)(lds + PG8_SA(b, h) + aoff + m * 2048 + k * 1024); } while (0)
; #define PG8_LDB(dst, b, h) do { _Pragma("unroll") for (int n = 0; n < 2; ++n) _Pragma("unroll") for (int k = 0; k < 2; ++k) dst[n][k] = *(const PG8_LAS bf16x8*)(lds + PG8_SB(b, h) + boff + n * 2048 + k * 1024); } while (0)
; #define PG8_WAIT_V(n) asm volatile("s_waitcnt vmcnt(" #n ")" ::: "memory")
; #define PG8_WAIT_L(n) asm volatile("s_waitcnt lgkmcnt(" #n ")" ::: "memory")
; #define PG8_BAR __builtin_amdgcn_s_barrier()
; #define PG8_SCHED __builtin_amdgcn_sched_barrier(0)
; template <class Epi, class Sched, bool ALIGN_EPI = false, bool SP2 = false>
; __device__ __forceinline__ void gemm_phase(PG8_LAS unsigned char* lds, const Gemm g, const Sched& S, const Epi& E) {
;     ...
;         const bool has_next = S.next(ui + 1, nxt);
;         const char* nA = has_next ? (const char*)g.A + (size_t)nxt.pm * tstep : cA; const char* nB = has_next ? (const char*)g.Bt + (size_t)nxt.pn * tstep : cB;
;         for (int t = 0; t < nt; t += 2) {
;             const bool last = (t == nt - 2);
;             const char* a1 = cA + (size_t)(t + 1) * kstep;
;             const char* a2 = last ? nA : cA + (size_t)(t + 2) * kstep; const char* b2 = last ? nB : cB + (size_t)(t + 2) * kstep;
;             const char* a3 = a2 + kstep; const char* b3 = b2 + kstep;
;             if (last && has_next) S.a_ready(nxt);
;             if constexpr (SP2) {
;             PG8_LDB(B0, 0, 0); PG8_LDB(B1, 0, 1); PG8_SCHED; PG8_LDA(At, 0, 0); PG8_STAGE(PG8_SA(1, 1), a1 + hstep, voffA);
;             PG8_WAIT_V(8); PG8_WAIT_L(0); PG8_BAR; PG8_MMA(0, 0, At, B0); PG8_MMA(0, 1, At, B1); PG8_BAR; PG8_SCHED;
;             PG8_LDA(At, 0, 1); PG8_STAGE(PG8_SB(0, 0), b2, voffB); PG8_STAGE(PG8_SB(0, 1), b2 + hstep, voffB); PG8_STAGE(PG8_SA(0, 0), a2, voffA);
;             PG8_WAIT_V(8); PG8_WAIT_L(0); PG8_BAR; PG8_MMA(1, 0, At, B0); PG8_MMA(1, 1, At, B1); PG8_BAR; PG8_SCHED;
.LBB0_300:
	s_ashr_i32 s13, s12, 31
	s_lshl_b64 s[16:17], s[12:13], 19
	s_add_u32 s16, s0, s16
	s_addc_u32 s17, s1, s17
	s_and_b64 s[18:19], s[4:5], exec
	s_cselect_b32 s13, s17, s25
	s_cselect_b32 s21, s16, s24
	s_ashr_i32 s11, s10, 31
	s_lshl_b64 s[18:19], s[10:11], 19
	s_add_u32 s18, s33, s18
	s_addc_u32 s19, s34, s19
	s_and_b64 s[28:29], s[4:5], exec
	s_cselect_b32 s11, s19, s27
	s_cselect_b32 s44, s18, s26
	s_add_u32 s24, s24, 0x40080
	s_addc_u32 s25, s25, 0
	s_add_u32 s45, s26, 0x100
	s_addc_u32 s46, s27, 0
	s_mov_b32 s47, -2
	s_add_u32 s26, s24, 0xfffc0080
	s_addc_u32 s27, s25, -1
	s_add_i32 s48, 0, 0x10000
	s_cmp_eq_u32 s47, 12
	s_cselect_b32 s29, s13, s27
	s_cselect_b32 s28, s21, s26
	v_add_u32_e32 v154, s48, v156
	s_cselect_b32 s27, s11, s46
	s_cselect_b32 s26, s44, s45
	s_add_i32 s50, 0, 0x14000
	ds_read_b128 v[94:97], v154
	ds_read_b128 v[134:137], v154 offset:1024
	ds_read_b128 v[158:161], v154 offset:2048
	ds_read_b128 v[162:165], v154 offset:3072
	v_add_u32_e32 v154, s50, v156
	ds_read_b128 v[166:169], v154
	ds_read_b128 v[170:173], v154 offset:1024
	ds_read_b128 v[174:177], v154 offset:2048
	ds_read_b128 v[186:189], v154 offset:3072
	v_lshl_add_u64 v[154:155], s[24:25], 0, v[150:151]
	s_add_i32 m0, s23, 0xc000
	ds_read_b128 v[190:193], v157
	ds_read_b128 v[194:197], v157 offset:1024
	ds_read_b128 v[198:201], v157 offset:2048
	ds_read_b128 v[202:205], v157 offset:3072
	ds_read_b128 v[206:209], v157 offset:4096
	ds_read_b128 v[210:213], v157 offset:5120
	ds_read_b128 v[214:217], v157 offset:6144
	ds_read_b128 v[218:221], v157 offset:7168
	global_load_lds_dwordx4 v[154:155], off
	v_lshl_add_u64 v[154:155], s[24:25], 0, v[152:153]
	s_add_i32 m0, s23, 0xe000
	s_nop 0
	global_load_lds_dwordx4 v[154:155], off
	s_waitcnt vmcnt(8) lgkmcnt(0)
	s_barrier
	v_mfma_f32_16x16x32_bf16 v[130:133], v[94:97], v[190:193], 0
	v_mfma_f32_16x16x32_bf16 v[126:129], v[158:161], v[190:193], 0
	v_mfma_f32_16x16x32_bf16 v[114:117], v[94:97], v[198:201], 0
	v_mfma_f32_16x16x32_bf16 v[110:113], v[158:161], v[198:201], 0
	v_mfma_f32_16x16x32_bf16 v[98:101], v[94:97], v[206:209], 0
	v_mfma_f32_16x16x32_bf16 v[90:93], v[158:161], v[206:209], 0
	v_mfma_f32_16x16x32_bf16 v[78:81], v[94:97], v[214:217], 0
	v_mfma_f32_16x16x32_bf16 v[74:77], v[158:161], v[214:217], 0
	v_mfma_f32_16x16x32_bf16 v[130:133], v[134:137], v[194:197], v[130:133]
	v_mfma_f32_16x16x32_bf16 v[126:129], v[162:165], v[194:197], v[126:129]
	v_mfma_f32_16x16x32_bf16 v[114:117], v[134:137], v[202:205], v[114:117]
	v_mfma_f32_16x16x32_bf16 v[110:113], v[162:165], v[202:205], v[110:113]
	v_mfma_f32_16x16x32_bf16 v[98:101], v[134:137], v[210:213], v[98:101]
	v_mfma_f32_16x16x32_bf16 v[90:93], v[162:165], v[210:213], v[90:93]
	v_mfma_f32_16x16x32_bf16 v[78:81], v[134:137], v[218:221], v[78:81]
	v_mfma_f32_16x16x32_bf16 v[74:77], v[162:165], v[218:221], v[74:77]
	v_mfma_f32_16x16x32_bf16 v[122:125], v[166:169], v[190:193], 0
	v_mfma_f32_16x16x32_bf16 v[118:121], v[174:177], v[190:193], 0
	v_mfma_f32_16x16x32_bf16 v[106:109], v[166:169], v[198:201], 0
	v_mfma_f32_16x16x32_bf16 v[102:105], v[174:177], v[198:201], 0
	v_mfma_f32_16x16x32_bf16 v[86:89], v[166:169], v[206:209], 0
	v_mfma_f32_16x16x32_bf16 v[82:85], v[174:177], v[206:209], 0
	v_mfma_f32_16x16x32_bf16 v[70:73], v[166:169], v[214:217], 0
	v_mfma_f32_16x16x32_bf16 v[66:69], v[174:177], v[214:217], 0
	v_mfma_f32_16x16x32_bf16 v[122:125], v[170:173], v[194:197], v[122:125]
	v_mfma_f32_16x16x32_bf16 v[118:121], v[186:189], v[194:197], v[118:121]
	v_mfma_f32_16x16x32_bf16 v[106:109], v[170:173], v[202:205], v[106:109]
	v_mfma_f32_16x16x32_bf16 v[102:105], v[186:189], v[202:205], v[102:105]
	v_mfma_f32_16x16x32_bf16 v[86:89], v[170:173], v[210:213], v[86:89]
	v_mfma_f32_16x16x32_bf16 v[82:85], v[186:189], v[210:213], v[82:85]
	v_mfma_f32_16x16x32_bf16 v[70:73], v[170:173], v[218:221], v[70:73]
	v_mfma_f32_16x16x32_bf16 v[66:69], v[186:189], v[218:221], v[66:69]
	s_barrier
	s_add_i32 s48, s48, s35
	v_lshl_add_u64 v[154:155], s[26:27], 0, v[142:143]
	s_mov_b32 m0, s48
	ds_read_b128 v[190:193], v157 offset:16384
	ds_read_b128 v[194:197], v157 offset:17408
	ds_read_b128 v[198:201], v157 offset:18432
	ds_read_b128 v[202:205], v157 offset:19456
	ds_read_b128 v[206:209], v157 offset:20480
	ds_read_b128 v[210:213], v157 offset:21504
	ds_read_b128 v[214:217], v157 offset:22528
	ds_read_b128 v[218:221], v157 offset:23552
	global_load_lds_dwordx4 v[154:155], off
	s_add_i32 m0, s48, 0x2000
	s_add_u32 s48, s26, 0x40000
	v_lshl_add_u64 v[180:181], s[26:27], 0, v[138:139]
	s_addc_u32 s49, s27, 0
	s_add_i32 s50, s50, s35
	global_load_lds_dwordx4 v[180:181], off
	v_lshl_add_u64 v[182:183], s[48:49], 0, v[142:143]
	s_mov_b32 m0, s50
	v_lshl_add_u64 v[222:223], s[28:29], 0, v[140:141]
	global_load_lds_dwordx4 v[182:183], off
	v_lshl_add_u64 v[182:183], s[48:49], 0, v[138:139]
	s_add_i32 m0, s50, 0x2000
	s_nop 0
	global_load_lds_dwordx4 v[182:183], off
	v_lshl_add_u64 v[182:183], s[28:29], 0, v[144:145]
	s_mov_b32 m0, s23
	s_nop 0
	global_load_lds_dwordx4 v[182:183], off
	s_mov_b32 m0, s37
	s_nop 0
	global_load_lds_dwordx4 v[222:223], off
	s_waitcnt vmcnt(8) lgkmcnt(0)
	s_barrier
; #define PG8_STAGE(bufoff, gbase, voff) do { _Pragma("unroll") for (int _i = 0; _i < 2; ++_i) \
;         __builtin_amdgcn_global_load_lds((const unsigned*)((const char*)(gbase) + (voff)[_i]), (PG8_LAS unsigned*)(lds + (bufoff) + ldsw + _i * 8192), 16, 0, 0); } while (0)
; #define PG8_LDA(dst, b, h) do { _Pragma("unroll") for (int m = 0; m < 4; ++m) _Pragma("unroll") for (int k = 0; k < 2; ++k) dst[m][k] = *(const PG8_LAS bf16x8*)(lds + PG8_SA(b, h) + aoff + m * 2048 + k * 1024); } while (0)
; #define PG8_LDB(dst, b, h) do { _Pragma("unroll") for (int n = 0; n < 2; ++n) _Pragma("unroll") for (int k = 0; k < 2; ++k) dst[n][k] = *(const PG8_LAS bf16x8*)(lds + PG8_SB(b, h) + boff + n * 2048 + k * 1024); } while (0)
; #define PG8_MMA(ai, bj, At, Bt) do { __builtin_amdgcn_s_setprio(1); _Pragma("unroll") for (int m = 0; m < 4; ++m) _Pragma("unroll") for (int n = 0; n < 2; ++n) _Pragma("unroll") for (int k = 0; k < 2; ++k) \
;         acc[ai][bj][m][n] = __builtin_amdgcn_mfma_f32_16x16x32_bf16(Bt[n][k], At[m][k], acc[ai][bj][m][n], 0, 0, 0); __builtin_amdgcn_s_setprio(0); } while (0)
; #define PG8_WAIT_V(n) asm volatile("s_waitcnt vmcnt(" #n ")" ::: "memory")
; #define PG8_WAIT_L(n) asm volatile("s_waitcnt lgkmcnt(" #n ")" ::: "memory")
; #define PG8_BAR __builtin_amdgcn_s_barrier()
; #define PG8_SCHED __builtin_amdgcn_sched_barrier(0)
; template <class Epi, class Sched, bool ALIGN_EPI = false, bool SP2 = false>
; __device__ __forceinline__ void gemm_phase(PG8_LAS unsigned char* lds, const Gemm g, const Sched& S, const Epi& E) {
;     ...
;             PG8_LDA(At, 0, 1); PG8_STAGE(PG8_SB(0, 0), b2, voffB); PG8_STAGE(PG8_SB(0, 1), b2 + hstep, voffB); PG8_STAGE(PG8_SA(0, 0), a2, voffA);
;             PG8_WAIT_V(8); PG8_WAIT_L(0); PG8_BAR; PG8_MMA(1, 0, At, B0); PG8_MMA(1, 1, At, B1); PG8_BAR; PG8_SCHED;
;             PG8_LDB(B0, 1, 0); PG8_LDB(B1, 1, 1); PG8_SCHED; PG8_LDA(At, 1, 0); PG8_STAGE(PG8_SA(0, 1), a2 + hstep, voffA);
;             PG8_WAIT_V(8); PG8_WAIT_L(0); PG8_BAR; PG8_MMA(0, 0, At, B0); PG8_MMA(0, 1, At, B1); PG8_BAR; PG8_SCHED;
	v_mfma_f32_16x16x32_bf16 v[62:65], v[94:97], v[190:193], 0
	v_mfma_f32_16x16x32_bf16 v[58:61], v[158:161], v[190:193], 0
	v_mfma_f32_16x16x32_bf16 v[50:53], v[94:97], v[198:201], 0
	v_mfma_f32_16x16x32_bf16 v[42:45], v[158:161], v[198:201], 0
	v_mfma_f32_16x16x32_bf16 v[34:37], v[94:97], v[206:209], 0
	v_mfma_f32_16x16x32_bf16 v[26:29], v[158:161], v[206:209], 0
	v_mfma_f32_16x16x32_bf16 v[18:21], v[94:97], v[214:217], 0
	v_mfma_f32_16x16x32_bf16 v[10:13], v[158:161], v[214:217], 0
	v_mfma_f32_16x16x32_bf16 v[62:65], v[134:137], v[194:197], v[62:65]
	v_mfma_f32_16x16x32_bf16 v[58:61], v[162:165], v[194:197], v[58:61]
	v_mfma_f32_16x16x32_bf16 v[50:53], v[134:137], v[202:205], v[50:53]
	v_mfma_f32_16x16x32_bf16 v[42:45], v[162:165], v[202:205], v[42:45]
	v_mfma_f32_16x16x32_bf16 v[34:37], v[134:137], v[210:213], v[34:37]
	v_mfma_f32_16x16x32_bf16 v[26:29], v[162:165], v[210:213], v[26:29]
	v_mfma_f32_16x16x32_bf16 v[18:21], v[134:137], v[218:221], v[18:21]
	v_mfma_f32_16x16x32_bf16 v[10:13], v[162:165], v[218:221], v[10:13]
	v_mfma_f32_16x16x32_bf16 v[54:57], v[166:169], v[190:193], 0
	v_mfma_f32_16x16x32_bf16 v[46:49], v[174:177], v[190:193], 0
	v_mfma_f32_16x16x32_bf16 v[38:41], v[166:169], v[198:201], 0
	v_mfma_f32_16x16x32_bf16 v[30:33], v[174:177], v[198:201], 0
	v_mfma_f32_16x16x32_bf16 v[22:25], v[166:169], v[206:209], 0
	v_mfma_f32_16x16x32_bf16 v[14:17], v[174:177], v[206:209], 0
	v_mfma_f32_16x16x32_bf16 v[6:9], v[166:169], v[214:217], 0
	v_mfma_f32_16x16x32_bf16 v[2:5], v[174:177], v[214:217], 0
	v_mfma_f32_16x16x32_bf16 v[54:57], v[170:173], v[194:197], v[54:57]
	v_mfma_f32_16x16x32_bf16 v[46:49], v[186:189], v[194:197], v[46:49]
	v_mfma_f32_16x16x32_bf16 v[38:41], v[170:173], v[202:205], v[38:41]
	v_mfma_f32_16x16x32_bf16 v[30:33], v[186:189], v[202:205], v[30:33]
	v_mfma_f32_16x16x32_bf16 v[22:25], v[170:173], v[210:213], v[22:25]
	v_mfma_f32_16x16x32_bf16 v[14:17], v[186:189], v[210:213], v[14:17]
	v_mfma_f32_16x16x32_bf16 v[6:9], v[170:173], v[218:221], v[6:9]
	v_mfma_f32_16x16x32_bf16 v[2:5], v[186:189], v[218:221], v[2:5]
	s_barrier
	s_add_i32 s48, 0, 0x18000
	s_add_i32 s49, 0, 0x1c000
	v_add_u32_e32 v162, s48, v156
	v_add_u32_e32 v179, s49, v156
	ds_read_b128 v[94:97], v162
	ds_read_b128 v[134:137], v162 offset:1024
	ds_read_b128 v[158:161], v162 offset:2048
	ds_read_b128 v[162:165], v162 offset:3072
	ds_read_b128 v[166:169], v179
	ds_read_b128 v[170:173], v179 offset:1024
	ds_read_b128 v[174:177], v179 offset:2048
	ds_read_b128 v[186:189], v179 offset:3072
	s_add_u32 s28, s28, 0x40000
	s_addc_u32 s29, s29, 0
	s_mov_b32 m0, s38
	v_lshl_add_u64 v[240:241], s[28:29], 0, v[144:145]
	ds_read_b128 v[190:193], v157 offset:32768
	ds_read_b128 v[194:197], v157 offset:33792
	ds_read_b128 v[198:201], v157 offset:34816
	ds_read_b128 v[202:205], v157 offset:35840
	ds_read_b128 v[206:209], v157 offset:36864
	ds_read_b128 v[210:213], v157 offset:37888
	ds_read_b128 v[214:217], v157 offset:38912
	ds_read_b128 v[218:221], v157 offset:39936
	global_load_lds_dwordx4 v[240:241], off
	v_lshl_add_u64 v[240:241], s[28:29], 0, v[140:141]
	s_mov_b32 m0, s39
	s_nop 0
	global_load_lds_dwordx4 v[240:241], off
	s_waitcnt vmcnt(8) lgkmcnt(0)
	s_barrier
	v_mfma_f32_16x16x32_bf16 v[130:133], v[94:97], v[190:193], v[130:133]
	v_mfma_f32_16x16x32_bf16 v[126:129], v[158:161], v[190:193], v[126:129]
	v_mfma_f32_16x16x32_bf16 v[114:117], v[94:97], v[198:201], v[114:117]
	v_mfma_f32_16x16x32_bf16 v[110:113], v[158:161], v[198:201], v[110:113]
	v_mfma_f32_16x16x32_bf16 v[98:101], v[94:97], v[206:209], v[98:101]
	v_mfma_f32_16x16x32_bf16 v[90:93], v[158:161], v[206:209], v[90:93]
	v_mfma_f32_16x16x32_bf16 v[78:81], v[94:97], v[214:217], v[78:81]
	v_mfma_f32_16x16x32_bf16 v[74:77], v[158:161], v[214:217], v[74:77]
	v_mfma_f32_16x16x32_bf16 v[130:133], v[134:137], v[194:197], v[130:133]
	v_mfma_f32_16x16x32_bf16 v[126:129], v[162:165], v[194:197], v[126:129]
	v_mfma_f32_16x16x32_bf16 v[114:117], v[134:137], v[202:205], v[114:117]
	v_mfma_f32_16x16x32_bf16 v[110:113], v[162:165], v[202:205], v[110:113]
	v_mfma_f32_16x16x32_bf16 v[98:101], v[134:137], v[210:213], v[98:101]
	v_mfma_f32_16x16x32_bf16 v[90:93], v[162:165], v[210:213], v[90:93]
	v_mfma_f32_16x16x32_bf16 v[78:81], v[134:137], v[218:221], v[78:81]
	v_mfma_f32_16x16x32_bf16 v[74:77], v[162:165], v[218:221], v[74:77]
	v_mfma_f32_16x16x32_bf16 v[122:125], v[166:169], v[190:193], v[122:125]
	v_mfma_f32_16x16x32_bf16 v[118:121], v[174:177], v[190:193], v[118:121]
	v_mfma_f32_16x16x32_bf16 v[106:109], v[166:169], v[198:201], v[106:109]
	v_mfma_f32_16x16x32_bf16 v[102:105], v[174:177], v[198:201], v[102:105]
	v_mfma_f32_16x16x32_bf16 v[86:89], v[166:169], v[206:209], v[86:89]
	v_mfma_f32_16x16x32_bf16 v[82:85], v[174:177], v[206:209], v[82:85]
	v_mfma_f32_16x16x32_bf16 v[70:73], v[166:169], v[214:217], v[70:73]
	v_mfma_f32_16x16x32_bf16 v[66:69], v[174:177], v[214:217], v[66:69]
	v_mfma_f32_16x16x32_bf16 v[122:125], v[170:173], v[194:197], v[122:125]
	v_mfma_f32_16x16x32_bf16 v[118:121], v[186:189], v[194:197], v[118:121]
	v_mfma_f32_16x16x32_bf16 v[106:109], v[170:173], v[202:205], v[106:109]
	v_mfma_f32_16x16x32_bf16 v[102:105], v[186:189], v[202:205], v[102:105]
	v_mfma_f32_16x16x32_bf16 v[86:89], v[170:173], v[210:213], v[86:89]
	v_mfma_f32_16x16x32_bf16 v[82:85], v[186:189], v[210:213], v[82:85]
	v_mfma_f32_16x16x32_bf16 v[70:73], v[170:173], v[218:221], v[70:73]
	v_mfma_f32_16x16x32_bf16 v[66:69], v[186:189], v[218:221], v[66:69]
	s_barrier
; #define PG8_STAGE(bufoff, gbase, voff) do { _Pragma("unroll") for (int _i = 0; _i < 2; ++_i) \
;         __builtin_amdgcn_global_load_lds((const unsigned*)((const char*)(gbase) + (voff)[_i]), (PG8_LAS unsigned*)(lds + (bufoff) + ldsw + _i * 8192), 16, 0, 0); } while (0)
; #define PG8_LDA(dst, b, h) do { _Pragma("unroll") for (int m = 0; m < 4; ++m) _Pragma("unroll") for (int k = 0; k < 2; ++k) dst[m][k] = *(const PG8_LAS bf16x8*)(lds + PG8_SA(b, h) + aoff + m * 2048 + k * 1024); } while (0)
; #define PG8_LDB(dst, b, h) do { _Pragma("unroll") for (int n = 0; n < 2; ++n) _Pragma("unroll") for (int k = 0; k < 2; ++k) dst[n][k] = *(const PG8_LAS bf16x8*)(lds + PG8_SB(b, h) + boff + n * 2048 + k * 1024); } while (0)
; #define PG8_MMA(ai, bj, At, Bt) do { __builtin_amdgcn_s_setprio(1); _Pragma("unroll") for (int m = 0; m < 4; ++m) _Pragma("unroll") for (int n = 0; n < 2; ++n) _Pragma("unroll") for (int k = 0; k < 2; ++k) \
;         acc[ai][bj][m][n] = __builtin_amdgcn_mfma_f32_16x16x32_bf16(Bt[n][k], At[m][k], acc[ai][bj][m][n], 0, 0, 0); __builtin_amdgcn_s_setprio(0); } while (0)
; #define PG8_WAIT_V(n) asm volatile("s_waitcnt vmcnt(" #n ")" ::: "memory")
; #define PG8_BAR __builtin_amdgcn_s_barrier()
; template <class Epi, class Sched, bool ALIGN_EPI = false, bool SP2 = false>
; __device__ __forceinline__ void gemm_phase(PG8_LAS unsigned char* lds, const Gemm g, const Sched& S, const Epi& E) {
;     ...
;         for (int t = 0; t < nt; t += 2) {
;             const bool last = (t == nt - 2);
;             const char* a1 = cA + (size_t)(t + 1) * kstep;
;             const char* a2 = last ? nA : cA + (size_t)(t + 2) * kstep; const char* b2 = last ? nB : cB + (size_t)(t + 2) * kstep;
;             const char* a3 = a2 + kstep; const char* b3 = b2 + kstep;
;             if (last && has_next) S.a_ready(nxt);
;             if constexpr (SP2) {
;             PG8_LDB(B0, 0, 0); PG8_LDB(B1, 0, 1); PG8_SCHED; PG8_LDA(At, 0, 0); PG8_STAGE(PG8_SA(1, 1), a1 + hstep, voffA);
;             PG8_WAIT_V(8); PG8_WAIT_L(0); PG8_BAR; PG8_MMA(0, 0, At, B0); PG8_MMA(0, 1, At, B1); PG8_BAR; PG8_SCHED;
;     ...
;             PG8_LDA(At, 1, 1); PG8_STAGE(PG8_SB(1, 0), b3, voffB); PG8_STAGE(PG8_SB(1, 1), b3 + hstep, voffB); PG8_STAGE(PG8_SA(1, 0), a3, voffA);
;             PG8_WAIT_V(8); PG8_WAIT_L(0); PG8_BAR; PG8_MMA(1, 0, At, B0); PG8_MMA(1, 1, At, B1); PG8_BAR; PG8_SCHED;
	s_add_i32 s28, s48, s35
	v_lshl_add_u64 v[154:155], v[154:155], 0, s[80:81]
	s_mov_b32 m0, s28
	ds_read_b128 v[190:193], v157 offset:49152
	ds_read_b128 v[194:197], v157 offset:50176
	ds_read_b128 v[198:201], v157 offset:51200
	ds_read_b128 v[202:205], v157 offset:52224
	ds_read_b128 v[206:209], v157 offset:53248
	ds_read_b128 v[210:213], v157 offset:54272
	ds_read_b128 v[214:217], v157 offset:55296
	ds_read_b128 v[218:221], v157 offset:56320
	global_load_lds_dwordx4 v[154:155], off
	s_add_i32 m0, s28, 0x2000
	s_add_u32 s26, s26, 0x40080
	v_lshl_add_u64 v[154:155], v[180:181], 0, s[80:81]
	s_addc_u32 s27, s27, 0
	s_add_i32 s28, s49, s35
	global_load_lds_dwordx4 v[154:155], off
	v_lshl_add_u64 v[154:155], s[26:27], 0, v[142:143]
	s_mov_b32 m0, s28
	s_nop 0
	global_load_lds_dwordx4 v[154:155], off
	v_lshl_add_u64 v[154:155], s[26:27], 0, v[138:139]
	s_add_i32 m0, s28, 0x2000
	s_nop 0
	global_load_lds_dwordx4 v[154:155], off
	v_lshl_add_u64 v[154:155], v[182:183], 0, s[80:81]
	s_mov_b32 m0, s40
	s_nop 0
	global_load_lds_dwordx4 v[154:155], off
	v_lshl_add_u64 v[154:155], v[222:223], 0, s[80:81]
	s_mov_b32 m0, s41
	s_nop 0
	global_load_lds_dwordx4 v[154:155], off
	s_waitcnt vmcnt(8) lgkmcnt(0)
	s_barrier
	v_mfma_f32_16x16x32_bf16 v[62:65], v[94:97], v[190:193], v[62:65]
	v_mfma_f32_16x16x32_bf16 v[58:61], v[158:161], v[190:193], v[58:61]
	v_mfma_f32_16x16x32_bf16 v[50:53], v[94:97], v[198:201], v[50:53]
	v_mfma_f32_16x16x32_bf16 v[42:45], v[158:161], v[198:201], v[42:45]
	v_mfma_f32_16x16x32_bf16 v[34:37], v[94:97], v[206:209], v[34:37]
	v_mfma_f32_16x16x32_bf16 v[26:29], v[158:161], v[206:209], v[26:29]
	v_mfma_f32_16x16x32_bf16 v[18:21], v[94:97], v[214:217], v[18:21]
	v_mfma_f32_16x16x32_bf16 v[10:13], v[158:161], v[214:217], v[10:13]
	v_mfma_f32_16x16x32_bf16 v[62:65], v[134:137], v[194:197], v[62:65]
	v_mfma_f32_16x16x32_bf16 v[58:61], v[162:165], v[194:197], v[58:61]
	v_mfma_f32_16x16x32_bf16 v[50:53], v[134:137], v[202:205], v[50:53]
	v_mfma_f32_16x16x32_bf16 v[42:45], v[162:165], v[202:205], v[42:45]
	v_mfma_f32_16x16x32_bf16 v[34:37], v[134:137], v[210:213], v[34:37]
	v_mfma_f32_16x16x32_bf16 v[26:29], v[162:165], v[210:213], v[26:29]
	v_mfma_f32_16x16x32_bf16 v[18:21], v[134:137], v[218:221], v[18:21]
	v_mfma_f32_16x16x32_bf16 v[10:13], v[162:165], v[218:221], v[10:13]
	v_mfma_f32_16x16x32_bf16 v[54:57], v[166:169], v[190:193], v[54:57]
	v_mfma_f32_16x16x32_bf16 v[46:49], v[174:177], v[190:193], v[46:49]
	v_mfma_f32_16x16x32_bf16 v[38:41], v[166:169], v[198:201], v[38:41]
	v_mfma_f32_16x16x32_bf16 v[30:33], v[174:177], v[198:201], v[30:33]
	v_mfma_f32_16x16x32_bf16 v[22:25], v[166:169], v[206:209], v[22:25]
	v_mfma_f32_16x16x32_bf16 v[14:17], v[174:177], v[206:209], v[14:17]
	v_mfma_f32_16x16x32_bf16 v[6:9], v[166:169], v[214:217], v[6:9]
	v_mfma_f32_16x16x32_bf16 v[2:5], v[174:177], v[214:217], v[2:5]
	v_mfma_f32_16x16x32_bf16 v[54:57], v[170:173], v[194:197], v[54:57]
	v_mfma_f32_16x16x32_bf16 v[46:49], v[186:189], v[194:197], v[46:49]
	v_mfma_f32_16x16x32_bf16 v[38:41], v[170:173], v[202:205], v[38:41]
	v_mfma_f32_16x16x32_bf16 v[30:33], v[186:189], v[202:205], v[30:33]
	v_mfma_f32_16x16x32_bf16 v[22:25], v[170:173], v[210:213], v[22:25]
	v_mfma_f32_16x16x32_bf16 v[14:17], v[186:189], v[210:213], v[14:17]
	v_mfma_f32_16x16x32_bf16 v[6:9], v[170:173], v[218:221], v[6:9]
	v_mfma_f32_16x16x32_bf16 v[2:5], v[186:189], v[218:221], v[2:5]
	s_barrier
	s_add_i32 s47, s47, 2
	s_add_u32 s24, s24, 0x100
	s_addc_u32 s25, s25, 0
	s_add_u32 s45, s45, 0x100
	s_addc_u32 s46, s46, 0
	s_cmp_gt_u32 s47, 13
	s_branch .LBB0_301
.LBB0_301:
	s_add_u32 s26, s24, 0xfffc0080
	s_addc_u32 s27, s25, -1
	s_add_i32 s48, 0, 0x10000
	s_cmp_eq_u32 s47, 12
	s_cselect_b32 s29, s13, s27
	s_cselect_b32 s28, s21, s26
	v_add_u32_e32 v154, s48, v156
	s_cselect_b32 s27, s11, s46
	s_cselect_b32 s26, s44, s45
	s_add_i32 s50, 0, 0x14000
	ds_read_b128 v[94:97], v154
	ds_read_b128 v[134:137], v154 offset:1024
	ds_read_b128 v[158:161], v154 offset:2048
	ds_read_b128 v[162:165], v154 offset:3072
	v_add_u32_e32 v154, s50, v156
	ds_read_b128 v[166:169], v154
	ds_read_b128 v[170:173], v154 offset:1024
	ds_read_b128 v[174:177], v154 offset:2048
	ds_read_b128 v[186:189], v154 offset:3072
	v_lshl_add_u64 v[154:155], s[24:25], 0, v[150:151]
	s_add_i32 m0, s23, 0xc000
	ds_read_b128 v[190:193], v157
	ds_read_b128 v[194:197], v157 offset:1024
	ds_read_b128 v[198:201], v157 offset:2048
	ds_read_b128 v[202:205], v157 offset:3072
	ds_read_b128 v[206:209], v157 offset:4096
	ds_read_b128 v[210:213], v157 offset:5120
	ds_read_b128 v[214:217], v157 offset:6144
	ds_read_b128 v[218:221], v157 offset:7168
	global_load_lds_dwordx4 v[154:155], off
	v_lshl_add_u64 v[154:155], s[24:25], 0, v[152:153]
	s_add_i32 m0, s23, 0xe000
	s_nop 0
	global_load_lds_dwordx4 v[154:155], off
	s_waitcnt vmcnt(8) lgkmcnt(0)
	s_barrier
; #define PG8_STAGE(bufoff, gbase, voff) do { _Pragma("unroll") for (int _i = 0; _i < 2; ++_i) \
;         __builtin_amdgcn_global_load_lds((const unsigned*)((const char*)(gbase) + (voff)[_i]), (PG8_LAS unsigned*)(lds + (bufoff) + ldsw + _i * 8192), 16, 0, 0); } while (0)
; #define PG8_LDA(dst, b, h) do { _Pragma("unroll") for (int m = 0; m < 4; ++m) _Pragma("unroll") for (int k = 0; k < 2; ++k) dst[m][k] = *(const PG8_LAS bf16x8*)(lds + PG8_SA(b, h) + aoff + m * 2048 + k * 1024); } while (0)
; #define PG8_LDB(dst, b, h) do { _Pragma("unroll") for (int n = 0; n < 2; ++n) _Pragma("unroll") for (int k = 0; k < 2; ++k) dst[n][k] = *(const PG8_LAS bf16x8*)(lds + PG8_SB(b, h) + boff + n * 2048 + k * 1024); } while (0)
; #define PG8_MMA(ai, bj, At, Bt) do { __builtin_amdgcn_s_setprio(1); _Pragma("unroll") for (int m = 0; m < 4; ++m) _Pragma("unroll") for (int n = 0; n < 2; ++n) _Pragma("unroll") for (int k = 0; k < 2; ++k) \
;         acc[ai][bj][m][n] = __builtin_amdgcn_mfma_f32_16x16x32_bf16(Bt[n][k], At[m][k], acc[ai][bj][m][n], 0, 0, 0); __builtin_amdgcn_s_setprio(0); } while (0)
; #define PG8_WAIT_V(n) asm volatile("s_waitcnt vmcnt(" #n ")" ::: "memory")
; #define PG8_WAIT_L(n) asm volatile("s_waitcnt lgkmcnt(" #n ")" ::: "memory")
; #define PG8_BAR __builtin_amdgcn_s_barrier()
; #define PG8_SCHED __builtin_amdgcn_sched_barrier(0)
; template <class Epi, class Sched, bool ALIGN_EPI = false, bool SP2 = false>
; __device__ __forceinline__ void gemm_phase(PG8_LAS unsigned char* lds, const Gemm g, const Sched& S, const Epi& E) {
;     ...
;             PG8_LDB(B0, 0, 0); PG8_LDB(B1, 0, 1); PG8_SCHED; PG8_LDA(At, 0, 0); PG8_STAGE(PG8_SA(1, 1), a1 + hstep, voffA);
;             PG8_WAIT_V(8); PG8_WAIT_L(0); PG8_BAR; PG8_MMA(0, 0, At, B0); PG8_MMA(0, 1, At, B1); PG8_BAR; PG8_SCHED;
;             PG8_LDA(At, 0, 1); PG8_STAGE(PG8_SB(0, 0), b2, voffB); PG8_STAGE(PG8_SB(0, 1), b2 + hstep, voffB); PG8_STAGE(PG8_SA(0, 0), a2, voffA);
;             PG8_WAIT_V(8); PG8_WAIT_L(0); PG8_BAR; PG8_MMA(1, 0, At, B0); PG8_MMA(1, 1, At, B1); PG8_BAR; PG8_SCHED;
	v_mfma_f32_16x16x32_bf16 v[130:133], v[94:97], v[190:193], v[130:133]
	v_mfma_f32_16x16x32_bf16 v[126:129], v[158:161], v[190:193], v[126:129]
	v_mfma_f32_16x16x32_bf16 v[114:117], v[94:97], v[198:201], v[114:117]
	v_mfma_f32_16x16x32_bf16 v[110:113], v[158:161], v[198:201], v[110:113]
	v_mfma_f32_16x16x32_bf16 v[98:101], v[94:97], v[206:209], v[98:101]
	v_mfma_f32_16x16x32_bf16 v[90:93], v[158:161], v[206:209], v[90:93]
	v_mfma_f32_16x16x32_bf16 v[78:81], v[94:97], v[214:217], v[78:81]
	v_mfma_f32_16x16x32_bf16 v[74:77], v[158:161], v[214:217], v[74:77]
	v_mfma_f32_16x16x32_bf16 v[130:133], v[134:137], v[194:197], v[130:133]
	v_mfma_f32_16x16x32_bf16 v[126:129], v[162:165], v[194:197], v[126:129]
	v_mfma_f32_16x16x32_bf16 v[114:117], v[134:137], v[202:205], v[114:117]
	v_mfma_f32_16x16x32_bf16 v[110:113], v[162:165], v[202:205], v[110:113]
	v_mfma_f32_16x16x32_bf16 v[98:101], v[134:137], v[210:213], v[98:101]
	v_mfma_f32_16x16x32_bf16 v[90:93], v[162:165], v[210:213], v[90:93]
	v_mfma_f32_16x16x32_bf16 v[78:81], v[134:137], v[218:221], v[78:81]
	v_mfma_f32_16x16x32_bf16 v[74:77], v[162:165], v[218:221], v[74:77]
	v_mfma_f32_16x16x32_bf16 v[122:125], v[166:169], v[190:193], v[122:125]
	v_mfma_f32_16x16x32_bf16 v[118:121], v[174:177], v[190:193], v[118:121]
	v_mfma_f32_16x16x32_bf16 v[106:109], v[166:169], v[198:201], v[106:109]
	v_mfma_f32_16x16x32_bf16 v[102:105], v[174:177], v[198:201], v[102:105]
	v_mfma_f32_16x16x32_bf16 v[86:89], v[166:169], v[206:209], v[86:89]
	v_mfma_f32_16x16x32_bf16 v[82:85], v[174:177], v[206:209], v[82:85]
	v_mfma_f32_16x16x32_bf16 v[70:73], v[166:169], v[214:217], v[70:73]
	v_mfma_f32_16x16x32_bf16 v[66:69], v[174:177], v[214:217], v[66:69]
	v_mfma_f32_16x16x32_bf16 v[122:125], v[170:173], v[194:197], v[122:125]
	v_mfma_f32_16x16x32_bf16 v[118:121], v[186:189], v[194:197], v[118:121]
	v_mfma_f32_16x16x32_bf16 v[106:109], v[170:173], v[202:205], v[106:109]
	v_mfma_f32_16x16x32_bf16 v[102:105], v[186:189], v[202:205], v[102:105]
	v_mfma_f32_16x16x32_bf16 v[86:89], v[170:173], v[210:213], v[86:89]
	v_mfma_f32_16x16x32_bf16 v[82:85], v[186:189], v[210:213], v[82:85]
	v_mfma_f32_16x16x32_bf16 v[70:73], v[170:173], v[218:221], v[70:73]
	v_mfma_f32_16x16x32_bf16 v[66:69], v[186:189], v[218:221], v[66:69]
	s_barrier
	s_add_i32 s48, s48, s35
	v_lshl_add_u64 v[154:155], s[26:27], 0, v[142:143]
	s_mov_b32 m0, s48
	ds_read_b128 v[190:193], v157 offset:16384
	ds_read_b128 v[194:197], v157 offset:17408
	ds_read_b128 v[198:201], v157 offset:18432
	ds_read_b128 v[202:205], v157 offset:19456
	ds_read_b128 v[206:209], v157 offset:20480
	ds_read_b128 v[210:213], v157 offset:21504
	ds_read_b128 v[214:217], v157 offset:22528
	ds_read_b128 v[218:221], v157 offset:23552
	global_load_lds_dwordx4 v[154:155], off
	s_add_i32 m0, s48, 0x2000
	s_add_u32 s48, s26, 0x40000
	v_lshl_add_u64 v[180:181], s[26:27], 0, v[138:139]
	s_addc_u32 s49, s27, 0
	s_add_i32 s50, s50, s35
	global_load_lds_dwordx4 v[180:181], off
	v_lshl_add_u64 v[182:183], s[48:49], 0, v[142:143]
	s_mov_b32 m0, s50
	v_lshl_add_u64 v[222:223], s[28:29], 0, v[140:141]
	global_load_lds_dwordx4 v[182:183], off
	v_lshl_add_u64 v[182:183], s[48:49], 0, v[138:139]
	s_add_i32 m0, s50, 0x2000
	s_nop 0
	global_load_lds_dwordx4 v[182:183], off
	v_lshl_add_u64 v[182:183], s[28:29], 0, v[144:145]
	s_mov_b32 m0, s23
	s_nop 0
	global_load_lds_dwordx4 v[182:183], off
	s_mov_b32 m0, s37
	s_nop 0
	global_load_lds_dwordx4 v[222:223], off
	s_waitcnt vmcnt(8) lgkmcnt(0)
	s_barrier
	v_mfma_f32_16x16x32_bf16 v[62:65], v[94:97], v[190:193], v[62:65]
	v_mfma_f32_16x16x32_bf16 v[58:61], v[158:161], v[190:193], v[58:61]
	v_mfma_f32_16x16x32_bf16 v[50:53], v[94:97], v[198:201], v[50:53]
	v_mfma_f32_16x16x32_bf16 v[42:45], v[158:161], v[198:201], v[42:45]
	v_mfma_f32_16x16x32_bf16 v[34:37], v[94:97], v[206:209], v[34:37]
	v_mfma_f32_16x16x32_bf16 v[26:29], v[158:161], v[206:209], v[26:29]
	v_mfma_f32_16x16x32_bf16 v[18:21], v[94:97], v[214:217], v[18:21]
	v_mfma_f32_16x16x32_bf16 v[10:13], v[158:161], v[214:217], v[10:13]
	v_mfma_f32_16x16x32_bf16 v[62:65], v[134:137], v[194:197], v[62:65]
	v_mfma_f32_16x16x32_bf16 v[58:61], v[162:165], v[194:197], v[58:61]
	v_mfma_f32_16x16x32_bf16 v[50:53], v[134:137], v[202:205], v[50:53]
	v_mfma_f32_16x16x32_bf16 v[42:45], v[162:165], v[202:205], v[42:45]
	v_mfma_f32_16x16x32_bf16 v[34:37], v[134:137], v[210:213], v[34:37]
	v_mfma_f32_16x16x32_bf16 v[26:29], v[162:165], v[210:213], v[26:29]
	v_mfma_f32_16x16x32_bf16 v[18:21], v[134:137], v[218:221], v[18:21]
	v_mfma_f32_16x16x32_bf16 v[10:13], v[162:165], v[218:221], v[10:13]
	v_mfma_f32_16x16x32_bf16 v[54:57], v[166:169], v[190:193], v[54:57]
	v_mfma_f32_16x16x32_bf16 v[46:49], v[174:177], v[190:193], v[46:49]
	v_mfma_f32_16x16x32_bf16 v[38:41], v[166:169], v[198:201], v[38:41]
	v_mfma_f32_16x16x32_bf16 v[30:33], v[174:177], v[198:201], v[30:33]
	v_mfma_f32_16x16x32_bf16 v[22:25], v[166:169], v[206:209], v[22:25]
	v_mfma_f32_16x16x32_bf16 v[14:17], v[174:177], v[206:209], v[14:17]
	v_mfma_f32_16x16x32_bf16 v[6:9], v[166:169], v[214:217], v[6:9]
	v_mfma_f32_16x16x32_bf16 v[2:5], v[174:177], v[214:217], v[2:5]
	v_mfma_f32_16x16x32_bf16 v[54:57], v[170:173], v[194:197], v[54:57]
	v_mfma_f32_16x16x32_bf16 v[46:49], v[186:189], v[194:197], v[46:49]
	v_mfma_f32_16x16x32_bf16 v[38:41], v[170:173], v[202:205], v[38:41]
	v_mfma_f32_16x16x32_bf16 v[30:33], v[186:189], v[202:205], v[30:33]
	v_mfma_f32_16x16x32_bf16 v[22:25], v[170:173], v[210:213], v[22:25]
	v_mfma_f32_16x16x32_bf16 v[14:17], v[186:189], v[210:213], v[14:17]
	v_mfma_f32_16x16x32_bf16 v[6:9], v[170:173], v[218:221], v[6:9]
	v_mfma_f32_16x16x32_bf16 v[2:5], v[186:189], v[218:221], v[2:5]
	s_barrier
; #define PG8_STAGE(bufoff, gbase, voff) do { _Pragma("unroll") for (int _i = 0; _i < 2; ++_i) \
;         __builtin_amdgcn_global_load_lds((const unsigned*)((const char*)(gbase) + (voff)[_i]), (PG8_LAS unsigned*)(lds + (bufoff) + ldsw + _i * 8192), 16, 0, 0); } while (0)
; #define PG8_LDA(dst, b, h) do { _Pragma("unroll") for (int m = 0; m < 4; ++m) _Pragma("unroll") for (int k = 0; k < 2; ++k) dst[m][k] = *(const PG8_LAS bf16x8*)(lds + PG8_SA(b, h) + aoff + m * 2048 + k * 1024); } while (0)
; #define PG8_LDB(dst, b, h) do { _Pragma("unroll") for (int n = 0; n < 2; ++n) _Pragma("unroll") for (int k = 0; k < 2; ++k) dst[n][k] = *(const PG8_LAS bf16x8*)(lds + PG8_SB(b, h) + boff + n * 2048 + k * 1024); } while (0)
; #define PG8_MMA(ai, bj, At, Bt) do { __builtin_amdgcn_s_setprio(1); _Pragma("unroll") for (int m = 0; m < 4; ++m) _Pragma("unroll") for (int n = 0; n < 2; ++n) _Pragma("unroll") for (int k = 0; k < 2; ++k) \
;         acc[ai][bj][m][n] = __builtin_amdgcn_mfma_f32_16x16x32_bf16(Bt[n][k], At[m][k], acc[ai][bj][m][n], 0, 0, 0); __builtin_amdgcn_s_setprio(0); } while (0)
; #define PG8_WAIT_V(n) asm volatile("s_waitcnt vmcnt(" #n ")" ::: "memory")
; #define PG8_WAIT_L(n) asm volatile("s_waitcnt lgkmcnt(" #n ")" ::: "memory")
; #define PG8_BAR __builtin_amdgcn_s_barrier()
; #define PG8_SCHED __builtin_amdgcn_sched_barrier(0)
; template <class Epi, class Sched, bool ALIGN_EPI = false, bool SP2 = false>
; __device__ __forceinline__ void gemm_phase(PG8_LAS unsigned char* lds, const Gemm g, const Sched& S, const Epi& E) {
;     ...
;             PG8_LDB(B0, 1, 0); PG8_LDB(B1, 1, 1); PG8_SCHED; PG8_LDA(At, 1, 0); PG8_STAGE(PG8_SA(0, 1), a2 + hstep, voffA);
;             PG8_WAIT_V(8); PG8_WAIT_L(0); PG8_BAR; PG8_MMA(0, 0, At, B0); PG8_MMA(0, 1, At, B1); PG8_BAR; PG8_SCHED;
;             PG8_LDA(At, 1, 1); PG8_STAGE(PG8_SB(1, 0), b3, voffB); PG8_STAGE(PG8_SB(1, 1), b3 + hstep, voffB); PG8_STAGE(PG8_SA(1, 0), a3, voffA);
;             PG8_WAIT_V(8); PG8_WAIT_L(0); PG8_BAR; PG8_MMA(1, 0, At, B0); PG8_MMA(1, 1, At, B1); PG8_BAR; PG8_SCHED;
;     ...
;         if constexpr (ALIGN_EPI) { if (wr == 0) PG8_BAR; }
	s_add_i32 s48, 0, 0x18000
	s_add_i32 s49, 0, 0x1c000
	v_add_u32_e32 v162, s48, v156
	v_add_u32_e32 v179, s49, v156
	ds_read_b128 v[94:97], v162
	ds_read_b128 v[134:137], v162 offset:1024
	ds_read_b128 v[158:161], v162 offset:2048
	ds_read_b128 v[162:165], v162 offset:3072
	ds_read_b128 v[166:169], v179
	ds_read_b128 v[170:173], v179 offset:1024
	ds_read_b128 v[174:177], v179 offset:2048
	ds_read_b128 v[186:189], v179 offset:3072
	s_add_u32 s28, s28, 0x40000
	s_addc_u32 s29, s29, 0
	s_mov_b32 m0, s38
	v_lshl_add_u64 v[240:241], s[28:29], 0, v[144:145]
	ds_read_b128 v[190:193], v157 offset:32768
	ds_read_b128 v[194:197], v157 offset:33792
	ds_read_b128 v[198:201], v157 offset:34816
	ds_read_b128 v[202:205], v157 offset:35840
	ds_read_b128 v[206:209], v157 offset:36864
	ds_read_b128 v[210:213], v157 offset:37888
	ds_read_b128 v[214:217], v157 offset:38912
	ds_read_b128 v[218:221], v157 offset:39936
	global_load_lds_dwordx4 v[240:241], off
	v_lshl_add_u64 v[240:241], s[28:29], 0, v[140:141]
	s_mov_b32 m0, s39
	s_nop 0
	global_load_lds_dwordx4 v[240:241], off
	s_waitcnt vmcnt(8) lgkmcnt(0)
	s_barrier
	v_mfma_f32_16x16x32_bf16 v[130:133], v[94:97], v[190:193], v[130:133]
	v_mfma_f32_16x16x32_bf16 v[126:129], v[158:161], v[190:193], v[126:129]
	v_mfma_f32_16x16x32_bf16 v[114:117], v[94:97], v[198:201], v[114:117]
	v_mfma_f32_16x16x32_bf16 v[110:113], v[158:161], v[198:201], v[110:113]
	v_mfma_f32_16x16x32_bf16 v[98:101], v[94:97], v[206:209], v[98:101]
	v_mfma_f32_16x16x32_bf16 v[90:93], v[158:161], v[206:209], v[90:93]
	v_mfma_f32_16x16x32_bf16 v[78:81], v[94:97], v[214:217], v[78:81]
	v_mfma_f32_16x16x32_bf16 v[74:77], v[158:161], v[214:217], v[74:77]
	v_mfma_f32_16x16x32_bf16 v[130:133], v[134:137], v[194:197], v[130:133]
	v_mfma_f32_16x16x32_bf16 v[126:129], v[162:165], v[194:197], v[126:129]
	v_mfma_f32_16x16x32_bf16 v[114:117], v[134:137], v[202:205], v[114:117]
	v_mfma_f32_16x16x32_bf16 v[110:113], v[162:165], v[202:205], v[110:113]
	v_mfma_f32_16x16x32_bf16 v[98:101], v[134:137], v[210:213], v[98:101]
	v_mfma_f32_16x16x32_bf16 v[90:93], v[162:165], v[210:213], v[90:93]
	v_mfma_f32_16x16x32_bf16 v[78:81], v[134:137], v[218:221], v[78:81]
	v_mfma_f32_16x16x32_bf16 v[74:77], v[162:165], v[218:221], v[74:77]
	v_mfma_f32_16x16x32_bf16 v[122:125], v[166:169], v[190:193], v[122:125]
	v_mfma_f32_16x16x32_bf16 v[118:121], v[174:177], v[190:193], v[118:121]
	v_mfma_f32_16x16x32_bf16 v[106:109], v[166:169], v[198:201], v[106:109]
	v_mfma_f32_16x16x32_bf16 v[102:105], v[174:177], v[198:201], v[102:105]
	v_mfma_f32_16x16x32_bf16 v[86:89], v[166:169], v[206:209], v[86:89]
	v_mfma_f32_16x16x32_bf16 v[82:85], v[174:177], v[206:209], v[82:85]
	v_mfma_f32_16x16x32_bf16 v[70:73], v[166:169], v[214:217], v[70:73]
	v_mfma_f32_16x16x32_bf16 v[66:69], v[174:177], v[214:217], v[66:69]
	v_mfma_f32_16x16x32_bf16 v[122:125], v[170:173], v[194:197], v[122:125]
	v_mfma_f32_16x16x32_bf16 v[118:121], v[186:189], v[194:197], v[118:121]
	v_mfma_f32_16x16x32_bf16 v[106:109], v[170:173], v[202:205], v[106:109]
	v_mfma_f32_16x16x32_bf16 v[102:105], v[186:189], v[202:205], v[102:105]
	v_mfma_f32_16x16x32_bf16 v[86:89], v[170:173], v[210:213], v[86:89]
	v_mfma_f32_16x16x32_bf16 v[82:85], v[186:189], v[210:213], v[82:85]
	v_mfma_f32_16x16x32_bf16 v[70:73], v[170:173], v[218:221], v[70:73]
	v_mfma_f32_16x16x32_bf16 v[66:69], v[186:189], v[218:221], v[66:69]
	s_barrier
	s_add_i32 s28, s48, s35
	v_lshl_add_u64 v[154:155], v[154:155], 0, s[80:81]
	s_mov_b32 m0, s28
	ds_read_b128 v[190:193], v157 offset:49152
	ds_read_b128 v[194:197], v157 offset:50176
	ds_read_b128 v[198:201], v157 offset:51200
	ds_read_b128 v[202:205], v157 offset:52224
	ds_read_b128 v[206:209], v157 offset:53248
	ds_read_b128 v[210:213], v157 offset:54272
	ds_read_b128 v[214:217], v157 offset:55296
	ds_read_b128 v[218:221], v157 offset:56320
	global_load_lds_dwordx4 v[154:155], off
	s_add_i32 m0, s28, 0x2000
	s_add_u32 s26, s26, 0x40080
	v_lshl_add_u64 v[154:155], v[180:181], 0, s[80:81]
	s_addc_u32 s27, s27, 0
	s_add_i32 s28, s49, s35
	global_load_lds_dwordx4 v[154:155], off
	v_lshl_add_u64 v[154:155], s[26:27], 0, v[142:143]
	s_mov_b32 m0, s28
	s_nop 0
	global_load_lds_dwordx4 v[154:155], off
	v_lshl_add_u64 v[154:155], s[26:27], 0, v[138:139]
	s_add_i32 m0, s28, 0x2000
	s_nop 0
	global_load_lds_dwordx4 v[154:155], off
	v_lshl_add_u64 v[154:155], v[182:183], 0, s[80:81]
	s_mov_b32 m0, s40
	s_nop 0
	global_load_lds_dwordx4 v[154:155], off
	v_lshl_add_u64 v[154:155], v[222:223], 0, s[80:81]
	s_mov_b32 m0, s41
	s_nop 0
	global_load_lds_dwordx4 v[154:155], off
	s_waitcnt vmcnt(8) lgkmcnt(0)
	s_barrier
	v_mfma_f32_16x16x32_bf16 v[62:65], v[94:97], v[190:193], v[62:65]
	v_mfma_f32_16x16x32_bf16 v[58:61], v[158:161], v[190:193], v[58:61]
	v_mfma_f32_16x16x32_bf16 v[50:53], v[94:97], v[198:201], v[50:53]
	v_mfma_f32_16x16x32_bf16 v[42:45], v[158:161], v[198:201], v[42:45]
	v_mfma_f32_16x16x32_bf16 v[34:37], v[94:97], v[206:209], v[34:37]
	v_mfma_f32_16x16x32_bf16 v[26:29], v[158:161], v[206:209], v[26:29]
	v_mfma_f32_16x16x32_bf16 v[18:21], v[94:97], v[214:217], v[18:21]
	v_mfma_f32_16x16x32_bf16 v[10:13], v[158:161], v[214:217], v[10:13]
	v_mfma_f32_16x16x32_bf16 v[62:65], v[134:137], v[194:197], v[62:65]
	v_mfma_f32_16x16x32_bf16 v[58:61], v[162:165], v[194:197], v[58:61]
	v_mfma_f32_16x16x32_bf16 v[50:53], v[134:137], v[202:205], v[50:53]
	v_mfma_f32_16x16x32_bf16 v[42:45], v[162:165], v[202:205], v[42:45]
	v_mfma_f32_16x16x32_bf16 v[34:37], v[134:137], v[210:213], v[34:37]
	v_mfma_f32_16x16x32_bf16 v[26:29], v[162:165], v[210:213], v[26:29]
	v_mfma_f32_16x16x32_bf16 v[18:21], v[134:137], v[218:221], v[18:21]
	v_mfma_f32_16x16x32_bf16 v[10:13], v[162:165], v[218:221], v[10:13]
	v_mfma_f32_16x16x32_bf16 v[54:57], v[166:169], v[190:193], v[54:57]
	v_mfma_f32_16x16x32_bf16 v[46:49], v[174:177], v[190:193], v[46:49]
	v_mfma_f32_16x16x32_bf16 v[38:41], v[166:169], v[198:201], v[38:41]
	v_mfma_f32_16x16x32_bf16 v[30:33], v[174:177], v[198:201], v[30:33]
	v_mfma_f32_16x16x32_bf16 v[22:25], v[166:169], v[206:209], v[22:25]
	v_mfma_f32_16x16x32_bf16 v[14:17], v[174:177], v[206:209], v[14:17]
	v_mfma_f32_16x16x32_bf16 v[6:9], v[166:169], v[214:217], v[6:9]
	v_mfma_f32_16x16x32_bf16 v[2:5], v[174:177], v[214:217], v[2:5]
	v_mfma_f32_16x16x32_bf16 v[54:57], v[170:173], v[194:197], v[54:57]
	v_mfma_f32_16x16x32_bf16 v[46:49], v[186:189], v[194:197], v[46:49]
	v_mfma_f32_16x16x32_bf16 v[38:41], v[170:173], v[202:205], v[38:41]
	v_mfma_f32_16x16x32_bf16 v[30:33], v[186:189], v[202:205], v[30:33]
	v_mfma_f32_16x16x32_bf16 v[22:25], v[170:173], v[210:213], v[22:25]
	v_mfma_f32_16x16x32_bf16 v[14:17], v[186:189], v[210:213], v[14:17]
	v_mfma_f32_16x16x32_bf16 v[6:9], v[170:173], v[218:221], v[6:9]
	v_mfma_f32_16x16x32_bf16 v[2:5], v[186:189], v[218:221], v[2:5]
	s_barrier
	s_add_i32 s47, s47, 2
	s_add_u32 s24, s24, 0x100
	s_addc_u32 s25, s25, 0
	s_add_u32 s45, s45, 0x100
	s_addc_u32 s46, s46, 0
	s_cmp_gt_u32 s47, 13
	s_cbranch_scc0 .LBB0_301
	s_and_b64 vcc, exec, s[8:9]
	s_cbranch_vccz .LBB0_304
	s_barrier

; #define PG8_STAGE(bufoff, gbase, voff) do { _Pragma("unroll") for (int _i = 0; _i < 2; ++_i) \
;         __builtin_amdgcn_global_load_lds((const unsigned*)((const char*)(gbase) + (voff)[_i]), (PG8_LAS unsigned*)(lds + (bufoff) + ldsw + _i * 8192), 16, 0, 0); } while (0)
; #define PG8_LDA(dst, b, h) do { _Pragma("unroll") for (int m = 0; m < 4; ++m) _Pragma("unroll") for (int k = 0; k < 2; ++k) dst[m][k] = *(const PG8_LAS bf16x8*)(lds + PG8_SA(b, h) + aoff + m * 2048 + k * 1024); } while (0)
; #define PG8_LDB(dst, b, h) do { _Pragma("unroll") for (int n = 0; n < 2; ++n) _Pragma("unroll") for (int k = 0; k < 2; ++k) dst[n][k] = *(const PG8_LAS bf16x8*)(lds + PG8_SB(b, h) + boff + n * 2048 + k * 1024); } while (0)
; #define PG8_WAIT_V(n) asm volatile("s_waitcnt vmcnt(" #n ")" ::: "memory")
; #define PG8_WAIT_L(n) asm volatile("s_waitcnt lgkmcnt(" #n ")" ::: "memory")
; #define PG8_BAR __builtin_amdgcn_s_barrier()
; #define PG8_SCHED __builtin_amdgcn_sched_barrier(0)
; template <class Epi, class Sched, bool ALIGN_EPI = false, bool SP2 = false>
; __device__ __forceinline__ void gemm_phase(PG8_LAS unsigned char* lds, const Gemm g, const Sched& S, const Epi& E) {
;     ...
;         const bool has_next = S.next(ui + 1, nxt);
;         const char* nA = has_next ? (const char*)g.A + (size_t)nxt.pm * tstep : cA; const char* nB = has_next ? (const char*)g.Bt + (size_t)nxt.pn * tstep : cB;
;         for (int t = 0; t < nt; t += 2) {
;             const bool last = (t == nt - 2);
;             const char* a1 = cA + (size_t)(t + 1) * kstep;
;             const char* a2 = last ? nA : cA + (size_t)(t + 2) * kstep; const char* b2 = last ? nB : cB + (size_t)(t + 2) * kstep;
;             const char* a3 = a2 + kstep; const char* b3 = b2 + kstep;
;             if (last && has_next) S.a_ready(nxt);
;             if constexpr (SP2) {
;             PG8_LDB(B0, 0, 0); PG8_LDB(B1, 0, 1); PG8_SCHED; PG8_LDA(At, 0, 0); PG8_STAGE(PG8_SA(1, 1), a1 + hstep, voffA);
;             PG8_WAIT_V(8); PG8_WAIT_L(0); PG8_BAR; PG8_MMA(0, 0, At, B0); PG8_MMA(0, 1, At, B1); PG8_BAR; PG8_SCHED;
;             PG8_LDA(At, 0, 1); PG8_STAGE(PG8_SB(0, 0), b2, voffB); PG8_STAGE(PG8_SB(0, 1), b2 + hstep, voffB); PG8_STAGE(PG8_SA(0, 0), a2, voffA);
;             PG8_WAIT_V(8); PG8_WAIT_L(0); PG8_BAR; PG8_MMA(1, 0, At, B0); PG8_MMA(1, 1, At, B1); PG8_BAR; PG8_SCHED;
.LBB0_317:
	s_ashr_i32 s13, s12, 31
	s_lshl_b64 s[16:17], s[12:13], 19
	s_add_u32 s16, s8, s16
	s_addc_u32 s17, s9, s17
	s_and_b64 s[18:19], s[4:5], exec
	s_cselect_b32 s13, s17, s25
	s_cselect_b32 s21, s16, s24
	s_ashr_i32 s11, s10, 31
	s_lshl_b64 s[18:19], s[10:11], 19
	s_add_u32 s18, s33, s18
	s_addc_u32 s19, s34, s19
	s_and_b64 s[28:29], s[4:5], exec
	s_cselect_b32 s11, s19, s27
	s_cselect_b32 s44, s18, s26
	s_add_u32 s24, s24, 0x40080
	s_addc_u32 s25, s25, 0
	s_add_u32 s45, s26, 0x100
	s_addc_u32 s46, s27, 0
	s_mov_b32 s47, -2
	s_add_u32 s26, s24, 0xfffc0080
	s_addc_u32 s27, s25, -1
	s_add_i32 s48, 0, 0x10000
	s_cmp_eq_u32 s47, 12
	s_cselect_b32 s29, s13, s27
	s_cselect_b32 s28, s21, s26
	v_add_u32_e32 v154, s48, v156
	s_cselect_b32 s27, s11, s46
	s_cselect_b32 s26, s44, s45
	s_add_i32 s50, 0, 0x14000
	ds_read_b128 v[94:97], v154
	ds_read_b128 v[134:137], v154 offset:1024
	ds_read_b128 v[158:161], v154 offset:2048
	ds_read_b128 v[162:165], v154 offset:3072
	v_add_u32_e32 v154, s50, v156
	ds_read_b128 v[166:169], v154
	ds_read_b128 v[170:173], v154 offset:1024
	ds_read_b128 v[174:177], v154 offset:2048
	ds_read_b128 v[186:189], v154 offset:3072
	v_lshl_add_u64 v[154:155], s[24:25], 0, v[150:151]
	s_add_i32 m0, s23, 0xc000
	ds_read_b128 v[190:193], v157
	ds_read_b128 v[194:197], v157 offset:1024
	ds_read_b128 v[198:201], v157 offset:2048
	ds_read_b128 v[202:205], v157 offset:3072
	ds_read_b128 v[206:209], v157 offset:4096
	ds_read_b128 v[210:213], v157 offset:5120
	ds_read_b128 v[214:217], v157 offset:6144
	ds_read_b128 v[218:221], v157 offset:7168
	global_load_lds_dwordx4 v[154:155], off
	v_lshl_add_u64 v[154:155], s[24:25], 0, v[152:153]
	s_add_i32 m0, s23, 0xe000
	s_nop 0
	global_load_lds_dwordx4 v[154:155], off
	s_waitcnt vmcnt(8) lgkmcnt(0)
	s_barrier
	v_mfma_f32_16x16x32_bf16 v[130:133], v[94:97], v[190:193], 0
	v_mfma_f32_16x16x32_bf16 v[126:129], v[158:161], v[190:193], 0
	v_mfma_f32_16x16x32_bf16 v[114:117], v[94:97], v[198:201], 0
	v_mfma_f32_16x16x32_bf16 v[110:113], v[158:161], v[198:201], 0
	v_mfma_f32_16x16x32_bf16 v[98:101], v[94:97], v[206:209], 0
	v_mfma_f32_16x16x32_bf16 v[90:93], v[158:161], v[206:209], 0
	v_mfma_f32_16x16x32_bf16 v[78:81], v[94:97], v[214:217], 0
	v_mfma_f32_16x16x32_bf16 v[74:77], v[158:161], v[214:217], 0
	v_mfma_f32_16x16x32_bf16 v[130:133], v[134:137], v[194:197], v[130:133]
	v_mfma_f32_16x16x32_bf16 v[126:129], v[162:165], v[194:197], v[126:129]
	v_mfma_f32_16x16x32_bf16 v[114:117], v[134:137], v[202:205], v[114:117]
	v_mfma_f32_16x16x32_bf16 v[110:113], v[162:165], v[202:205], v[110:113]
	v_mfma_f32_16x16x32_bf16 v[98:101], v[134:137], v[210:213], v[98:101]
	v_mfma_f32_16x16x32_bf16 v[90:93], v[162:165], v[210:213], v[90:93]
	v_mfma_f32_16x16x32_bf16 v[78:81], v[134:137], v[218:221], v[78:81]
	v_mfma_f32_16x16x32_bf16 v[74:77], v[162:165], v[218:221], v[74:77]
	v_mfma_f32_16x16x32_bf16 v[122:125], v[166:169], v[190:193], 0
	v_mfma_f32_16x16x32_bf16 v[118:121], v[174:177], v[190:193], 0
	v_mfma_f32_16x16x32_bf16 v[106:109], v[166:169], v[198:201], 0
	v_mfma_f32_16x16x32_bf16 v[102:105], v[174:177], v[198:201], 0
	v_mfma_f32_16x16x32_bf16 v[86:89], v[166:169], v[206:209], 0
	v_mfma_f32_16x16x32_bf16 v[82:85], v[174:177], v[206:209], 0
	v_mfma_f32_16x16x32_bf16 v[70:73], v[166:169], v[214:217], 0
	v_mfma_f32_16x16x32_bf16 v[66:69], v[174:177], v[214:217], 0
	v_mfma_f32_16x16x32_bf16 v[122:125], v[170:173], v[194:197], v[122:125]
	v_mfma_f32_16x16x32_bf16 v[118:121], v[186:189], v[194:197], v[118:121]
	v_mfma_f32_16x16x32_bf16 v[106:109], v[170:173], v[202:205], v[106:109]
	v_mfma_f32_16x16x32_bf16 v[102:105], v[186:189], v[202:205], v[102:105]
	v_mfma_f32_16x16x32_bf16 v[86:89], v[170:173], v[210:213], v[86:89]
	v_mfma_f32_16x16x32_bf16 v[82:85], v[186:189], v[210:213], v[82:85]
	v_mfma_f32_16x16x32_bf16 v[70:73], v[170:173], v[218:221], v[70:73]
	v_mfma_f32_16x16x32_bf16 v[66:69], v[186:189], v[218:221], v[66:69]
	s_barrier
	s_add_i32 s48, s48, s35
	v_lshl_add_u64 v[154:155], s[26:27], 0, v[142:143]
	s_mov_b32 m0, s48
	ds_read_b128 v[190:193], v157 offset:16384
	ds_read_b128 v[194:197], v157 offset:17408
	ds_read_b128 v[198:201], v157 offset:18432
	ds_read_b128 v[202:205], v157 offset:19456
	ds_read_b128 v[206:209], v157 offset:20480
	ds_read_b128 v[210:213], v157 offset:21504
	ds_read_b128 v[214:217], v157 offset:22528
	ds_read_b128 v[218:221], v157 offset:23552
	global_load_lds_dwordx4 v[154:155], off
	s_add_i32 m0, s48, 0x2000
	s_add_u32 s48, s26, 0x40000
	v_lshl_add_u64 v[180:181], s[26:27], 0, v[138:139]
	s_addc_u32 s49, s27, 0
	s_add_i32 s50, s50, s35
	global_load_lds_dwordx4 v[180:181], off
	v_lshl_add_u64 v[182:183], s[48:49], 0, v[142:143]
	s_mov_b32 m0, s50
	v_lshl_add_u64 v[222:223], s[28:29], 0, v[140:141]
	global_load_lds_dwordx4 v[182:183], off
	v_lshl_add_u64 v[182:183], s[48:49], 0, v[138:139]
	s_add_i32 m0, s50, 0x2000
	s_nop 0
	global_load_lds_dwordx4 v[182:183], off
	v_lshl_add_u64 v[182:183], s[28:29], 0, v[144:145]
	s_mov_b32 m0, s23
	s_nop 0
	global_load_lds_dwordx4 v[182:183], off
	s_mov_b32 m0, s37
	s_nop 0
	global_load_lds_dwordx4 v[222:223], off
	s_waitcnt vmcnt(8) lgkmcnt(0)
	s_barrier
; #define PG8_STAGE(bufoff, gbase, voff) do { _Pragma("unroll") for (int _i = 0; _i < 2; ++_i) \
;         __builtin_amdgcn_global_load_lds((const unsigned*)((const char*)(gbase) + (voff)[_i]), (PG8_LAS unsigned*)(lds + (bufoff) + ldsw + _i * 8192), 16, 0, 0); } while (0)
; #define PG8_LDA(dst, b, h) do { _Pragma("unroll") for (int m = 0; m < 4; ++m) _Pragma("unroll") for (int k = 0; k < 2; ++k) dst[m][k] = *(const PG8_LAS bf16x8*)(lds + PG8_SA(b, h) + aoff + m * 2048 + k * 1024); } while (0)
; #define PG8_LDB(dst, b, h) do { _Pragma("unroll") for (int n = 0; n < 2; ++n) _Pragma("unroll") for (int k = 0; k < 2; ++k) dst[n][k] = *(const PG8_LAS bf16x8*)(lds + PG8_SB(b, h) + boff + n * 2048 + k * 1024); } while (0)
; #define PG8_MMA(ai, bj, At, Bt) do { __builtin_amdgcn_s_setprio(1); _Pragma("unroll") for (int m = 0; m < 4; ++m) _Pragma("unroll") for (int n = 0; n < 2; ++n) _Pragma("unroll") for (int k = 0; k < 2; ++k) \
;         acc[ai][bj][m][n] = __builtin_amdgcn_mfma_f32_16x16x32_bf16(Bt[n][k], At[m][k], acc[ai][bj][m][n], 0, 0, 0); __builtin_amdgcn_s_setprio(0); } while (0)
; #define PG8_WAIT_V(n) asm volatile("s_waitcnt vmcnt(" #n ")" ::: "memory")
; #define PG8_WAIT_L(n) asm volatile("s_waitcnt lgkmcnt(" #n ")" ::: "memory")
; #define PG8_BAR __builtin_amdgcn_s_barrier()
; #define PG8_SCHED __builtin_amdgcn_sched_barrier(0)
; template <class Epi, class Sched, bool ALIGN_EPI = false, bool SP2 = false>
; __device__ __forceinline__ void gemm_phase(PG8_LAS unsigned char* lds, const Gemm g, const Sched& S, const Epi& E) {
;     ...
;             PG8_LDA(At, 0, 1); PG8_STAGE(PG8_SB(0, 0), b2, voffB); PG8_STAGE(PG8_SB(0, 1), b2 + hstep, voffB); PG8_STAGE(PG8_SA(0, 0), a2, voffA);
;             PG8_WAIT_V(8); PG8_WAIT_L(0); PG8_BAR; PG8_MMA(1, 0, At, B0); PG8_MMA(1, 1, At, B1); PG8_BAR; PG8_SCHED;
;             PG8_LDB(B0, 1, 0); PG8_LDB(B1, 1, 1); PG8_SCHED; PG8_LDA(At, 1, 0); PG8_STAGE(PG8_SA(0, 1), a2 + hstep, voffA);
;             PG8_WAIT_V(8); PG8_WAIT_L(0); PG8_BAR; PG8_MMA(0, 0, At, B0); PG8_MMA(0, 1, At, B1); PG8_BAR; PG8_SCHED;
	v_mfma_f32_16x16x32_bf16 v[62:65], v[94:97], v[190:193], 0
	v_mfma_f32_16x16x32_bf16 v[58:61], v[158:161], v[190:193], 0
	v_mfma_f32_16x16x32_bf16 v[50:53], v[94:97], v[198:201], 0
	v_mfma_f32_16x16x32_bf16 v[42:45], v[158:161], v[198:201], 0
	v_mfma_f32_16x16x32_bf16 v[34:37], v[94:97], v[206:209], 0
	v_mfma_f32_16x16x32_bf16 v[26:29], v[158:161], v[206:209], 0
	v_mfma_f32_16x16x32_bf16 v[18:21], v[94:97], v[214:217], 0
	v_mfma_f32_16x16x32_bf16 v[10:13], v[158:161], v[214:217], 0
	v_mfma_f32_16x16x32_bf16 v[62:65], v[134:137], v[194:197], v[62:65]
	v_mfma_f32_16x16x32_bf16 v[58:61], v[162:165], v[194:197], v[58:61]
	v_mfma_f32_16x16x32_bf16 v[50:53], v[134:137], v[202:205], v[50:53]
	v_mfma_f32_16x16x32_bf16 v[42:45], v[162:165], v[202:205], v[42:45]
	v_mfma_f32_16x16x32_bf16 v[34:37], v[134:137], v[210:213], v[34:37]
	v_mfma_f32_16x16x32_bf16 v[26:29], v[162:165], v[210:213], v[26:29]
	v_mfma_f32_16x16x32_bf16 v[18:21], v[134:137], v[218:221], v[18:21]
	v_mfma_f32_16x16x32_bf16 v[10:13], v[162:165], v[218:221], v[10:13]
	v_mfma_f32_16x16x32_bf16 v[54:57], v[166:169], v[190:193], 0
	v_mfma_f32_16x16x32_bf16 v[46:49], v[174:177], v[190:193], 0
	v_mfma_f32_16x16x32_bf16 v[38:41], v[166:169], v[198:201], 0
	v_mfma_f32_16x16x32_bf16 v[30:33], v[174:177], v[198:201], 0
	v_mfma_f32_16x16x32_bf16 v[22:25], v[166:169], v[206:209], 0
	v_mfma_f32_16x16x32_bf16 v[14:17], v[174:177], v[206:209], 0
	v_mfma_f32_16x16x32_bf16 v[6:9], v[166:169], v[214:217], 0
	v_mfma_f32_16x16x32_bf16 v[2:5], v[174:177], v[214:217], 0
	v_mfma_f32_16x16x32_bf16 v[54:57], v[170:173], v[194:197], v[54:57]
	v_mfma_f32_16x16x32_bf16 v[46:49], v[186:189], v[194:197], v[46:49]
	v_mfma_f32_16x16x32_bf16 v[38:41], v[170:173], v[202:205], v[38:41]
	v_mfma_f32_16x16x32_bf16 v[30:33], v[186:189], v[202:205], v[30:33]
	v_mfma_f32_16x16x32_bf16 v[22:25], v[170:173], v[210:213], v[22:25]
	v_mfma_f32_16x16x32_bf16 v[14:17], v[186:189], v[210:213], v[14:17]
	v_mfma_f32_16x16x32_bf16 v[6:9], v[170:173], v[218:221], v[6:9]
	v_mfma_f32_16x16x32_bf16 v[2:5], v[186:189], v[218:221], v[2:5]
	s_barrier
	s_add_i32 s48, 0, 0x18000
	s_add_i32 s49, 0, 0x1c000
	v_add_u32_e32 v162, s48, v156
	v_add_u32_e32 v179, s49, v156
	ds_read_b128 v[94:97], v162
	ds_read_b128 v[134:137], v162 offset:1024
	ds_read_b128 v[158:161], v162 offset:2048
	ds_read_b128 v[162:165], v162 offset:3072
	ds_read_b128 v[166:169], v179
	ds_read_b128 v[170:173], v179 offset:1024
	ds_read_b128 v[174:177], v179 offset:2048
	ds_read_b128 v[186:189], v179 offset:3072
	s_add_u32 s28, s28, 0x40000
	s_addc_u32 s29, s29, 0
	s_mov_b32 m0, s38
	v_lshl_add_u64 v[240:241], s[28:29], 0, v[144:145]
	ds_read_b128 v[190:193], v157 offset:32768
	ds_read_b128 v[194:197], v157 offset:33792
	ds_read_b128 v[198:201], v157 offset:34816
	ds_read_b128 v[202:205], v157 offset:35840
	ds_read_b128 v[206:209], v157 offset:36864
	ds_read_b128 v[210:213], v157 offset:37888
	ds_read_b128 v[214:217], v157 offset:38912
	ds_read_b128 v[218:221], v157 offset:39936
	global_load_lds_dwordx4 v[240:241], off
	v_lshl_add_u64 v[240:241], s[28:29], 0, v[140:141]
	s_mov_b32 m0, s39
	s_nop 0
	global_load_lds_dwordx4 v[240:241], off
	s_waitcnt vmcnt(8) lgkmcnt(0)
	s_barrier
	v_mfma_f32_16x16x32_bf16 v[130:133], v[94:97], v[190:193], v[130:133]
	v_mfma_f32_16x16x32_bf16 v[126:129], v[158:161], v[190:193], v[126:129]
	v_mfma_f32_16x16x32_bf16 v[114:117], v[94:97], v[198:201], v[114:117]
	v_mfma_f32_16x16x32_bf16 v[110:113], v[158:161], v[198:201], v[110:113]
	v_mfma_f32_16x16x32_bf16 v[98:101], v[94:97], v[206:209], v[98:101]
	v_mfma_f32_16x16x32_bf16 v[90:93], v[158:161], v[206:209], v[90:93]
	v_mfma_f32_16x16x32_bf16 v[78:81], v[94:97], v[214:217], v[78:81]
	v_mfma_f32_16x16x32_bf16 v[74:77], v[158:161], v[214:217], v[74:77]
	v_mfma_f32_16x16x32_bf16 v[130:133], v[134:137], v[194:197], v[130:133]
	v_mfma_f32_16x16x32_bf16 v[126:129], v[162:165], v[194:197], v[126:129]
	v_mfma_f32_16x16x32_bf16 v[114:117], v[134:137], v[202:205], v[114:117]
	v_mfma_f32_16x16x32_bf16 v[110:113], v[162:165], v[202:205], v[110:113]
	v_mfma_f32_16x16x32_bf16 v[98:101], v[134:137], v[210:213], v[98:101]
	v_mfma_f32_16x16x32_bf16 v[90:93], v[162:165], v[210:213], v[90:93]
	v_mfma_f32_16x16x32_bf16 v[78:81], v[134:137], v[218:221], v[78:81]
	v_mfma_f32_16x16x32_bf16 v[74:77], v[162:165], v[218:221], v[74:77]
	v_mfma_f32_16x16x32_bf16 v[122:125], v[166:169], v[190:193], v[122:125]
	v_mfma_f32_16x16x32_bf16 v[118:121], v[174:177], v[190:193], v[118:121]
	v_mfma_f32_16x16x32_bf16 v[106:109], v[166:169], v[198:201], v[106:109]
	v_mfma_f32_16x16x32_bf16 v[102:105], v[174:177], v[198:201], v[102:105]
	v_mfma_f32_16x16x32_bf16 v[86:89], v[166:169], v[206:209], v[86:89]
	v_mfma_f32_16x16x32_bf16 v[82:85], v[174:177], v[206:209], v[82:85]
	v_mfma_f32_16x16x32_bf16 v[70:73], v[166:169], v[214:217], v[70:73]
	v_mfma_f32_16x16x32_bf16 v[66:69], v[174:177], v[214:217], v[66:69]
	v_mfma_f32_16x16x32_bf16 v[122:125], v[170:173], v[194:197], v[122:125]
	v_mfma_f32_16x16x32_bf16 v[118:121], v[186:189], v[194:197], v[118:121]
	v_mfma_f32_16x16x32_bf16 v[106:109], v[170:173], v[202:205], v[106:109]
	v_mfma_f32_16x16x32_bf16 v[102:105], v[186:189], v[202:205], v[102:105]
	v_mfma_f32_16x16x32_bf16 v[86:89], v[170:173], v[210:213], v[86:89]
	v_mfma_f32_16x16x32_bf16 v[82:85], v[186:189], v[210:213], v[82:85]
	v_mfma_f32_16x16x32_bf16 v[70:73], v[170:173], v[218:221], v[70:73]
	v_mfma_f32_16x16x32_bf16 v[66:69], v[186:189], v[218:221], v[66:69]
	s_barrier
; #define PG8_STAGE(bufoff, gbase, voff) do { _Pragma("unroll") for (int _i = 0; _i < 2; ++_i) \
;         __builtin_amdgcn_global_load_lds((const unsigned*)((const char*)(gbase) + (voff)[_i]), (PG8_LAS unsigned*)(lds + (bufoff) + ldsw + _i * 8192), 16, 0, 0); } while (0)
; #define PG8_LDA(dst, b, h) do { _Pragma("unroll") for (int m = 0; m < 4; ++m) _Pragma("unroll") for (int k = 0; k < 2; ++k) dst[m][k] = *(const PG8_LAS bf16x8*)(lds + PG8_SA(b, h) + aoff + m * 2048 + k * 1024); } while (0)
; #define PG8_LDB(dst, b, h) do { _Pragma("unroll") for (int n = 0; n < 2; ++n) _Pragma("unroll") for (int k = 0; k < 2; ++k) dst[n][k] = *(const PG8_LAS bf16x8*)(lds + PG8_SB(b, h) + boff + n * 2048 + k * 1024); } while (0)
; #define PG8_MMA(ai, bj, At, Bt) do { __builtin_amdgcn_s_setprio(1); _Pragma("unroll") for (int m = 0; m < 4; ++m) _Pragma("unroll") for (int n = 0; n < 2; ++n) _Pragma("unroll") for (int k = 0; k < 2; ++k) \
;         acc[ai][bj][m][n] = __builtin_amdgcn_mfma_f32_16x16x32_bf16(Bt[n][k], At[m][k], acc[ai][bj][m][n], 0, 0, 0); __builtin_amdgcn_s_setprio(0); } while (0)
; #define PG8_WAIT_V(n) asm volatile("s_waitcnt vmcnt(" #n ")" ::: "memory")
; #define PG8_BAR __builtin_amdgcn_s_barrier()
; template <class Epi, class Sched, bool ALIGN_EPI = false, bool SP2 = false>
; __device__ __forceinline__ void gemm_phase(PG8_LAS unsigned char* lds, const Gemm g, const Sched& S, const Epi& E) {
;     ...
;         for (int t = 0; t < nt; t += 2) {
;             const bool last = (t == nt - 2);
;             const char* a1 = cA + (size_t)(t + 1) * kstep;
;             const char* a2 = last ? nA : cA + (size_t)(t + 2) * kstep; const char* b2 = last ? nB : cB + (size_t)(t + 2) * kstep;
;             const char* a3 = a2 + kstep; const char* b3 = b2 + kstep;
;             if (last && has_next) S.a_ready(nxt);
;             if constexpr (SP2) {
;             PG8_LDB(B0, 0, 0); PG8_LDB(B1, 0, 1); PG8_SCHED; PG8_LDA(At, 0, 0); PG8_STAGE(PG8_SA(1, 1), a1 + hstep, voffA);
;             PG8_WAIT_V(8); PG8_WAIT_L(0); PG8_BAR; PG8_MMA(0, 0, At, B0); PG8_MMA(0, 1, At, B1); PG8_BAR; PG8_SCHED;
;     ...
;             PG8_LDA(At, 1, 1); PG8_STAGE(PG8_SB(1, 0), b3, voffB); PG8_STAGE(PG8_SB(1, 1), b3 + hstep, voffB); PG8_STAGE(PG8_SA(1, 0), a3, voffA);
;             PG8_WAIT_V(8); PG8_WAIT_L(0); PG8_BAR; PG8_MMA(1, 0, At, B0); PG8_MMA(1, 1, At, B1); PG8_BAR; PG8_SCHED;
	s_add_i32 s28, s48, s35
	v_lshl_add_u64 v[154:155], v[154:155], 0, s[80:81]
	s_mov_b32 m0, s28
	ds_read_b128 v[190:193], v157 offset:49152
	ds_read_b128 v[194:197], v157 offset:50176
	ds_read_b128 v[198:201], v157 offset:51200
	ds_read_b128 v[202:205], v157 offset:52224
	ds_read_b128 v[206:209], v157 offset:53248
	ds_read_b128 v[210:213], v157 offset:54272
	ds_read_b128 v[214:217], v157 offset:55296
	ds_read_b128 v[218:221], v157 offset:56320
	global_load_lds_dwordx4 v[154:155], off
	s_add_i32 m0, s28, 0x2000
	s_add_u32 s26, s26, 0x40080
	v_lshl_add_u64 v[154:155], v[180:181], 0, s[80:81]
	s_addc_u32 s27, s27, 0
	s_add_i32 s28, s49, s35
	global_load_lds_dwordx4 v[154:155], off
	v_lshl_add_u64 v[154:155], s[26:27], 0, v[142:143]
	s_mov_b32 m0, s28
	s_nop 0
	global_load_lds_dwordx4 v[154:155], off
	v_lshl_add_u64 v[154:155], s[26:27], 0, v[138:139]
	s_add_i32 m0, s28, 0x2000
	s_nop 0
	global_load_lds_dwordx4 v[154:155], off
	v_lshl_add_u64 v[154:155], v[182:183], 0, s[80:81]
	s_mov_b32 m0, s40
	s_nop 0
	global_load_lds_dwordx4 v[154:155], off
	v_lshl_add_u64 v[154:155], v[222:223], 0, s[80:81]
	s_mov_b32 m0, s41
	s_nop 0
	global_load_lds_dwordx4 v[154:155], off
	s_waitcnt vmcnt(8) lgkmcnt(0)
	s_barrier
	v_mfma_f32_16x16x32_bf16 v[62:65], v[94:97], v[190:193], v[62:65]
	v_mfma_f32_16x16x32_bf16 v[58:61], v[158:161], v[190:193], v[58:61]
	v_mfma_f32_16x16x32_bf16 v[50:53], v[94:97], v[198:201], v[50:53]
	v_mfma_f32_16x16x32_bf16 v[42:45], v[158:161], v[198:201], v[42:45]
	v_mfma_f32_16x16x32_bf16 v[34:37], v[94:97], v[206:209], v[34:37]
	v_mfma_f32_16x16x32_bf16 v[26:29], v[158:161], v[206:209], v[26:29]
	v_mfma_f32_16x16x32_bf16 v[18:21], v[94:97], v[214:217], v[18:21]
	v_mfma_f32_16x16x32_bf16 v[10:13], v[158:161], v[214:217], v[10:13]
	v_mfma_f32_16x16x32_bf16 v[62:65], v[134:137], v[194:197], v[62:65]
	v_mfma_f32_16x16x32_bf16 v[58:61], v[162:165], v[194:197], v[58:61]
	v_mfma_f32_16x16x32_bf16 v[50:53], v[134:137], v[202:205], v[50:53]
	v_mfma_f32_16x16x32_bf16 v[42:45], v[162:165], v[202:205], v[42:45]
	v_mfma_f32_16x16x32_bf16 v[34:37], v[134:137], v[210:213], v[34:37]
	v_mfma_f32_16x16x32_bf16 v[26:29], v[162:165], v[210:213], v[26:29]
	v_mfma_f32_16x16x32_bf16 v[18:21], v[134:137], v[218:221], v[18:21]
	v_mfma_f32_16x16x32_bf16 v[10:13], v[162:165], v[218:221], v[10:13]
	v_mfma_f32_16x16x32_bf16 v[54:57], v[166:169], v[190:193], v[54:57]
	v_mfma_f32_16x16x32_bf16 v[46:49], v[174:177], v[190:193], v[46:49]
	v_mfma_f32_16x16x32_bf16 v[38:41], v[166:169], v[198:201], v[38:41]
	v_mfma_f32_16x16x32_bf16 v[30:33], v[174:177], v[198:201], v[30:33]
	v_mfma_f32_16x16x32_bf16 v[22:25], v[166:169], v[206:209], v[22:25]
	v_mfma_f32_16x16x32_bf16 v[14:17], v[174:177], v[206:209], v[14:17]
	v_mfma_f32_16x16x32_bf16 v[6:9], v[166:169], v[214:217], v[6:9]
	v_mfma_f32_16x16x32_bf16 v[2:5], v[174:177], v[214:217], v[2:5]
	v_mfma_f32_16x16x32_bf16 v[54:57], v[170:173], v[194:197], v[54:57]
	v_mfma_f32_16x16x32_bf16 v[46:49], v[186:189], v[194:197], v[46:49]
	v_mfma_f32_16x16x32_bf16 v[38:41], v[170:173], v[202:205], v[38:41]
	v_mfma_f32_16x16x32_bf16 v[30:33], v[186:189], v[202:205], v[30:33]
	v_mfma_f32_16x16x32_bf16 v[22:25], v[170:173], v[210:213], v[22:25]
	v_mfma_f32_16x16x32_bf16 v[14:17], v[186:189], v[210:213], v[14:17]
	v_mfma_f32_16x16x32_bf16 v[6:9], v[170:173], v[218:221], v[6:9]
	v_mfma_f32_16x16x32_bf16 v[2:5], v[186:189], v[218:221], v[2:5]
	s_barrier
	s_add_i32 s47, s47, 2
	s_add_u32 s24, s24, 0x100
	s_addc_u32 s25, s25, 0
	s_add_u32 s45, s45, 0x100
	s_addc_u32 s46, s46, 0
	s_cmp_gt_u32 s47, 13
	s_branch .LBB0_318
.LBB0_318:
	s_add_u32 s26, s24, 0xfffc0080
	s_addc_u32 s27, s25, -1
	s_add_i32 s48, 0, 0x10000
	s_cmp_eq_u32 s47, 12
	s_cselect_b32 s29, s13, s27
	s_cselect_b32 s28, s21, s26
	v_add_u32_e32 v154, s48, v156
	s_cselect_b32 s27, s11, s46
	s_cselect_b32 s26, s44, s45
	s_add_i32 s50, 0, 0x14000
	ds_read_b128 v[94:97], v154
	ds_read_b128 v[134:137], v154 offset:1024
	ds_read_b128 v[158:161], v154 offset:2048
	ds_read_b128 v[162:165], v154 offset:3072
	v_add_u32_e32 v154, s50, v156
	ds_read_b128 v[166:169], v154
	ds_read_b128 v[170:173], v154 offset:1024
	ds_read_b128 v[174:177], v154 offset:2048
	ds_read_b128 v[186:189], v154 offset:3072
	v_lshl_add_u64 v[154:155], s[24:25], 0, v[150:151]
	s_add_i32 m0, s23, 0xc000
	ds_read_b128 v[190:193], v157
	ds_read_b128 v[194:197], v157 offset:1024
	ds_read_b128 v[198:201], v157 offset:2048
	ds_read_b128 v[202:205], v157 offset:3072
	ds_read_b128 v[206:209], v157 offset:4096
	ds_read_b128 v[210:213], v157 offset:5120
	ds_read_b128 v[214:217], v157 offset:6144
	ds_read_b128 v[218:221], v157 offset:7168
	global_load_lds_dwordx4 v[154:155], off
	v_lshl_add_u64 v[154:155], s[24:25], 0, v[152:153]
	s_add_i32 m0, s23, 0xe000
	s_nop 0
	global_load_lds_dwordx4 v[154:155], off
	s_waitcnt vmcnt(8) lgkmcnt(0)
	s_barrier
; #define PG8_STAGE(bufoff, gbase, voff) do { _Pragma("unroll") for (int _i = 0; _i < 2; ++_i) \
;         __builtin_amdgcn_global_load_lds((const unsigned*)((const char*)(gbase) + (voff)[_i]), (PG8_LAS unsigned*)(lds + (bufoff) + ldsw + _i * 8192), 16, 0, 0); } while (0)
; #define PG8_LDA(dst, b, h) do { _Pragma("unroll") for (int m = 0; m < 4; ++m) _Pragma("unroll") for (int k = 0; k < 2; ++k) dst[m][k] = *(const PG8_LAS bf16x8*)(lds + PG8_SA(b, h) + aoff + m * 2048 + k * 1024); } while (0)
; #define PG8_LDB(dst, b, h) do { _Pragma("unroll") for (int n = 0; n < 2; ++n) _Pragma("unroll") for (int k = 0; k < 2; ++k) dst[n][k] = *(const PG8_LAS bf16x8*)(lds + PG8_SB(b, h) + boff + n * 2048 + k * 1024); } while (0)
; #define PG8_MMA(ai, bj, At, Bt) do { __builtin_amdgcn_s_setprio(1); _Pragma("unroll") for (int m = 0; m < 4; ++m) _Pragma("unroll") for (int n = 0; n < 2; ++n) _Pragma("unroll") for (int k = 0; k < 2; ++k) \
;         acc[ai][bj][m][n] = __builtin_amdgcn_mfma_f32_16x16x32_bf16(Bt[n][k], At[m][k], acc[ai][bj][m][n], 0, 0, 0); __builtin_amdgcn_s_setprio(0); } while (0)
; #define PG8_WAIT_V(n) asm volatile("s_waitcnt vmcnt(" #n ")" ::: "memory")
; #define PG8_WAIT_L(n) asm volatile("s_waitcnt lgkmcnt(" #n ")" ::: "memory")
; #define PG8_BAR __builtin_amdgcn_s_barrier()
; #define PG8_SCHED __builtin_amdgcn_sched_barrier(0)
; template <class Epi, class Sched, bool ALIGN_EPI = false, bool SP2 = false>
; __device__ __forceinline__ void gemm_phase(PG8_LAS unsigned char* lds, const Gemm g, const Sched& S, const Epi& E) {
;     ...
;             PG8_LDB(B0, 0, 0); PG8_LDB(B1, 0, 1); PG8_SCHED; PG8_LDA(At, 0, 0); PG8_STAGE(PG8_SA(1, 1), a1 + hstep, voffA);
;             PG8_WAIT_V(8); PG8_WAIT_L(0); PG8_BAR; PG8_MMA(0, 0, At, B0); PG8_MMA(0, 1, At, B1); PG8_BAR; PG8_SCHED;
;             PG8_LDA(At, 0, 1); PG8_STAGE(PG8_SB(0, 0), b2, voffB); PG8_STAGE(PG8_SB(0, 1), b2 + hstep, voffB); PG8_STAGE(PG8_SA(0, 0), a2, voffA);
;             PG8_WAIT_V(8); PG8_WAIT_L(0); PG8_BAR; PG8_MMA(1, 0, At, B0); PG8_MMA(1, 1, At, B1); PG8_BAR; PG8_SCHED;
	v_mfma_f32_16x16x32_bf16 v[130:133], v[94:97], v[190:193], v[130:133]
	v_mfma_f32_16x16x32_bf16 v[126:129], v[158:161], v[190:193], v[126:129]
	v_mfma_f32_16x16x32_bf16 v[114:117], v[94:97], v[198:201], v[114:117]
	v_mfma_f32_16x16x32_bf16 v[110:113], v[158:161], v[198:201], v[110:113]
	v_mfma_f32_16x16x32_bf16 v[98:101], v[94:97], v[206:209], v[98:101]
	v_mfma_f32_16x16x32_bf16 v[90:93], v[158:161], v[206:209], v[90:93]
	v_mfma_f32_16x16x32_bf16 v[78:81], v[94:97], v[214:217], v[78:81]
	v_mfma_f32_16x16x32_bf16 v[74:77], v[158:161], v[214:217], v[74:77]
	v_mfma_f32_16x16x32_bf16 v[130:133], v[134:137], v[194:197], v[130:133]
	v_mfma_f32_16x16x32_bf16 v[126:129], v[162:165], v[194:197], v[126:129]
	v_mfma_f32_16x16x32_bf16 v[114:117], v[134:137], v[202:205], v[114:117]
	v_mfma_f32_16x16x32_bf16 v[110:113], v[162:165], v[202:205], v[110:113]
	v_mfma_f32_16x16x32_bf16 v[98:101], v[134:137], v[210:213], v[98:101]
	v_mfma_f32_16x16x32_bf16 v[90:93], v[162:165], v[210:213], v[90:93]
	v_mfma_f32_16x16x32_bf16 v[78:81], v[134:137], v[218:221], v[78:81]
	v_mfma_f32_16x16x32_bf16 v[74:77], v[162:165], v[218:221], v[74:77]
	v_mfma_f32_16x16x32_bf16 v[122:125], v[166:169], v[190:193], v[122:125]
	v_mfma_f32_16x16x32_bf16 v[118:121], v[174:177], v[190:193], v[118:121]
	v_mfma_f32_16x16x32_bf16 v[106:109], v[166:169], v[198:201], v[106:109]
	v_mfma_f32_16x16x32_bf16 v[102:105], v[174:177], v[198:201], v[102:105]
	v_mfma_f32_16x16x32_bf16 v[86:89], v[166:169], v[206:209], v[86:89]
	v_mfma_f32_16x16x32_bf16 v[82:85], v[174:177], v[206:209], v[82:85]
	v_mfma_f32_16x16x32_bf16 v[70:73], v[166:169], v[214:217], v[70:73]
	v_mfma_f32_16x16x32_bf16 v[66:69], v[174:177], v[214:217], v[66:69]
	v_mfma_f32_16x16x32_bf16 v[122:125], v[170:173], v[194:197], v[122:125]
	v_mfma_f32_16x16x32_bf16 v[118:121], v[186:189], v[194:197], v[118:121]
	v_mfma_f32_16x16x32_bf16 v[106:109], v[170:173], v[202:205], v[106:109]
	v_mfma_f32_16x16x32_bf16 v[102:105], v[186:189], v[202:205], v[102:105]
	v_mfma_f32_16x16x32_bf16 v[86:89], v[170:173], v[210:213], v[86:89]
	v_mfma_f32_16x16x32_bf16 v[82:85], v[186:189], v[210:213], v[82:85]
	v_mfma_f32_16x16x32_bf16 v[70:73], v[170:173], v[218:221], v[70:73]
	v_mfma_f32_16x16x32_bf16 v[66:69], v[186:189], v[218:221], v[66:69]
	s_barrier
	s_add_i32 s48, s48, s35
	v_lshl_add_u64 v[154:155], s[26:27], 0, v[142:143]
	s_mov_b32 m0, s48
	ds_read_b128 v[190:193], v157 offset:16384
	ds_read_b128 v[194:197], v157 offset:17408
	ds_read_b128 v[198:201], v157 offset:18432
	ds_read_b128 v[202:205], v157 offset:19456
	ds_read_b128 v[206:209], v157 offset:20480
	ds_read_b128 v[210:213], v157 offset:21504
	ds_read_b128 v[214:217], v157 offset:22528
	ds_read_b128 v[218:221], v157 offset:23552
	global_load_lds_dwordx4 v[154:155], off
	s_add_i32 m0, s48, 0x2000
	s_add_u32 s48, s26, 0x40000
	v_lshl_add_u64 v[180:181], s[26:27], 0, v[138:139]
	s_addc_u32 s49, s27, 0
	s_add_i32 s50, s50, s35
	global_load_lds_dwordx4 v[180:181], off
	v_lshl_add_u64 v[182:183], s[48:49], 0, v[142:143]
	s_mov_b32 m0, s50
	v_lshl_add_u64 v[222:223], s[28:29], 0, v[140:141]
	global_load_lds_dwordx4 v[182:183], off
	v_lshl_add_u64 v[182:183], s[48:49], 0, v[138:139]
	s_add_i32 m0, s50, 0x2000
	s_nop 0
	global_load_lds_dwordx4 v[182:183], off
	v_lshl_add_u64 v[182:183], s[28:29], 0, v[144:145]
	s_mov_b32 m0, s23
	s_nop 0
	global_load_lds_dwordx4 v[182:183], off
	s_mov_b32 m0, s37
	s_nop 0
	global_load_lds_dwordx4 v[222:223], off
	s_waitcnt vmcnt(8) lgkmcnt(0)
	s_barrier
	v_mfma_f32_16x16x32_bf16 v[62:65], v[94:97], v[190:193], v[62:65]
	v_mfma_f32_16x16x32_bf16 v[58:61], v[158:161], v[190:193], v[58:61]
	v_mfma_f32_16x16x32_bf16 v[50:53], v[94:97], v[198:201], v[50:53]
	v_mfma_f32_16x16x32_bf16 v[42:45], v[158:161], v[198:201], v[42:45]
	v_mfma_f32_16x16x32_bf16 v[34:37], v[94:97], v[206:209], v[34:37]
	v_mfma_f32_16x16x32_bf16 v[26:29], v[158:161], v[206:209], v[26:29]
	v_mfma_f32_16x16x32_bf16 v[18:21], v[94:97], v[214:217], v[18:21]
	v_mfma_f32_16x16x32_bf16 v[10:13], v[158:161], v[214:217], v[10:13]
	v_mfma_f32_16x16x32_bf16 v[62:65], v[134:137], v[194:197], v[62:65]
	v_mfma_f32_16x16x32_bf16 v[58:61], v[162:165], v[194:197], v[58:61]
	v_mfma_f32_16x16x32_bf16 v[50:53], v[134:137], v[202:205], v[50:53]
	v_mfma_f32_16x16x32_bf16 v[42:45], v[162:165], v[202:205], v[42:45]
	v_mfma_f32_16x16x32_bf16 v[34:37], v[134:137], v[210:213], v[34:37]
	v_mfma_f32_16x16x32_bf16 v[26:29], v[162:165], v[210:213], v[26:29]
	v_mfma_f32_16x16x32_bf16 v[18:21], v[134:137], v[218:221], v[18:21]
	v_mfma_f32_16x16x32_bf16 v[10:13], v[162:165], v[218:221], v[10:13]
	v_mfma_f32_16x16x32_bf16 v[54:57], v[166:169], v[190:193], v[54:57]
	v_mfma_f32_16x16x32_bf16 v[46:49], v[174:177], v[190:193], v[46:49]
	v_mfma_f32_16x16x32_bf16 v[38:41], v[166:169], v[198:201], v[38:41]
	v_mfma_f32_16x16x32_bf16 v[30:33], v[174:177], v[198:201], v[30:33]
	v_mfma_f32_16x16x32_bf16 v[22:25], v[166:169], v[206:209], v[22:25]
	v_mfma_f32_16x16x32_bf16 v[14:17], v[174:177], v[206:209], v[14:17]
	v_mfma_f32_16x16x32_bf16 v[6:9], v[166:169], v[214:217], v[6:9]
	v_mfma_f32_16x16x32_bf16 v[2:5], v[174:177], v[214:217], v[2:5]
	v_mfma_f32_16x16x32_bf16 v[54:57], v[170:173], v[194:197], v[54:57]
	v_mfma_f32_16x16x32_bf16 v[46:49], v[186:189], v[194:197], v[46:49]
	v_mfma_f32_16x16x32_bf16 v[38:41], v[170:173], v[202:205], v[38:41]
	v_mfma_f32_16x16x32_bf16 v[30:33], v[186:189], v[202:205], v[30:33]
	v_mfma_f32_16x16x32_bf16 v[22:25], v[170:173], v[210:213], v[22:25]
	v_mfma_f32_16x16x32_bf16 v[14:17], v[186:189], v[210:213], v[14:17]
	v_mfma_f32_16x16x32_bf16 v[6:9], v[170:173], v[218:221], v[6:9]
	v_mfma_f32_16x16x32_bf16 v[2:5], v[186:189], v[218:221], v[2:5]
	s_barrier
; #define PG8_STAGE(bufoff, gbase, voff) do { _Pragma("unroll") for (int _i = 0; _i < 2; ++_i) \
;         __builtin_amdgcn_global_load_lds((const unsigned*)((const char*)(gbase) + (voff)[_i]), (PG8_LAS unsigned*)(lds + (bufoff) + ldsw + _i * 8192), 16, 0, 0); } while (0)
; #define PG8_LDA(dst, b, h) do { _Pragma("unroll") for (int m = 0; m < 4; ++m) _Pragma("unroll") for (int k = 0; k < 2; ++k) dst[m][k] = *(const PG8_LAS bf16x8*)(lds + PG8_SA(b, h) + aoff + m * 2048 + k * 1024); } while (0)
; #define PG8_LDB(dst, b, h) do { _Pragma("unroll") for (int n = 0; n < 2; ++n) _Pragma("unroll") for (int k = 0; k < 2; ++k) dst[n][k] = *(const PG8_LAS bf16x8*)(lds + PG8_SB(b, h) + boff + n * 2048 + k * 1024); } while (0)
; #define PG8_MMA(ai, bj, At, Bt) do { __builtin_amdgcn_s_setprio(1); _Pragma("unroll") for (int m = 0; m < 4; ++m) _Pragma("unroll") for (int n = 0; n < 2; ++n) _Pragma("unroll") for (int k = 0; k < 2; ++k) \
;         acc[ai][bj][m][n] = __builtin_amdgcn_mfma_f32_16x16x32_bf16(Bt[n][k], At[m][k], acc[ai][bj][m][n], 0, 0, 0); __builtin_amdgcn_s_setprio(0); } while (0)
; #define PG8_WAIT_V(n) asm volatile("s_waitcnt vmcnt(" #n ")" ::: "memory")
; #define PG8_WAIT_L(n) asm volatile("s_waitcnt lgkmcnt(" #n ")" ::: "memory")
; #define PG8_BAR __builtin_amdgcn_s_barrier()
; #define PG8_SCHED __builtin_amdgcn_sched_barrier(0)
; template <class Epi, class Sched, bool ALIGN_EPI = false, bool SP2 = false>
; __device__ __forceinline__ void gemm_phase(PG8_LAS unsigned char* lds, const Gemm g, const Sched& S, const Epi& E) {
;     ...
;             PG8_LDB(B0, 1, 0); PG8_LDB(B1, 1, 1); PG8_SCHED; PG8_LDA(At, 1, 0); PG8_STAGE(PG8_SA(0, 1), a2 + hstep, voffA);
;             PG8_WAIT_V(8); PG8_WAIT_L(0); PG8_BAR; PG8_MMA(0, 0, At, B0); PG8_MMA(0, 1, At, B1); PG8_BAR; PG8_SCHED;
;             PG8_LDA(At, 1, 1); PG8_STAGE(PG8_SB(1, 0), b3, voffB); PG8_STAGE(PG8_SB(1, 1), b3 + hstep, voffB); PG8_STAGE(PG8_SA(1, 0), a3, voffA);
;             PG8_WAIT_V(8); PG8_WAIT_L(0); PG8_BAR; PG8_MMA(1, 0, At, B0); PG8_MMA(1, 1, At, B1); PG8_BAR; PG8_SCHED;
;     ...
;         if constexpr (ALIGN_EPI) { if (wr == 0) PG8_BAR; }
	s_add_i32 s48, 0, 0x18000
	s_add_i32 s49, 0, 0x1c000
	v_add_u32_e32 v162, s48, v156
	v_add_u32_e32 v179, s49, v156
	ds_read_b128 v[94:97], v162
	ds_read_b128 v[134:137], v162 offset:1024
	ds_read_b128 v[158:161], v162 offset:2048
	ds_read_b128 v[162:165], v162 offset:3072
	ds_read_b128 v[166:169], v179
	ds_read_b128 v[170:173], v179 offset:1024
	ds_read_b128 v[174:177], v179 offset:2048
	ds_read_b128 v[186:189], v179 offset:3072
	s_add_u32 s28, s28, 0x40000
	s_addc_u32 s29, s29, 0
	s_mov_b32 m0, s38
	v_lshl_add_u64 v[240:241], s[28:29], 0, v[144:145]
	ds_read_b128 v[190:193], v157 offset:32768
	ds_read_b128 v[194:197], v157 offset:33792
	ds_read_b128 v[198:201], v157 offset:34816
	ds_read_b128 v[202:205], v157 offset:35840
	ds_read_b128 v[206:209], v157 offset:36864
	ds_read_b128 v[210:213], v157 offset:37888
	ds_read_b128 v[214:217], v157 offset:38912
	ds_read_b128 v[218:221], v157 offset:39936
	global_load_lds_dwordx4 v[240:241], off
	v_lshl_add_u64 v[240:241], s[28:29], 0, v[140:141]
	s_mov_b32 m0, s39
	s_nop 0
	global_load_lds_dwordx4 v[240:241], off
	s_waitcnt vmcnt(8) lgkmcnt(0)
	s_barrier
	v_mfma_f32_16x16x32_bf16 v[130:133], v[94:97], v[190:193], v[130:133]
	v_mfma_f32_16x16x32_bf16 v[126:129], v[158:161], v[190:193], v[126:129]
	v_mfma_f32_16x16x32_bf16 v[114:117], v[94:97], v[198:201], v[114:117]
	v_mfma_f32_16x16x32_bf16 v[110:113], v[158:161], v[198:201], v[110:113]
	v_mfma_f32_16x16x32_bf16 v[98:101], v[94:97], v[206:209], v[98:101]
	v_mfma_f32_16x16x32_bf16 v[90:93], v[158:161], v[206:209], v[90:93]
	v_mfma_f32_16x16x32_bf16 v[78:81], v[94:97], v[214:217], v[78:81]
	v_mfma_f32_16x16x32_bf16 v[74:77], v[158:161], v[214:217], v[74:77]
	v_mfma_f32_16x16x32_bf16 v[130:133], v[134:137], v[194:197], v[130:133]
	v_mfma_f32_16x16x32_bf16 v[126:129], v[162:165], v[194:197], v[126:129]
	v_mfma_f32_16x16x32_bf16 v[114:117], v[134:137], v[202:205], v[114:117]
	v_mfma_f32_16x16x32_bf16 v[110:113], v[162:165], v[202:205], v[110:113]
	v_mfma_f32_16x16x32_bf16 v[98:101], v[134:137], v[210:213], v[98:101]
	v_mfma_f32_16x16x32_bf16 v[90:93], v[162:165], v[210:213], v[90:93]
	v_mfma_f32_16x16x32_bf16 v[78:81], v[134:137], v[218:221], v[78:81]
	v_mfma_f32_16x16x32_bf16 v[74:77], v[162:165], v[218:221], v[74:77]
	v_mfma_f32_16x16x32_bf16 v[122:125], v[166:169], v[190:193], v[122:125]
	v_mfma_f32_16x16x32_bf16 v[118:121], v[174:177], v[190:193], v[118:121]
	v_mfma_f32_16x16x32_bf16 v[106:109], v[166:169], v[198:201], v[106:109]
	v_mfma_f32_16x16x32_bf16 v[102:105], v[174:177], v[198:201], v[102:105]
	v_mfma_f32_16x16x32_bf16 v[86:89], v[166:169], v[206:209], v[86:89]
	v_mfma_f32_16x16x32_bf16 v[82:85], v[174:177], v[206:209], v[82:85]
	v_mfma_f32_16x16x32_bf16 v[70:73], v[166:169], v[214:217], v[70:73]
	v_mfma_f32_16x16x32_bf16 v[66:69], v[174:177], v[214:217], v[66:69]
	v_mfma_f32_16x16x32_bf16 v[122:125], v[170:173], v[194:197], v[122:125]
	v_mfma_f32_16x16x32_bf16 v[118:121], v[186:189], v[194:197], v[118:121]
	v_mfma_f32_16x16x32_bf16 v[106:109], v[170:173], v[202:205], v[106:109]
	v_mfma_f32_16x16x32_bf16 v[102:105], v[186:189], v[202:205], v[102:105]
	v_mfma_f32_16x16x32_bf16 v[86:89], v[170:173], v[210:213], v[86:89]
	v_mfma_f32_16x16x32_bf16 v[82:85], v[186:189], v[210:213], v[82:85]
	v_mfma_f32_16x16x32_bf16 v[70:73], v[170:173], v[218:221], v[70:73]
	v_mfma_f32_16x16x32_bf16 v[66:69], v[186:189], v[218:221], v[66:69]
	s_barrier
	s_add_i32 s28, s48, s35
	v_lshl_add_u64 v[154:155], v[154:155], 0, s[80:81]
	s_mov_b32 m0, s28
	ds_read_b128 v[190:193], v157 offset:49152
	ds_read_b128 v[194:197], v157 offset:50176
	ds_read_b128 v[198:201], v157 offset:51200
	ds_read_b128 v[202:205], v157 offset:52224
	ds_read_b128 v[206:209], v157 offset:53248
	ds_read_b128 v[210:213], v157 offset:54272
	ds_read_b128 v[214:217], v157 offset:55296
	ds_read_b128 v[218:221], v157 offset:56320
	global_load_lds_dwordx4 v[154:155], off
	s_add_i32 m0, s28, 0x2000
	s_add_u32 s26, s26, 0x40080
	v_lshl_add_u64 v[154:155], v[180:181], 0, s[80:81]
	s_addc_u32 s27, s27, 0
	s_add_i32 s28, s49, s35
	global_load_lds_dwordx4 v[154:155], off
	v_lshl_add_u64 v[154:155], s[26:27], 0, v[142:143]
	s_mov_b32 m0, s28
	s_nop 0
	global_load_lds_dwordx4 v[154:155], off
	v_lshl_add_u64 v[154:155], s[26:27], 0, v[138:139]
	s_add_i32 m0, s28, 0x2000
	s_nop 0
	global_load_lds_dwordx4 v[154:155], off
	v_lshl_add_u64 v[154:155], v[182:183], 0, s[80:81]
	s_mov_b32 m0, s40
	s_nop 0
	global_load_lds_dwordx4 v[154:155], off
	v_lshl_add_u64 v[154:155], v[222:223], 0, s[80:81]
	s_mov_b32 m0, s41
	s_nop 0
	global_load_lds_dwordx4 v[154:155], off
	s_waitcnt vmcnt(8) lgkmcnt(0)
	s_barrier
	v_mfma_f32_16x16x32_bf16 v[62:65], v[94:97], v[190:193], v[62:65]
	v_mfma_f32_16x16x32_bf16 v[58:61], v[158:161], v[190:193], v[58:61]
	v_mfma_f32_16x16x32_bf16 v[50:53], v[94:97], v[198:201], v[50:53]
	v_mfma_f32_16x16x32_bf16 v[42:45], v[158:161], v[198:201], v[42:45]
	v_mfma_f32_16x16x32_bf16 v[34:37], v[94:97], v[206:209], v[34:37]
	v_mfma_f32_16x16x32_bf16 v[26:29], v[158:161], v[206:209], v[26:29]
	v_mfma_f32_16x16x32_bf16 v[18:21], v[94:97], v[214:217], v[18:21]
	v_mfma_f32_16x16x32_bf16 v[10:13], v[158:161], v[214:217], v[10:13]
	v_mfma_f32_16x16x32_bf16 v[62:65], v[134:137], v[194:197], v[62:65]
	v_mfma_f32_16x16x32_bf16 v[58:61], v[162:165], v[194:197], v[58:61]
	v_mfma_f32_16x16x32_bf16 v[50:53], v[134:137], v[202:205], v[50:53]
	v_mfma_f32_16x16x32_bf16 v[42:45], v[162:165], v[202:205], v[42:45]
	v_mfma_f32_16x16x32_bf16 v[34:37], v[134:137], v[210:213], v[34:37]
	v_mfma_f32_16x16x32_bf16 v[26:29], v[162:165], v[210:213], v[26:29]
	v_mfma_f32_16x16x32_bf16 v[18:21], v[134:137], v[218:221], v[18:21]
	v_mfma_f32_16x16x32_bf16 v[10:13], v[162:165], v[218:221], v[10:13]
	v_mfma_f32_16x16x32_bf16 v[54:57], v[166:169], v[190:193], v[54:57]
	v_mfma_f32_16x16x32_bf16 v[46:49], v[174:177], v[190:193], v[46:49]
	v_mfma_f32_16x16x32_bf16 v[38:41], v[166:169], v[198:201], v[38:41]
	v_mfma_f32_16x16x32_bf16 v[30:33], v[174:177], v[198:201], v[30:33]
	v_mfma_f32_16x16x32_bf16 v[22:25], v[166:169], v[206:209], v[22:25]
	v_mfma_f32_16x16x32_bf16 v[14:17], v[174:177], v[206:209], v[14:17]
	v_mfma_f32_16x16x32_bf16 v[6:9], v[166:169], v[214:217], v[6:9]
	v_mfma_f32_16x16x32_bf16 v[2:5], v[174:177], v[214:217], v[2:5]
	v_mfma_f32_16x16x32_bf16 v[54:57], v[170:173], v[194:197], v[54:57]
	v_mfma_f32_16x16x32_bf16 v[46:49], v[186:189], v[194:197], v[46:49]
	v_mfma_f32_16x16x32_bf16 v[38:41], v[170:173], v[202:205], v[38:41]
	v_mfma_f32_16x16x32_bf16 v[30:33], v[186:189], v[202:205], v[30:33]
	v_mfma_f32_16x16x32_bf16 v[22:25], v[170:173], v[210:213], v[22:25]
	v_mfma_f32_16x16x32_bf16 v[14:17], v[186:189], v[210:213], v[14:17]
	v_mfma_f32_16x16x32_bf16 v[6:9], v[170:173], v[218:221], v[6:9]
	v_mfma_f32_16x16x32_bf16 v[2:5], v[186:189], v[218:221], v[2:5]
	s_barrier
	s_add_i32 s47, s47, 2
	s_add_u32 s24, s24, 0x100
	s_addc_u32 s25, s25, 0
	s_add_u32 s45, s45, 0x100
	s_addc_u32 s46, s46, 0
	s_cmp_gt_u32 s47, 13
	s_cbranch_scc0 .LBB0_318
	s_and_b64 vcc, exec, s[6:7]
	s_cbranch_vccz .LBB0_321
	s_barrier

; #define PG8_STAGE(bufoff, gbase, voff) do { _Pragma("unroll") for (int _i = 0; _i < 2; ++_i) \
;         __builtin_amdgcn_global_load_lds((const unsigned*)((const char*)(gbase) + (voff)[_i]), (PG8_LAS unsigned*)(lds + (bufoff) + ldsw + _i * 8192), 16, 0, 0); } while (0)
; #define PG8_LDA(dst, b, h) do { _Pragma("unroll") for (int m = 0; m < 4; ++m) _Pragma("unroll") for (int k = 0; k < 2; ++k) dst[m][k] = *(const PG8_LAS bf16x8*)(lds + PG8_SA(b, h) + aoff + m * 2048 + k * 1024); } while (0)
; #define PG8_LDB(dst, b, h) do { _Pragma("unroll") for (int n = 0; n < 2; ++n) _Pragma("unroll") for (int k = 0; k < 2; ++k) dst[n][k] = *(const PG8_LAS bf16x8*)(lds + PG8_SB(b, h) + boff + n * 2048 + k * 1024); } while (0)
; #define PG8_WAIT_V(n) asm volatile("s_waitcnt vmcnt(" #n ")" ::: "memory")
; #define PG8_WAIT_L(n) asm volatile("s_waitcnt lgkmcnt(" #n ")" ::: "memory")
; #define PG8_BAR __builtin_amdgcn_s_barrier()
; #define PG8_SCHED __builtin_amdgcn_sched_barrier(0)
; template <class Epi, class Sched, bool ALIGN_EPI = false, bool SP2 = false>
; __device__ __forceinline__ void gemm_phase(PG8_LAS unsigned char* lds, const Gemm g, const Sched& S, const Epi& E) {
;     ...
;         const bool has_next = S.next(ui + 1, nxt);
;         const char* nA = has_next ? (const char*)g.A + (size_t)nxt.pm * tstep : cA; const char* nB = has_next ? (const char*)g.Bt + (size_t)nxt.pn * tstep : cB;
;         for (int t = 0; t < nt; t += 2) {
;             const bool last = (t == nt - 2);
;             const char* a1 = cA + (size_t)(t + 1) * kstep;
;             const char* a2 = last ? nA : cA + (size_t)(t + 2) * kstep; const char* b2 = last ? nB : cB + (size_t)(t + 2) * kstep;
;             const char* a3 = a2 + kstep; const char* b3 = b2 + kstep;
;             if (last && has_next) S.a_ready(nxt);
;             if constexpr (SP2) {
;             PG8_LDB(B0, 0, 0); PG8_LDB(B1, 0, 1); PG8_SCHED; PG8_LDA(At, 0, 0); PG8_STAGE(PG8_SA(1, 1), a1 + hstep, voffA);
;             PG8_WAIT_V(8); PG8_WAIT_L(0); PG8_BAR; PG8_MMA(0, 0, At, B0); PG8_MMA(0, 1, At, B1); PG8_BAR; PG8_SCHED;
;             PG8_LDA(At, 0, 1); PG8_STAGE(PG8_SB(0, 0), b2, voffB); PG8_STAGE(PG8_SB(0, 1), b2 + hstep, voffB); PG8_STAGE(PG8_SA(0, 0), a2, voffA);
;             PG8_WAIT_V(8); PG8_WAIT_L(0); PG8_BAR; PG8_MMA(1, 0, At, B0); PG8_MMA(1, 1, At, B1); PG8_BAR; PG8_SCHED;
.LBB0_1061:
	s_ashr_i32 s23, s22, 31
	s_lshl_b64 s[24:25], s[22:23], 19
	s_add_u32 s24, s42, s24
	s_addc_u32 s25, s43, s25
	s_and_b64 s[26:27], s[6:7], exec
	s_cselect_b32 s23, s25, s35
	s_cselect_b32 s29, s24, s34
	s_ashr_i32 s21, s20, 31
	s_lshl_b64 s[26:27], s[20:21], 19
	s_add_u32 s26, s40, s26
	s_addc_u32 s27, s41, s27
	s_and_b64 s[38:39], s[6:7], exec
	s_cselect_b32 s21, s27, s37
	s_cselect_b32 s31, s26, s36
	s_add_u32 s34, s34, 0x40080
	s_addc_u32 s35, s35, 0
	s_add_u32 s56, s36, 0x100
	s_addc_u32 s57, s37, 0
	s_mov_b32 s58, -2
	s_waitcnt lgkmcnt(0)
	s_add_u32 s36, s34, 0xfffc0080
	s_addc_u32 s37, s35, -1
	s_add_i32 s59, 0, 0x10000
	s_cmp_eq_u32 s58, 12
	s_cselect_b32 s39, s23, s37
	s_cselect_b32 s38, s29, s36
	s_cselect_b32 s37, s21, s57
	s_cselect_b32 s36, s31, s56
	s_add_i32 s62, 0, 0x14000
	v_add_u32_e32 v142, s59, v179
	v_add_u32_e32 v170, s62, v179
	ds_read_b128 v[130:133], v142
	ds_read_b128 v[134:137], v142 offset:1024
	ds_read_b128 v[138:141], v142 offset:2048
	ds_read_b128 v[142:145], v142 offset:3072
	ds_read_b128 v[146:149], v170
	ds_read_b128 v[150:153], v170 offset:1024
	ds_read_b128 v[166:169], v170 offset:2048
	ds_read_b128 v[170:173], v170 offset:3072
	v_lshl_add_u64 v[212:213], s[34:35], 0, v[162:163]
	s_add_i32 m0, s46, 0xc000
	ds_read_b128 v[174:177], v187
	ds_read_b128 v[180:183], v187 offset:1024
	ds_read_b128 v[188:191], v187 offset:2048
	ds_read_b128 v[192:195], v187 offset:3072
	ds_read_b128 v[196:199], v187 offset:4096
	ds_read_b128 v[200:203], v187 offset:5120
	ds_read_b128 v[204:207], v187 offset:6144
	ds_read_b128 v[208:211], v187 offset:7168
	global_load_lds_dwordx4 v[212:213], off
	v_lshl_add_u64 v[212:213], s[34:35], 0, v[164:165]
	s_add_i32 m0, s46, 0xe000
	s_nop 0
	global_load_lds_dwordx4 v[212:213], off
	s_waitcnt vmcnt(8) lgkmcnt(0)
	s_barrier
	v_mfma_f32_16x16x32_bf16 v[126:129], v[130:133], v[174:177], 0
	v_mfma_f32_16x16x32_bf16 v[122:125], v[138:141], v[174:177], 0
	v_mfma_f32_16x16x32_bf16 v[110:113], v[130:133], v[188:191], 0
	v_mfma_f32_16x16x32_bf16 v[106:109], v[138:141], v[188:191], 0
	v_mfma_f32_16x16x32_bf16 v[94:97], v[130:133], v[196:199], 0
	v_mfma_f32_16x16x32_bf16 v[90:93], v[138:141], v[196:199], 0
	v_mfma_f32_16x16x32_bf16 v[78:81], v[130:133], v[204:207], 0
	v_mfma_f32_16x16x32_bf16 v[74:77], v[138:141], v[204:207], 0
	v_mfma_f32_16x16x32_bf16 v[126:129], v[134:137], v[180:183], v[126:129]
	v_mfma_f32_16x16x32_bf16 v[122:125], v[142:145], v[180:183], v[122:125]
	v_mfma_f32_16x16x32_bf16 v[110:113], v[134:137], v[192:195], v[110:113]
	v_mfma_f32_16x16x32_bf16 v[106:109], v[142:145], v[192:195], v[106:109]
	v_mfma_f32_16x16x32_bf16 v[94:97], v[134:137], v[200:203], v[94:97]
	v_mfma_f32_16x16x32_bf16 v[90:93], v[142:145], v[200:203], v[90:93]
	v_mfma_f32_16x16x32_bf16 v[78:81], v[134:137], v[208:211], v[78:81]
	v_mfma_f32_16x16x32_bf16 v[74:77], v[142:145], v[208:211], v[74:77]
	v_mfma_f32_16x16x32_bf16 v[118:121], v[146:149], v[174:177], 0
	v_mfma_f32_16x16x32_bf16 v[114:117], v[166:169], v[174:177], 0
	v_mfma_f32_16x16x32_bf16 v[102:105], v[146:149], v[188:191], 0
	v_mfma_f32_16x16x32_bf16 v[98:101], v[166:169], v[188:191], 0
	v_mfma_f32_16x16x32_bf16 v[86:89], v[146:149], v[196:199], 0
	v_mfma_f32_16x16x32_bf16 v[82:85], v[166:169], v[196:199], 0
	v_mfma_f32_16x16x32_bf16 v[70:73], v[146:149], v[204:207], 0
	v_mfma_f32_16x16x32_bf16 v[66:69], v[166:169], v[204:207], 0
	v_mfma_f32_16x16x32_bf16 v[118:121], v[150:153], v[180:183], v[118:121]
	v_mfma_f32_16x16x32_bf16 v[114:117], v[170:173], v[180:183], v[114:117]
	v_mfma_f32_16x16x32_bf16 v[102:105], v[150:153], v[192:195], v[102:105]
	v_mfma_f32_16x16x32_bf16 v[98:101], v[170:173], v[192:195], v[98:101]
	v_mfma_f32_16x16x32_bf16 v[86:89], v[150:153], v[200:203], v[86:89]
	v_mfma_f32_16x16x32_bf16 v[82:85], v[170:173], v[200:203], v[82:85]
	v_mfma_f32_16x16x32_bf16 v[70:73], v[150:153], v[208:211], v[70:73]
	v_mfma_f32_16x16x32_bf16 v[66:69], v[170:173], v[208:211], v[66:69]
	s_barrier
	s_add_i32 s59, s59, s33
	v_lshl_add_u64 v[212:213], s[36:37], 0, v[156:157]
	s_mov_b32 m0, s59
	ds_read_b128 v[174:177], v187 offset:16384
	ds_read_b128 v[180:183], v187 offset:17408
	ds_read_b128 v[188:191], v187 offset:18432
	ds_read_b128 v[192:195], v187 offset:19456
	ds_read_b128 v[196:199], v187 offset:20480
	ds_read_b128 v[200:203], v187 offset:21504
	ds_read_b128 v[204:207], v187 offset:22528
	ds_read_b128 v[208:211], v187 offset:23552
	global_load_lds_dwordx4 v[212:213], off
	s_add_i32 m0, s59, 0x2000
	s_add_u32 s60, s36, 0x40000
	v_lshl_add_u64 v[214:215], s[36:37], 0, v[160:161]
	s_addc_u32 s61, s37, 0
	s_add_i32 s59, s62, s33
	global_load_lds_dwordx4 v[214:215], off
	v_lshl_add_u64 v[216:217], s[60:61], 0, v[156:157]
	s_mov_b32 m0, s59
	v_lshl_add_u64 v[218:219], s[38:39], 0, v[158:159]
	global_load_lds_dwordx4 v[216:217], off
	v_lshl_add_u64 v[216:217], s[60:61], 0, v[160:161]
	s_add_i32 m0, s59, 0x2000
	s_nop 0
	global_load_lds_dwordx4 v[216:217], off
	v_lshl_add_u64 v[216:217], s[38:39], 0, v[154:155]
	s_mov_b32 m0, s46
	s_nop 0
	global_load_lds_dwordx4 v[216:217], off
	s_mov_b32 m0, s47
	s_nop 0
	global_load_lds_dwordx4 v[218:219], off
	s_waitcnt vmcnt(8) lgkmcnt(0)
	s_barrier
; #define PG8_STAGE(bufoff, gbase, voff) do { _Pragma("unroll") for (int _i = 0; _i < 2; ++_i) \
;         __builtin_amdgcn_global_load_lds((const unsigned*)((const char*)(gbase) + (voff)[_i]), (PG8_LAS unsigned*)(lds + (bufoff) + ldsw + _i * 8192), 16, 0, 0); } while (0)
; #define PG8_LDA(dst, b, h) do { _Pragma("unroll") for (int m = 0; m < 4; ++m) _Pragma("unroll") for (int k = 0; k < 2; ++k) dst[m][k] = *(const PG8_LAS bf16x8*)(lds + PG8_SA(b, h) + aoff + m * 2048 + k * 1024); } while (0)
; #define PG8_LDB(dst, b, h) do { _Pragma("unroll") for (int n = 0; n < 2; ++n) _Pragma("unroll") for (int k = 0; k < 2; ++k) dst[n][k] = *(const PG8_LAS bf16x8*)(lds + PG8_SB(b, h) + boff + n * 2048 + k * 1024); } while (0)
; #define PG8_MMA(ai, bj, At, Bt) do { __builtin_amdgcn_s_setprio(1); _Pragma("unroll") for (int m = 0; m < 4; ++m) _Pragma("unroll") for (int n = 0; n < 2; ++n) _Pragma("unroll") for (int k = 0; k < 2; ++k) \
;         acc[ai][bj][m][n] = __builtin_amdgcn_mfma_f32_16x16x32_bf16(Bt[n][k], At[m][k], acc[ai][bj][m][n], 0, 0, 0); __builtin_amdgcn_s_setprio(0); } while (0)
; #define PG8_WAIT_V(n) asm volatile("s_waitcnt vmcnt(" #n ")" ::: "memory")
; #define PG8_WAIT_L(n) asm volatile("s_waitcnt lgkmcnt(" #n ")" ::: "memory")
; #define PG8_BAR __builtin_amdgcn_s_barrier()
; #define PG8_SCHED __builtin_amdgcn_sched_barrier(0)
; template <class Epi, class Sched, bool ALIGN_EPI = false, bool SP2 = false>
; __device__ __forceinline__ void gemm_phase(PG8_LAS unsigned char* lds, const Gemm g, const Sched& S, const Epi& E) {
;     ...
;             PG8_LDA(At, 0, 1); PG8_STAGE(PG8_SB(0, 0), b2, voffB); PG8_STAGE(PG8_SB(0, 1), b2 + hstep, voffB); PG8_STAGE(PG8_SA(0, 0), a2, voffA);
;             PG8_WAIT_V(8); PG8_WAIT_L(0); PG8_BAR; PG8_MMA(1, 0, At, B0); PG8_MMA(1, 1, At, B1); PG8_BAR; PG8_SCHED;
;             PG8_LDB(B0, 1, 0); PG8_LDB(B1, 1, 1); PG8_SCHED; PG8_LDA(At, 1, 0); PG8_STAGE(PG8_SA(0, 1), a2 + hstep, voffA);
;             PG8_WAIT_V(8); PG8_WAIT_L(0); PG8_BAR; PG8_MMA(0, 0, At, B0); PG8_MMA(0, 1, At, B1); PG8_BAR; PG8_SCHED;
	v_mfma_f32_16x16x32_bf16 v[62:65], v[130:133], v[174:177], 0
	v_mfma_f32_16x16x32_bf16 v[58:61], v[138:141], v[174:177], 0
	v_mfma_f32_16x16x32_bf16 v[46:49], v[130:133], v[188:191], 0
	v_mfma_f32_16x16x32_bf16 v[42:45], v[138:141], v[188:191], 0
	v_mfma_f32_16x16x32_bf16 v[30:33], v[130:133], v[196:199], 0
	v_mfma_f32_16x16x32_bf16 v[26:29], v[138:141], v[196:199], 0
	v_mfma_f32_16x16x32_bf16 v[14:17], v[130:133], v[204:207], 0
	v_mfma_f32_16x16x32_bf16 v[10:13], v[138:141], v[204:207], 0
	v_mfma_f32_16x16x32_bf16 v[62:65], v[134:137], v[180:183], v[62:65]
	v_mfma_f32_16x16x32_bf16 v[58:61], v[142:145], v[180:183], v[58:61]
	v_mfma_f32_16x16x32_bf16 v[46:49], v[134:137], v[192:195], v[46:49]
	v_mfma_f32_16x16x32_bf16 v[42:45], v[142:145], v[192:195], v[42:45]
	v_mfma_f32_16x16x32_bf16 v[30:33], v[134:137], v[200:203], v[30:33]
	v_mfma_f32_16x16x32_bf16 v[26:29], v[142:145], v[200:203], v[26:29]
	v_mfma_f32_16x16x32_bf16 v[14:17], v[134:137], v[208:211], v[14:17]
	v_mfma_f32_16x16x32_bf16 v[10:13], v[142:145], v[208:211], v[10:13]
	v_mfma_f32_16x16x32_bf16 v[54:57], v[146:149], v[174:177], 0
	v_mfma_f32_16x16x32_bf16 v[50:53], v[166:169], v[174:177], 0
	v_mfma_f32_16x16x32_bf16 v[38:41], v[146:149], v[188:191], 0
	v_mfma_f32_16x16x32_bf16 v[34:37], v[166:169], v[188:191], 0
	v_mfma_f32_16x16x32_bf16 v[22:25], v[146:149], v[196:199], 0
	v_mfma_f32_16x16x32_bf16 v[18:21], v[166:169], v[196:199], 0
	v_mfma_f32_16x16x32_bf16 v[6:9], v[146:149], v[204:207], 0
	v_mfma_f32_16x16x32_bf16 v[2:5], v[166:169], v[204:207], 0
	v_mfma_f32_16x16x32_bf16 v[54:57], v[150:153], v[180:183], v[54:57]
	v_mfma_f32_16x16x32_bf16 v[50:53], v[170:173], v[180:183], v[50:53]
	v_mfma_f32_16x16x32_bf16 v[38:41], v[150:153], v[192:195], v[38:41]
	v_mfma_f32_16x16x32_bf16 v[34:37], v[170:173], v[192:195], v[34:37]
	v_mfma_f32_16x16x32_bf16 v[22:25], v[150:153], v[200:203], v[22:25]
	v_mfma_f32_16x16x32_bf16 v[18:21], v[170:173], v[200:203], v[18:21]
	v_mfma_f32_16x16x32_bf16 v[6:9], v[150:153], v[208:211], v[6:9]
	v_mfma_f32_16x16x32_bf16 v[2:5], v[170:173], v[208:211], v[2:5]
	s_barrier
	s_add_i32 s59, 0, 0x18000
	s_add_i32 s60, 0, 0x1c000
	v_add_u32_e32 v142, s59, v179
	v_add_u32_e32 v170, s60, v179
	ds_read_b128 v[130:133], v142
	ds_read_b128 v[134:137], v142 offset:1024
	ds_read_b128 v[138:141], v142 offset:2048
	ds_read_b128 v[142:145], v142 offset:3072
	ds_read_b128 v[146:149], v170
	ds_read_b128 v[150:153], v170 offset:1024
	ds_read_b128 v[166:169], v170 offset:2048
	ds_read_b128 v[170:173], v170 offset:3072
	s_add_u32 s38, s38, 0x40000
	s_addc_u32 s39, s39, 0
	s_mov_b32 m0, s48
	v_lshl_add_u64 v[220:221], s[38:39], 0, v[154:155]
	ds_read_b128 v[174:177], v187 offset:32768
	ds_read_b128 v[180:183], v187 offset:33792
	ds_read_b128 v[188:191], v187 offset:34816
	ds_read_b128 v[192:195], v187 offset:35840
	ds_read_b128 v[196:199], v187 offset:36864
	ds_read_b128 v[200:203], v187 offset:37888
	ds_read_b128 v[204:207], v187 offset:38912
	ds_read_b128 v[208:211], v187 offset:39936
	global_load_lds_dwordx4 v[220:221], off
	v_lshl_add_u64 v[220:221], s[38:39], 0, v[158:159]
	s_mov_b32 m0, s49
	s_nop 0
	global_load_lds_dwordx4 v[220:221], off
	s_waitcnt vmcnt(8) lgkmcnt(0)
	s_barrier
	v_mfma_f32_16x16x32_bf16 v[126:129], v[130:133], v[174:177], v[126:129]
	v_mfma_f32_16x16x32_bf16 v[122:125], v[138:141], v[174:177], v[122:125]
	v_mfma_f32_16x16x32_bf16 v[110:113], v[130:133], v[188:191], v[110:113]
	v_mfma_f32_16x16x32_bf16 v[106:109], v[138:141], v[188:191], v[106:109]
	v_mfma_f32_16x16x32_bf16 v[94:97], v[130:133], v[196:199], v[94:97]
	v_mfma_f32_16x16x32_bf16 v[90:93], v[138:141], v[196:199], v[90:93]
	v_mfma_f32_16x16x32_bf16 v[78:81], v[130:133], v[204:207], v[78:81]
	v_mfma_f32_16x16x32_bf16 v[74:77], v[138:141], v[204:207], v[74:77]
	v_mfma_f32_16x16x32_bf16 v[126:129], v[134:137], v[180:183], v[126:129]
	v_mfma_f32_16x16x32_bf16 v[122:125], v[142:145], v[180:183], v[122:125]
	v_mfma_f32_16x16x32_bf16 v[110:113], v[134:137], v[192:195], v[110:113]
	v_mfma_f32_16x16x32_bf16 v[106:109], v[142:145], v[192:195], v[106:109]
	v_mfma_f32_16x16x32_bf16 v[94:97], v[134:137], v[200:203], v[94:97]
	v_mfma_f32_16x16x32_bf16 v[90:93], v[142:145], v[200:203], v[90:93]
	v_mfma_f32_16x16x32_bf16 v[78:81], v[134:137], v[208:211], v[78:81]
	v_mfma_f32_16x16x32_bf16 v[74:77], v[142:145], v[208:211], v[74:77]
	v_mfma_f32_16x16x32_bf16 v[118:121], v[146:149], v[174:177], v[118:121]
	v_mfma_f32_16x16x32_bf16 v[114:117], v[166:169], v[174:177], v[114:117]
	v_mfma_f32_16x16x32_bf16 v[102:105], v[146:149], v[188:191], v[102:105]
	v_mfma_f32_16x16x32_bf16 v[98:101], v[166:169], v[188:191], v[98:101]
	v_mfma_f32_16x16x32_bf16 v[86:89], v[146:149], v[196:199], v[86:89]
	v_mfma_f32_16x16x32_bf16 v[82:85], v[166:169], v[196:199], v[82:85]
	v_mfma_f32_16x16x32_bf16 v[70:73], v[146:149], v[204:207], v[70:73]
	v_mfma_f32_16x16x32_bf16 v[66:69], v[166:169], v[204:207], v[66:69]
	v_mfma_f32_16x16x32_bf16 v[118:121], v[150:153], v[180:183], v[118:121]
	v_mfma_f32_16x16x32_bf16 v[114:117], v[170:173], v[180:183], v[114:117]
	v_mfma_f32_16x16x32_bf16 v[102:105], v[150:153], v[192:195], v[102:105]
	v_mfma_f32_16x16x32_bf16 v[98:101], v[170:173], v[192:195], v[98:101]
	v_mfma_f32_16x16x32_bf16 v[86:89], v[150:153], v[200:203], v[86:89]
	v_mfma_f32_16x16x32_bf16 v[82:85], v[170:173], v[200:203], v[82:85]
	v_mfma_f32_16x16x32_bf16 v[70:73], v[150:153], v[208:211], v[70:73]
	v_mfma_f32_16x16x32_bf16 v[66:69], v[170:173], v[208:211], v[66:69]
	s_barrier
; #define PG8_STAGE(bufoff, gbase, voff) do { _Pragma("unroll") for (int _i = 0; _i < 2; ++_i) \
;         __builtin_amdgcn_global_load_lds((const unsigned*)((const char*)(gbase) + (voff)[_i]), (PG8_LAS unsigned*)(lds + (bufoff) + ldsw + _i * 8192), 16, 0, 0); } while (0)
; #define PG8_LDA(dst, b, h) do { _Pragma("unroll") for (int m = 0; m < 4; ++m) _Pragma("unroll") for (int k = 0; k < 2; ++k) dst[m][k] = *(const PG8_LAS bf16x8*)(lds + PG8_SA(b, h) + aoff + m * 2048 + k * 1024); } while (0)
; #define PG8_LDB(dst, b, h) do { _Pragma("unroll") for (int n = 0; n < 2; ++n) _Pragma("unroll") for (int k = 0; k < 2; ++k) dst[n][k] = *(const PG8_LAS bf16x8*)(lds + PG8_SB(b, h) + boff + n * 2048 + k * 1024); } while (0)
; #define PG8_MMA(ai, bj, At, Bt) do { __builtin_amdgcn_s_setprio(1); _Pragma("unroll") for (int m = 0; m < 4; ++m) _Pragma("unroll") for (int n = 0; n < 2; ++n) _Pragma("unroll") for (int k = 0; k < 2; ++k) \
;         acc[ai][bj][m][n] = __builtin_amdgcn_mfma_f32_16x16x32_bf16(Bt[n][k], At[m][k], acc[ai][bj][m][n], 0, 0, 0); __builtin_amdgcn_s_setprio(0); } while (0)
; #define PG8_WAIT_V(n) asm volatile("s_waitcnt vmcnt(" #n ")" ::: "memory")
; #define PG8_BAR __builtin_amdgcn_s_barrier()
; template <class Epi, class Sched, bool ALIGN_EPI = false, bool SP2 = false>
; __device__ __forceinline__ void gemm_phase(PG8_LAS unsigned char* lds, const Gemm g, const Sched& S, const Epi& E) {
;     ...
;         for (int t = 0; t < nt; t += 2) {
;             const bool last = (t == nt - 2);
;             const char* a1 = cA + (size_t)(t + 1) * kstep;
;             const char* a2 = last ? nA : cA + (size_t)(t + 2) * kstep; const char* b2 = last ? nB : cB + (size_t)(t + 2) * kstep;
;             const char* a3 = a2 + kstep; const char* b3 = b2 + kstep;
;             if (last && has_next) S.a_ready(nxt);
;             if constexpr (SP2) {
;             PG8_LDB(B0, 0, 0); PG8_LDB(B1, 0, 1); PG8_SCHED; PG8_LDA(At, 0, 0); PG8_STAGE(PG8_SA(1, 1), a1 + hstep, voffA);
;             PG8_WAIT_V(8); PG8_WAIT_L(0); PG8_BAR; PG8_MMA(0, 0, At, B0); PG8_MMA(0, 1, At, B1); PG8_BAR; PG8_SCHED;
;     ...
;             PG8_LDA(At, 1, 1); PG8_STAGE(PG8_SB(1, 0), b3, voffB); PG8_STAGE(PG8_SB(1, 1), b3 + hstep, voffB); PG8_STAGE(PG8_SA(1, 0), a3, voffA);
;             PG8_WAIT_V(8); PG8_WAIT_L(0); PG8_BAR; PG8_MMA(1, 0, At, B0); PG8_MMA(1, 1, At, B1); PG8_BAR; PG8_SCHED;
	s_add_i32 s38, s59, s33
	v_lshl_add_u64 v[212:213], v[212:213], 0, s[80:81]
	s_mov_b32 m0, s38
	ds_read_b128 v[174:177], v187 offset:49152
	ds_read_b128 v[180:183], v187 offset:50176
	ds_read_b128 v[188:191], v187 offset:51200
	ds_read_b128 v[192:195], v187 offset:52224
	ds_read_b128 v[196:199], v187 offset:53248
	ds_read_b128 v[200:203], v187 offset:54272
	ds_read_b128 v[204:207], v187 offset:55296
	ds_read_b128 v[208:211], v187 offset:56320
	global_load_lds_dwordx4 v[212:213], off
	s_add_i32 m0, s38, 0x2000
	s_add_u32 s36, s36, 0x40080
	v_lshl_add_u64 v[212:213], v[214:215], 0, s[80:81]
	s_addc_u32 s37, s37, 0
	s_add_i32 s38, s60, s33
	global_load_lds_dwordx4 v[212:213], off
	v_lshl_add_u64 v[212:213], s[36:37], 0, v[156:157]
	s_mov_b32 m0, s38
	s_nop 0
	global_load_lds_dwordx4 v[212:213], off
	v_lshl_add_u64 v[212:213], s[36:37], 0, v[160:161]
	s_add_i32 m0, s38, 0x2000
	s_nop 0
	global_load_lds_dwordx4 v[212:213], off
	v_lshl_add_u64 v[212:213], v[216:217], 0, s[80:81]
	s_mov_b32 m0, s51
	s_nop 0
	global_load_lds_dwordx4 v[212:213], off
	v_lshl_add_u64 v[212:213], v[218:219], 0, s[80:81]
	s_mov_b32 m0, s52
	s_nop 0
	global_load_lds_dwordx4 v[212:213], off
	s_waitcnt vmcnt(8) lgkmcnt(0)
	s_barrier
	v_mfma_f32_16x16x32_bf16 v[62:65], v[130:133], v[174:177], v[62:65]
	v_mfma_f32_16x16x32_bf16 v[58:61], v[138:141], v[174:177], v[58:61]
	v_mfma_f32_16x16x32_bf16 v[46:49], v[130:133], v[188:191], v[46:49]
	v_mfma_f32_16x16x32_bf16 v[42:45], v[138:141], v[188:191], v[42:45]
	v_mfma_f32_16x16x32_bf16 v[30:33], v[130:133], v[196:199], v[30:33]
	v_mfma_f32_16x16x32_bf16 v[26:29], v[138:141], v[196:199], v[26:29]
	v_mfma_f32_16x16x32_bf16 v[14:17], v[130:133], v[204:207], v[14:17]
	v_mfma_f32_16x16x32_bf16 v[10:13], v[138:141], v[204:207], v[10:13]
	v_mfma_f32_16x16x32_bf16 v[62:65], v[134:137], v[180:183], v[62:65]
	v_mfma_f32_16x16x32_bf16 v[58:61], v[142:145], v[180:183], v[58:61]
	v_mfma_f32_16x16x32_bf16 v[46:49], v[134:137], v[192:195], v[46:49]
	v_mfma_f32_16x16x32_bf16 v[42:45], v[142:145], v[192:195], v[42:45]
	v_mfma_f32_16x16x32_bf16 v[30:33], v[134:137], v[200:203], v[30:33]
	v_mfma_f32_16x16x32_bf16 v[26:29], v[142:145], v[200:203], v[26:29]
	v_mfma_f32_16x16x32_bf16 v[14:17], v[134:137], v[208:211], v[14:17]
	v_mfma_f32_16x16x32_bf16 v[10:13], v[142:145], v[208:211], v[10:13]
	v_mfma_f32_16x16x32_bf16 v[54:57], v[146:149], v[174:177], v[54:57]
	v_mfma_f32_16x16x32_bf16 v[50:53], v[166:169], v[174:177], v[50:53]
	v_mfma_f32_16x16x32_bf16 v[38:41], v[146:149], v[188:191], v[38:41]
	v_mfma_f32_16x16x32_bf16 v[34:37], v[166:169], v[188:191], v[34:37]
	v_mfma_f32_16x16x32_bf16 v[22:25], v[146:149], v[196:199], v[22:25]
	v_mfma_f32_16x16x32_bf16 v[18:21], v[166:169], v[196:199], v[18:21]
	v_mfma_f32_16x16x32_bf16 v[6:9], v[146:149], v[204:207], v[6:9]
	v_mfma_f32_16x16x32_bf16 v[2:5], v[166:169], v[204:207], v[2:5]
	v_mfma_f32_16x16x32_bf16 v[54:57], v[150:153], v[180:183], v[54:57]
	v_mfma_f32_16x16x32_bf16 v[50:53], v[170:173], v[180:183], v[50:53]
	v_mfma_f32_16x16x32_bf16 v[38:41], v[150:153], v[192:195], v[38:41]
	v_mfma_f32_16x16x32_bf16 v[34:37], v[170:173], v[192:195], v[34:37]
	v_mfma_f32_16x16x32_bf16 v[22:25], v[150:153], v[200:203], v[22:25]
	v_mfma_f32_16x16x32_bf16 v[18:21], v[170:173], v[200:203], v[18:21]
	v_mfma_f32_16x16x32_bf16 v[6:9], v[150:153], v[208:211], v[6:9]
	v_mfma_f32_16x16x32_bf16 v[2:5], v[170:173], v[208:211], v[2:5]
	s_barrier
	s_add_i32 s58, s58, 2
	s_add_u32 s34, s34, 0x100
	s_addc_u32 s35, s35, 0
	s_add_u32 s56, s56, 0x100
	s_addc_u32 s57, s57, 0
	s_cmp_gt_u32 s58, 13
	s_branch .LBB0_1062
.LBB0_1062:
	s_add_u32 s36, s34, 0xfffc0080
	s_addc_u32 s37, s35, -1
	s_add_i32 s59, 0, 0x10000
	s_cmp_eq_u32 s58, 12
	s_cselect_b32 s39, s23, s37
	s_cselect_b32 s38, s29, s36
	s_cselect_b32 s37, s21, s57
	s_cselect_b32 s36, s31, s56
	s_add_i32 s62, 0, 0x14000
	v_add_u32_e32 v142, s59, v179
	v_add_u32_e32 v170, s62, v179
	ds_read_b128 v[130:133], v142
	ds_read_b128 v[134:137], v142 offset:1024
	ds_read_b128 v[138:141], v142 offset:2048
	ds_read_b128 v[142:145], v142 offset:3072
	ds_read_b128 v[146:149], v170
	ds_read_b128 v[150:153], v170 offset:1024
	ds_read_b128 v[166:169], v170 offset:2048
	ds_read_b128 v[170:173], v170 offset:3072
	v_lshl_add_u64 v[212:213], s[34:35], 0, v[162:163]
	s_add_i32 m0, s46, 0xc000
	ds_read_b128 v[174:177], v187
	ds_read_b128 v[180:183], v187 offset:1024
	ds_read_b128 v[188:191], v187 offset:2048
	ds_read_b128 v[192:195], v187 offset:3072
	ds_read_b128 v[196:199], v187 offset:4096
	ds_read_b128 v[200:203], v187 offset:5120
	ds_read_b128 v[204:207], v187 offset:6144
	ds_read_b128 v[208:211], v187 offset:7168
	global_load_lds_dwordx4 v[212:213], off
	v_lshl_add_u64 v[212:213], s[34:35], 0, v[164:165]
	s_add_i32 m0, s46, 0xe000
	s_nop 0
	global_load_lds_dwordx4 v[212:213], off
	s_waitcnt vmcnt(8) lgkmcnt(0)
	s_barrier
; #define PG8_STAGE(bufoff, gbase, voff) do { _Pragma("unroll") for (int _i = 0; _i < 2; ++_i) \
;         __builtin_amdgcn_global_load_lds((const unsigned*)((const char*)(gbase) + (voff)[_i]), (PG8_LAS unsigned*)(lds + (bufoff) + ldsw + _i * 8192), 16, 0, 0); } while (0)
; #define PG8_LDA(dst, b, h) do { _Pragma("unroll") for (int m = 0; m < 4; ++m) _Pragma("unroll") for (int k = 0; k < 2; ++k) dst[m][k] = *(const PG8_LAS bf16x8*)(lds + PG8_SA(b, h) + aoff + m * 2048 + k * 1024); } while (0)
; #define PG8_LDB(dst, b, h) do { _Pragma("unroll") for (int n = 0; n < 2; ++n) _Pragma("unroll") for (int k = 0; k < 2; ++k) dst[n][k] = *(const PG8_LAS bf16x8*)(lds + PG8_SB(b, h) + boff + n * 2048 + k * 1024); } while (0)
; #define PG8_MMA(ai, bj, At, Bt) do { __builtin_amdgcn_s_setprio(1); _Pragma("unroll") for (int m = 0; m < 4; ++m) _Pragma("unroll") for (int n = 0; n < 2; ++n) _Pragma("unroll") for (int k = 0; k < 2; ++k) \
;         acc[ai][bj][m][n] = __builtin_amdgcn_mfma_f32_16x16x32_bf16(Bt[n][k], At[m][k], acc[ai][bj][m][n], 0, 0, 0); __builtin_amdgcn_s_setprio(0); } while (0)
; #define PG8_WAIT_V(n) asm volatile("s_waitcnt vmcnt(" #n ")" ::: "memory")
; #define PG8_WAIT_L(n) asm volatile("s_waitcnt lgkmcnt(" #n ")" ::: "memory")
; #define PG8_BAR __builtin_amdgcn_s_barrier()
; #define PG8_SCHED __builtin_amdgcn_sched_barrier(0)
; template <class Epi, class Sched, bool ALIGN_EPI = false, bool SP2 = false>
; __device__ __forceinline__ void gemm_phase(PG8_LAS unsigned char* lds, const Gemm g, const Sched& S, const Epi& E) {
;     ...
;             PG8_LDB(B0, 0, 0); PG8_LDB(B1, 0, 1); PG8_SCHED; PG8_LDA(At, 0, 0); PG8_STAGE(PG8_SA(1, 1), a1 + hstep, voffA);
;             PG8_WAIT_V(8); PG8_WAIT_L(0); PG8_BAR; PG8_MMA(0, 0, At, B0); PG8_MMA(0, 1, At, B1); PG8_BAR; PG8_SCHED;
;             PG8_LDA(At, 0, 1); PG8_STAGE(PG8_SB(0, 0), b2, voffB); PG8_STAGE(PG8_SB(0, 1), b2 + hstep, voffB); PG8_STAGE(PG8_SA(0, 0), a2, voffA);
;             PG8_WAIT_V(8); PG8_WAIT_L(0); PG8_BAR; PG8_MMA(1, 0, At, B0); PG8_MMA(1, 1, At, B1); PG8_BAR; PG8_SCHED;
	v_mfma_f32_16x16x32_bf16 v[126:129], v[130:133], v[174:177], v[126:129]
	v_mfma_f32_16x16x32_bf16 v[122:125], v[138:141], v[174:177], v[122:125]
	v_mfma_f32_16x16x32_bf16 v[110:113], v[130:133], v[188:191], v[110:113]
	v_mfma_f32_16x16x32_bf16 v[106:109], v[138:141], v[188:191], v[106:109]
	v_mfma_f32_16x16x32_bf16 v[94:97], v[130:133], v[196:199], v[94:97]
	v_mfma_f32_16x16x32_bf16 v[90:93], v[138:141], v[196:199], v[90:93]
	v_mfma_f32_16x16x32_bf16 v[78:81], v[130:133], v[204:207], v[78:81]
	v_mfma_f32_16x16x32_bf16 v[74:77], v[138:141], v[204:207], v[74:77]
	v_mfma_f32_16x16x32_bf16 v[126:129], v[134:137], v[180:183], v[126:129]
	v_mfma_f32_16x16x32_bf16 v[122:125], v[142:145], v[180:183], v[122:125]
	v_mfma_f32_16x16x32_bf16 v[110:113], v[134:137], v[192:195], v[110:113]
	v_mfma_f32_16x16x32_bf16 v[106:109], v[142:145], v[192:195], v[106:109]
	v_mfma_f32_16x16x32_bf16 v[94:97], v[134:137], v[200:203], v[94:97]
	v_mfma_f32_16x16x32_bf16 v[90:93], v[142:145], v[200:203], v[90:93]
	v_mfma_f32_16x16x32_bf16 v[78:81], v[134:137], v[208:211], v[78:81]
	v_mfma_f32_16x16x32_bf16 v[74:77], v[142:145], v[208:211], v[74:77]
	v_mfma_f32_16x16x32_bf16 v[118:121], v[146:149], v[174:177], v[118:121]
	v_mfma_f32_16x16x32_bf16 v[114:117], v[166:169], v[174:177], v[114:117]
	v_mfma_f32_16x16x32_bf16 v[102:105], v[146:149], v[188:191], v[102:105]
	v_mfma_f32_16x16x32_bf16 v[98:101], v[166:169], v[188:191], v[98:101]
	v_mfma_f32_16x16x32_bf16 v[86:89], v[146:149], v[196:199], v[86:89]
	v_mfma_f32_16x16x32_bf16 v[82:85], v[166:169], v[196:199], v[82:85]
	v_mfma_f32_16x16x32_bf16 v[70:73], v[146:149], v[204:207], v[70:73]
	v_mfma_f32_16x16x32_bf16 v[66:69], v[166:169], v[204:207], v[66:69]
	v_mfma_f32_16x16x32_bf16 v[118:121], v[150:153], v[180:183], v[118:121]
	v_mfma_f32_16x16x32_bf16 v[114:117], v[170:173], v[180:183], v[114:117]
	v_mfma_f32_16x16x32_bf16 v[102:105], v[150:153], v[192:195], v[102:105]
	v_mfma_f32_16x16x32_bf16 v[98:101], v[170:173], v[192:195], v[98:101]
	v_mfma_f32_16x16x32_bf16 v[86:89], v[150:153], v[200:203], v[86:89]
	v_mfma_f32_16x16x32_bf16 v[82:85], v[170:173], v[200:203], v[82:85]
	v_mfma_f32_16x16x32_bf16 v[70:73], v[150:153], v[208:211], v[70:73]
	v_mfma_f32_16x16x32_bf16 v[66:69], v[170:173], v[208:211], v[66:69]
	s_barrier
	s_add_i32 s59, s59, s33
	v_lshl_add_u64 v[212:213], s[36:37], 0, v[156:157]
	s_mov_b32 m0, s59
	ds_read_b128 v[174:177], v187 offset:16384
	ds_read_b128 v[180:183], v187 offset:17408
	ds_read_b128 v[188:191], v187 offset:18432
	ds_read_b128 v[192:195], v187 offset:19456
	ds_read_b128 v[196:199], v187 offset:20480
	ds_read_b128 v[200:203], v187 offset:21504
	ds_read_b128 v[204:207], v187 offset:22528
	ds_read_b128 v[208:211], v187 offset:23552
	global_load_lds_dwordx4 v[212:213], off
	s_add_i32 m0, s59, 0x2000
	s_add_u32 s60, s36, 0x40000
	v_lshl_add_u64 v[214:215], s[36:37], 0, v[160:161]
	s_addc_u32 s61, s37, 0
	s_add_i32 s59, s62, s33
	global_load_lds_dwordx4 v[214:215], off
	v_lshl_add_u64 v[216:217], s[60:61], 0, v[156:157]
	s_mov_b32 m0, s59
	v_lshl_add_u64 v[218:219], s[38:39], 0, v[158:159]
	global_load_lds_dwordx4 v[216:217], off
	v_lshl_add_u64 v[216:217], s[60:61], 0, v[160:161]
	s_add_i32 m0, s59, 0x2000
	s_nop 0
	global_load_lds_dwordx4 v[216:217], off
	v_lshl_add_u64 v[216:217], s[38:39], 0, v[154:155]
	s_mov_b32 m0, s46
	s_nop 0
	global_load_lds_dwordx4 v[216:217], off
	s_mov_b32 m0, s47
	s_nop 0
	global_load_lds_dwordx4 v[218:219], off
	s_waitcnt vmcnt(8) lgkmcnt(0)
	s_barrier
	v_mfma_f32_16x16x32_bf16 v[62:65], v[130:133], v[174:177], v[62:65]
	v_mfma_f32_16x16x32_bf16 v[58:61], v[138:141], v[174:177], v[58:61]
	v_mfma_f32_16x16x32_bf16 v[46:49], v[130:133], v[188:191], v[46:49]
	v_mfma_f32_16x16x32_bf16 v[42:45], v[138:141], v[188:191], v[42:45]
	v_mfma_f32_16x16x32_bf16 v[30:33], v[130:133], v[196:199], v[30:33]
	v_mfma_f32_16x16x32_bf16 v[26:29], v[138:141], v[196:199], v[26:29]
	v_mfma_f32_16x16x32_bf16 v[14:17], v[130:133], v[204:207], v[14:17]
	v_mfma_f32_16x16x32_bf16 v[10:13], v[138:141], v[204:207], v[10:13]
	v_mfma_f32_16x16x32_bf16 v[62:65], v[134:137], v[180:183], v[62:65]
	v_mfma_f32_16x16x32_bf16 v[58:61], v[142:145], v[180:183], v[58:61]
	v_mfma_f32_16x16x32_bf16 v[46:49], v[134:137], v[192:195], v[46:49]
	v_mfma_f32_16x16x32_bf16 v[42:45], v[142:145], v[192:195], v[42:45]
	v_mfma_f32_16x16x32_bf16 v[30:33], v[134:137], v[200:203], v[30:33]
	v_mfma_f32_16x16x32_bf16 v[26:29], v[142:145], v[200:203], v[26:29]
	v_mfma_f32_16x16x32_bf16 v[14:17], v[134:137], v[208:211], v[14:17]
	v_mfma_f32_16x16x32_bf16 v[10:13], v[142:145], v[208:211], v[10:13]
	v_mfma_f32_16x16x32_bf16 v[54:57], v[146:149], v[174:177], v[54:57]
	v_mfma_f32_16x16x32_bf16 v[50:53], v[166:169], v[174:177], v[50:53]
	v_mfma_f32_16x16x32_bf16 v[38:41], v[146:149], v[188:191], v[38:41]
	v_mfma_f32_16x16x32_bf16 v[34:37], v[166:169], v[188:191], v[34:37]
	v_mfma_f32_16x16x32_bf16 v[22:25], v[146:149], v[196:199], v[22:25]
	v_mfma_f32_16x16x32_bf16 v[18:21], v[166:169], v[196:199], v[18:21]
	v_mfma_f32_16x16x32_bf16 v[6:9], v[146:149], v[204:207], v[6:9]
	v_mfma_f32_16x16x32_bf16 v[2:5], v[166:169], v[204:207], v[2:5]
	v_mfma_f32_16x16x32_bf16 v[54:57], v[150:153], v[180:183], v[54:57]
	v_mfma_f32_16x16x32_bf16 v[50:53], v[170:173], v[180:183], v[50:53]
	v_mfma_f32_16x16x32_bf16 v[38:41], v[150:153], v[192:195], v[38:41]
	v_mfma_f32_16x16x32_bf16 v[34:37], v[170:173], v[192:195], v[34:37]
	v_mfma_f32_16x16x32_bf16 v[22:25], v[150:153], v[200:203], v[22:25]
	v_mfma_f32_16x16x32_bf16 v[18:21], v[170:173], v[200:203], v[18:21]
	v_mfma_f32_16x16x32_bf16 v[6:9], v[150:153], v[208:211], v[6:9]
	v_mfma_f32_16x16x32_bf16 v[2:5], v[170:173], v[208:211], v[2:5]
	s_barrier
; #define PG8_STAGE(bufoff, gbase, voff) do { _Pragma("unroll") for (int _i = 0; _i < 2; ++_i) \
;         __builtin_amdgcn_global_load_lds((const unsigned*)((const char*)(gbase) + (voff)[_i]), (PG8_LAS unsigned*)(lds + (bufoff) + ldsw + _i * 8192), 16, 0, 0); } while (0)
; #define PG8_LDA(dst, b, h) do { _Pragma("unroll") for (int m = 0; m < 4; ++m) _Pragma("unroll") for (int k = 0; k < 2; ++k) dst[m][k] = *(const PG8_LAS bf16x8*)(lds + PG8_SA(b, h) + aoff + m * 2048 + k * 1024); } while (0)
; #define PG8_LDB(dst, b, h) do { _Pragma("unroll") for (int n = 0; n < 2; ++n) _Pragma("unroll") for (int k = 0; k < 2; ++k) dst[n][k] = *(const PG8_LAS bf16x8*)(lds + PG8_SB(b, h) + boff + n * 2048 + k * 1024); } while (0)
; #define PG8_MMA(ai, bj, At, Bt) do { __builtin_amdgcn_s_setprio(1); _Pragma("unroll") for (int m = 0; m < 4; ++m) _Pragma("unroll") for (int n = 0; n < 2; ++n) _Pragma("unroll") for (int k = 0; k < 2; ++k) \
;         acc[ai][bj][m][n] = __builtin_amdgcn_mfma_f32_16x16x32_bf16(Bt[n][k], At[m][k], acc[ai][bj][m][n], 0, 0, 0); __builtin_amdgcn_s_setprio(0); } while (0)
; #define PG8_WAIT_V(n) asm volatile("s_waitcnt vmcnt(" #n ")" ::: "memory")
; #define PG8_WAIT_L(n) asm volatile("s_waitcnt lgkmcnt(" #n ")" ::: "memory")
; #define PG8_BAR __builtin_amdgcn_s_barrier()
; #define PG8_SCHED __builtin_amdgcn_sched_barrier(0)
; template <class Epi, class Sched, bool ALIGN_EPI = false, bool SP2 = false>
; __device__ __forceinline__ void gemm_phase(PG8_LAS unsigned char* lds, const Gemm g, const Sched& S, const Epi& E) {
;     ...
;             PG8_LDB(B0, 1, 0); PG8_LDB(B1, 1, 1); PG8_SCHED; PG8_LDA(At, 1, 0); PG8_STAGE(PG8_SA(0, 1), a2 + hstep, voffA);
;             PG8_WAIT_V(8); PG8_WAIT_L(0); PG8_BAR; PG8_MMA(0, 0, At, B0); PG8_MMA(0, 1, At, B1); PG8_BAR; PG8_SCHED;
	s_add_i32 s59, 0, 0x18000
	s_add_i32 s60, 0, 0x1c000
	v_add_u32_e32 v142, s59, v179
	v_add_u32_e32 v170, s60, v179
	ds_read_b128 v[130:133], v142
	ds_read_b128 v[134:137], v142 offset:1024
	ds_read_b128 v[138:141], v142 offset:2048
	ds_read_b128 v[142:145], v142 offset:3072
	ds_read_b128 v[146:149], v170
	ds_read_b128 v[150:153], v170 offset:1024
	ds_read_b128 v[166:169], v170 offset:2048
	ds_read_b128 v[170:173], v170 offset:3072
	s_add_u32 s38, s38, 0x40000
	s_addc_u32 s39, s39, 0
	s_mov_b32 m0, s48
	v_lshl_add_u64 v[220:221], s[38:39], 0, v[154:155]
	ds_read_b128 v[174:177], v187 offset:32768
	ds_read_b128 v[180:183], v187 offset:33792
	ds_read_b128 v[188:191], v187 offset:34816
	ds_read_b128 v[192:195], v187 offset:35840
	ds_read_b128 v[196:199], v187 offset:36864
	ds_read_b128 v[200:203], v187 offset:37888
	ds_read_b128 v[204:207], v187 offset:38912
	ds_read_b128 v[208:211], v187 offset:39936
	global_load_lds_dwordx4 v[220:221], off
	v_lshl_add_u64 v[220:221], s[38:39], 0, v[158:159]
	s_mov_b32 m0, s49
	s_nop 0
	global_load_lds_dwordx4 v[220:221], off
	s_waitcnt vmcnt(8) lgkmcnt(0)
	s_barrier
	v_mfma_f32_16x16x32_bf16 v[126:129], v[130:133], v[174:177], v[126:129]
	v_mfma_f32_16x16x32_bf16 v[122:125], v[138:141], v[174:177], v[122:125]
	v_mfma_f32_16x16x32_bf16 v[110:113], v[130:133], v[188:191], v[110:113]
	v_mfma_f32_16x16x32_bf16 v[106:109], v[138:141], v[188:191], v[106:109]
	v_mfma_f32_16x16x32_bf16 v[94:97], v[130:133], v[196:199], v[94:97]
	v_mfma_f32_16x16x32_bf16 v[90:93], v[138:141], v[196:199], v[90:93]
	v_mfma_f32_16x16x32_bf16 v[78:81], v[130:133], v[204:207], v[78:81]
	v_mfma_f32_16x16x32_bf16 v[74:77], v[138:141], v[204:207], v[74:77]
	v_mfma_f32_16x16x32_bf16 v[126:129], v[134:137], v[180:183], v[126:129]
	v_mfma_f32_16x16x32_bf16 v[122:125], v[142:145], v[180:183], v[122:125]
	v_mfma_f32_16x16x32_bf16 v[110:113], v[134:137], v[192:195], v[110:113]
	v_mfma_f32_16x16x32_bf16 v[106:109], v[142:145], v[192:195], v[106:109]
	v_mfma_f32_16x16x32_bf16 v[94:97], v[134:137], v[200:203], v[94:97]
	v_mfma_f32_16x16x32_bf16 v[90:93], v[142:145], v[200:203], v[90:93]
	v_mfma_f32_16x16x32_bf16 v[78:81], v[134:137], v[208:211], v[78:81]
	v_mfma_f32_16x16x32_bf16 v[74:77], v[142:145], v[208:211], v[74:77]
	v_mfma_f32_16x16x32_bf16 v[118:121], v[146:149], v[174:177], v[118:121]
	v_mfma_f32_16x16x32_bf16 v[114:117], v[166:169], v[174:177], v[114:117]
	v_mfma_f32_16x16x32_bf16 v[102:105], v[146:149], v[188:191], v[102:105]
	v_mfma_f32_16x16x32_bf16 v[98:101], v[166:169], v[188:191], v[98:101]
	v_mfma_f32_16x16x32_bf16 v[86:89], v[146:149], v[196:199], v[86:89]
	v_mfma_f32_16x16x32_bf16 v[82:85], v[166:169], v[196:199], v[82:85]
	v_mfma_f32_16x16x32_bf16 v[70:73], v[146:149], v[204:207], v[70:73]
	v_mfma_f32_16x16x32_bf16 v[66:69], v[166:169], v[204:207], v[66:69]
	v_mfma_f32_16x16x32_bf16 v[118:121], v[150:153], v[180:183], v[118:121]
	v_mfma_f32_16x16x32_bf16 v[114:117], v[170:173], v[180:183], v[114:117]
	v_mfma_f32_16x16x32_bf16 v[102:105], v[150:153], v[192:195], v[102:105]
	v_mfma_f32_16x16x32_bf16 v[98:101], v[170:173], v[192:195], v[98:101]
	v_mfma_f32_16x16x32_bf16 v[86:89], v[150:153], v[200:203], v[86:89]
	v_mfma_f32_16x16x32_bf16 v[82:85], v[170:173], v[200:203], v[82:85]
	v_mfma_f32_16x16x32_bf16 v[70:73], v[150:153], v[208:211], v[70:73]
	v_mfma_f32_16x16x32_bf16 v[66:69], v[170:173], v[208:211], v[66:69]
	s_barrier
; #define PG8_STAGE(bufoff, gbase, voff) do { _Pragma("unroll") for (int _i = 0; _i < 2; ++_i) \
;         __builtin_amdgcn_global_load_lds((const unsigned*)((const char*)(gbase) + (voff)[_i]), (PG8_LAS unsigned*)(lds + (bufoff) + ldsw + _i * 8192), 16, 0, 0); } while (0)
; #define PG8_LDA(dst, b, h) do { _Pragma("unroll") for (int m = 0; m < 4; ++m) _Pragma("unroll") for (int k = 0; k < 2; ++k) dst[m][k] = *(const PG8_LAS bf16x8*)(lds + PG8_SA(b, h) + aoff + m * 2048 + k * 1024); } while (0)
; #define PG8_MMA(ai, bj, At, Bt) do { __builtin_amdgcn_s_setprio(1); _Pragma("unroll") for (int m = 0; m < 4; ++m) _Pragma("unroll") for (int n = 0; n < 2; ++n) _Pragma("unroll") for (int k = 0; k < 2; ++k) \
;         acc[ai][bj][m][n] = __builtin_amdgcn_mfma_f32_16x16x32_bf16(Bt[n][k], At[m][k], acc[ai][bj][m][n], 0, 0, 0); __builtin_amdgcn_s_setprio(0); } while (0)
; #define PG8_WAIT_V(n) asm volatile("s_waitcnt vmcnt(" #n ")" ::: "memory")
; #define PG8_WAIT_L(n) asm volatile("s_waitcnt lgkmcnt(" #n ")" ::: "memory")
; #define PG8_BAR __builtin_amdgcn_s_barrier()
; #define PG8_SCHED __builtin_amdgcn_sched_barrier(0)
; template <class Epi, class Sched, bool ALIGN_EPI = false, bool SP2 = false>
; __device__ __forceinline__ void gemm_phase(PG8_LAS unsigned char* lds, const Gemm g, const Sched& S, const Epi& E) {
;     ...
;             PG8_LDA(At, 1, 1); PG8_STAGE(PG8_SB(1, 0), b3, voffB); PG8_STAGE(PG8_SB(1, 1), b3 + hstep, voffB); PG8_STAGE(PG8_SA(1, 0), a3, voffA);
;             PG8_WAIT_V(8); PG8_WAIT_L(0); PG8_BAR; PG8_MMA(1, 0, At, B0); PG8_MMA(1, 1, At, B1); PG8_BAR; PG8_SCHED;
;     ...
;         if constexpr (ALIGN_EPI) { if (wr == 0) PG8_BAR; }
	s_add_i32 s38, s59, s33
	v_lshl_add_u64 v[212:213], v[212:213], 0, s[80:81]
	s_mov_b32 m0, s38
	ds_read_b128 v[174:177], v187 offset:49152
	ds_read_b128 v[180:183], v187 offset:50176
	ds_read_b128 v[188:191], v187 offset:51200
	ds_read_b128 v[192:195], v187 offset:52224
	ds_read_b128 v[196:199], v187 offset:53248
	ds_read_b128 v[200:203], v187 offset:54272
	ds_read_b128 v[204:207], v187 offset:55296
	ds_read_b128 v[208:211], v187 offset:56320
	global_load_lds_dwordx4 v[212:213], off
	s_add_i32 m0, s38, 0x2000
	s_add_u32 s36, s36, 0x40080
	v_lshl_add_u64 v[212:213], v[214:215], 0, s[80:81]
	s_addc_u32 s37, s37, 0
	s_add_i32 s38, s60, s33
	global_load_lds_dwordx4 v[212:213], off
	v_lshl_add_u64 v[212:213], s[36:37], 0, v[156:157]
	s_mov_b32 m0, s38
	s_nop 0
	global_load_lds_dwordx4 v[212:213], off
	v_lshl_add_u64 v[212:213], s[36:37], 0, v[160:161]
	s_add_i32 m0, s38, 0x2000
	s_nop 0
	global_load_lds_dwordx4 v[212:213], off
	v_lshl_add_u64 v[212:213], v[216:217], 0, s[80:81]
	s_mov_b32 m0, s51
	s_nop 0
	global_load_lds_dwordx4 v[212:213], off
	v_lshl_add_u64 v[212:213], v[218:219], 0, s[80:81]
	s_mov_b32 m0, s52
	s_nop 0
	global_load_lds_dwordx4 v[212:213], off
	s_waitcnt vmcnt(8) lgkmcnt(0)
	s_barrier
	v_mfma_f32_16x16x32_bf16 v[62:65], v[130:133], v[174:177], v[62:65]
	v_mfma_f32_16x16x32_bf16 v[58:61], v[138:141], v[174:177], v[58:61]
	v_mfma_f32_16x16x32_bf16 v[46:49], v[130:133], v[188:191], v[46:49]
	v_mfma_f32_16x16x32_bf16 v[42:45], v[138:141], v[188:191], v[42:45]
	v_mfma_f32_16x16x32_bf16 v[30:33], v[130:133], v[196:199], v[30:33]
	v_mfma_f32_16x16x32_bf16 v[26:29], v[138:141], v[196:199], v[26:29]
	v_mfma_f32_16x16x32_bf16 v[14:17], v[130:133], v[204:207], v[14:17]
	v_mfma_f32_16x16x32_bf16 v[10:13], v[138:141], v[204:207], v[10:13]
	v_mfma_f32_16x16x32_bf16 v[62:65], v[134:137], v[180:183], v[62:65]
	v_mfma_f32_16x16x32_bf16 v[58:61], v[142:145], v[180:183], v[58:61]
	v_mfma_f32_16x16x32_bf16 v[46:49], v[134:137], v[192:195], v[46:49]
	v_mfma_f32_16x16x32_bf16 v[42:45], v[142:145], v[192:195], v[42:45]
	v_mfma_f32_16x16x32_bf16 v[30:33], v[134:137], v[200:203], v[30:33]
	v_mfma_f32_16x16x32_bf16 v[26:29], v[142:145], v[200:203], v[26:29]
	v_mfma_f32_16x16x32_bf16 v[14:17], v[134:137], v[208:211], v[14:17]
	v_mfma_f32_16x16x32_bf16 v[10:13], v[142:145], v[208:211], v[10:13]
	v_mfma_f32_16x16x32_bf16 v[54:57], v[146:149], v[174:177], v[54:57]
	v_mfma_f32_16x16x32_bf16 v[50:53], v[166:169], v[174:177], v[50:53]
	v_mfma_f32_16x16x32_bf16 v[38:41], v[146:149], v[188:191], v[38:41]
	v_mfma_f32_16x16x32_bf16 v[34:37], v[166:169], v[188:191], v[34:37]
	v_mfma_f32_16x16x32_bf16 v[22:25], v[146:149], v[196:199], v[22:25]
	v_mfma_f32_16x16x32_bf16 v[18:21], v[166:169], v[196:199], v[18:21]
	v_mfma_f32_16x16x32_bf16 v[6:9], v[146:149], v[204:207], v[6:9]
	v_mfma_f32_16x16x32_bf16 v[2:5], v[166:169], v[204:207], v[2:5]
	v_mfma_f32_16x16x32_bf16 v[54:57], v[150:153], v[180:183], v[54:57]
	v_mfma_f32_16x16x32_bf16 v[50:53], v[170:173], v[180:183], v[50:53]
	v_mfma_f32_16x16x32_bf16 v[38:41], v[150:153], v[192:195], v[38:41]
	v_mfma_f32_16x16x32_bf16 v[34:37], v[170:173], v[192:195], v[34:37]
	v_mfma_f32_16x16x32_bf16 v[22:25], v[150:153], v[200:203], v[22:25]
	v_mfma_f32_16x16x32_bf16 v[18:21], v[170:173], v[200:203], v[18:21]
	v_mfma_f32_16x16x32_bf16 v[6:9], v[150:153], v[208:211], v[6:9]
	v_mfma_f32_16x16x32_bf16 v[2:5], v[170:173], v[208:211], v[2:5]
	s_barrier
	s_add_i32 s58, s58, 2
	s_add_u32 s34, s34, 0x100
	s_addc_u32 s35, s35, 0
	s_add_u32 s56, s56, 0x100
	s_addc_u32 s57, s57, 0
	s_cmp_gt_u32 s58, 13
	s_cbranch_scc0 .LBB0_1062
	s_and_b64 vcc, exec, s[18:19]
	s_cbranch_vccz .LBB0_1065
	s_barrier

; #define PG8_STAGE(bufoff, gbase, voff) do { _Pragma("unroll") for (int _i = 0; _i < 2; ++_i) \
;         __builtin_amdgcn_global_load_lds((const unsigned*)((const char*)(gbase) + (voff)[_i]), (PG8_LAS unsigned*)(lds + (bufoff) + ldsw + _i * 8192), 16, 0, 0); } while (0)
; #define PG8_LDA(dst, b, h) do { _Pragma("unroll") for (int m = 0; m < 4; ++m) _Pragma("unroll") for (int k = 0; k < 2; ++k) dst[m][k] = *(const PG8_LAS bf16x8*)(lds + PG8_SA(b, h) + aoff + m * 2048 + k * 1024); } while (0)
; #define PG8_LDB(dst, b, h) do { _Pragma("unroll") for (int n = 0; n < 2; ++n) _Pragma("unroll") for (int k = 0; k < 2; ++k) dst[n][k] = *(const PG8_LAS bf16x8*)(lds + PG8_SB(b, h) + boff + n * 2048 + k * 1024); } while (0)
; #define PG8_WAIT_V(n) asm volatile("s_waitcnt vmcnt(" #n ")" ::: "memory")
; #define PG8_WAIT_L(n) asm volatile("s_waitcnt lgkmcnt(" #n ")" ::: "memory")
; #define PG8_BAR __builtin_amdgcn_s_barrier()
; #define PG8_SCHED __builtin_amdgcn_sched_barrier(0)
; template <class Epi, class Sched, bool ALIGN_EPI = false, bool SP2 = false>
; __device__ __forceinline__ void gemm_phase(PG8_LAS unsigned char* lds, const Gemm g, const Sched& S, const Epi& E) {
;     ...
;         const bool has_next = S.next(ui + 1, nxt);
;         const char* nA = has_next ? (const char*)g.A + (size_t)nxt.pm * tstep : cA; const char* nB = has_next ? (const char*)g.Bt + (size_t)nxt.pn * tstep : cB;
;         for (int t = 0; t < nt; t += 2) {
;             const bool last = (t == nt - 2);
;             const char* a1 = cA + (size_t)(t + 1) * kstep;
;             const char* a2 = last ? nA : cA + (size_t)(t + 2) * kstep; const char* b2 = last ? nB : cB + (size_t)(t + 2) * kstep;
;             const char* a3 = a2 + kstep; const char* b3 = b2 + kstep;
;             if (last && has_next) S.a_ready(nxt);
;             if constexpr (SP2) {
;             PG8_LDB(B0, 0, 0); PG8_LDB(B1, 0, 1); PG8_SCHED; PG8_LDA(At, 0, 0); PG8_STAGE(PG8_SA(1, 1), a1 + hstep, voffA);
;             PG8_WAIT_V(8); PG8_WAIT_L(0); PG8_BAR; PG8_MMA(0, 0, At, B0); PG8_MMA(0, 1, At, B1); PG8_BAR; PG8_SCHED;
;             PG8_LDA(At, 0, 1); PG8_STAGE(PG8_SB(0, 0), b2, voffB); PG8_STAGE(PG8_SB(0, 1), b2 + hstep, voffB); PG8_STAGE(PG8_SA(0, 0), a2, voffA);
;             PG8_WAIT_V(8); PG8_WAIT_L(0); PG8_BAR; PG8_MMA(1, 0, At, B0); PG8_MMA(1, 1, At, B1); PG8_BAR; PG8_SCHED;
.LBB0_1105:
	s_ashr_i32 s19, s18, 31
	s_lshl_b64 s[20:21], s[18:19], 19
	s_add_u32 s20, s42, s20
	s_addc_u32 s21, s43, s21
	s_and_b64 s[22:23], s[6:7], exec
	s_cselect_b32 s19, s21, s29
	s_cselect_b32 s25, s20, s28
	s_ashr_i32 s17, s16, 31
	s_lshl_b64 s[22:23], s[16:17], 19
	s_add_u32 s22, s40, s22
	s_addc_u32 s23, s41, s23
	s_and_b64 s[34:35], s[6:7], exec
	s_cselect_b32 s17, s23, s31
	s_cselect_b32 s27, s22, s30
	s_add_u32 s28, s28, 0x40080
	s_addc_u32 s29, s29, 0
	s_add_u32 s52, s30, 0x100
	s_addc_u32 s53, s31, 0
	s_mov_b32 s54, -2
	s_waitcnt lgkmcnt(0)
	s_add_u32 s30, s28, 0xfffc0080
	s_addc_u32 s31, s29, -1
	s_add_i32 s55, 0, 0x10000
	s_cmp_eq_u32 s54, 12
	s_cselect_b32 s35, s19, s31
	s_cselect_b32 s34, s25, s30
	s_cselect_b32 s31, s17, s53
	s_cselect_b32 s30, s27, s52
	s_add_i32 s58, 0, 0x14000
	v_add_u32_e32 v142, s55, v179
	v_add_u32_e32 v158, s58, v179
	ds_read_b128 v[130:133], v142
	ds_read_b128 v[134:137], v142 offset:1024
	ds_read_b128 v[138:141], v142 offset:2048
	ds_read_b128 v[142:145], v142 offset:3072
	ds_read_b128 v[146:149], v158
	ds_read_b128 v[150:153], v158 offset:1024
	ds_read_b128 v[154:157], v158 offset:2048
	ds_read_b128 v[158:161], v158 offset:3072
	v_lshl_add_u64 v[212:213], s[28:29], 0, v[194:195]
	s_add_i32 m0, s36, 0xc000
	ds_read_b128 v[162:165], v211
	ds_read_b128 v[166:169], v211 offset:1024
	ds_read_b128 v[170:173], v211 offset:2048
	ds_read_b128 v[174:177], v211 offset:3072
	ds_read_b128 v[180:183], v211 offset:4096
	ds_read_b128 v[198:201], v211 offset:5120
	ds_read_b128 v[202:205], v211 offset:6144
	ds_read_b128 v[206:209], v211 offset:7168
	global_load_lds_dwordx4 v[212:213], off
	v_lshl_add_u64 v[212:213], s[28:29], 0, v[196:197]
	s_add_i32 m0, s36, 0xe000
	s_nop 0
	global_load_lds_dwordx4 v[212:213], off
	s_waitcnt vmcnt(8) lgkmcnt(0)
	s_barrier
	v_mfma_f32_16x16x32_bf16 v[126:129], v[130:133], v[162:165], 0
	v_mfma_f32_16x16x32_bf16 v[122:125], v[138:141], v[162:165], 0
	v_mfma_f32_16x16x32_bf16 v[110:113], v[130:133], v[170:173], 0
	v_mfma_f32_16x16x32_bf16 v[106:109], v[138:141], v[170:173], 0
	v_mfma_f32_16x16x32_bf16 v[94:97], v[130:133], v[180:183], 0
	v_mfma_f32_16x16x32_bf16 v[90:93], v[138:141], v[180:183], 0
	v_mfma_f32_16x16x32_bf16 v[78:81], v[130:133], v[202:205], 0
	v_mfma_f32_16x16x32_bf16 v[74:77], v[138:141], v[202:205], 0
	v_mfma_f32_16x16x32_bf16 v[126:129], v[134:137], v[166:169], v[126:129]
	v_mfma_f32_16x16x32_bf16 v[122:125], v[142:145], v[166:169], v[122:125]
	v_mfma_f32_16x16x32_bf16 v[110:113], v[134:137], v[174:177], v[110:113]
	v_mfma_f32_16x16x32_bf16 v[106:109], v[142:145], v[174:177], v[106:109]
	v_mfma_f32_16x16x32_bf16 v[94:97], v[134:137], v[198:201], v[94:97]
	v_mfma_f32_16x16x32_bf16 v[90:93], v[142:145], v[198:201], v[90:93]
	v_mfma_f32_16x16x32_bf16 v[78:81], v[134:137], v[206:209], v[78:81]
	v_mfma_f32_16x16x32_bf16 v[74:77], v[142:145], v[206:209], v[74:77]
	v_mfma_f32_16x16x32_bf16 v[118:121], v[146:149], v[162:165], 0
	v_mfma_f32_16x16x32_bf16 v[114:117], v[154:157], v[162:165], 0
	v_mfma_f32_16x16x32_bf16 v[102:105], v[146:149], v[170:173], 0
	v_mfma_f32_16x16x32_bf16 v[98:101], v[154:157], v[170:173], 0
	v_mfma_f32_16x16x32_bf16 v[86:89], v[146:149], v[180:183], 0
	v_mfma_f32_16x16x32_bf16 v[82:85], v[154:157], v[180:183], 0
	v_mfma_f32_16x16x32_bf16 v[70:73], v[146:149], v[202:205], 0
	v_mfma_f32_16x16x32_bf16 v[66:69], v[154:157], v[202:205], 0
	v_mfma_f32_16x16x32_bf16 v[118:121], v[150:153], v[166:169], v[118:121]
	v_mfma_f32_16x16x32_bf16 v[114:117], v[158:161], v[166:169], v[114:117]
	v_mfma_f32_16x16x32_bf16 v[102:105], v[150:153], v[174:177], v[102:105]
	v_mfma_f32_16x16x32_bf16 v[98:101], v[158:161], v[174:177], v[98:101]
	v_mfma_f32_16x16x32_bf16 v[86:89], v[150:153], v[198:201], v[86:89]
	v_mfma_f32_16x16x32_bf16 v[82:85], v[158:161], v[198:201], v[82:85]
	v_mfma_f32_16x16x32_bf16 v[70:73], v[150:153], v[206:209], v[70:73]
	v_mfma_f32_16x16x32_bf16 v[66:69], v[158:161], v[206:209], v[66:69]
	s_barrier
	s_add_i32 s55, s55, s33
	v_lshl_add_u64 v[212:213], s[30:31], 0, v[188:189]
	s_mov_b32 m0, s55
	ds_read_b128 v[162:165], v211 offset:16384
	ds_read_b128 v[166:169], v211 offset:17408
	ds_read_b128 v[170:173], v211 offset:18432
	ds_read_b128 v[174:177], v211 offset:19456
	ds_read_b128 v[180:183], v211 offset:20480
	ds_read_b128 v[198:201], v211 offset:21504
	ds_read_b128 v[202:205], v211 offset:22528
	ds_read_b128 v[206:209], v211 offset:23552
	global_load_lds_dwordx4 v[212:213], off
	s_add_i32 m0, s55, 0x2000
	s_add_u32 s56, s30, 0x40000
	v_lshl_add_u64 v[214:215], s[30:31], 0, v[192:193]
	s_addc_u32 s57, s31, 0
	s_add_i32 s55, s58, s33
	global_load_lds_dwordx4 v[214:215], off
	v_lshl_add_u64 v[216:217], s[56:57], 0, v[188:189]
	s_mov_b32 m0, s55
	v_lshl_add_u64 v[218:219], s[34:35], 0, v[190:191]
	global_load_lds_dwordx4 v[216:217], off
	v_lshl_add_u64 v[216:217], s[56:57], 0, v[192:193]
	s_add_i32 m0, s55, 0x2000
	s_nop 0
	global_load_lds_dwordx4 v[216:217], off
	v_lshl_add_u64 v[216:217], s[34:35], 0, v[186:187]
	s_mov_b32 m0, s36
	s_nop 0
	global_load_lds_dwordx4 v[216:217], off
	s_mov_b32 m0, s37
	s_nop 0
	global_load_lds_dwordx4 v[218:219], off
	s_waitcnt vmcnt(8) lgkmcnt(0)
	s_barrier
; #define PG8_STAGE(bufoff, gbase, voff) do { _Pragma("unroll") for (int _i = 0; _i < 2; ++_i) \
;         __builtin_amdgcn_global_load_lds((const unsigned*)((const char*)(gbase) + (voff)[_i]), (PG8_LAS unsigned*)(lds + (bufoff) + ldsw + _i * 8192), 16, 0, 0); } while (0)
; #define PG8_LDA(dst, b, h) do { _Pragma("unroll") for (int m = 0; m < 4; ++m) _Pragma("unroll") for (int k = 0; k < 2; ++k) dst[m][k] = *(const PG8_LAS bf16x8*)(lds + PG8_SA(b, h) + aoff + m * 2048 + k * 1024); } while (0)
; #define PG8_LDB(dst, b, h) do { _Pragma("unroll") for (int n = 0; n < 2; ++n) _Pragma("unroll") for (int k = 0; k < 2; ++k) dst[n][k] = *(const PG8_LAS bf16x8*)(lds + PG8_SB(b, h) + boff + n * 2048 + k * 1024); } while (0)
; #define PG8_MMA(ai, bj, At, Bt) do { __builtin_amdgcn_s_setprio(1); _Pragma("unroll") for (int m = 0; m < 4; ++m) _Pragma("unroll") for (int n = 0; n < 2; ++n) _Pragma("unroll") for (int k = 0; k < 2; ++k) \
;         acc[ai][bj][m][n] = __builtin_amdgcn_mfma_f32_16x16x32_bf16(Bt[n][k], At[m][k], acc[ai][bj][m][n], 0, 0, 0); __builtin_amdgcn_s_setprio(0); } while (0)
; #define PG8_WAIT_V(n) asm volatile("s_waitcnt vmcnt(" #n ")" ::: "memory")
; #define PG8_WAIT_L(n) asm volatile("s_waitcnt lgkmcnt(" #n ")" ::: "memory")
; #define PG8_BAR __builtin_amdgcn_s_barrier()
; #define PG8_SCHED __builtin_amdgcn_sched_barrier(0)
; template <class Epi, class Sched, bool ALIGN_EPI = false, bool SP2 = false>
; __device__ __forceinline__ void gemm_phase(PG8_LAS unsigned char* lds, const Gemm g, const Sched& S, const Epi& E) {
;     ...
;             PG8_LDA(At, 0, 1); PG8_STAGE(PG8_SB(0, 0), b2, voffB); PG8_STAGE(PG8_SB(0, 1), b2 + hstep, voffB); PG8_STAGE(PG8_SA(0, 0), a2, voffA);
;             PG8_WAIT_V(8); PG8_WAIT_L(0); PG8_BAR; PG8_MMA(1, 0, At, B0); PG8_MMA(1, 1, At, B1); PG8_BAR; PG8_SCHED;
;             PG8_LDB(B0, 1, 0); PG8_LDB(B1, 1, 1); PG8_SCHED; PG8_LDA(At, 1, 0); PG8_STAGE(PG8_SA(0, 1), a2 + hstep, voffA);
;             PG8_WAIT_V(8); PG8_WAIT_L(0); PG8_BAR; PG8_MMA(0, 0, At, B0); PG8_MMA(0, 1, At, B1); PG8_BAR; PG8_SCHED;
	v_mfma_f32_16x16x32_bf16 v[62:65], v[130:133], v[162:165], 0
	v_mfma_f32_16x16x32_bf16 v[58:61], v[138:141], v[162:165], 0
	v_mfma_f32_16x16x32_bf16 v[46:49], v[130:133], v[170:173], 0
	v_mfma_f32_16x16x32_bf16 v[42:45], v[138:141], v[170:173], 0
	v_mfma_f32_16x16x32_bf16 v[30:33], v[130:133], v[180:183], 0
	v_mfma_f32_16x16x32_bf16 v[26:29], v[138:141], v[180:183], 0
	v_mfma_f32_16x16x32_bf16 v[14:17], v[130:133], v[202:205], 0
	v_mfma_f32_16x16x32_bf16 v[10:13], v[138:141], v[202:205], 0
	v_mfma_f32_16x16x32_bf16 v[62:65], v[134:137], v[166:169], v[62:65]
	v_mfma_f32_16x16x32_bf16 v[58:61], v[142:145], v[166:169], v[58:61]
	v_mfma_f32_16x16x32_bf16 v[46:49], v[134:137], v[174:177], v[46:49]
	v_mfma_f32_16x16x32_bf16 v[42:45], v[142:145], v[174:177], v[42:45]
	v_mfma_f32_16x16x32_bf16 v[30:33], v[134:137], v[198:201], v[30:33]
	v_mfma_f32_16x16x32_bf16 v[26:29], v[142:145], v[198:201], v[26:29]
	v_mfma_f32_16x16x32_bf16 v[14:17], v[134:137], v[206:209], v[14:17]
	v_mfma_f32_16x16x32_bf16 v[10:13], v[142:145], v[206:209], v[10:13]
	v_mfma_f32_16x16x32_bf16 v[54:57], v[146:149], v[162:165], 0
	v_mfma_f32_16x16x32_bf16 v[50:53], v[154:157], v[162:165], 0
	v_mfma_f32_16x16x32_bf16 v[38:41], v[146:149], v[170:173], 0
	v_mfma_f32_16x16x32_bf16 v[34:37], v[154:157], v[170:173], 0
	v_mfma_f32_16x16x32_bf16 v[22:25], v[146:149], v[180:183], 0
	v_mfma_f32_16x16x32_bf16 v[18:21], v[154:157], v[180:183], 0
	v_mfma_f32_16x16x32_bf16 v[6:9], v[146:149], v[202:205], 0
	v_mfma_f32_16x16x32_bf16 v[2:5], v[154:157], v[202:205], 0
	v_mfma_f32_16x16x32_bf16 v[54:57], v[150:153], v[166:169], v[54:57]
	v_mfma_f32_16x16x32_bf16 v[50:53], v[158:161], v[166:169], v[50:53]
	v_mfma_f32_16x16x32_bf16 v[38:41], v[150:153], v[174:177], v[38:41]
	v_mfma_f32_16x16x32_bf16 v[34:37], v[158:161], v[174:177], v[34:37]
	v_mfma_f32_16x16x32_bf16 v[22:25], v[150:153], v[198:201], v[22:25]
	v_mfma_f32_16x16x32_bf16 v[18:21], v[158:161], v[198:201], v[18:21]
	v_mfma_f32_16x16x32_bf16 v[6:9], v[150:153], v[206:209], v[6:9]
	v_mfma_f32_16x16x32_bf16 v[2:5], v[158:161], v[206:209], v[2:5]
	s_barrier
	s_add_i32 s55, 0, 0x18000
	s_add_i32 s56, 0, 0x1c000
	v_add_u32_e32 v142, s55, v179
	v_add_u32_e32 v158, s56, v179
	ds_read_b128 v[130:133], v142
	ds_read_b128 v[134:137], v142 offset:1024
	ds_read_b128 v[138:141], v142 offset:2048
	ds_read_b128 v[142:145], v142 offset:3072
	ds_read_b128 v[146:149], v158
	ds_read_b128 v[150:153], v158 offset:1024
	ds_read_b128 v[154:157], v158 offset:2048
	ds_read_b128 v[158:161], v158 offset:3072
	s_add_u32 s34, s34, 0x40000
	s_addc_u32 s35, s35, 0
	s_mov_b32 m0, s38
	v_lshl_add_u64 v[220:221], s[34:35], 0, v[186:187]
	ds_read_b128 v[162:165], v211 offset:32768
	ds_read_b128 v[166:169], v211 offset:33792
	ds_read_b128 v[170:173], v211 offset:34816
	ds_read_b128 v[174:177], v211 offset:35840
	ds_read_b128 v[180:183], v211 offset:36864
	ds_read_b128 v[198:201], v211 offset:37888
	ds_read_b128 v[202:205], v211 offset:38912
	ds_read_b128 v[206:209], v211 offset:39936
	global_load_lds_dwordx4 v[220:221], off
	v_lshl_add_u64 v[220:221], s[34:35], 0, v[190:191]
	s_mov_b32 m0, s39
	s_nop 0
	global_load_lds_dwordx4 v[220:221], off
	s_waitcnt vmcnt(8) lgkmcnt(0)
	s_barrier
	v_mfma_f32_16x16x32_bf16 v[126:129], v[130:133], v[162:165], v[126:129]
	v_mfma_f32_16x16x32_bf16 v[122:125], v[138:141], v[162:165], v[122:125]
	v_mfma_f32_16x16x32_bf16 v[110:113], v[130:133], v[170:173], v[110:113]
	v_mfma_f32_16x16x32_bf16 v[106:109], v[138:141], v[170:173], v[106:109]
	v_mfma_f32_16x16x32_bf16 v[94:97], v[130:133], v[180:183], v[94:97]
	v_mfma_f32_16x16x32_bf16 v[90:93], v[138:141], v[180:183], v[90:93]
	v_mfma_f32_16x16x32_bf16 v[78:81], v[130:133], v[202:205], v[78:81]
	v_mfma_f32_16x16x32_bf16 v[74:77], v[138:141], v[202:205], v[74:77]
	v_mfma_f32_16x16x32_bf16 v[126:129], v[134:137], v[166:169], v[126:129]
	v_mfma_f32_16x16x32_bf16 v[122:125], v[142:145], v[166:169], v[122:125]
	v_mfma_f32_16x16x32_bf16 v[110:113], v[134:137], v[174:177], v[110:113]
	v_mfma_f32_16x16x32_bf16 v[106:109], v[142:145], v[174:177], v[106:109]
	v_mfma_f32_16x16x32_bf16 v[94:97], v[134:137], v[198:201], v[94:97]
	v_mfma_f32_16x16x32_bf16 v[90:93], v[142:145], v[198:201], v[90:93]
	v_mfma_f32_16x16x32_bf16 v[78:81], v[134:137], v[206:209], v[78:81]
	v_mfma_f32_16x16x32_bf16 v[74:77], v[142:145], v[206:209], v[74:77]
	v_mfma_f32_16x16x32_bf16 v[118:121], v[146:149], v[162:165], v[118:121]
	v_mfma_f32_16x16x32_bf16 v[114:117], v[154:157], v[162:165], v[114:117]
	v_mfma_f32_16x16x32_bf16 v[102:105], v[146:149], v[170:173], v[102:105]
	v_mfma_f32_16x16x32_bf16 v[98:101], v[154:157], v[170:173], v[98:101]
	v_mfma_f32_16x16x32_bf16 v[86:89], v[146:149], v[180:183], v[86:89]
	v_mfma_f32_16x16x32_bf16 v[82:85], v[154:157], v[180:183], v[82:85]
	v_mfma_f32_16x16x32_bf16 v[70:73], v[146:149], v[202:205], v[70:73]
	v_mfma_f32_16x16x32_bf16 v[66:69], v[154:157], v[202:205], v[66:69]
	v_mfma_f32_16x16x32_bf16 v[118:121], v[150:153], v[166:169], v[118:121]
	v_mfma_f32_16x16x32_bf16 v[114:117], v[158:161], v[166:169], v[114:117]
	v_mfma_f32_16x16x32_bf16 v[102:105], v[150:153], v[174:177], v[102:105]
	v_mfma_f32_16x16x32_bf16 v[98:101], v[158:161], v[174:177], v[98:101]
	v_mfma_f32_16x16x32_bf16 v[86:89], v[150:153], v[198:201], v[86:89]
	v_mfma_f32_16x16x32_bf16 v[82:85], v[158:161], v[198:201], v[82:85]
	v_mfma_f32_16x16x32_bf16 v[70:73], v[150:153], v[206:209], v[70:73]
	v_mfma_f32_16x16x32_bf16 v[66:69], v[158:161], v[206:209], v[66:69]
	s_barrier
; #define PG8_STAGE(bufoff, gbase, voff) do { _Pragma("unroll") for (int _i = 0; _i < 2; ++_i) \
;         __builtin_amdgcn_global_load_lds((const unsigned*)((const char*)(gbase) + (voff)[_i]), (PG8_LAS unsigned*)(lds + (bufoff) + ldsw + _i * 8192), 16, 0, 0); } while (0)
; #define PG8_LDA(dst, b, h) do { _Pragma("unroll") for (int m = 0; m < 4; ++m) _Pragma("unroll") for (int k = 0; k < 2; ++k) dst[m][k] = *(const PG8_LAS bf16x8*)(lds + PG8_SA(b, h) + aoff + m * 2048 + k * 1024); } while (0)
; #define PG8_LDB(dst, b, h) do { _Pragma("unroll") for (int n = 0; n < 2; ++n) _Pragma("unroll") for (int k = 0; k < 2; ++k) dst[n][k] = *(const PG8_LAS bf16x8*)(lds + PG8_SB(b, h) + boff + n * 2048 + k * 1024); } while (0)
; template <class Epi, class Sched, bool ALIGN_EPI = false, bool SP2 = false>
; __device__ __forceinline__ void gemm_phase(PG8_LAS unsigned char* lds, const Gemm g, const Sched& S, const Epi& E) {
;     ...
;         for (int t = 0; t < nt; t += 2) {
;             const bool last = (t == nt - 2);
;             const char* a1 = cA + (size_t)(t + 1) * kstep;
;             const char* a2 = last ? nA : cA + (size_t)(t + 2) * kstep; const char* b2 = last ? nB : cB + (size_t)(t + 2) * kstep;
;             const char* a3 = a2 + kstep; const char* b3 = b2 + kstep;
;             if (last && has_next) S.a_ready(nxt);
;             if constexpr (SP2) {
;             PG8_LDB(B0, 0, 0); PG8_LDB(B1, 0, 1); PG8_SCHED; PG8_LDA(At, 0, 0); PG8_STAGE(PG8_SA(1, 1), a1 + hstep, voffA);
;             PG8_WAIT_V(8); PG8_WAIT_L(0); PG8_BAR; PG8_MMA(0, 0, At, B0); PG8_MMA(0, 1, At, B1); PG8_BAR; PG8_SCHED;
;             PG8_LDA(At, 0, 1); PG8_STAGE(PG8_SB(0, 0), b2, voffB); PG8_STAGE(PG8_SB(0, 1), b2 + hstep, voffB); PG8_STAGE(PG8_SA(0, 0), a2, voffA);
;             PG8_WAIT_V(8); PG8_WAIT_L(0); PG8_BAR; PG8_MMA(1, 0, At, B0); PG8_MMA(1, 1, At, B1); PG8_BAR; PG8_SCHED;
;             PG8_LDB(B0, 1, 0); PG8_LDB(B1, 1, 1); PG8_SCHED; PG8_LDA(At, 1, 0); PG8_STAGE(PG8_SA(0, 1), a2 + hstep, voffA);
;             PG8_WAIT_V(8); PG8_WAIT_L(0); PG8_BAR; PG8_MMA(0, 0, At, B0); PG8_MMA(0, 1, At, B1); PG8_BAR; PG8_SCHED;
;             PG8_LDA(At, 1, 1); PG8_STAGE(PG8_SB(1, 0), b3, voffB); PG8_STAGE(PG8_SB(1, 1), b3 + hstep, voffB); PG8_STAGE(PG8_SA(1, 0), a3, voffA);
;             PG8_WAIT_V(8); PG8_WAIT_L(0); PG8_BAR; PG8_MMA(1, 0, At, B0); PG8_MMA(1, 1, At, B1); PG8_BAR; PG8_SCHED;
	s_add_i32 s34, s55, s33
	v_lshl_add_u64 v[212:213], v[212:213], 0, s[80:81]
	s_mov_b32 m0, s34
	ds_read_b128 v[162:165], v211 offset:49152
	ds_read_b128 v[166:169], v211 offset:50176
	ds_read_b128 v[170:173], v211 offset:51200
	ds_read_b128 v[174:177], v211 offset:52224
	ds_read_b128 v[180:183], v211 offset:53248
	ds_read_b128 v[198:201], v211 offset:54272
	ds_read_b128 v[202:205], v211 offset:55296
	ds_read_b128 v[206:209], v211 offset:56320
	global_load_lds_dwordx4 v[212:213], off
	s_add_i32 m0, s34, 0x2000
	s_add_u32 s30, s30, 0x40080
	v_lshl_add_u64 v[212:213], v[214:215], 0, s[80:81]
	s_addc_u32 s31, s31, 0
	s_add_i32 s34, s56, s33
	global_load_lds_dwordx4 v[212:213], off
	v_lshl_add_u64 v[212:213], s[30:31], 0, v[188:189]
	s_mov_b32 m0, s34
	s_nop 0
	global_load_lds_dwordx4 v[212:213], off
	v_lshl_add_u64 v[212:213], s[30:31], 0, v[192:193]
	s_add_i32 m0, s34, 0x2000
	s_nop 0
	global_load_lds_dwordx4 v[212:213], off
	v_lshl_add_u64 v[212:213], v[216:217], 0, s[80:81]
	s_mov_b32 m0, s47
	s_nop 0
	global_load_lds_dwordx4 v[212:213], off
	v_lshl_add_u64 v[212:213], v[218:219], 0, s[80:81]
	s_mov_b32 m0, s48
	s_nop 0
	global_load_lds_dwordx4 v[212:213], off
	s_waitcnt vmcnt(8) lgkmcnt(0)
	s_barrier
	v_mfma_f32_16x16x32_bf16 v[62:65], v[130:133], v[162:165], v[62:65]
	v_mfma_f32_16x16x32_bf16 v[58:61], v[138:141], v[162:165], v[58:61]
	v_mfma_f32_16x16x32_bf16 v[46:49], v[130:133], v[170:173], v[46:49]
	v_mfma_f32_16x16x32_bf16 v[42:45], v[138:141], v[170:173], v[42:45]
	v_mfma_f32_16x16x32_bf16 v[30:33], v[130:133], v[180:183], v[30:33]
	v_mfma_f32_16x16x32_bf16 v[26:29], v[138:141], v[180:183], v[26:29]
	v_mfma_f32_16x16x32_bf16 v[14:17], v[130:133], v[202:205], v[14:17]
	v_mfma_f32_16x16x32_bf16 v[10:13], v[138:141], v[202:205], v[10:13]
	v_mfma_f32_16x16x32_bf16 v[62:65], v[134:137], v[166:169], v[62:65]
	v_mfma_f32_16x16x32_bf16 v[58:61], v[142:145], v[166:169], v[58:61]
	v_mfma_f32_16x16x32_bf16 v[46:49], v[134:137], v[174:177], v[46:49]
	v_mfma_f32_16x16x32_bf16 v[42:45], v[142:145], v[174:177], v[42:45]
	v_mfma_f32_16x16x32_bf16 v[30:33], v[134:137], v[198:201], v[30:33]
	v_mfma_f32_16x16x32_bf16 v[26:29], v[142:145], v[198:201], v[26:29]
	v_mfma_f32_16x16x32_bf16 v[14:17], v[134:137], v[206:209], v[14:17]
	v_mfma_f32_16x16x32_bf16 v[10:13], v[142:145], v[206:209], v[10:13]
	v_mfma_f32_16x16x32_bf16 v[54:57], v[146:149], v[162:165], v[54:57]
	v_mfma_f32_16x16x32_bf16 v[50:53], v[154:157], v[162:165], v[50:53]
	v_mfma_f32_16x16x32_bf16 v[38:41], v[146:149], v[170:173], v[38:41]
	v_mfma_f32_16x16x32_bf16 v[34:37], v[154:157], v[170:173], v[34:37]
	v_mfma_f32_16x16x32_bf16 v[22:25], v[146:149], v[180:183], v[22:25]
	v_mfma_f32_16x16x32_bf16 v[18:21], v[154:157], v[180:183], v[18:21]
	v_mfma_f32_16x16x32_bf16 v[6:9], v[146:149], v[202:205], v[6:9]
	v_mfma_f32_16x16x32_bf16 v[2:5], v[154:157], v[202:205], v[2:5]
	v_mfma_f32_16x16x32_bf16 v[54:57], v[150:153], v[166:169], v[54:57]
	v_mfma_f32_16x16x32_bf16 v[50:53], v[158:161], v[166:169], v[50:53]
	v_mfma_f32_16x16x32_bf16 v[38:41], v[150:153], v[174:177], v[38:41]
	v_mfma_f32_16x16x32_bf16 v[34:37], v[158:161], v[174:177], v[34:37]
	v_mfma_f32_16x16x32_bf16 v[22:25], v[150:153], v[198:201], v[22:25]
	v_mfma_f32_16x16x32_bf16 v[18:21], v[158:161], v[198:201], v[18:21]
	v_mfma_f32_16x16x32_bf16 v[6:9], v[150:153], v[206:209], v[6:9]
	v_mfma_f32_16x16x32_bf16 v[2:5], v[158:161], v[206:209], v[2:5]
	s_barrier
	s_add_i32 s54, s54, 2
	s_add_u32 s28, s28, 0x100
	s_addc_u32 s29, s29, 0
	s_add_u32 s52, s52, 0x100
	s_addc_u32 s53, s53, 0
	s_cmp_gt_u32 s54, 13
	s_branch .LBB0_1106
.LBB0_1106:
	s_add_u32 s30, s28, 0xfffc0080
	s_addc_u32 s31, s29, -1
	s_add_i32 s55, 0, 0x10000
	s_cmp_eq_u32 s54, 12
	s_cselect_b32 s35, s19, s31
	s_cselect_b32 s34, s25, s30
	s_cselect_b32 s31, s17, s53
	s_cselect_b32 s30, s27, s52
	s_add_i32 s58, 0, 0x14000
	v_add_u32_e32 v142, s55, v179
	v_add_u32_e32 v158, s58, v179
	ds_read_b128 v[130:133], v142
	ds_read_b128 v[134:137], v142 offset:1024
	ds_read_b128 v[138:141], v142 offset:2048
	ds_read_b128 v[142:145], v142 offset:3072
	ds_read_b128 v[146:149], v158
	ds_read_b128 v[150:153], v158 offset:1024
	ds_read_b128 v[154:157], v158 offset:2048
	ds_read_b128 v[158:161], v158 offset:3072
	v_lshl_add_u64 v[212:213], s[28:29], 0, v[194:195]
	s_add_i32 m0, s36, 0xc000
	ds_read_b128 v[162:165], v211
	ds_read_b128 v[166:169], v211 offset:1024
	ds_read_b128 v[170:173], v211 offset:2048
	ds_read_b128 v[174:177], v211 offset:3072
	ds_read_b128 v[180:183], v211 offset:4096
	ds_read_b128 v[198:201], v211 offset:5120
	ds_read_b128 v[202:205], v211 offset:6144
	ds_read_b128 v[206:209], v211 offset:7168
	global_load_lds_dwordx4 v[212:213], off
	v_lshl_add_u64 v[212:213], s[28:29], 0, v[196:197]
	s_add_i32 m0, s36, 0xe000
	s_nop 0
	global_load_lds_dwordx4 v[212:213], off
	s_waitcnt vmcnt(8) lgkmcnt(0)
	s_barrier
; #define PG8_STAGE(bufoff, gbase, voff) do { _Pragma("unroll") for (int _i = 0; _i < 2; ++_i) \
;         __builtin_amdgcn_global_load_lds((const unsigned*)((const char*)(gbase) + (voff)[_i]), (PG8_LAS unsigned*)(lds + (bufoff) + ldsw + _i * 8192), 16, 0, 0); } while (0)
; #define PG8_LDA(dst, b, h) do { _Pragma("unroll") for (int m = 0; m < 4; ++m) _Pragma("unroll") for (int k = 0; k < 2; ++k) dst[m][k] = *(const PG8_LAS bf16x8*)(lds + PG8_SA(b, h) + aoff + m * 2048 + k * 1024); } while (0)
; #define PG8_LDB(dst, b, h) do { _Pragma("unroll") for (int n = 0; n < 2; ++n) _Pragma("unroll") for (int k = 0; k < 2; ++k) dst[n][k] = *(const PG8_LAS bf16x8*)(lds + PG8_SB(b, h) + boff + n * 2048 + k * 1024); } while (0)
; #define PG8_MMA(ai, bj, At, Bt) do { __builtin_amdgcn_s_setprio(1); _Pragma("unroll") for (int m = 0; m < 4; ++m) _Pragma("unroll") for (int n = 0; n < 2; ++n) _Pragma("unroll") for (int k = 0; k < 2; ++k) \
;         acc[ai][bj][m][n] = __builtin_amdgcn_mfma_f32_16x16x32_bf16(Bt[n][k], At[m][k], acc[ai][bj][m][n], 0, 0, 0); __builtin_amdgcn_s_setprio(0); } while (0)
; #define PG8_WAIT_V(n) asm volatile("s_waitcnt vmcnt(" #n ")" ::: "memory")
; template <class Epi, class Sched, bool ALIGN_EPI = false, bool SP2 = false>
; __device__ __forceinline__ void gemm_phase(PG8_LAS unsigned char* lds, const Gemm g, const Sched& S, const Epi& E) {
;     ...
;             PG8_LDB(B0, 0, 0); PG8_LDB(B1, 0, 1); PG8_SCHED; PG8_LDA(At, 0, 0); PG8_STAGE(PG8_SA(1, 1), a1 + hstep, voffA);
;             PG8_WAIT_V(8); PG8_WAIT_L(0); PG8_BAR; PG8_MMA(0, 0, At, B0); PG8_MMA(0, 1, At, B1); PG8_BAR; PG8_SCHED;
;             PG8_LDA(At, 0, 1); PG8_STAGE(PG8_SB(0, 0), b2, voffB); PG8_STAGE(PG8_SB(0, 1), b2 + hstep, voffB); PG8_STAGE(PG8_SA(0, 0), a2, voffA);
;             PG8_WAIT_V(8); PG8_WAIT_L(0); PG8_BAR; PG8_MMA(1, 0, At, B0); PG8_MMA(1, 1, At, B1); PG8_BAR; PG8_SCHED;
;             PG8_LDB(B0, 1, 0); PG8_LDB(B1, 1, 1); PG8_SCHED; PG8_LDA(At, 1, 0); PG8_STAGE(PG8_SA(0, 1), a2 + hstep, voffA);
;             PG8_WAIT_V(8); PG8_WAIT_L(0); PG8_BAR; PG8_MMA(0, 0, At, B0); PG8_MMA(0, 1, At, B1); PG8_BAR; PG8_SCHED;
;             PG8_LDA(At, 1, 1); PG8_STAGE(PG8_SB(1, 0), b3, voffB); PG8_STAGE(PG8_SB(1, 1), b3 + hstep, voffB); PG8_STAGE(PG8_SA(1, 0), a3, voffA);
;             PG8_WAIT_V(8); PG8_WAIT_L(0); PG8_BAR; PG8_MMA(1, 0, At, B0); PG8_MMA(1, 1, At, B1); PG8_BAR; PG8_SCHED;
	v_mfma_f32_16x16x32_bf16 v[126:129], v[130:133], v[162:165], v[126:129]
	v_mfma_f32_16x16x32_bf16 v[122:125], v[138:141], v[162:165], v[122:125]
	v_mfma_f32_16x16x32_bf16 v[110:113], v[130:133], v[170:173], v[110:113]
	v_mfma_f32_16x16x32_bf16 v[106:109], v[138:141], v[170:173], v[106:109]
	v_mfma_f32_16x16x32_bf16 v[94:97], v[130:133], v[180:183], v[94:97]
	v_mfma_f32_16x16x32_bf16 v[90:93], v[138:141], v[180:183], v[90:93]
	v_mfma_f32_16x16x32_bf16 v[78:81], v[130:133], v[202:205], v[78:81]
	v_mfma_f32_16x16x32_bf16 v[74:77], v[138:141], v[202:205], v[74:77]
	v_mfma_f32_16x16x32_bf16 v[126:129], v[134:137], v[166:169], v[126:129]
	v_mfma_f32_16x16x32_bf16 v[122:125], v[142:145], v[166:169], v[122:125]
	v_mfma_f32_16x16x32_bf16 v[110:113], v[134:137], v[174:177], v[110:113]
	v_mfma_f32_16x16x32_bf16 v[106:109], v[142:145], v[174:177], v[106:109]
	v_mfma_f32_16x16x32_bf16 v[94:97], v[134:137], v[198:201], v[94:97]
	v_mfma_f32_16x16x32_bf16 v[90:93], v[142:145], v[198:201], v[90:93]
	v_mfma_f32_16x16x32_bf16 v[78:81], v[134:137], v[206:209], v[78:81]
	v_mfma_f32_16x16x32_bf16 v[74:77], v[142:145], v[206:209], v[74:77]
	v_mfma_f32_16x16x32_bf16 v[118:121], v[146:149], v[162:165], v[118:121]
	v_mfma_f32_16x16x32_bf16 v[114:117], v[154:157], v[162:165], v[114:117]
	v_mfma_f32_16x16x32_bf16 v[102:105], v[146:149], v[170:173], v[102:105]
	v_mfma_f32_16x16x32_bf16 v[98:101], v[154:157], v[170:173], v[98:101]
	v_mfma_f32_16x16x32_bf16 v[86:89], v[146:149], v[180:183], v[86:89]
	v_mfma_f32_16x16x32_bf16 v[82:85], v[154:157], v[180:183], v[82:85]
	v_mfma_f32_16x16x32_bf16 v[70:73], v[146:149], v[202:205], v[70:73]
	v_mfma_f32_16x16x32_bf16 v[66:69], v[154:157], v[202:205], v[66:69]
	v_mfma_f32_16x16x32_bf16 v[118:121], v[150:153], v[166:169], v[118:121]
	v_mfma_f32_16x16x32_bf16 v[114:117], v[158:161], v[166:169], v[114:117]
	v_mfma_f32_16x16x32_bf16 v[102:105], v[150:153], v[174:177], v[102:105]
	v_mfma_f32_16x16x32_bf16 v[98:101], v[158:161], v[174:177], v[98:101]
	v_mfma_f32_16x16x32_bf16 v[86:89], v[150:153], v[198:201], v[86:89]
	v_mfma_f32_16x16x32_bf16 v[82:85], v[158:161], v[198:201], v[82:85]
	v_mfma_f32_16x16x32_bf16 v[70:73], v[150:153], v[206:209], v[70:73]
	v_mfma_f32_16x16x32_bf16 v[66:69], v[158:161], v[206:209], v[66:69]
	s_barrier
	s_add_i32 s55, s55, s33
	v_lshl_add_u64 v[212:213], s[30:31], 0, v[188:189]
	s_mov_b32 m0, s55
	ds_read_b128 v[162:165], v211 offset:16384
	ds_read_b128 v[166:169], v211 offset:17408
	ds_read_b128 v[170:173], v211 offset:18432
	ds_read_b128 v[174:177], v211 offset:19456
	ds_read_b128 v[180:183], v211 offset:20480
	ds_read_b128 v[198:201], v211 offset:21504
	ds_read_b128 v[202:205], v211 offset:22528
	ds_read_b128 v[206:209], v211 offset:23552
	global_load_lds_dwordx4 v[212:213], off
	s_add_i32 m0, s55, 0x2000
	s_add_u32 s56, s30, 0x40000
	v_lshl_add_u64 v[214:215], s[30:31], 0, v[192:193]
	s_addc_u32 s57, s31, 0
	s_add_i32 s55, s58, s33
	global_load_lds_dwordx4 v[214:215], off
	v_lshl_add_u64 v[216:217], s[56:57], 0, v[188:189]
	s_mov_b32 m0, s55
	v_lshl_add_u64 v[218:219], s[34:35], 0, v[190:191]
	global_load_lds_dwordx4 v[216:217], off
	v_lshl_add_u64 v[216:217], s[56:57], 0, v[192:193]
	s_add_i32 m0, s55, 0x2000
	s_nop 0
	global_load_lds_dwordx4 v[216:217], off
	v_lshl_add_u64 v[216:217], s[34:35], 0, v[186:187]
	s_mov_b32 m0, s36
	s_nop 0
	global_load_lds_dwordx4 v[216:217], off
	s_mov_b32 m0, s37
	s_nop 0
	global_load_lds_dwordx4 v[218:219], off
	s_waitcnt vmcnt(8) lgkmcnt(0)
	s_barrier
	v_mfma_f32_16x16x32_bf16 v[62:65], v[130:133], v[162:165], v[62:65]
	v_mfma_f32_16x16x32_bf16 v[58:61], v[138:141], v[162:165], v[58:61]
	v_mfma_f32_16x16x32_bf16 v[46:49], v[130:133], v[170:173], v[46:49]
	v_mfma_f32_16x16x32_bf16 v[42:45], v[138:141], v[170:173], v[42:45]
	v_mfma_f32_16x16x32_bf16 v[30:33], v[130:133], v[180:183], v[30:33]
	v_mfma_f32_16x16x32_bf16 v[26:29], v[138:141], v[180:183], v[26:29]
	v_mfma_f32_16x16x32_bf16 v[14:17], v[130:133], v[202:205], v[14:17]
	v_mfma_f32_16x16x32_bf16 v[10:13], v[138:141], v[202:205], v[10:13]
	v_mfma_f32_16x16x32_bf16 v[62:65], v[134:137], v[166:169], v[62:65]
	v_mfma_f32_16x16x32_bf16 v[58:61], v[142:145], v[166:169], v[58:61]
	v_mfma_f32_16x16x32_bf16 v[46:49], v[134:137], v[174:177], v[46:49]
	v_mfma_f32_16x16x32_bf16 v[42:45], v[142:145], v[174:177], v[42:45]
	v_mfma_f32_16x16x32_bf16 v[30:33], v[134:137], v[198:201], v[30:33]
	v_mfma_f32_16x16x32_bf16 v[26:29], v[142:145], v[198:201], v[26:29]
	v_mfma_f32_16x16x32_bf16 v[14:17], v[134:137], v[206:209], v[14:17]
	v_mfma_f32_16x16x32_bf16 v[10:13], v[142:145], v[206:209], v[10:13]
	v_mfma_f32_16x16x32_bf16 v[54:57], v[146:149], v[162:165], v[54:57]
	v_mfma_f32_16x16x32_bf16 v[50:53], v[154:157], v[162:165], v[50:53]
	v_mfma_f32_16x16x32_bf16 v[38:41], v[146:149], v[170:173], v[38:41]
	v_mfma_f32_16x16x32_bf16 v[34:37], v[154:157], v[170:173], v[34:37]
	v_mfma_f32_16x16x32_bf16 v[22:25], v[146:149], v[180:183], v[22:25]
	v_mfma_f32_16x16x32_bf16 v[18:21], v[154:157], v[180:183], v[18:21]
	v_mfma_f32_16x16x32_bf16 v[6:9], v[146:149], v[202:205], v[6:9]
	v_mfma_f32_16x16x32_bf16 v[2:5], v[154:157], v[202:205], v[2:5]
	v_mfma_f32_16x16x32_bf16 v[54:57], v[150:153], v[166:169], v[54:57]
	v_mfma_f32_16x16x32_bf16 v[50:53], v[158:161], v[166:169], v[50:53]
	v_mfma_f32_16x16x32_bf16 v[38:41], v[150:153], v[174:177], v[38:41]
	v_mfma_f32_16x16x32_bf16 v[34:37], v[158:161], v[174:177], v[34:37]
	v_mfma_f32_16x16x32_bf16 v[22:25], v[150:153], v[198:201], v[22:25]
	v_mfma_f32_16x16x32_bf16 v[18:21], v[158:161], v[198:201], v[18:21]
	v_mfma_f32_16x16x32_bf16 v[6:9], v[150:153], v[206:209], v[6:9]
	v_mfma_f32_16x16x32_bf16 v[2:5], v[158:161], v[206:209], v[2:5]
	s_barrier
; #define PG8_STAGE(bufoff, gbase, voff) do { _Pragma("unroll") for (int _i = 0; _i < 2; ++_i) \
;         __builtin_amdgcn_global_load_lds((const unsigned*)((const char*)(gbase) + (voff)[_i]), (PG8_LAS unsigned*)(lds + (bufoff) + ldsw + _i * 8192), 16, 0, 0); } while (0)
; #define PG8_LDA(dst, b, h) do { _Pragma("unroll") for (int m = 0; m < 4; ++m) _Pragma("unroll") for (int k = 0; k < 2; ++k) dst[m][k] = *(const PG8_LAS bf16x8*)(lds + PG8_SA(b, h) + aoff + m * 2048 + k * 1024); } while (0)
; #define PG8_LDB(dst, b, h) do { _Pragma("unroll") for (int n = 0; n < 2; ++n) _Pragma("unroll") for (int k = 0; k < 2; ++k) dst[n][k] = *(const PG8_LAS bf16x8*)(lds + PG8_SB(b, h) + boff + n * 2048 + k * 1024); } while (0)
; #define PG8_MMA(ai, bj, At, Bt) do { __builtin_amdgcn_s_setprio(1); _Pragma("unroll") for (int m = 0; m < 4; ++m) _Pragma("unroll") for (int n = 0; n < 2; ++n) _Pragma("unroll") for (int k = 0; k < 2; ++k) \
;         acc[ai][bj][m][n] = __builtin_amdgcn_mfma_f32_16x16x32_bf16(Bt[n][k], At[m][k], acc[ai][bj][m][n], 0, 0, 0); __builtin_amdgcn_s_setprio(0); } while (0)
; #define PG8_WAIT_V(n) asm volatile("s_waitcnt vmcnt(" #n ")" ::: "memory")
; #define PG8_WAIT_L(n) asm volatile("s_waitcnt lgkmcnt(" #n ")" ::: "memory")
; #define PG8_BAR __builtin_amdgcn_s_barrier()
; #define PG8_SCHED __builtin_amdgcn_sched_barrier(0)
; template <class Epi, class Sched, bool ALIGN_EPI = false, bool SP2 = false>
; __device__ __forceinline__ void gemm_phase(PG8_LAS unsigned char* lds, const Gemm g, const Sched& S, const Epi& E) {
;     ...
;             PG8_LDB(B0, 1, 0); PG8_LDB(B1, 1, 1); PG8_SCHED; PG8_LDA(At, 1, 0); PG8_STAGE(PG8_SA(0, 1), a2 + hstep, voffA);
;             PG8_WAIT_V(8); PG8_WAIT_L(0); PG8_BAR; PG8_MMA(0, 0, At, B0); PG8_MMA(0, 1, At, B1); PG8_BAR; PG8_SCHED;
	s_add_i32 s55, 0, 0x18000
	s_add_i32 s56, 0, 0x1c000
	v_add_u32_e32 v142, s55, v179
	v_add_u32_e32 v158, s56, v179
	ds_read_b128 v[130:133], v142
	ds_read_b128 v[134:137], v142 offset:1024
	ds_read_b128 v[138:141], v142 offset:2048
	ds_read_b128 v[142:145], v142 offset:3072
	ds_read_b128 v[146:149], v158
	ds_read_b128 v[150:153], v158 offset:1024
	ds_read_b128 v[154:157], v158 offset:2048
	ds_read_b128 v[158:161], v158 offset:3072
	s_add_u32 s34, s34, 0x40000
	s_addc_u32 s35, s35, 0
	s_mov_b32 m0, s38
	v_lshl_add_u64 v[220:221], s[34:35], 0, v[186:187]
	ds_read_b128 v[162:165], v211 offset:32768
	ds_read_b128 v[166:169], v211 offset:33792
	ds_read_b128 v[170:173], v211 offset:34816
	ds_read_b128 v[174:177], v211 offset:35840
	ds_read_b128 v[180:183], v211 offset:36864
	ds_read_b128 v[198:201], v211 offset:37888
	ds_read_b128 v[202:205], v211 offset:38912
	ds_read_b128 v[206:209], v211 offset:39936
	global_load_lds_dwordx4 v[220:221], off
	v_lshl_add_u64 v[220:221], s[34:35], 0, v[190:191]
	s_mov_b32 m0, s39
	s_nop 0
	global_load_lds_dwordx4 v[220:221], off
	s_waitcnt vmcnt(8) lgkmcnt(0)
	s_barrier
	v_mfma_f32_16x16x32_bf16 v[126:129], v[130:133], v[162:165], v[126:129]
	v_mfma_f32_16x16x32_bf16 v[122:125], v[138:141], v[162:165], v[122:125]
	v_mfma_f32_16x16x32_bf16 v[110:113], v[130:133], v[170:173], v[110:113]
	v_mfma_f32_16x16x32_bf16 v[106:109], v[138:141], v[170:173], v[106:109]
	v_mfma_f32_16x16x32_bf16 v[94:97], v[130:133], v[180:183], v[94:97]
	v_mfma_f32_16x16x32_bf16 v[90:93], v[138:141], v[180:183], v[90:93]
	v_mfma_f32_16x16x32_bf16 v[78:81], v[130:133], v[202:205], v[78:81]
	v_mfma_f32_16x16x32_bf16 v[74:77], v[138:141], v[202:205], v[74:77]
	v_mfma_f32_16x16x32_bf16 v[126:129], v[134:137], v[166:169], v[126:129]
	v_mfma_f32_16x16x32_bf16 v[122:125], v[142:145], v[166:169], v[122:125]
	v_mfma_f32_16x16x32_bf16 v[110:113], v[134:137], v[174:177], v[110:113]
	v_mfma_f32_16x16x32_bf16 v[106:109], v[142:145], v[174:177], v[106:109]
	v_mfma_f32_16x16x32_bf16 v[94:97], v[134:137], v[198:201], v[94:97]
	v_mfma_f32_16x16x32_bf16 v[90:93], v[142:145], v[198:201], v[90:93]
	v_mfma_f32_16x16x32_bf16 v[78:81], v[134:137], v[206:209], v[78:81]
	v_mfma_f32_16x16x32_bf16 v[74:77], v[142:145], v[206:209], v[74:77]
	v_mfma_f32_16x16x32_bf16 v[118:121], v[146:149], v[162:165], v[118:121]
	v_mfma_f32_16x16x32_bf16 v[114:117], v[154:157], v[162:165], v[114:117]
	v_mfma_f32_16x16x32_bf16 v[102:105], v[146:149], v[170:173], v[102:105]
	v_mfma_f32_16x16x32_bf16 v[98:101], v[154:157], v[170:173], v[98:101]
	v_mfma_f32_16x16x32_bf16 v[86:89], v[146:149], v[180:183], v[86:89]
	v_mfma_f32_16x16x32_bf16 v[82:85], v[154:157], v[180:183], v[82:85]
	v_mfma_f32_16x16x32_bf16 v[70:73], v[146:149], v[202:205], v[70:73]
	v_mfma_f32_16x16x32_bf16 v[66:69], v[154:157], v[202:205], v[66:69]
	v_mfma_f32_16x16x32_bf16 v[118:121], v[150:153], v[166:169], v[118:121]
	v_mfma_f32_16x16x32_bf16 v[114:117], v[158:161], v[166:169], v[114:117]
	v_mfma_f32_16x16x32_bf16 v[102:105], v[150:153], v[174:177], v[102:105]
	v_mfma_f32_16x16x32_bf16 v[98:101], v[158:161], v[174:177], v[98:101]
	v_mfma_f32_16x16x32_bf16 v[86:89], v[150:153], v[198:201], v[86:89]
	v_mfma_f32_16x16x32_bf16 v[82:85], v[158:161], v[198:201], v[82:85]
	v_mfma_f32_16x16x32_bf16 v[70:73], v[150:153], v[206:209], v[70:73]
	v_mfma_f32_16x16x32_bf16 v[66:69], v[158:161], v[206:209], v[66:69]
	s_barrier
; #define PG8_STAGE(bufoff, gbase, voff) do { _Pragma("unroll") for (int _i = 0; _i < 2; ++_i) \
;         __builtin_amdgcn_global_load_lds((const unsigned*)((const char*)(gbase) + (voff)[_i]), (PG8_LAS unsigned*)(lds + (bufoff) + ldsw + _i * 8192), 16, 0, 0); } while (0)
; #define PG8_LDA(dst, b, h) do { _Pragma("unroll") for (int m = 0; m < 4; ++m) _Pragma("unroll") for (int k = 0; k < 2; ++k) dst[m][k] = *(const PG8_LAS bf16x8*)(lds + PG8_SA(b, h) + aoff + m * 2048 + k * 1024); } while (0)
; #define PG8_MMA(ai, bj, At, Bt) do { __builtin_amdgcn_s_setprio(1); _Pragma("unroll") for (int m = 0; m < 4; ++m) _Pragma("unroll") for (int n = 0; n < 2; ++n) _Pragma("unroll") for (int k = 0; k < 2; ++k) \
;         acc[ai][bj][m][n] = __builtin_amdgcn_mfma_f32_16x16x32_bf16(Bt[n][k], At[m][k], acc[ai][bj][m][n], 0, 0, 0); __builtin_amdgcn_s_setprio(0); } while (0)
; #define PG8_WAIT_V(n) asm volatile("s_waitcnt vmcnt(" #n ")" ::: "memory")
; #define PG8_WAIT_L(n) asm volatile("s_waitcnt lgkmcnt(" #n ")" ::: "memory")
; #define PG8_BAR __builtin_amdgcn_s_barrier()
; #define PG8_SCHED __builtin_amdgcn_sched_barrier(0)
; template <class Epi, class Sched, bool ALIGN_EPI = false, bool SP2 = false>
; __device__ __forceinline__ void gemm_phase(PG8_LAS unsigned char* lds, const Gemm g, const Sched& S, const Epi& E) {
;     ...
;             PG8_LDA(At, 1, 1); PG8_STAGE(PG8_SB(1, 0), b3, voffB); PG8_STAGE(PG8_SB(1, 1), b3 + hstep, voffB); PG8_STAGE(PG8_SA(1, 0), a3, voffA);
;             PG8_WAIT_V(8); PG8_WAIT_L(0); PG8_BAR; PG8_MMA(1, 0, At, B0); PG8_MMA(1, 1, At, B1); PG8_BAR; PG8_SCHED;
;     ...
;         if constexpr (ALIGN_EPI) { if (wr == 0) PG8_BAR; }
	s_add_i32 s34, s55, s33
	v_lshl_add_u64 v[212:213], v[212:213], 0, s[80:81]
	s_mov_b32 m0, s34
	ds_read_b128 v[162:165], v211 offset:49152
	ds_read_b128 v[166:169], v211 offset:50176
	ds_read_b128 v[170:173], v211 offset:51200
	ds_read_b128 v[174:177], v211 offset:52224
	ds_read_b128 v[180:183], v211 offset:53248
	ds_read_b128 v[198:201], v211 offset:54272
	ds_read_b128 v[202:205], v211 offset:55296
	ds_read_b128 v[206:209], v211 offset:56320
	global_load_lds_dwordx4 v[212:213], off
	s_add_i32 m0, s34, 0x2000
	s_add_u32 s30, s30, 0x40080
	v_lshl_add_u64 v[212:213], v[214:215], 0, s[80:81]
	s_addc_u32 s31, s31, 0
	s_add_i32 s34, s56, s33
	global_load_lds_dwordx4 v[212:213], off
	v_lshl_add_u64 v[212:213], s[30:31], 0, v[188:189]
	s_mov_b32 m0, s34
	s_nop 0
	global_load_lds_dwordx4 v[212:213], off
	v_lshl_add_u64 v[212:213], s[30:31], 0, v[192:193]
	s_add_i32 m0, s34, 0x2000
	s_nop 0
	global_load_lds_dwordx4 v[212:213], off
	v_lshl_add_u64 v[212:213], v[216:217], 0, s[80:81]
	s_mov_b32 m0, s47
	s_nop 0
	global_load_lds_dwordx4 v[212:213], off
	v_lshl_add_u64 v[212:213], v[218:219], 0, s[80:81]
	s_mov_b32 m0, s48
	s_nop 0
	global_load_lds_dwordx4 v[212:213], off
	s_waitcnt vmcnt(8) lgkmcnt(0)
	s_barrier
	v_mfma_f32_16x16x32_bf16 v[62:65], v[130:133], v[162:165], v[62:65]
	v_mfma_f32_16x16x32_bf16 v[58:61], v[138:141], v[162:165], v[58:61]
	v_mfma_f32_16x16x32_bf16 v[46:49], v[130:133], v[170:173], v[46:49]
	v_mfma_f32_16x16x32_bf16 v[42:45], v[138:141], v[170:173], v[42:45]
	v_mfma_f32_16x16x32_bf16 v[30:33], v[130:133], v[180:183], v[30:33]
	v_mfma_f32_16x16x32_bf16 v[26:29], v[138:141], v[180:183], v[26:29]
	v_mfma_f32_16x16x32_bf16 v[14:17], v[130:133], v[202:205], v[14:17]
	v_mfma_f32_16x16x32_bf16 v[10:13], v[138:141], v[202:205], v[10:13]
	v_mfma_f32_16x16x32_bf16 v[62:65], v[134:137], v[166:169], v[62:65]
	v_mfma_f32_16x16x32_bf16 v[58:61], v[142:145], v[166:169], v[58:61]
	v_mfma_f32_16x16x32_bf16 v[46:49], v[134:137], v[174:177], v[46:49]
	v_mfma_f32_16x16x32_bf16 v[42:45], v[142:145], v[174:177], v[42:45]
	v_mfma_f32_16x16x32_bf16 v[30:33], v[134:137], v[198:201], v[30:33]
	v_mfma_f32_16x16x32_bf16 v[26:29], v[142:145], v[198:201], v[26:29]
	v_mfma_f32_16x16x32_bf16 v[14:17], v[134:137], v[206:209], v[14:17]
	v_mfma_f32_16x16x32_bf16 v[10:13], v[142:145], v[206:209], v[10:13]
	v_mfma_f32_16x16x32_bf16 v[54:57], v[146:149], v[162:165], v[54:57]
	v_mfma_f32_16x16x32_bf16 v[50:53], v[154:157], v[162:165], v[50:53]
	v_mfma_f32_16x16x32_bf16 v[38:41], v[146:149], v[170:173], v[38:41]
	v_mfma_f32_16x16x32_bf16 v[34:37], v[154:157], v[170:173], v[34:37]
	v_mfma_f32_16x16x32_bf16 v[22:25], v[146:149], v[180:183], v[22:25]
	v_mfma_f32_16x16x32_bf16 v[18:21], v[154:157], v[180:183], v[18:21]
	v_mfma_f32_16x16x32_bf16 v[6:9], v[146:149], v[202:205], v[6:9]
	v_mfma_f32_16x16x32_bf16 v[2:5], v[154:157], v[202:205], v[2:5]
	v_mfma_f32_16x16x32_bf16 v[54:57], v[150:153], v[166:169], v[54:57]
	v_mfma_f32_16x16x32_bf16 v[50:53], v[158:161], v[166:169], v[50:53]
	v_mfma_f32_16x16x32_bf16 v[38:41], v[150:153], v[174:177], v[38:41]
	v_mfma_f32_16x16x32_bf16 v[34:37], v[158:161], v[174:177], v[34:37]
	v_mfma_f32_16x16x32_bf16 v[22:25], v[150:153], v[198:201], v[22:25]
	v_mfma_f32_16x16x32_bf16 v[18:21], v[158:161], v[198:201], v[18:21]
	v_mfma_f32_16x16x32_bf16 v[6:9], v[150:153], v[206:209], v[6:9]
	v_mfma_f32_16x16x32_bf16 v[2:5], v[158:161], v[206:209], v[2:5]
	s_barrier
	s_add_i32 s54, s54, 2
	s_add_u32 s28, s28, 0x100
	s_addc_u32 s29, s29, 0
	s_add_u32 s52, s52, 0x100
	s_addc_u32 s53, s53, 0
	s_cmp_gt_u32 s54, 13
	s_cbranch_scc0 .LBB0_1106
	s_and_b64 vcc, exec, s[14:15]
	s_cbranch_vccz .LBB0_1109
	s_barrier

; #define PG8_STAGE(bufoff, gbase, voff) do { _Pragma("unroll") for (int _i = 0; _i < 2; ++_i) \
;         __builtin_amdgcn_global_load_lds((const unsigned*)((const char*)(gbase) + (voff)[_i]), (PG8_LAS unsigned*)(lds + (bufoff) + ldsw + _i * 8192), 16, 0, 0); } while (0)
; #define PG8_LDA(dst, b, h) do { _Pragma("unroll") for (int m = 0; m < 4; ++m) _Pragma("unroll") for (int k = 0; k < 2; ++k) dst[m][k] = *(const PG8_LAS bf16x8*)(lds + PG8_SA(b, h) + aoff + m * 2048 + k * 1024); } while (0)
; #define PG8_LDB(dst, b, h) do { _Pragma("unroll") for (int n = 0; n < 2; ++n) _Pragma("unroll") for (int k = 0; k < 2; ++k) dst[n][k] = *(const PG8_LAS bf16x8*)(lds + PG8_SB(b, h) + boff + n * 2048 + k * 1024); } while (0)
; #define PG8_WAIT_V(n) asm volatile("s_waitcnt vmcnt(" #n ")" ::: "memory")
; #define PG8_WAIT_L(n) asm volatile("s_waitcnt lgkmcnt(" #n ")" ::: "memory")
; #define PG8_BAR __builtin_amdgcn_s_barrier()
; #define PG8_SCHED __builtin_amdgcn_sched_barrier(0)
; template <class Epi, class Sched, bool ALIGN_EPI = false, bool SP2 = false>
; __device__ __forceinline__ void gemm_phase(PG8_LAS unsigned char* lds, const Gemm g, const Sched& S, const Epi& E) {
;     ...
;     for (;;) {
;         const bool has_next = S.next(ui + 1, nxt);
;         const char* nA = has_next ? (const char*)g.A + (size_t)nxt.pm * tstep : cA; const char* nB = has_next ? (const char*)g.Bt + (size_t)nxt.pn * tstep : cB;
;         for (int t = 0; t < nt; t += 2) {
;             const bool last = (t == nt - 2);
;             const char* a1 = cA + (size_t)(t + 1) * kstep;
;             const char* a2 = last ? nA : cA + (size_t)(t + 2) * kstep; const char* b2 = last ? nB : cB + (size_t)(t + 2) * kstep;
;             const char* a3 = a2 + kstep; const char* b3 = b2 + kstep;
;             if (last && has_next) S.a_ready(nxt);
;             if constexpr (SP2) {
;             PG8_LDB(B0, 0, 0); PG8_LDB(B1, 0, 1); PG8_SCHED; PG8_LDA(At, 0, 0); PG8_STAGE(PG8_SA(1, 1), a1 + hstep, voffA);
;             PG8_WAIT_V(8); PG8_WAIT_L(0); PG8_BAR; PG8_MMA(0, 0, At, B0); PG8_MMA(0, 1, At, B1); PG8_BAR; PG8_SCHED;
;             PG8_LDA(At, 0, 1); PG8_STAGE(PG8_SB(0, 0), b2, voffB); PG8_STAGE(PG8_SB(0, 1), b2 + hstep, voffB); PG8_STAGE(PG8_SA(0, 0), a2, voffA);
;             PG8_WAIT_V(8); PG8_WAIT_L(0); PG8_BAR; PG8_MMA(1, 0, At, B0); PG8_MMA(1, 1, At, B1); PG8_BAR; PG8_SCHED;
.LBB0_1248:
	s_ashr_i32 s17, s16, 31
	s_lshl_b64 s[18:19], s[16:17], 19
	s_add_u32 s18, s0, s18
	s_addc_u32 s19, s1, s19
	s_and_b64 s[20:21], s[4:5], exec
	s_cselect_b32 s17, s19, s25
	s_cselect_b32 s45, s18, s24
	s_ashr_i32 s15, s14, 31
	s_lshl_b64 s[20:21], s[14:15], 19
	s_add_u32 s20, s34, s20
	s_addc_u32 s21, s35, s21
	s_and_b64 s[28:29], s[4:5], exec
	s_cselect_b32 s15, s21, s27
	s_cselect_b32 s46, s20, s26
	s_add_u32 s24, s24, 0x40080
	s_addc_u32 s25, s25, 0
	s_add_u32 s47, s26, 0x100
	s_addc_u32 s48, s27, 0
	s_mov_b32 s49, -2
	s_add_u32 s26, s24, 0xfffc0080
	s_addc_u32 s27, s25, -1
	s_add_i32 s50, 0, 0x10000
	s_cmp_eq_u32 s49, 12
	s_cselect_b32 s29, s17, s27
	s_cselect_b32 s28, s45, s26
	v_add_u32_e32 v156, s50, v158
	s_cselect_b32 s27, s15, s48
	s_cselect_b32 s26, s46, s47
	s_add_i32 s52, 0, 0x14000
	ds_read_b128 v[66:69], v156
	ds_read_b128 v[118:121], v156 offset:1024
	ds_read_b128 v[152:155], v156 offset:2048
	ds_read_b128 v[162:165], v156 offset:3072
	v_add_u32_e32 v156, s52, v158
	ds_read_b128 v[166:169], v156
	ds_read_b128 v[170:173], v156 offset:1024
	ds_read_b128 v[174:177], v156 offset:2048
	ds_read_b128 v[180:183], v156 offset:3072
	v_lshl_add_u64 v[156:157], s[24:25], 0, v[148:149]
	s_add_i32 m0, s33, 0xc000
	ds_read_b128 v[186:189], v160
	ds_read_b128 v[190:193], v160 offset:1024
	ds_read_b128 v[194:197], v160 offset:2048
	ds_read_b128 v[198:201], v160 offset:3072
	ds_read_b128 v[202:205], v160 offset:4096
	ds_read_b128 v[206:209], v160 offset:5120
	ds_read_b128 v[210:213], v160 offset:6144
	ds_read_b128 v[214:217], v160 offset:7168
	global_load_lds_dwordx4 v[156:157], off
	v_lshl_add_u64 v[156:157], s[24:25], 0, v[150:151]
	s_add_i32 m0, s33, 0xe000
	s_nop 0
	global_load_lds_dwordx4 v[156:157], off
	s_waitcnt vmcnt(8) lgkmcnt(0)
	s_barrier
	v_mfma_f32_16x16x32_bf16 v[134:137], v[66:69], v[186:189], 0
	v_mfma_f32_16x16x32_bf16 v[126:129], v[152:155], v[186:189], 0
	v_mfma_f32_16x16x32_bf16 v[114:117], v[66:69], v[194:197], 0
	v_mfma_f32_16x16x32_bf16 v[110:113], v[152:155], v[194:197], 0
	v_mfma_f32_16x16x32_bf16 v[98:101], v[66:69], v[202:205], 0
	v_mfma_f32_16x16x32_bf16 v[94:97], v[152:155], v[202:205], 0
	v_mfma_f32_16x16x32_bf16 v[82:85], v[66:69], v[210:213], 0
	v_mfma_f32_16x16x32_bf16 v[78:81], v[152:155], v[210:213], 0
	v_mfma_f32_16x16x32_bf16 v[134:137], v[118:121], v[190:193], v[134:137]
	v_mfma_f32_16x16x32_bf16 v[126:129], v[162:165], v[190:193], v[126:129]
	v_mfma_f32_16x16x32_bf16 v[114:117], v[118:121], v[198:201], v[114:117]
	v_mfma_f32_16x16x32_bf16 v[110:113], v[162:165], v[198:201], v[110:113]
	v_mfma_f32_16x16x32_bf16 v[98:101], v[118:121], v[206:209], v[98:101]
	v_mfma_f32_16x16x32_bf16 v[94:97], v[162:165], v[206:209], v[94:97]
	v_mfma_f32_16x16x32_bf16 v[82:85], v[118:121], v[214:217], v[82:85]
	v_mfma_f32_16x16x32_bf16 v[78:81], v[162:165], v[214:217], v[78:81]
	v_mfma_f32_16x16x32_bf16 v[130:133], v[166:169], v[186:189], 0
	v_mfma_f32_16x16x32_bf16 v[122:125], v[174:177], v[186:189], 0
	v_mfma_f32_16x16x32_bf16 v[106:109], v[166:169], v[194:197], 0
	v_mfma_f32_16x16x32_bf16 v[102:105], v[174:177], v[194:197], 0
	v_mfma_f32_16x16x32_bf16 v[90:93], v[166:169], v[202:205], 0
	v_mfma_f32_16x16x32_bf16 v[86:89], v[174:177], v[202:205], 0
	v_mfma_f32_16x16x32_bf16 v[74:77], v[166:169], v[210:213], 0
	v_mfma_f32_16x16x32_bf16 v[70:73], v[174:177], v[210:213], 0
	v_mfma_f32_16x16x32_bf16 v[130:133], v[170:173], v[190:193], v[130:133]
	v_mfma_f32_16x16x32_bf16 v[122:125], v[180:183], v[190:193], v[122:125]
	v_mfma_f32_16x16x32_bf16 v[106:109], v[170:173], v[198:201], v[106:109]
	v_mfma_f32_16x16x32_bf16 v[102:105], v[180:183], v[198:201], v[102:105]
	v_mfma_f32_16x16x32_bf16 v[90:93], v[170:173], v[206:209], v[90:93]
	v_mfma_f32_16x16x32_bf16 v[86:89], v[180:183], v[206:209], v[86:89]
	v_mfma_f32_16x16x32_bf16 v[74:77], v[170:173], v[214:217], v[74:77]
	v_mfma_f32_16x16x32_bf16 v[70:73], v[180:183], v[214:217], v[70:73]
	s_barrier
	s_add_i32 s50, s50, s36
	v_lshl_add_u64 v[156:157], s[26:27], 0, v[142:143]
	s_mov_b32 m0, s50
	ds_read_b128 v[186:189], v160 offset:16384
	ds_read_b128 v[190:193], v160 offset:17408
	ds_read_b128 v[194:197], v160 offset:18432
	ds_read_b128 v[198:201], v160 offset:19456
	ds_read_b128 v[202:205], v160 offset:20480
	ds_read_b128 v[206:209], v160 offset:21504
	ds_read_b128 v[210:213], v160 offset:22528
	ds_read_b128 v[214:217], v160 offset:23552
	global_load_lds_dwordx4 v[156:157], off
	s_add_i32 m0, s50, 0x2000
	s_add_u32 s50, s26, 0x40000
	v_lshl_add_u64 v[218:219], s[26:27], 0, v[138:139]
	s_addc_u32 s51, s27, 0
	s_add_i32 s52, s52, s36
	global_load_lds_dwordx4 v[218:219], off
	v_lshl_add_u64 v[220:221], s[50:51], 0, v[142:143]
	s_mov_b32 m0, s52
	v_lshl_add_u64 v[222:223], s[28:29], 0, v[140:141]
	global_load_lds_dwordx4 v[220:221], off
	v_lshl_add_u64 v[220:221], s[50:51], 0, v[138:139]
	s_add_i32 m0, s52, 0x2000
	s_nop 0
	global_load_lds_dwordx4 v[220:221], off
	v_lshl_add_u64 v[220:221], s[28:29], 0, v[144:145]
	s_mov_b32 m0, s33
	s_nop 0
	global_load_lds_dwordx4 v[220:221], off
	s_mov_b32 m0, s38
	s_nop 0
	global_load_lds_dwordx4 v[222:223], off
	s_waitcnt vmcnt(8) lgkmcnt(0)
	s_barrier
; #define PG8_STAGE(bufoff, gbase, voff) do { _Pragma("unroll") for (int _i = 0; _i < 2; ++_i) \
;         __builtin_amdgcn_global_load_lds((const unsigned*)((const char*)(gbase) + (voff)[_i]), (PG8_LAS unsigned*)(lds + (bufoff) + ldsw + _i * 8192), 16, 0, 0); } while (0)
; #define PG8_LDA(dst, b, h) do { _Pragma("unroll") for (int m = 0; m < 4; ++m) _Pragma("unroll") for (int k = 0; k < 2; ++k) dst[m][k] = *(const PG8_LAS bf16x8*)(lds + PG8_SA(b, h) + aoff + m * 2048 + k * 1024); } while (0)
; #define PG8_LDB(dst, b, h) do { _Pragma("unroll") for (int n = 0; n < 2; ++n) _Pragma("unroll") for (int k = 0; k < 2; ++k) dst[n][k] = *(const PG8_LAS bf16x8*)(lds + PG8_SB(b, h) + boff + n * 2048 + k * 1024); } while (0)
; #define PG8_MMA(ai, bj, At, Bt) do { __builtin_amdgcn_s_setprio(1); _Pragma("unroll") for (int m = 0; m < 4; ++m) _Pragma("unroll") for (int n = 0; n < 2; ++n) _Pragma("unroll") for (int k = 0; k < 2; ++k) \
;         acc[ai][bj][m][n] = __builtin_amdgcn_mfma_f32_16x16x32_bf16(Bt[n][k], At[m][k], acc[ai][bj][m][n], 0, 0, 0); __builtin_amdgcn_s_setprio(0); } while (0)
; #define PG8_WAIT_V(n) asm volatile("s_waitcnt vmcnt(" #n ")" ::: "memory")
; #define PG8_WAIT_L(n) asm volatile("s_waitcnt lgkmcnt(" #n ")" ::: "memory")
; #define PG8_BAR __builtin_amdgcn_s_barrier()
; #define PG8_SCHED __builtin_amdgcn_sched_barrier(0)
; template <class Epi, class Sched, bool ALIGN_EPI = false, bool SP2 = false>
; __device__ __forceinline__ void gemm_phase(PG8_LAS unsigned char* lds, const Gemm g, const Sched& S, const Epi& E) {
;     ...
;             PG8_LDA(At, 0, 1); PG8_STAGE(PG8_SB(0, 0), b2, voffB); PG8_STAGE(PG8_SB(0, 1), b2 + hstep, voffB); PG8_STAGE(PG8_SA(0, 0), a2, voffA);
;             PG8_WAIT_V(8); PG8_WAIT_L(0); PG8_BAR; PG8_MMA(1, 0, At, B0); PG8_MMA(1, 1, At, B1); PG8_BAR; PG8_SCHED;
;             PG8_LDB(B0, 1, 0); PG8_LDB(B1, 1, 1); PG8_SCHED; PG8_LDA(At, 1, 0); PG8_STAGE(PG8_SA(0, 1), a2 + hstep, voffA);
;             PG8_WAIT_V(8); PG8_WAIT_L(0); PG8_BAR; PG8_MMA(0, 0, At, B0); PG8_MMA(0, 1, At, B1); PG8_BAR; PG8_SCHED;
	v_mfma_f32_16x16x32_bf16 v[62:65], v[66:69], v[186:189], 0
	v_mfma_f32_16x16x32_bf16 v[58:61], v[152:155], v[186:189], 0
	v_mfma_f32_16x16x32_bf16 v[46:49], v[66:69], v[194:197], 0
	v_mfma_f32_16x16x32_bf16 v[42:45], v[152:155], v[194:197], 0
	v_mfma_f32_16x16x32_bf16 v[30:33], v[66:69], v[202:205], 0
	v_mfma_f32_16x16x32_bf16 v[26:29], v[152:155], v[202:205], 0
	v_mfma_f32_16x16x32_bf16 v[14:17], v[66:69], v[210:213], 0
	v_mfma_f32_16x16x32_bf16 v[10:13], v[152:155], v[210:213], 0
	v_mfma_f32_16x16x32_bf16 v[62:65], v[118:121], v[190:193], v[62:65]
	v_mfma_f32_16x16x32_bf16 v[58:61], v[162:165], v[190:193], v[58:61]
	v_mfma_f32_16x16x32_bf16 v[46:49], v[118:121], v[198:201], v[46:49]
	v_mfma_f32_16x16x32_bf16 v[42:45], v[162:165], v[198:201], v[42:45]
	v_mfma_f32_16x16x32_bf16 v[30:33], v[118:121], v[206:209], v[30:33]
	v_mfma_f32_16x16x32_bf16 v[26:29], v[162:165], v[206:209], v[26:29]
	v_mfma_f32_16x16x32_bf16 v[14:17], v[118:121], v[214:217], v[14:17]
	v_mfma_f32_16x16x32_bf16 v[10:13], v[162:165], v[214:217], v[10:13]
	v_mfma_f32_16x16x32_bf16 v[54:57], v[166:169], v[186:189], 0
	v_mfma_f32_16x16x32_bf16 v[50:53], v[174:177], v[186:189], 0
	v_mfma_f32_16x16x32_bf16 v[38:41], v[166:169], v[194:197], 0
	v_mfma_f32_16x16x32_bf16 v[34:37], v[174:177], v[194:197], 0
	v_mfma_f32_16x16x32_bf16 v[22:25], v[166:169], v[202:205], 0
	v_mfma_f32_16x16x32_bf16 v[18:21], v[174:177], v[202:205], 0
	v_mfma_f32_16x16x32_bf16 v[6:9], v[166:169], v[210:213], 0
	v_mfma_f32_16x16x32_bf16 v[2:5], v[174:177], v[210:213], 0
	v_mfma_f32_16x16x32_bf16 v[54:57], v[170:173], v[190:193], v[54:57]
	v_mfma_f32_16x16x32_bf16 v[50:53], v[180:183], v[190:193], v[50:53]
	v_mfma_f32_16x16x32_bf16 v[38:41], v[170:173], v[198:201], v[38:41]
	v_mfma_f32_16x16x32_bf16 v[34:37], v[180:183], v[198:201], v[34:37]
	v_mfma_f32_16x16x32_bf16 v[22:25], v[170:173], v[206:209], v[22:25]
	v_mfma_f32_16x16x32_bf16 v[18:21], v[180:183], v[206:209], v[18:21]
	v_mfma_f32_16x16x32_bf16 v[6:9], v[170:173], v[214:217], v[6:9]
	v_mfma_f32_16x16x32_bf16 v[2:5], v[180:183], v[214:217], v[2:5]
	s_barrier
	s_add_i32 s50, 0, 0x18000
	v_add_u32_e32 v161, s50, v158
	s_add_i32 s51, 0, 0x1c000
	ds_read_b128 v[66:69], v161
	ds_read_b128 v[118:121], v161 offset:1024
	ds_read_b128 v[152:155], v161 offset:2048
	ds_read_b128 v[162:165], v161 offset:3072
	v_add_u32_e32 v161, s51, v158
	ds_read_b128 v[166:169], v161
	ds_read_b128 v[170:173], v161 offset:1024
	ds_read_b128 v[174:177], v161 offset:2048
	ds_read_b128 v[180:183], v161 offset:3072
	s_add_u32 s28, s28, 0x40000
	s_addc_u32 s29, s29, 0
	s_mov_b32 m0, s39
	v_lshl_add_u64 v[240:241], s[28:29], 0, v[144:145]
	ds_read_b128 v[186:189], v160 offset:32768
	ds_read_b128 v[190:193], v160 offset:33792
	ds_read_b128 v[194:197], v160 offset:34816
	ds_read_b128 v[198:201], v160 offset:35840
	ds_read_b128 v[202:205], v160 offset:36864
	ds_read_b128 v[206:209], v160 offset:37888
	ds_read_b128 v[210:213], v160 offset:38912
	ds_read_b128 v[214:217], v160 offset:39936
	global_load_lds_dwordx4 v[240:241], off
	v_lshl_add_u64 v[240:241], s[28:29], 0, v[140:141]
	s_mov_b32 m0, s40
	s_nop 0
	global_load_lds_dwordx4 v[240:241], off
	s_waitcnt vmcnt(8) lgkmcnt(0)
	s_barrier
	v_mfma_f32_16x16x32_bf16 v[134:137], v[66:69], v[186:189], v[134:137]
	v_mfma_f32_16x16x32_bf16 v[126:129], v[152:155], v[186:189], v[126:129]
	v_mfma_f32_16x16x32_bf16 v[114:117], v[66:69], v[194:197], v[114:117]
	v_mfma_f32_16x16x32_bf16 v[110:113], v[152:155], v[194:197], v[110:113]
	v_mfma_f32_16x16x32_bf16 v[98:101], v[66:69], v[202:205], v[98:101]
	v_mfma_f32_16x16x32_bf16 v[94:97], v[152:155], v[202:205], v[94:97]
	v_mfma_f32_16x16x32_bf16 v[82:85], v[66:69], v[210:213], v[82:85]
	v_mfma_f32_16x16x32_bf16 v[78:81], v[152:155], v[210:213], v[78:81]
	v_mfma_f32_16x16x32_bf16 v[134:137], v[118:121], v[190:193], v[134:137]
	v_mfma_f32_16x16x32_bf16 v[126:129], v[162:165], v[190:193], v[126:129]
	v_mfma_f32_16x16x32_bf16 v[114:117], v[118:121], v[198:201], v[114:117]
	v_mfma_f32_16x16x32_bf16 v[110:113], v[162:165], v[198:201], v[110:113]
	v_mfma_f32_16x16x32_bf16 v[98:101], v[118:121], v[206:209], v[98:101]
	v_mfma_f32_16x16x32_bf16 v[94:97], v[162:165], v[206:209], v[94:97]
	v_mfma_f32_16x16x32_bf16 v[82:85], v[118:121], v[214:217], v[82:85]
	v_mfma_f32_16x16x32_bf16 v[78:81], v[162:165], v[214:217], v[78:81]
	v_mfma_f32_16x16x32_bf16 v[130:133], v[166:169], v[186:189], v[130:133]
	v_mfma_f32_16x16x32_bf16 v[122:125], v[174:177], v[186:189], v[122:125]
	v_mfma_f32_16x16x32_bf16 v[106:109], v[166:169], v[194:197], v[106:109]
	v_mfma_f32_16x16x32_bf16 v[102:105], v[174:177], v[194:197], v[102:105]
	v_mfma_f32_16x16x32_bf16 v[90:93], v[166:169], v[202:205], v[90:93]
	v_mfma_f32_16x16x32_bf16 v[86:89], v[174:177], v[202:205], v[86:89]
	v_mfma_f32_16x16x32_bf16 v[74:77], v[166:169], v[210:213], v[74:77]
	v_mfma_f32_16x16x32_bf16 v[70:73], v[174:177], v[210:213], v[70:73]
	v_mfma_f32_16x16x32_bf16 v[130:133], v[170:173], v[190:193], v[130:133]
	v_mfma_f32_16x16x32_bf16 v[122:125], v[180:183], v[190:193], v[122:125]
	v_mfma_f32_16x16x32_bf16 v[106:109], v[170:173], v[198:201], v[106:109]
	v_mfma_f32_16x16x32_bf16 v[102:105], v[180:183], v[198:201], v[102:105]
	v_mfma_f32_16x16x32_bf16 v[90:93], v[170:173], v[206:209], v[90:93]
	v_mfma_f32_16x16x32_bf16 v[86:89], v[180:183], v[206:209], v[86:89]
	v_mfma_f32_16x16x32_bf16 v[74:77], v[170:173], v[214:217], v[74:77]
	v_mfma_f32_16x16x32_bf16 v[70:73], v[180:183], v[214:217], v[70:73]
	s_barrier
; #define PG8_STAGE(bufoff, gbase, voff) do { _Pragma("unroll") for (int _i = 0; _i < 2; ++_i) \
;         __builtin_amdgcn_global_load_lds((const unsigned*)((const char*)(gbase) + (voff)[_i]), (PG8_LAS unsigned*)(lds + (bufoff) + ldsw + _i * 8192), 16, 0, 0); } while (0)
; #define PG8_LDA(dst, b, h) do { _Pragma("unroll") for (int m = 0; m < 4; ++m) _Pragma("unroll") for (int k = 0; k < 2; ++k) dst[m][k] = *(const PG8_LAS bf16x8*)(lds + PG8_SA(b, h) + aoff + m * 2048 + k * 1024); } while (0)
; #define PG8_LDB(dst, b, h) do { _Pragma("unroll") for (int n = 0; n < 2; ++n) _Pragma("unroll") for (int k = 0; k < 2; ++k) dst[n][k] = *(const PG8_LAS bf16x8*)(lds + PG8_SB(b, h) + boff + n * 2048 + k * 1024); } while (0)
; template <class Epi, class Sched, bool ALIGN_EPI = false, bool SP2 = false>
; __device__ __forceinline__ void gemm_phase(PG8_LAS unsigned char* lds, const Gemm g, const Sched& S, const Epi& E) {
;     ...
;         for (int t = 0; t < nt; t += 2) {
;             const bool last = (t == nt - 2);
;             const char* a1 = cA + (size_t)(t + 1) * kstep;
;             const char* a2 = last ? nA : cA + (size_t)(t + 2) * kstep; const char* b2 = last ? nB : cB + (size_t)(t + 2) * kstep;
;             const char* a3 = a2 + kstep; const char* b3 = b2 + kstep;
;             if (last && has_next) S.a_ready(nxt);
;             if constexpr (SP2) {
;             PG8_LDB(B0, 0, 0); PG8_LDB(B1, 0, 1); PG8_SCHED; PG8_LDA(At, 0, 0); PG8_STAGE(PG8_SA(1, 1), a1 + hstep, voffA);
;             PG8_WAIT_V(8); PG8_WAIT_L(0); PG8_BAR; PG8_MMA(0, 0, At, B0); PG8_MMA(0, 1, At, B1); PG8_BAR; PG8_SCHED;
;             PG8_LDA(At, 0, 1); PG8_STAGE(PG8_SB(0, 0), b2, voffB); PG8_STAGE(PG8_SB(0, 1), b2 + hstep, voffB); PG8_STAGE(PG8_SA(0, 0), a2, voffA);
;             PG8_WAIT_V(8); PG8_WAIT_L(0); PG8_BAR; PG8_MMA(1, 0, At, B0); PG8_MMA(1, 1, At, B1); PG8_BAR; PG8_SCHED;
;             PG8_LDB(B0, 1, 0); PG8_LDB(B1, 1, 1); PG8_SCHED; PG8_LDA(At, 1, 0); PG8_STAGE(PG8_SA(0, 1), a2 + hstep, voffA);
;             PG8_WAIT_V(8); PG8_WAIT_L(0); PG8_BAR; PG8_MMA(0, 0, At, B0); PG8_MMA(0, 1, At, B1); PG8_BAR; PG8_SCHED;
;             PG8_LDA(At, 1, 1); PG8_STAGE(PG8_SB(1, 0), b3, voffB); PG8_STAGE(PG8_SB(1, 1), b3 + hstep, voffB); PG8_STAGE(PG8_SA(1, 0), a3, voffA);
;             PG8_WAIT_V(8); PG8_WAIT_L(0); PG8_BAR; PG8_MMA(1, 0, At, B0); PG8_MMA(1, 1, At, B1); PG8_BAR; PG8_SCHED;
	s_add_i32 s28, s50, s36
	v_lshl_add_u64 v[156:157], v[156:157], 0, s[80:81]
	s_mov_b32 m0, s28
	ds_read_b128 v[186:189], v160 offset:49152
	ds_read_b128 v[190:193], v160 offset:50176
	ds_read_b128 v[194:197], v160 offset:51200
	ds_read_b128 v[198:201], v160 offset:52224
	ds_read_b128 v[202:205], v160 offset:53248
	ds_read_b128 v[206:209], v160 offset:54272
	ds_read_b128 v[210:213], v160 offset:55296
	ds_read_b128 v[214:217], v160 offset:56320
	global_load_lds_dwordx4 v[156:157], off
	s_add_i32 m0, s28, 0x2000
	s_add_u32 s26, s26, 0x40080
	v_lshl_add_u64 v[156:157], v[218:219], 0, s[80:81]
	s_addc_u32 s27, s27, 0
	s_add_i32 s28, s51, s36
	global_load_lds_dwordx4 v[156:157], off
	v_lshl_add_u64 v[156:157], s[26:27], 0, v[142:143]
	s_mov_b32 m0, s28
	s_nop 0
	global_load_lds_dwordx4 v[156:157], off
	v_lshl_add_u64 v[156:157], s[26:27], 0, v[138:139]
	s_add_i32 m0, s28, 0x2000
	s_nop 0
	global_load_lds_dwordx4 v[156:157], off
	v_lshl_add_u64 v[156:157], v[220:221], 0, s[80:81]
	s_mov_b32 m0, s41
	s_nop 0
	global_load_lds_dwordx4 v[156:157], off
	v_lshl_add_u64 v[156:157], v[222:223], 0, s[80:81]
	s_mov_b32 m0, s42
	s_nop 0
	global_load_lds_dwordx4 v[156:157], off
	s_waitcnt vmcnt(8) lgkmcnt(0)
	s_barrier
	v_mfma_f32_16x16x32_bf16 v[62:65], v[66:69], v[186:189], v[62:65]
	v_mfma_f32_16x16x32_bf16 v[58:61], v[152:155], v[186:189], v[58:61]
	v_mfma_f32_16x16x32_bf16 v[46:49], v[66:69], v[194:197], v[46:49]
	v_mfma_f32_16x16x32_bf16 v[42:45], v[152:155], v[194:197], v[42:45]
	v_mfma_f32_16x16x32_bf16 v[30:33], v[66:69], v[202:205], v[30:33]
	v_mfma_f32_16x16x32_bf16 v[26:29], v[152:155], v[202:205], v[26:29]
	v_mfma_f32_16x16x32_bf16 v[14:17], v[66:69], v[210:213], v[14:17]
	v_mfma_f32_16x16x32_bf16 v[10:13], v[152:155], v[210:213], v[10:13]
	v_mfma_f32_16x16x32_bf16 v[62:65], v[118:121], v[190:193], v[62:65]
	v_mfma_f32_16x16x32_bf16 v[58:61], v[162:165], v[190:193], v[58:61]
	v_mfma_f32_16x16x32_bf16 v[46:49], v[118:121], v[198:201], v[46:49]
	v_mfma_f32_16x16x32_bf16 v[42:45], v[162:165], v[198:201], v[42:45]
	v_mfma_f32_16x16x32_bf16 v[30:33], v[118:121], v[206:209], v[30:33]
	v_mfma_f32_16x16x32_bf16 v[26:29], v[162:165], v[206:209], v[26:29]
	v_mfma_f32_16x16x32_bf16 v[14:17], v[118:121], v[214:217], v[14:17]
	v_mfma_f32_16x16x32_bf16 v[10:13], v[162:165], v[214:217], v[10:13]
	v_mfma_f32_16x16x32_bf16 v[54:57], v[166:169], v[186:189], v[54:57]
	v_mfma_f32_16x16x32_bf16 v[50:53], v[174:177], v[186:189], v[50:53]
	v_mfma_f32_16x16x32_bf16 v[38:41], v[166:169], v[194:197], v[38:41]
	v_mfma_f32_16x16x32_bf16 v[34:37], v[174:177], v[194:197], v[34:37]
	v_mfma_f32_16x16x32_bf16 v[22:25], v[166:169], v[202:205], v[22:25]
	v_mfma_f32_16x16x32_bf16 v[18:21], v[174:177], v[202:205], v[18:21]
	v_mfma_f32_16x16x32_bf16 v[6:9], v[166:169], v[210:213], v[6:9]
	v_mfma_f32_16x16x32_bf16 v[2:5], v[174:177], v[210:213], v[2:5]
	v_mfma_f32_16x16x32_bf16 v[54:57], v[170:173], v[190:193], v[54:57]
	v_mfma_f32_16x16x32_bf16 v[50:53], v[180:183], v[190:193], v[50:53]
	v_mfma_f32_16x16x32_bf16 v[38:41], v[170:173], v[198:201], v[38:41]
	v_mfma_f32_16x16x32_bf16 v[34:37], v[180:183], v[198:201], v[34:37]
	v_mfma_f32_16x16x32_bf16 v[22:25], v[170:173], v[206:209], v[22:25]
	v_mfma_f32_16x16x32_bf16 v[18:21], v[180:183], v[206:209], v[18:21]
	v_mfma_f32_16x16x32_bf16 v[6:9], v[170:173], v[214:217], v[6:9]
	v_mfma_f32_16x16x32_bf16 v[2:5], v[180:183], v[214:217], v[2:5]
	s_barrier
	s_add_i32 s49, s49, 2
	s_add_u32 s24, s24, 0x100
	s_addc_u32 s25, s25, 0
	s_add_u32 s47, s47, 0x100
	s_addc_u32 s48, s48, 0
	s_cmp_gt_u32 s49, 13
	s_branch .LBB0_1249
.LBB0_1249:
	s_add_u32 s26, s24, 0xfffc0080
	s_addc_u32 s27, s25, -1
	s_add_i32 s50, 0, 0x10000
	s_cmp_eq_u32 s49, 12
	s_cselect_b32 s29, s17, s27
	s_cselect_b32 s28, s45, s26
	v_add_u32_e32 v156, s50, v158
	s_cselect_b32 s27, s15, s48
	s_cselect_b32 s26, s46, s47
	s_add_i32 s52, 0, 0x14000
	ds_read_b128 v[66:69], v156
	ds_read_b128 v[118:121], v156 offset:1024
	ds_read_b128 v[152:155], v156 offset:2048
	ds_read_b128 v[162:165], v156 offset:3072
	v_add_u32_e32 v156, s52, v158
	ds_read_b128 v[166:169], v156
	ds_read_b128 v[170:173], v156 offset:1024
	ds_read_b128 v[174:177], v156 offset:2048
	ds_read_b128 v[180:183], v156 offset:3072
	v_lshl_add_u64 v[156:157], s[24:25], 0, v[148:149]
	s_add_i32 m0, s33, 0xc000
	ds_read_b128 v[186:189], v160
	ds_read_b128 v[190:193], v160 offset:1024
	ds_read_b128 v[194:197], v160 offset:2048
	ds_read_b128 v[198:201], v160 offset:3072
	ds_read_b128 v[202:205], v160 offset:4096
	ds_read_b128 v[206:209], v160 offset:5120
	ds_read_b128 v[210:213], v160 offset:6144
	ds_read_b128 v[214:217], v160 offset:7168
	global_load_lds_dwordx4 v[156:157], off
	v_lshl_add_u64 v[156:157], s[24:25], 0, v[150:151]
	s_add_i32 m0, s33, 0xe000
	s_nop 0
	global_load_lds_dwordx4 v[156:157], off
	s_waitcnt vmcnt(8) lgkmcnt(0)
	s_barrier
; #define PG8_STAGE(bufoff, gbase, voff) do { _Pragma("unroll") for (int _i = 0; _i < 2; ++_i) \
;         __builtin_amdgcn_global_load_lds((const unsigned*)((const char*)(gbase) + (voff)[_i]), (PG8_LAS unsigned*)(lds + (bufoff) + ldsw + _i * 8192), 16, 0, 0); } while (0)
; #define PG8_LDA(dst, b, h) do { _Pragma("unroll") for (int m = 0; m < 4; ++m) _Pragma("unroll") for (int k = 0; k < 2; ++k) dst[m][k] = *(const PG8_LAS bf16x8*)(lds + PG8_SA(b, h) + aoff + m * 2048 + k * 1024); } while (0)
; #define PG8_LDB(dst, b, h) do { _Pragma("unroll") for (int n = 0; n < 2; ++n) _Pragma("unroll") for (int k = 0; k < 2; ++k) dst[n][k] = *(const PG8_LAS bf16x8*)(lds + PG8_SB(b, h) + boff + n * 2048 + k * 1024); } while (0)
; #define PG8_MMA(ai, bj, At, Bt) do { __builtin_amdgcn_s_setprio(1); _Pragma("unroll") for (int m = 0; m < 4; ++m) _Pragma("unroll") for (int n = 0; n < 2; ++n) _Pragma("unroll") for (int k = 0; k < 2; ++k) \
;         acc[ai][bj][m][n] = __builtin_amdgcn_mfma_f32_16x16x32_bf16(Bt[n][k], At[m][k], acc[ai][bj][m][n], 0, 0, 0); __builtin_amdgcn_s_setprio(0); } while (0)
; #define PG8_WAIT_V(n) asm volatile("s_waitcnt vmcnt(" #n ")" ::: "memory")
; template <class Epi, class Sched, bool ALIGN_EPI = false, bool SP2 = false>
; __device__ __forceinline__ void gemm_phase(PG8_LAS unsigned char* lds, const Gemm g, const Sched& S, const Epi& E) {
;     ...
;             PG8_LDB(B0, 0, 0); PG8_LDB(B1, 0, 1); PG8_SCHED; PG8_LDA(At, 0, 0); PG8_STAGE(PG8_SA(1, 1), a1 + hstep, voffA);
;             PG8_WAIT_V(8); PG8_WAIT_L(0); PG8_BAR; PG8_MMA(0, 0, At, B0); PG8_MMA(0, 1, At, B1); PG8_BAR; PG8_SCHED;
;             PG8_LDA(At, 0, 1); PG8_STAGE(PG8_SB(0, 0), b2, voffB); PG8_STAGE(PG8_SB(0, 1), b2 + hstep, voffB); PG8_STAGE(PG8_SA(0, 0), a2, voffA);
;             PG8_WAIT_V(8); PG8_WAIT_L(0); PG8_BAR; PG8_MMA(1, 0, At, B0); PG8_MMA(1, 1, At, B1); PG8_BAR; PG8_SCHED;
;             PG8_LDB(B0, 1, 0); PG8_LDB(B1, 1, 1); PG8_SCHED; PG8_LDA(At, 1, 0); PG8_STAGE(PG8_SA(0, 1), a2 + hstep, voffA);
;             PG8_WAIT_V(8); PG8_WAIT_L(0); PG8_BAR; PG8_MMA(0, 0, At, B0); PG8_MMA(0, 1, At, B1); PG8_BAR; PG8_SCHED;
;             PG8_LDA(At, 1, 1); PG8_STAGE(PG8_SB(1, 0), b3, voffB); PG8_STAGE(PG8_SB(1, 1), b3 + hstep, voffB); PG8_STAGE(PG8_SA(1, 0), a3, voffA);
;             PG8_WAIT_V(8); PG8_WAIT_L(0); PG8_BAR; PG8_MMA(1, 0, At, B0); PG8_MMA(1, 1, At, B1); PG8_BAR; PG8_SCHED;
	v_mfma_f32_16x16x32_bf16 v[134:137], v[66:69], v[186:189], v[134:137]
	v_mfma_f32_16x16x32_bf16 v[126:129], v[152:155], v[186:189], v[126:129]
	v_mfma_f32_16x16x32_bf16 v[114:117], v[66:69], v[194:197], v[114:117]
	v_mfma_f32_16x16x32_bf16 v[110:113], v[152:155], v[194:197], v[110:113]
	v_mfma_f32_16x16x32_bf16 v[98:101], v[66:69], v[202:205], v[98:101]
	v_mfma_f32_16x16x32_bf16 v[94:97], v[152:155], v[202:205], v[94:97]
	v_mfma_f32_16x16x32_bf16 v[82:85], v[66:69], v[210:213], v[82:85]
	v_mfma_f32_16x16x32_bf16 v[78:81], v[152:155], v[210:213], v[78:81]
	v_mfma_f32_16x16x32_bf16 v[134:137], v[118:121], v[190:193], v[134:137]
	v_mfma_f32_16x16x32_bf16 v[126:129], v[162:165], v[190:193], v[126:129]
	v_mfma_f32_16x16x32_bf16 v[114:117], v[118:121], v[198:201], v[114:117]
	v_mfma_f32_16x16x32_bf16 v[110:113], v[162:165], v[198:201], v[110:113]
	v_mfma_f32_16x16x32_bf16 v[98:101], v[118:121], v[206:209], v[98:101]
	v_mfma_f32_16x16x32_bf16 v[94:97], v[162:165], v[206:209], v[94:97]
	v_mfma_f32_16x16x32_bf16 v[82:85], v[118:121], v[214:217], v[82:85]
	v_mfma_f32_16x16x32_bf16 v[78:81], v[162:165], v[214:217], v[78:81]
	v_mfma_f32_16x16x32_bf16 v[130:133], v[166:169], v[186:189], v[130:133]
	v_mfma_f32_16x16x32_bf16 v[122:125], v[174:177], v[186:189], v[122:125]
	v_mfma_f32_16x16x32_bf16 v[106:109], v[166:169], v[194:197], v[106:109]
	v_mfma_f32_16x16x32_bf16 v[102:105], v[174:177], v[194:197], v[102:105]
	v_mfma_f32_16x16x32_bf16 v[90:93], v[166:169], v[202:205], v[90:93]
	v_mfma_f32_16x16x32_bf16 v[86:89], v[174:177], v[202:205], v[86:89]
	v_mfma_f32_16x16x32_bf16 v[74:77], v[166:169], v[210:213], v[74:77]
	v_mfma_f32_16x16x32_bf16 v[70:73], v[174:177], v[210:213], v[70:73]
	v_mfma_f32_16x16x32_bf16 v[130:133], v[170:173], v[190:193], v[130:133]
	v_mfma_f32_16x16x32_bf16 v[122:125], v[180:183], v[190:193], v[122:125]
	v_mfma_f32_16x16x32_bf16 v[106:109], v[170:173], v[198:201], v[106:109]
	v_mfma_f32_16x16x32_bf16 v[102:105], v[180:183], v[198:201], v[102:105]
	v_mfma_f32_16x16x32_bf16 v[90:93], v[170:173], v[206:209], v[90:93]
	v_mfma_f32_16x16x32_bf16 v[86:89], v[180:183], v[206:209], v[86:89]
	v_mfma_f32_16x16x32_bf16 v[74:77], v[170:173], v[214:217], v[74:77]
	v_mfma_f32_16x16x32_bf16 v[70:73], v[180:183], v[214:217], v[70:73]
	s_barrier
	s_add_i32 s50, s50, s36
	v_lshl_add_u64 v[156:157], s[26:27], 0, v[142:143]
	s_mov_b32 m0, s50
	ds_read_b128 v[186:189], v160 offset:16384
	ds_read_b128 v[190:193], v160 offset:17408
	ds_read_b128 v[194:197], v160 offset:18432
	ds_read_b128 v[198:201], v160 offset:19456
	ds_read_b128 v[202:205], v160 offset:20480
	ds_read_b128 v[206:209], v160 offset:21504
	ds_read_b128 v[210:213], v160 offset:22528
	ds_read_b128 v[214:217], v160 offset:23552
	global_load_lds_dwordx4 v[156:157], off
	s_add_i32 m0, s50, 0x2000
	s_add_u32 s50, s26, 0x40000
	v_lshl_add_u64 v[218:219], s[26:27], 0, v[138:139]
	s_addc_u32 s51, s27, 0
	s_add_i32 s52, s52, s36
	global_load_lds_dwordx4 v[218:219], off
	v_lshl_add_u64 v[220:221], s[50:51], 0, v[142:143]
	s_mov_b32 m0, s52
	v_lshl_add_u64 v[222:223], s[28:29], 0, v[140:141]
	global_load_lds_dwordx4 v[220:221], off
	v_lshl_add_u64 v[220:221], s[50:51], 0, v[138:139]
	s_add_i32 m0, s52, 0x2000
	s_nop 0
	global_load_lds_dwordx4 v[220:221], off
	v_lshl_add_u64 v[220:221], s[28:29], 0, v[144:145]
	s_mov_b32 m0, s33
	s_nop 0
	global_load_lds_dwordx4 v[220:221], off
	s_mov_b32 m0, s38
	s_nop 0
	global_load_lds_dwordx4 v[222:223], off
	s_waitcnt vmcnt(8) lgkmcnt(0)
	s_barrier
	v_mfma_f32_16x16x32_bf16 v[62:65], v[66:69], v[186:189], v[62:65]
	v_mfma_f32_16x16x32_bf16 v[58:61], v[152:155], v[186:189], v[58:61]
	v_mfma_f32_16x16x32_bf16 v[46:49], v[66:69], v[194:197], v[46:49]
	v_mfma_f32_16x16x32_bf16 v[42:45], v[152:155], v[194:197], v[42:45]
	v_mfma_f32_16x16x32_bf16 v[30:33], v[66:69], v[202:205], v[30:33]
	v_mfma_f32_16x16x32_bf16 v[26:29], v[152:155], v[202:205], v[26:29]
	v_mfma_f32_16x16x32_bf16 v[14:17], v[66:69], v[210:213], v[14:17]
	v_mfma_f32_16x16x32_bf16 v[10:13], v[152:155], v[210:213], v[10:13]
	v_mfma_f32_16x16x32_bf16 v[62:65], v[118:121], v[190:193], v[62:65]
	v_mfma_f32_16x16x32_bf16 v[58:61], v[162:165], v[190:193], v[58:61]
	v_mfma_f32_16x16x32_bf16 v[46:49], v[118:121], v[198:201], v[46:49]
	v_mfma_f32_16x16x32_bf16 v[42:45], v[162:165], v[198:201], v[42:45]
	v_mfma_f32_16x16x32_bf16 v[30:33], v[118:121], v[206:209], v[30:33]
	v_mfma_f32_16x16x32_bf16 v[26:29], v[162:165], v[206:209], v[26:29]
	v_mfma_f32_16x16x32_bf16 v[14:17], v[118:121], v[214:217], v[14:17]
	v_mfma_f32_16x16x32_bf16 v[10:13], v[162:165], v[214:217], v[10:13]
	v_mfma_f32_16x16x32_bf16 v[54:57], v[166:169], v[186:189], v[54:57]
	v_mfma_f32_16x16x32_bf16 v[50:53], v[174:177], v[186:189], v[50:53]
	v_mfma_f32_16x16x32_bf16 v[38:41], v[166:169], v[194:197], v[38:41]
	v_mfma_f32_16x16x32_bf16 v[34:37], v[174:177], v[194:197], v[34:37]
	v_mfma_f32_16x16x32_bf16 v[22:25], v[166:169], v[202:205], v[22:25]
	v_mfma_f32_16x16x32_bf16 v[18:21], v[174:177], v[202:205], v[18:21]
	v_mfma_f32_16x16x32_bf16 v[6:9], v[166:169], v[210:213], v[6:9]
	v_mfma_f32_16x16x32_bf16 v[2:5], v[174:177], v[210:213], v[2:5]
	v_mfma_f32_16x16x32_bf16 v[54:57], v[170:173], v[190:193], v[54:57]
	v_mfma_f32_16x16x32_bf16 v[50:53], v[180:183], v[190:193], v[50:53]
	v_mfma_f32_16x16x32_bf16 v[38:41], v[170:173], v[198:201], v[38:41]
	v_mfma_f32_16x16x32_bf16 v[34:37], v[180:183], v[198:201], v[34:37]
	v_mfma_f32_16x16x32_bf16 v[22:25], v[170:173], v[206:209], v[22:25]
	v_mfma_f32_16x16x32_bf16 v[18:21], v[180:183], v[206:209], v[18:21]
	v_mfma_f32_16x16x32_bf16 v[6:9], v[170:173], v[214:217], v[6:9]
	v_mfma_f32_16x16x32_bf16 v[2:5], v[180:183], v[214:217], v[2:5]
	s_barrier
; #define PG8_STAGE(bufoff, gbase, voff) do { _Pragma("unroll") for (int _i = 0; _i < 2; ++_i) \
;         __builtin_amdgcn_global_load_lds((const unsigned*)((const char*)(gbase) + (voff)[_i]), (PG8_LAS unsigned*)(lds + (bufoff) + ldsw + _i * 8192), 16, 0, 0); } while (0)
; #define PG8_LDA(dst, b, h) do { _Pragma("unroll") for (int m = 0; m < 4; ++m) _Pragma("unroll") for (int k = 0; k < 2; ++k) dst[m][k] = *(const PG8_LAS bf16x8*)(lds + PG8_SA(b, h) + aoff + m * 2048 + k * 1024); } while (0)
; #define PG8_LDB(dst, b, h) do { _Pragma("unroll") for (int n = 0; n < 2; ++n) _Pragma("unroll") for (int k = 0; k < 2; ++k) dst[n][k] = *(const PG8_LAS bf16x8*)(lds + PG8_SB(b, h) + boff + n * 2048 + k * 1024); } while (0)
; #define PG8_MMA(ai, bj, At, Bt) do { __builtin_amdgcn_s_setprio(1); _Pragma("unroll") for (int m = 0; m < 4; ++m) _Pragma("unroll") for (int n = 0; n < 2; ++n) _Pragma("unroll") for (int k = 0; k < 2; ++k) \
;         acc[ai][bj][m][n] = __builtin_amdgcn_mfma_f32_16x16x32_bf16(Bt[n][k], At[m][k], acc[ai][bj][m][n], 0, 0, 0); __builtin_amdgcn_s_setprio(0); } while (0)
; #define PG8_WAIT_V(n) asm volatile("s_waitcnt vmcnt(" #n ")" ::: "memory")
; #define PG8_WAIT_L(n) asm volatile("s_waitcnt lgkmcnt(" #n ")" ::: "memory")
; #define PG8_BAR __builtin_amdgcn_s_barrier()
; #define PG8_SCHED __builtin_amdgcn_sched_barrier(0)
; template <class Epi, class Sched, bool ALIGN_EPI = false, bool SP2 = false>
; __device__ __forceinline__ void gemm_phase(PG8_LAS unsigned char* lds, const Gemm g, const Sched& S, const Epi& E) {
;     ...
;             PG8_LDB(B0, 1, 0); PG8_LDB(B1, 1, 1); PG8_SCHED; PG8_LDA(At, 1, 0); PG8_STAGE(PG8_SA(0, 1), a2 + hstep, voffA);
;             PG8_WAIT_V(8); PG8_WAIT_L(0); PG8_BAR; PG8_MMA(0, 0, At, B0); PG8_MMA(0, 1, At, B1); PG8_BAR; PG8_SCHED;
	s_add_i32 s50, 0, 0x18000
	v_add_u32_e32 v161, s50, v158
	s_add_i32 s51, 0, 0x1c000
	ds_read_b128 v[66:69], v161
	ds_read_b128 v[118:121], v161 offset:1024
	ds_read_b128 v[152:155], v161 offset:2048
	ds_read_b128 v[162:165], v161 offset:3072
	v_add_u32_e32 v161, s51, v158
	ds_read_b128 v[166:169], v161
	ds_read_b128 v[170:173], v161 offset:1024
	ds_read_b128 v[174:177], v161 offset:2048
	ds_read_b128 v[180:183], v161 offset:3072
	s_add_u32 s28, s28, 0x40000
	s_addc_u32 s29, s29, 0
	s_mov_b32 m0, s39
	v_lshl_add_u64 v[240:241], s[28:29], 0, v[144:145]
	ds_read_b128 v[186:189], v160 offset:32768
	ds_read_b128 v[190:193], v160 offset:33792
	ds_read_b128 v[194:197], v160 offset:34816
	ds_read_b128 v[198:201], v160 offset:35840
	ds_read_b128 v[202:205], v160 offset:36864
	ds_read_b128 v[206:209], v160 offset:37888
	ds_read_b128 v[210:213], v160 offset:38912
	ds_read_b128 v[214:217], v160 offset:39936
	global_load_lds_dwordx4 v[240:241], off
	v_lshl_add_u64 v[240:241], s[28:29], 0, v[140:141]
	s_mov_b32 m0, s40
	s_nop 0
	global_load_lds_dwordx4 v[240:241], off
	s_waitcnt vmcnt(8) lgkmcnt(0)
	s_barrier
	v_mfma_f32_16x16x32_bf16 v[134:137], v[66:69], v[186:189], v[134:137]
	v_mfma_f32_16x16x32_bf16 v[126:129], v[152:155], v[186:189], v[126:129]
	v_mfma_f32_16x16x32_bf16 v[114:117], v[66:69], v[194:197], v[114:117]
	v_mfma_f32_16x16x32_bf16 v[110:113], v[152:155], v[194:197], v[110:113]
	v_mfma_f32_16x16x32_bf16 v[98:101], v[66:69], v[202:205], v[98:101]
	v_mfma_f32_16x16x32_bf16 v[94:97], v[152:155], v[202:205], v[94:97]
	v_mfma_f32_16x16x32_bf16 v[82:85], v[66:69], v[210:213], v[82:85]
	v_mfma_f32_16x16x32_bf16 v[78:81], v[152:155], v[210:213], v[78:81]
	v_mfma_f32_16x16x32_bf16 v[134:137], v[118:121], v[190:193], v[134:137]
	v_mfma_f32_16x16x32_bf16 v[126:129], v[162:165], v[190:193], v[126:129]
	v_mfma_f32_16x16x32_bf16 v[114:117], v[118:121], v[198:201], v[114:117]
	v_mfma_f32_16x16x32_bf16 v[110:113], v[162:165], v[198:201], v[110:113]
	v_mfma_f32_16x16x32_bf16 v[98:101], v[118:121], v[206:209], v[98:101]
	v_mfma_f32_16x16x32_bf16 v[94:97], v[162:165], v[206:209], v[94:97]
	v_mfma_f32_16x16x32_bf16 v[82:85], v[118:121], v[214:217], v[82:85]
	v_mfma_f32_16x16x32_bf16 v[78:81], v[162:165], v[214:217], v[78:81]
	v_mfma_f32_16x16x32_bf16 v[130:133], v[166:169], v[186:189], v[130:133]
	v_mfma_f32_16x16x32_bf16 v[122:125], v[174:177], v[186:189], v[122:125]
	v_mfma_f32_16x16x32_bf16 v[106:109], v[166:169], v[194:197], v[106:109]
	v_mfma_f32_16x16x32_bf16 v[102:105], v[174:177], v[194:197], v[102:105]
	v_mfma_f32_16x16x32_bf16 v[90:93], v[166:169], v[202:205], v[90:93]
	v_mfma_f32_16x16x32_bf16 v[86:89], v[174:177], v[202:205], v[86:89]
	v_mfma_f32_16x16x32_bf16 v[74:77], v[166:169], v[210:213], v[74:77]
	v_mfma_f32_16x16x32_bf16 v[70:73], v[174:177], v[210:213], v[70:73]
	v_mfma_f32_16x16x32_bf16 v[130:133], v[170:173], v[190:193], v[130:133]
	v_mfma_f32_16x16x32_bf16 v[122:125], v[180:183], v[190:193], v[122:125]
	v_mfma_f32_16x16x32_bf16 v[106:109], v[170:173], v[198:201], v[106:109]
	v_mfma_f32_16x16x32_bf16 v[102:105], v[180:183], v[198:201], v[102:105]
	v_mfma_f32_16x16x32_bf16 v[90:93], v[170:173], v[206:209], v[90:93]
	v_mfma_f32_16x16x32_bf16 v[86:89], v[180:183], v[206:209], v[86:89]
	v_mfma_f32_16x16x32_bf16 v[74:77], v[170:173], v[214:217], v[74:77]
	v_mfma_f32_16x16x32_bf16 v[70:73], v[180:183], v[214:217], v[70:73]
	s_barrier
; #define PG8_STAGE(bufoff, gbase, voff) do { _Pragma("unroll") for (int _i = 0; _i < 2; ++_i) \
;         __builtin_amdgcn_global_load_lds((const unsigned*)((const char*)(gbase) + (voff)[_i]), (PG8_LAS unsigned*)(lds + (bufoff) + ldsw + _i * 8192), 16, 0, 0); } while (0)
; #define PG8_LDA(dst, b, h) do { _Pragma("unroll") for (int m = 0; m < 4; ++m) _Pragma("unroll") for (int k = 0; k < 2; ++k) dst[m][k] = *(const PG8_LAS bf16x8*)(lds + PG8_SA(b, h) + aoff + m * 2048 + k * 1024); } while (0)
; #define PG8_MMA(ai, bj, At, Bt) do { __builtin_amdgcn_s_setprio(1); _Pragma("unroll") for (int m = 0; m < 4; ++m) _Pragma("unroll") for (int n = 0; n < 2; ++n) _Pragma("unroll") for (int k = 0; k < 2; ++k) \
;         acc[ai][bj][m][n] = __builtin_amdgcn_mfma_f32_16x16x32_bf16(Bt[n][k], At[m][k], acc[ai][bj][m][n], 0, 0, 0); __builtin_amdgcn_s_setprio(0); } while (0)
; #define PG8_WAIT_V(n) asm volatile("s_waitcnt vmcnt(" #n ")" ::: "memory")
; #define PG8_WAIT_L(n) asm volatile("s_waitcnt lgkmcnt(" #n ")" ::: "memory")
; #define PG8_BAR __builtin_amdgcn_s_barrier()
; #define PG8_SCHED __builtin_amdgcn_sched_barrier(0)
; template <class Epi, class Sched, bool ALIGN_EPI = false, bool SP2 = false>
; __device__ __forceinline__ void gemm_phase(PG8_LAS unsigned char* lds, const Gemm g, const Sched& S, const Epi& E) {
;     ...
;             PG8_LDA(At, 1, 1); PG8_STAGE(PG8_SB(1, 0), b3, voffB); PG8_STAGE(PG8_SB(1, 1), b3 + hstep, voffB); PG8_STAGE(PG8_SA(1, 0), a3, voffA);
;             PG8_WAIT_V(8); PG8_WAIT_L(0); PG8_BAR; PG8_MMA(1, 0, At, B0); PG8_MMA(1, 1, At, B1); PG8_BAR; PG8_SCHED;
;     ...
;         if constexpr (ALIGN_EPI) { if (wr == 0) PG8_BAR; }
	s_add_i32 s28, s50, s36
	v_lshl_add_u64 v[156:157], v[156:157], 0, s[80:81]
	s_mov_b32 m0, s28
	ds_read_b128 v[186:189], v160 offset:49152
	ds_read_b128 v[190:193], v160 offset:50176
	ds_read_b128 v[194:197], v160 offset:51200
	ds_read_b128 v[198:201], v160 offset:52224
	ds_read_b128 v[202:205], v160 offset:53248
	ds_read_b128 v[206:209], v160 offset:54272
	ds_read_b128 v[210:213], v160 offset:55296
	ds_read_b128 v[214:217], v160 offset:56320
	global_load_lds_dwordx4 v[156:157], off
	s_add_i32 m0, s28, 0x2000
	s_add_u32 s26, s26, 0x40080
	v_lshl_add_u64 v[156:157], v[218:219], 0, s[80:81]
	s_addc_u32 s27, s27, 0
	s_add_i32 s28, s51, s36
	global_load_lds_dwordx4 v[156:157], off
	v_lshl_add_u64 v[156:157], s[26:27], 0, v[142:143]
	s_mov_b32 m0, s28
	s_nop 0
	global_load_lds_dwordx4 v[156:157], off
	v_lshl_add_u64 v[156:157], s[26:27], 0, v[138:139]
	s_add_i32 m0, s28, 0x2000
	s_nop 0
	global_load_lds_dwordx4 v[156:157], off
	v_lshl_add_u64 v[156:157], v[220:221], 0, s[80:81]
	s_mov_b32 m0, s41
	s_nop 0
	global_load_lds_dwordx4 v[156:157], off
	v_lshl_add_u64 v[156:157], v[222:223], 0, s[80:81]
	s_mov_b32 m0, s42
	s_nop 0
	global_load_lds_dwordx4 v[156:157], off
	s_waitcnt vmcnt(8) lgkmcnt(0)
	s_barrier
	v_mfma_f32_16x16x32_bf16 v[62:65], v[66:69], v[186:189], v[62:65]
	v_mfma_f32_16x16x32_bf16 v[58:61], v[152:155], v[186:189], v[58:61]
	v_mfma_f32_16x16x32_bf16 v[46:49], v[66:69], v[194:197], v[46:49]
	v_mfma_f32_16x16x32_bf16 v[42:45], v[152:155], v[194:197], v[42:45]
	v_mfma_f32_16x16x32_bf16 v[30:33], v[66:69], v[202:205], v[30:33]
	v_mfma_f32_16x16x32_bf16 v[26:29], v[152:155], v[202:205], v[26:29]
	v_mfma_f32_16x16x32_bf16 v[14:17], v[66:69], v[210:213], v[14:17]
	v_mfma_f32_16x16x32_bf16 v[10:13], v[152:155], v[210:213], v[10:13]
	v_mfma_f32_16x16x32_bf16 v[62:65], v[118:121], v[190:193], v[62:65]
	v_mfma_f32_16x16x32_bf16 v[58:61], v[162:165], v[190:193], v[58:61]
	v_mfma_f32_16x16x32_bf16 v[46:49], v[118:121], v[198:201], v[46:49]
	v_mfma_f32_16x16x32_bf16 v[42:45], v[162:165], v[198:201], v[42:45]
	v_mfma_f32_16x16x32_bf16 v[30:33], v[118:121], v[206:209], v[30:33]
	v_mfma_f32_16x16x32_bf16 v[26:29], v[162:165], v[206:209], v[26:29]
	v_mfma_f32_16x16x32_bf16 v[14:17], v[118:121], v[214:217], v[14:17]
	v_mfma_f32_16x16x32_bf16 v[10:13], v[162:165], v[214:217], v[10:13]
	v_mfma_f32_16x16x32_bf16 v[54:57], v[166:169], v[186:189], v[54:57]
	v_mfma_f32_16x16x32_bf16 v[50:53], v[174:177], v[186:189], v[50:53]
	v_mfma_f32_16x16x32_bf16 v[38:41], v[166:169], v[194:197], v[38:41]
	v_mfma_f32_16x16x32_bf16 v[34:37], v[174:177], v[194:197], v[34:37]
	v_mfma_f32_16x16x32_bf16 v[22:25], v[166:169], v[202:205], v[22:25]
	v_mfma_f32_16x16x32_bf16 v[18:21], v[174:177], v[202:205], v[18:21]
	v_mfma_f32_16x16x32_bf16 v[6:9], v[166:169], v[210:213], v[6:9]
	v_mfma_f32_16x16x32_bf16 v[2:5], v[174:177], v[210:213], v[2:5]
	v_mfma_f32_16x16x32_bf16 v[54:57], v[170:173], v[190:193], v[54:57]
	v_mfma_f32_16x16x32_bf16 v[50:53], v[180:183], v[190:193], v[50:53]
	v_mfma_f32_16x16x32_bf16 v[38:41], v[170:173], v[198:201], v[38:41]
	v_mfma_f32_16x16x32_bf16 v[34:37], v[180:183], v[198:201], v[34:37]
	v_mfma_f32_16x16x32_bf16 v[22:25], v[170:173], v[206:209], v[22:25]
	v_mfma_f32_16x16x32_bf16 v[18:21], v[180:183], v[206:209], v[18:21]
	v_mfma_f32_16x16x32_bf16 v[6:9], v[170:173], v[214:217], v[6:9]
	v_mfma_f32_16x16x32_bf16 v[2:5], v[180:183], v[214:217], v[2:5]
	s_barrier
	s_add_i32 s49, s49, 2
	s_add_u32 s24, s24, 0x100
	s_addc_u32 s25, s25, 0
	s_add_u32 s47, s47, 0x100
	s_addc_u32 s48, s48, 0
	s_cmp_gt_u32 s49, 13
	s_cbranch_scc0 .LBB0_1249
	s_and_b64 vcc, exec, s[12:13]
	s_cbranch_vccz .LBB0_1252
	s_barrier

; #define PG8_STAGE(bufoff, gbase, voff) do { _Pragma("unroll") for (int _i = 0; _i < 2; ++_i) \
;         __builtin_amdgcn_global_load_lds((const unsigned*)((const char*)(gbase) + (voff)[_i]), (PG8_LAS unsigned*)(lds + (bufoff) + ldsw + _i * 8192), 16, 0, 0); } while (0)
; #define PG8_LDA(dst, b, h) do { _Pragma("unroll") for (int m = 0; m < 4; ++m) _Pragma("unroll") for (int k = 0; k < 2; ++k) dst[m][k] = *(const PG8_LAS bf16x8*)(lds + PG8_SA(b, h) + aoff + m * 2048 + k * 1024); } while (0)
; #define PG8_LDB(dst, b, h) do { _Pragma("unroll") for (int n = 0; n < 2; ++n) _Pragma("unroll") for (int k = 0; k < 2; ++k) dst[n][k] = *(const PG8_LAS bf16x8*)(lds + PG8_SB(b, h) + boff + n * 2048 + k * 1024); } while (0)
; #define PG8_WAIT_V(n) asm volatile("s_waitcnt vmcnt(" #n ")" ::: "memory")
; #define PG8_WAIT_L(n) asm volatile("s_waitcnt lgkmcnt(" #n ")" ::: "memory")
; #define PG8_BAR __builtin_amdgcn_s_barrier()
; #define PG8_SCHED __builtin_amdgcn_sched_barrier(0)
; template <class Epi, class Sched, bool ALIGN_EPI = false, bool SP2 = false>
; __device__ __forceinline__ void gemm_phase(PG8_LAS unsigned char* lds, const Gemm g, const Sched& S, const Epi& E) {
;     ...
;     for (;;) {
;         const bool has_next = S.next(ui + 1, nxt);
;         const char* nA = has_next ? (const char*)g.A + (size_t)nxt.pm * tstep : cA; const char* nB = has_next ? (const char*)g.Bt + (size_t)nxt.pn * tstep : cB;
;         for (int t = 0; t < nt; t += 2) {
;             const bool last = (t == nt - 2);
;             const char* a1 = cA + (size_t)(t + 1) * kstep;
;             const char* a2 = last ? nA : cA + (size_t)(t + 2) * kstep; const char* b2 = last ? nB : cB + (size_t)(t + 2) * kstep;
;             const char* a3 = a2 + kstep; const char* b3 = b2 + kstep;
;             if (last && has_next) S.a_ready(nxt);
;             if constexpr (SP2) {
;             PG8_LDB(B0, 0, 0); PG8_LDB(B1, 0, 1); PG8_SCHED; PG8_LDA(At, 0, 0); PG8_STAGE(PG8_SA(1, 1), a1 + hstep, voffA);
;             PG8_WAIT_V(8); PG8_WAIT_L(0); PG8_BAR; PG8_MMA(0, 0, At, B0); PG8_MMA(0, 1, At, B1); PG8_BAR; PG8_SCHED;
;             PG8_LDA(At, 0, 1); PG8_STAGE(PG8_SB(0, 0), b2, voffB); PG8_STAGE(PG8_SB(0, 1), b2 + hstep, voffB); PG8_STAGE(PG8_SA(0, 0), a2, voffA);
;             PG8_WAIT_V(8); PG8_WAIT_L(0); PG8_BAR; PG8_MMA(1, 0, At, B0); PG8_MMA(1, 1, At, B1); PG8_BAR; PG8_SCHED;
.LBB0_1329:
	s_add_u32 s49, s22, 0x100
	s_addc_u32 s50, s23, 0
	s_mov_b32 s51, -2
	s_add_u32 s22, s20, 0x100
	s_addc_u32 s23, s21, 0
	s_add_i32 s52, 0, 0x10000
	s_cmp_eq_u32 s51, 40
	s_cselect_b32 s27, s7, s23
	s_cselect_b32 s26, s6, s22
	v_add_u32_e32 v157, s52, v154
	s_cselect_b32 s25, s19, s50
	s_cselect_b32 s24, s18, s49
	s_add_i32 s53, 0, 0x14000
	ds_read_b128 v[142:145], v157
	ds_read_b128 v[146:149], v157 offset:1024
	ds_read_b128 v[150:153], v157 offset:2048
	ds_read_b128 v[158:161], v157 offset:3072
	v_add_u32_e32 v157, s53, v154
	ds_read_b128 v[162:165], v157
	ds_read_b128 v[166:169], v157 offset:1024
	ds_read_b128 v[170:173], v157 offset:2048
	ds_read_b128 v[174:177], v157 offset:3072
	v_lshl_add_u64 v[214:215], s[20:21], 0, v[138:139]
	s_add_i32 m0, s37, 0xc000
	ds_read_b128 v[180:183], v156
	ds_read_b128 v[186:189], v156 offset:1024
	ds_read_b128 v[190:193], v156 offset:2048
	ds_read_b128 v[194:197], v156 offset:3072
	ds_read_b128 v[198:201], v156 offset:4096
	ds_read_b128 v[202:205], v156 offset:5120
	ds_read_b128 v[206:209], v156 offset:6144
	ds_read_b128 v[210:213], v156 offset:7168
	global_load_lds_dwordx4 v[214:215], off
	v_lshl_add_u64 v[214:215], s[20:21], 0, v[140:141]
	s_add_i32 m0, s37, 0xe000
	s_nop 0
	global_load_lds_dwordx4 v[214:215], off
	s_waitcnt vmcnt(8) lgkmcnt(0)
	s_barrier
	v_mfma_f32_16x16x32_bf16 v[126:129], v[142:145], v[180:183], 0
	v_mfma_f32_16x16x32_bf16 v[122:125], v[150:153], v[180:183], 0
	v_mfma_f32_16x16x32_bf16 v[114:117], v[142:145], v[190:193], 0
	v_mfma_f32_16x16x32_bf16 v[106:109], v[150:153], v[190:193], 0
	v_mfma_f32_16x16x32_bf16 v[98:101], v[142:145], v[198:201], 0
	v_mfma_f32_16x16x32_bf16 v[90:93], v[150:153], v[198:201], 0
	v_mfma_f32_16x16x32_bf16 v[82:85], v[142:145], v[206:209], 0
	v_mfma_f32_16x16x32_bf16 v[74:77], v[150:153], v[206:209], 0
	v_mfma_f32_16x16x32_bf16 v[126:129], v[146:149], v[186:189], v[126:129]
	v_mfma_f32_16x16x32_bf16 v[122:125], v[158:161], v[186:189], v[122:125]
	v_mfma_f32_16x16x32_bf16 v[114:117], v[146:149], v[194:197], v[114:117]
	v_mfma_f32_16x16x32_bf16 v[106:109], v[158:161], v[194:197], v[106:109]
	v_mfma_f32_16x16x32_bf16 v[98:101], v[146:149], v[202:205], v[98:101]
	v_mfma_f32_16x16x32_bf16 v[90:93], v[158:161], v[202:205], v[90:93]
	v_mfma_f32_16x16x32_bf16 v[82:85], v[146:149], v[210:213], v[82:85]
	v_mfma_f32_16x16x32_bf16 v[74:77], v[158:161], v[210:213], v[74:77]
	v_mfma_f32_16x16x32_bf16 v[118:121], v[162:165], v[180:183], 0
	v_mfma_f32_16x16x32_bf16 v[110:113], v[170:173], v[180:183], 0
	v_mfma_f32_16x16x32_bf16 v[102:105], v[162:165], v[190:193], 0
	v_mfma_f32_16x16x32_bf16 v[94:97], v[170:173], v[190:193], 0
	v_mfma_f32_16x16x32_bf16 v[86:89], v[162:165], v[198:201], 0
	v_mfma_f32_16x16x32_bf16 v[78:81], v[170:173], v[198:201], 0
	v_mfma_f32_16x16x32_bf16 v[70:73], v[162:165], v[206:209], 0
	v_mfma_f32_16x16x32_bf16 v[66:69], v[170:173], v[206:209], 0
	v_mfma_f32_16x16x32_bf16 v[118:121], v[166:169], v[186:189], v[118:121]
	v_mfma_f32_16x16x32_bf16 v[110:113], v[174:177], v[186:189], v[110:113]
	v_mfma_f32_16x16x32_bf16 v[102:105], v[166:169], v[194:197], v[102:105]
	v_mfma_f32_16x16x32_bf16 v[94:97], v[174:177], v[194:197], v[94:97]
	v_mfma_f32_16x16x32_bf16 v[86:89], v[166:169], v[202:205], v[86:89]
	v_mfma_f32_16x16x32_bf16 v[78:81], v[174:177], v[202:205], v[78:81]
	v_mfma_f32_16x16x32_bf16 v[70:73], v[166:169], v[210:213], v[70:73]
	v_mfma_f32_16x16x32_bf16 v[66:69], v[174:177], v[210:213], v[66:69]
	s_barrier
	s_add_i32 s20, s52, s36
	v_lshl_add_u64 v[214:215], s[24:25], 0, v[132:133]
	s_mov_b32 m0, s20
	ds_read_b128 v[180:183], v156 offset:16384
	ds_read_b128 v[186:189], v156 offset:17408
	ds_read_b128 v[190:193], v156 offset:18432
	ds_read_b128 v[194:197], v156 offset:19456
	ds_read_b128 v[198:201], v156 offset:20480
	ds_read_b128 v[202:205], v156 offset:21504
	ds_read_b128 v[206:209], v156 offset:22528
	ds_read_b128 v[210:213], v156 offset:23552
	global_load_lds_dwordx4 v[214:215], off
	s_add_i32 m0, s20, 0x2000
	s_add_u32 s20, s24, 0xb0000
	v_lshl_add_u64 v[216:217], s[24:25], 0, v[136:137]
	s_addc_u32 s21, s25, 0
	s_add_i32 s52, s53, s36
	global_load_lds_dwordx4 v[216:217], off
	v_lshl_add_u64 v[218:219], s[20:21], 0, v[132:133]
	s_mov_b32 m0, s52
	v_lshl_add_u64 v[220:221], s[26:27], 0, v[134:135]
	global_load_lds_dwordx4 v[218:219], off
	v_lshl_add_u64 v[218:219], s[20:21], 0, v[136:137]
	s_add_i32 m0, s52, 0x2000
	s_nop 0
	global_load_lds_dwordx4 v[218:219], off
	v_lshl_add_u64 v[218:219], s[26:27], 0, v[130:131]
	s_mov_b32 m0, s37
	s_nop 0
	global_load_lds_dwordx4 v[218:219], off
	s_mov_b32 m0, s38
	s_nop 0
	global_load_lds_dwordx4 v[220:221], off
	s_waitcnt vmcnt(8) lgkmcnt(0)
	s_barrier
; #define PG8_STAGE(bufoff, gbase, voff) do { _Pragma("unroll") for (int _i = 0; _i < 2; ++_i) \
;         __builtin_amdgcn_global_load_lds((const unsigned*)((const char*)(gbase) + (voff)[_i]), (PG8_LAS unsigned*)(lds + (bufoff) + ldsw + _i * 8192), 16, 0, 0); } while (0)
; #define PG8_LDA(dst, b, h) do { _Pragma("unroll") for (int m = 0; m < 4; ++m) _Pragma("unroll") for (int k = 0; k < 2; ++k) dst[m][k] = *(const PG8_LAS bf16x8*)(lds + PG8_SA(b, h) + aoff + m * 2048 + k * 1024); } while (0)
; #define PG8_LDB(dst, b, h) do { _Pragma("unroll") for (int n = 0; n < 2; ++n) _Pragma("unroll") for (int k = 0; k < 2; ++k) dst[n][k] = *(const PG8_LAS bf16x8*)(lds + PG8_SB(b, h) + boff + n * 2048 + k * 1024); } while (0)
; #define PG8_MMA(ai, bj, At, Bt) do { __builtin_amdgcn_s_setprio(1); _Pragma("unroll") for (int m = 0; m < 4; ++m) _Pragma("unroll") for (int n = 0; n < 2; ++n) _Pragma("unroll") for (int k = 0; k < 2; ++k) \
;         acc[ai][bj][m][n] = __builtin_amdgcn_mfma_f32_16x16x32_bf16(Bt[n][k], At[m][k], acc[ai][bj][m][n], 0, 0, 0); __builtin_amdgcn_s_setprio(0); } while (0)
; #define PG8_WAIT_V(n) asm volatile("s_waitcnt vmcnt(" #n ")" ::: "memory")
; #define PG8_WAIT_L(n) asm volatile("s_waitcnt lgkmcnt(" #n ")" ::: "memory")
; #define PG8_BAR __builtin_amdgcn_s_barrier()
; #define PG8_SCHED __builtin_amdgcn_sched_barrier(0)
; template <class Epi, class Sched, bool ALIGN_EPI = false, bool SP2 = false>
; __device__ __forceinline__ void gemm_phase(PG8_LAS unsigned char* lds, const Gemm g, const Sched& S, const Epi& E) {
;     ...
;             PG8_LDA(At, 0, 1); PG8_STAGE(PG8_SB(0, 0), b2, voffB); PG8_STAGE(PG8_SB(0, 1), b2 + hstep, voffB); PG8_STAGE(PG8_SA(0, 0), a2, voffA);
;             PG8_WAIT_V(8); PG8_WAIT_L(0); PG8_BAR; PG8_MMA(1, 0, At, B0); PG8_MMA(1, 1, At, B1); PG8_BAR; PG8_SCHED;
;             PG8_LDB(B0, 1, 0); PG8_LDB(B1, 1, 1); PG8_SCHED; PG8_LDA(At, 1, 0); PG8_STAGE(PG8_SA(0, 1), a2 + hstep, voffA);
;             PG8_WAIT_V(8); PG8_WAIT_L(0); PG8_BAR; PG8_MMA(0, 0, At, B0); PG8_MMA(0, 1, At, B1); PG8_BAR; PG8_SCHED;
	v_mfma_f32_16x16x32_bf16 v[62:65], v[142:145], v[180:183], 0
	v_mfma_f32_16x16x32_bf16 v[58:61], v[150:153], v[180:183], 0
	v_mfma_f32_16x16x32_bf16 v[50:53], v[142:145], v[190:193], 0
	v_mfma_f32_16x16x32_bf16 v[42:45], v[150:153], v[190:193], 0
	v_mfma_f32_16x16x32_bf16 v[34:37], v[142:145], v[198:201], 0
	v_mfma_f32_16x16x32_bf16 v[26:29], v[150:153], v[198:201], 0
	v_mfma_f32_16x16x32_bf16 v[18:21], v[142:145], v[206:209], 0
	v_mfma_f32_16x16x32_bf16 v[10:13], v[150:153], v[206:209], 0
	v_mfma_f32_16x16x32_bf16 v[62:65], v[146:149], v[186:189], v[62:65]
	v_mfma_f32_16x16x32_bf16 v[58:61], v[158:161], v[186:189], v[58:61]
	v_mfma_f32_16x16x32_bf16 v[50:53], v[146:149], v[194:197], v[50:53]
	v_mfma_f32_16x16x32_bf16 v[42:45], v[158:161], v[194:197], v[42:45]
	v_mfma_f32_16x16x32_bf16 v[34:37], v[146:149], v[202:205], v[34:37]
	v_mfma_f32_16x16x32_bf16 v[26:29], v[158:161], v[202:205], v[26:29]
	v_mfma_f32_16x16x32_bf16 v[18:21], v[146:149], v[210:213], v[18:21]
	v_mfma_f32_16x16x32_bf16 v[10:13], v[158:161], v[210:213], v[10:13]
	v_mfma_f32_16x16x32_bf16 v[54:57], v[162:165], v[180:183], 0
	v_mfma_f32_16x16x32_bf16 v[46:49], v[170:173], v[180:183], 0
	v_mfma_f32_16x16x32_bf16 v[38:41], v[162:165], v[190:193], 0
	v_mfma_f32_16x16x32_bf16 v[30:33], v[170:173], v[190:193], 0
	v_mfma_f32_16x16x32_bf16 v[22:25], v[162:165], v[198:201], 0
	v_mfma_f32_16x16x32_bf16 v[14:17], v[170:173], v[198:201], 0
	v_mfma_f32_16x16x32_bf16 v[6:9], v[162:165], v[206:209], 0
	v_mfma_f32_16x16x32_bf16 v[2:5], v[170:173], v[206:209], 0
	v_mfma_f32_16x16x32_bf16 v[54:57], v[166:169], v[186:189], v[54:57]
	v_mfma_f32_16x16x32_bf16 v[46:49], v[174:177], v[186:189], v[46:49]
	v_mfma_f32_16x16x32_bf16 v[38:41], v[166:169], v[194:197], v[38:41]
	v_mfma_f32_16x16x32_bf16 v[30:33], v[174:177], v[194:197], v[30:33]
	v_mfma_f32_16x16x32_bf16 v[22:25], v[166:169], v[202:205], v[22:25]
	v_mfma_f32_16x16x32_bf16 v[14:17], v[174:177], v[202:205], v[14:17]
	v_mfma_f32_16x16x32_bf16 v[6:9], v[166:169], v[210:213], v[6:9]
	v_mfma_f32_16x16x32_bf16 v[2:5], v[174:177], v[210:213], v[2:5]
	s_barrier
	s_add_i32 s52, 0, 0x18000
	v_add_u32_e32 v157, s52, v154
	s_add_i32 s53, 0, 0x1c000
	ds_read_b128 v[142:145], v157
	ds_read_b128 v[146:149], v157 offset:1024
	ds_read_b128 v[150:153], v157 offset:2048
	ds_read_b128 v[158:161], v157 offset:3072
	v_add_u32_e32 v157, s53, v154
	ds_read_b128 v[162:165], v157
	ds_read_b128 v[166:169], v157 offset:1024
	ds_read_b128 v[170:173], v157 offset:2048
	ds_read_b128 v[174:177], v157 offset:3072
	s_add_u32 s20, s26, 0xb0000
	s_addc_u32 s21, s27, 0
	s_mov_b32 m0, s39
	v_lshl_add_u64 v[222:223], s[20:21], 0, v[130:131]
	ds_read_b128 v[180:183], v156 offset:32768
	ds_read_b128 v[186:189], v156 offset:33792
	ds_read_b128 v[190:193], v156 offset:34816
	ds_read_b128 v[194:197], v156 offset:35840
	ds_read_b128 v[198:201], v156 offset:36864
	ds_read_b128 v[202:205], v156 offset:37888
	ds_read_b128 v[206:209], v156 offset:38912
	ds_read_b128 v[210:213], v156 offset:39936
	global_load_lds_dwordx4 v[222:223], off
	v_lshl_add_u64 v[222:223], s[20:21], 0, v[134:135]
	s_mov_b32 m0, s40
	s_nop 0
	global_load_lds_dwordx4 v[222:223], off
	s_waitcnt vmcnt(8) lgkmcnt(0)
	s_barrier
	v_mfma_f32_16x16x32_bf16 v[126:129], v[142:145], v[180:183], v[126:129]
	v_mfma_f32_16x16x32_bf16 v[122:125], v[150:153], v[180:183], v[122:125]
	v_mfma_f32_16x16x32_bf16 v[114:117], v[142:145], v[190:193], v[114:117]
	v_mfma_f32_16x16x32_bf16 v[106:109], v[150:153], v[190:193], v[106:109]
	v_mfma_f32_16x16x32_bf16 v[98:101], v[142:145], v[198:201], v[98:101]
	v_mfma_f32_16x16x32_bf16 v[90:93], v[150:153], v[198:201], v[90:93]
	v_mfma_f32_16x16x32_bf16 v[82:85], v[142:145], v[206:209], v[82:85]
	v_mfma_f32_16x16x32_bf16 v[74:77], v[150:153], v[206:209], v[74:77]
	v_mfma_f32_16x16x32_bf16 v[126:129], v[146:149], v[186:189], v[126:129]
	v_mfma_f32_16x16x32_bf16 v[122:125], v[158:161], v[186:189], v[122:125]
	v_mfma_f32_16x16x32_bf16 v[114:117], v[146:149], v[194:197], v[114:117]
	v_mfma_f32_16x16x32_bf16 v[106:109], v[158:161], v[194:197], v[106:109]
	v_mfma_f32_16x16x32_bf16 v[98:101], v[146:149], v[202:205], v[98:101]
	v_mfma_f32_16x16x32_bf16 v[90:93], v[158:161], v[202:205], v[90:93]
	v_mfma_f32_16x16x32_bf16 v[82:85], v[146:149], v[210:213], v[82:85]
	v_mfma_f32_16x16x32_bf16 v[74:77], v[158:161], v[210:213], v[74:77]
	v_mfma_f32_16x16x32_bf16 v[118:121], v[162:165], v[180:183], v[118:121]
	v_mfma_f32_16x16x32_bf16 v[110:113], v[170:173], v[180:183], v[110:113]
	v_mfma_f32_16x16x32_bf16 v[102:105], v[162:165], v[190:193], v[102:105]
	v_mfma_f32_16x16x32_bf16 v[94:97], v[170:173], v[190:193], v[94:97]
	v_mfma_f32_16x16x32_bf16 v[86:89], v[162:165], v[198:201], v[86:89]
	v_mfma_f32_16x16x32_bf16 v[78:81], v[170:173], v[198:201], v[78:81]
	v_mfma_f32_16x16x32_bf16 v[70:73], v[162:165], v[206:209], v[70:73]
	v_mfma_f32_16x16x32_bf16 v[66:69], v[170:173], v[206:209], v[66:69]
	v_mfma_f32_16x16x32_bf16 v[118:121], v[166:169], v[186:189], v[118:121]
	v_mfma_f32_16x16x32_bf16 v[110:113], v[174:177], v[186:189], v[110:113]
	v_mfma_f32_16x16x32_bf16 v[102:105], v[166:169], v[194:197], v[102:105]
	v_mfma_f32_16x16x32_bf16 v[94:97], v[174:177], v[194:197], v[94:97]
	v_mfma_f32_16x16x32_bf16 v[86:89], v[166:169], v[202:205], v[86:89]
	v_mfma_f32_16x16x32_bf16 v[78:81], v[174:177], v[202:205], v[78:81]
	v_mfma_f32_16x16x32_bf16 v[70:73], v[166:169], v[210:213], v[70:73]
	v_mfma_f32_16x16x32_bf16 v[66:69], v[174:177], v[210:213], v[66:69]
	s_barrier
; #define PG8_STAGE(bufoff, gbase, voff) do { _Pragma("unroll") for (int _i = 0; _i < 2; ++_i) \
;         __builtin_amdgcn_global_load_lds((const unsigned*)((const char*)(gbase) + (voff)[_i]), (PG8_LAS unsigned*)(lds + (bufoff) + ldsw + _i * 8192), 16, 0, 0); } while (0)
; #define PG8_LDA(dst, b, h) do { _Pragma("unroll") for (int m = 0; m < 4; ++m) _Pragma("unroll") for (int k = 0; k < 2; ++k) dst[m][k] = *(const PG8_LAS bf16x8*)(lds + PG8_SA(b, h) + aoff + m * 2048 + k * 1024); } while (0)
; #define PG8_LDB(dst, b, h) do { _Pragma("unroll") for (int n = 0; n < 2; ++n) _Pragma("unroll") for (int k = 0; k < 2; ++k) dst[n][k] = *(const PG8_LAS bf16x8*)(lds + PG8_SB(b, h) + boff + n * 2048 + k * 1024); } while (0)
; template <class Epi, class Sched, bool ALIGN_EPI = false, bool SP2 = false>
; __device__ __forceinline__ void gemm_phase(PG8_LAS unsigned char* lds, const Gemm g, const Sched& S, const Epi& E) {
;     ...
;         for (int t = 0; t < nt; t += 2) {
;             const bool last = (t == nt - 2);
;             const char* a1 = cA + (size_t)(t + 1) * kstep;
;             const char* a2 = last ? nA : cA + (size_t)(t + 2) * kstep; const char* b2 = last ? nB : cB + (size_t)(t + 2) * kstep;
;             const char* a3 = a2 + kstep; const char* b3 = b2 + kstep;
;             if (last && has_next) S.a_ready(nxt);
;             if constexpr (SP2) {
;             PG8_LDB(B0, 0, 0); PG8_LDB(B1, 0, 1); PG8_SCHED; PG8_LDA(At, 0, 0); PG8_STAGE(PG8_SA(1, 1), a1 + hstep, voffA);
;             PG8_WAIT_V(8); PG8_WAIT_L(0); PG8_BAR; PG8_MMA(0, 0, At, B0); PG8_MMA(0, 1, At, B1); PG8_BAR; PG8_SCHED;
;             PG8_LDA(At, 0, 1); PG8_STAGE(PG8_SB(0, 0), b2, voffB); PG8_STAGE(PG8_SB(0, 1), b2 + hstep, voffB); PG8_STAGE(PG8_SA(0, 0), a2, voffA);
;             PG8_WAIT_V(8); PG8_WAIT_L(0); PG8_BAR; PG8_MMA(1, 0, At, B0); PG8_MMA(1, 1, At, B1); PG8_BAR; PG8_SCHED;
;             PG8_LDB(B0, 1, 0); PG8_LDB(B1, 1, 1); PG8_SCHED; PG8_LDA(At, 1, 0); PG8_STAGE(PG8_SA(0, 1), a2 + hstep, voffA);
;             PG8_WAIT_V(8); PG8_WAIT_L(0); PG8_BAR; PG8_MMA(0, 0, At, B0); PG8_MMA(0, 1, At, B1); PG8_BAR; PG8_SCHED;
;             PG8_LDA(At, 1, 1); PG8_STAGE(PG8_SB(1, 0), b3, voffB); PG8_STAGE(PG8_SB(1, 1), b3 + hstep, voffB); PG8_STAGE(PG8_SA(1, 0), a3, voffA);
;             PG8_WAIT_V(8); PG8_WAIT_L(0); PG8_BAR; PG8_MMA(1, 0, At, B0); PG8_MMA(1, 1, At, B1); PG8_BAR; PG8_SCHED;
	s_add_i32 s20, s52, s36
	v_lshl_add_u64 v[214:215], v[214:215], 0, s[80:81]
	s_mov_b32 m0, s20
	ds_read_b128 v[180:183], v156 offset:49152
	ds_read_b128 v[186:189], v156 offset:50176
	ds_read_b128 v[190:193], v156 offset:51200
	ds_read_b128 v[194:197], v156 offset:52224
	ds_read_b128 v[198:201], v156 offset:53248
	ds_read_b128 v[202:205], v156 offset:54272
	ds_read_b128 v[206:209], v156 offset:55296
	ds_read_b128 v[210:213], v156 offset:56320
	global_load_lds_dwordx4 v[214:215], off
	s_add_i32 m0, s20, 0x2000
	s_add_u32 s20, s24, 0xb0080
	v_lshl_add_u64 v[214:215], v[216:217], 0, s[80:81]
	s_addc_u32 s21, s25, 0
	s_add_i32 s24, s53, s36
	global_load_lds_dwordx4 v[214:215], off
	v_lshl_add_u64 v[214:215], s[20:21], 0, v[132:133]
	s_mov_b32 m0, s24
	s_nop 0
	global_load_lds_dwordx4 v[214:215], off
	v_lshl_add_u64 v[214:215], s[20:21], 0, v[136:137]
	s_add_i32 m0, s24, 0x2000
	s_nop 0
	global_load_lds_dwordx4 v[214:215], off
	v_lshl_add_u64 v[214:215], v[218:219], 0, s[80:81]
	s_mov_b32 m0, s41
	s_nop 0
	global_load_lds_dwordx4 v[214:215], off
	v_lshl_add_u64 v[214:215], v[220:221], 0, s[80:81]
	s_mov_b32 m0, s42
	s_nop 0
	global_load_lds_dwordx4 v[214:215], off
	s_waitcnt vmcnt(8) lgkmcnt(0)
	s_barrier
	v_mfma_f32_16x16x32_bf16 v[62:65], v[142:145], v[180:183], v[62:65]
	v_mfma_f32_16x16x32_bf16 v[58:61], v[150:153], v[180:183], v[58:61]
	v_mfma_f32_16x16x32_bf16 v[50:53], v[142:145], v[190:193], v[50:53]
	v_mfma_f32_16x16x32_bf16 v[42:45], v[150:153], v[190:193], v[42:45]
	v_mfma_f32_16x16x32_bf16 v[34:37], v[142:145], v[198:201], v[34:37]
	v_mfma_f32_16x16x32_bf16 v[26:29], v[150:153], v[198:201], v[26:29]
	v_mfma_f32_16x16x32_bf16 v[18:21], v[142:145], v[206:209], v[18:21]
	v_mfma_f32_16x16x32_bf16 v[10:13], v[150:153], v[206:209], v[10:13]
	v_mfma_f32_16x16x32_bf16 v[62:65], v[146:149], v[186:189], v[62:65]
	v_mfma_f32_16x16x32_bf16 v[58:61], v[158:161], v[186:189], v[58:61]
	v_mfma_f32_16x16x32_bf16 v[50:53], v[146:149], v[194:197], v[50:53]
	v_mfma_f32_16x16x32_bf16 v[42:45], v[158:161], v[194:197], v[42:45]
	v_mfma_f32_16x16x32_bf16 v[34:37], v[146:149], v[202:205], v[34:37]
	v_mfma_f32_16x16x32_bf16 v[26:29], v[158:161], v[202:205], v[26:29]
	v_mfma_f32_16x16x32_bf16 v[18:21], v[146:149], v[210:213], v[18:21]
	v_mfma_f32_16x16x32_bf16 v[10:13], v[158:161], v[210:213], v[10:13]
	v_mfma_f32_16x16x32_bf16 v[54:57], v[162:165], v[180:183], v[54:57]
	v_mfma_f32_16x16x32_bf16 v[46:49], v[170:173], v[180:183], v[46:49]
	v_mfma_f32_16x16x32_bf16 v[38:41], v[162:165], v[190:193], v[38:41]
	v_mfma_f32_16x16x32_bf16 v[30:33], v[170:173], v[190:193], v[30:33]
	v_mfma_f32_16x16x32_bf16 v[22:25], v[162:165], v[198:201], v[22:25]
	v_mfma_f32_16x16x32_bf16 v[14:17], v[170:173], v[198:201], v[14:17]
	v_mfma_f32_16x16x32_bf16 v[6:9], v[162:165], v[206:209], v[6:9]
	v_mfma_f32_16x16x32_bf16 v[2:5], v[170:173], v[206:209], v[2:5]
	v_mfma_f32_16x16x32_bf16 v[54:57], v[166:169], v[186:189], v[54:57]
	v_mfma_f32_16x16x32_bf16 v[46:49], v[174:177], v[186:189], v[46:49]
	v_mfma_f32_16x16x32_bf16 v[38:41], v[166:169], v[194:197], v[38:41]
	v_mfma_f32_16x16x32_bf16 v[30:33], v[174:177], v[194:197], v[30:33]
	v_mfma_f32_16x16x32_bf16 v[22:25], v[166:169], v[202:205], v[22:25]
	v_mfma_f32_16x16x32_bf16 v[14:17], v[174:177], v[202:205], v[14:17]
	v_mfma_f32_16x16x32_bf16 v[6:9], v[166:169], v[210:213], v[6:9]
	v_mfma_f32_16x16x32_bf16 v[2:5], v[174:177], v[210:213], v[2:5]
	s_barrier
	s_add_i32 s51, s51, 2
	s_add_u32 s49, s49, 0x100
	s_addc_u32 s50, s50, 0
	s_cmp_gt_u32 s51, 41
	s_mov_b64 s[20:21], s[22:23]
	s_branch .LBB0_1330
.LBB0_1330:
	s_add_u32 s22, s20, 0x100
	s_addc_u32 s23, s21, 0
	s_add_i32 s52, 0, 0x10000
	s_cmp_eq_u32 s51, 40
	s_cselect_b32 s27, s7, s23
	s_cselect_b32 s26, s6, s22
	v_add_u32_e32 v157, s52, v154
	s_cselect_b32 s25, s19, s50
	s_cselect_b32 s24, s18, s49
	s_add_i32 s53, 0, 0x14000
	ds_read_b128 v[142:145], v157
	ds_read_b128 v[146:149], v157 offset:1024
	ds_read_b128 v[150:153], v157 offset:2048
	ds_read_b128 v[158:161], v157 offset:3072
	v_add_u32_e32 v157, s53, v154
	ds_read_b128 v[162:165], v157
	ds_read_b128 v[166:169], v157 offset:1024
	ds_read_b128 v[170:173], v157 offset:2048
	ds_read_b128 v[174:177], v157 offset:3072
	v_lshl_add_u64 v[214:215], s[20:21], 0, v[138:139]
	s_add_i32 m0, s37, 0xc000
	ds_read_b128 v[180:183], v156
	ds_read_b128 v[186:189], v156 offset:1024
	ds_read_b128 v[190:193], v156 offset:2048
	ds_read_b128 v[194:197], v156 offset:3072
	ds_read_b128 v[198:201], v156 offset:4096
	ds_read_b128 v[202:205], v156 offset:5120
	ds_read_b128 v[206:209], v156 offset:6144
	ds_read_b128 v[210:213], v156 offset:7168
	global_load_lds_dwordx4 v[214:215], off
	v_lshl_add_u64 v[214:215], s[20:21], 0, v[140:141]
	s_add_i32 m0, s37, 0xe000
	s_nop 0
	global_load_lds_dwordx4 v[214:215], off
	s_waitcnt vmcnt(8) lgkmcnt(0)
	s_barrier
; #define PG8_STAGE(bufoff, gbase, voff) do { _Pragma("unroll") for (int _i = 0; _i < 2; ++_i) \
;         __builtin_amdgcn_global_load_lds((const unsigned*)((const char*)(gbase) + (voff)[_i]), (PG8_LAS unsigned*)(lds + (bufoff) + ldsw + _i * 8192), 16, 0, 0); } while (0)
; #define PG8_LDA(dst, b, h) do { _Pragma("unroll") for (int m = 0; m < 4; ++m) _Pragma("unroll") for (int k = 0; k < 2; ++k) dst[m][k] = *(const PG8_LAS bf16x8*)(lds + PG8_SA(b, h) + aoff + m * 2048 + k * 1024); } while (0)
; #define PG8_LDB(dst, b, h) do { _Pragma("unroll") for (int n = 0; n < 2; ++n) _Pragma("unroll") for (int k = 0; k < 2; ++k) dst[n][k] = *(const PG8_LAS bf16x8*)(lds + PG8_SB(b, h) + boff + n * 2048 + k * 1024); } while (0)
; #define PG8_MMA(ai, bj, At, Bt) do { __builtin_amdgcn_s_setprio(1); _Pragma("unroll") for (int m = 0; m < 4; ++m) _Pragma("unroll") for (int n = 0; n < 2; ++n) _Pragma("unroll") for (int k = 0; k < 2; ++k) \
;         acc[ai][bj][m][n] = __builtin_amdgcn_mfma_f32_16x16x32_bf16(Bt[n][k], At[m][k], acc[ai][bj][m][n], 0, 0, 0); __builtin_amdgcn_s_setprio(0); } while (0)
; #define PG8_WAIT_V(n) asm volatile("s_waitcnt vmcnt(" #n ")" ::: "memory")
; template <class Epi, class Sched, bool ALIGN_EPI = false, bool SP2 = false>
; __device__ __forceinline__ void gemm_phase(PG8_LAS unsigned char* lds, const Gemm g, const Sched& S, const Epi& E) {
;     ...
;             PG8_LDB(B0, 0, 0); PG8_LDB(B1, 0, 1); PG8_SCHED; PG8_LDA(At, 0, 0); PG8_STAGE(PG8_SA(1, 1), a1 + hstep, voffA);
;             PG8_WAIT_V(8); PG8_WAIT_L(0); PG8_BAR; PG8_MMA(0, 0, At, B0); PG8_MMA(0, 1, At, B1); PG8_BAR; PG8_SCHED;
;             PG8_LDA(At, 0, 1); PG8_STAGE(PG8_SB(0, 0), b2, voffB); PG8_STAGE(PG8_SB(0, 1), b2 + hstep, voffB); PG8_STAGE(PG8_SA(0, 0), a2, voffA);
;             PG8_WAIT_V(8); PG8_WAIT_L(0); PG8_BAR; PG8_MMA(1, 0, At, B0); PG8_MMA(1, 1, At, B1); PG8_BAR; PG8_SCHED;
;             PG8_LDB(B0, 1, 0); PG8_LDB(B1, 1, 1); PG8_SCHED; PG8_LDA(At, 1, 0); PG8_STAGE(PG8_SA(0, 1), a2 + hstep, voffA);
;             PG8_WAIT_V(8); PG8_WAIT_L(0); PG8_BAR; PG8_MMA(0, 0, At, B0); PG8_MMA(0, 1, At, B1); PG8_BAR; PG8_SCHED;
;             PG8_LDA(At, 1, 1); PG8_STAGE(PG8_SB(1, 0), b3, voffB); PG8_STAGE(PG8_SB(1, 1), b3 + hstep, voffB); PG8_STAGE(PG8_SA(1, 0), a3, voffA);
;             PG8_WAIT_V(8); PG8_WAIT_L(0); PG8_BAR; PG8_MMA(1, 0, At, B0); PG8_MMA(1, 1, At, B1); PG8_BAR; PG8_SCHED;
	v_mfma_f32_16x16x32_bf16 v[126:129], v[142:145], v[180:183], v[126:129]
	v_mfma_f32_16x16x32_bf16 v[122:125], v[150:153], v[180:183], v[122:125]
	v_mfma_f32_16x16x32_bf16 v[114:117], v[142:145], v[190:193], v[114:117]
	v_mfma_f32_16x16x32_bf16 v[106:109], v[150:153], v[190:193], v[106:109]
	v_mfma_f32_16x16x32_bf16 v[98:101], v[142:145], v[198:201], v[98:101]
	v_mfma_f32_16x16x32_bf16 v[90:93], v[150:153], v[198:201], v[90:93]
	v_mfma_f32_16x16x32_bf16 v[82:85], v[142:145], v[206:209], v[82:85]
	v_mfma_f32_16x16x32_bf16 v[74:77], v[150:153], v[206:209], v[74:77]
	v_mfma_f32_16x16x32_bf16 v[126:129], v[146:149], v[186:189], v[126:129]
	v_mfma_f32_16x16x32_bf16 v[122:125], v[158:161], v[186:189], v[122:125]
	v_mfma_f32_16x16x32_bf16 v[114:117], v[146:149], v[194:197], v[114:117]
	v_mfma_f32_16x16x32_bf16 v[106:109], v[158:161], v[194:197], v[106:109]
	v_mfma_f32_16x16x32_bf16 v[98:101], v[146:149], v[202:205], v[98:101]
	v_mfma_f32_16x16x32_bf16 v[90:93], v[158:161], v[202:205], v[90:93]
	v_mfma_f32_16x16x32_bf16 v[82:85], v[146:149], v[210:213], v[82:85]
	v_mfma_f32_16x16x32_bf16 v[74:77], v[158:161], v[210:213], v[74:77]
	v_mfma_f32_16x16x32_bf16 v[118:121], v[162:165], v[180:183], v[118:121]
	v_mfma_f32_16x16x32_bf16 v[110:113], v[170:173], v[180:183], v[110:113]
	v_mfma_f32_16x16x32_bf16 v[102:105], v[162:165], v[190:193], v[102:105]
	v_mfma_f32_16x16x32_bf16 v[94:97], v[170:173], v[190:193], v[94:97]
	v_mfma_f32_16x16x32_bf16 v[86:89], v[162:165], v[198:201], v[86:89]
	v_mfma_f32_16x16x32_bf16 v[78:81], v[170:173], v[198:201], v[78:81]
	v_mfma_f32_16x16x32_bf16 v[70:73], v[162:165], v[206:209], v[70:73]
	v_mfma_f32_16x16x32_bf16 v[66:69], v[170:173], v[206:209], v[66:69]
	v_mfma_f32_16x16x32_bf16 v[118:121], v[166:169], v[186:189], v[118:121]
	v_mfma_f32_16x16x32_bf16 v[110:113], v[174:177], v[186:189], v[110:113]
	v_mfma_f32_16x16x32_bf16 v[102:105], v[166:169], v[194:197], v[102:105]
	v_mfma_f32_16x16x32_bf16 v[94:97], v[174:177], v[194:197], v[94:97]
	v_mfma_f32_16x16x32_bf16 v[86:89], v[166:169], v[202:205], v[86:89]
	v_mfma_f32_16x16x32_bf16 v[78:81], v[174:177], v[202:205], v[78:81]
	v_mfma_f32_16x16x32_bf16 v[70:73], v[166:169], v[210:213], v[70:73]
	v_mfma_f32_16x16x32_bf16 v[66:69], v[174:177], v[210:213], v[66:69]
	s_barrier
	s_add_i32 s20, s52, s36
	v_lshl_add_u64 v[214:215], s[24:25], 0, v[132:133]
	s_mov_b32 m0, s20
	ds_read_b128 v[180:183], v156 offset:16384
	ds_read_b128 v[186:189], v156 offset:17408
	ds_read_b128 v[190:193], v156 offset:18432
	ds_read_b128 v[194:197], v156 offset:19456
	ds_read_b128 v[198:201], v156 offset:20480
	ds_read_b128 v[202:205], v156 offset:21504
	ds_read_b128 v[206:209], v156 offset:22528
	ds_read_b128 v[210:213], v156 offset:23552
	global_load_lds_dwordx4 v[214:215], off
	s_add_i32 m0, s20, 0x2000
	s_add_u32 s20, s24, 0xb0000
	v_lshl_add_u64 v[216:217], s[24:25], 0, v[136:137]
	s_addc_u32 s21, s25, 0
	s_add_i32 s52, s53, s36
	global_load_lds_dwordx4 v[216:217], off
	v_lshl_add_u64 v[218:219], s[20:21], 0, v[132:133]
	s_mov_b32 m0, s52
	v_lshl_add_u64 v[220:221], s[26:27], 0, v[134:135]
	global_load_lds_dwordx4 v[218:219], off
	v_lshl_add_u64 v[218:219], s[20:21], 0, v[136:137]
	s_add_i32 m0, s52, 0x2000
	s_nop 0
	global_load_lds_dwordx4 v[218:219], off
	v_lshl_add_u64 v[218:219], s[26:27], 0, v[130:131]
	s_mov_b32 m0, s37
	s_nop 0
	global_load_lds_dwordx4 v[218:219], off
	s_mov_b32 m0, s38
	s_nop 0
	global_load_lds_dwordx4 v[220:221], off
	s_waitcnt vmcnt(8) lgkmcnt(0)
	s_barrier
	v_mfma_f32_16x16x32_bf16 v[62:65], v[142:145], v[180:183], v[62:65]
	v_mfma_f32_16x16x32_bf16 v[58:61], v[150:153], v[180:183], v[58:61]
	v_mfma_f32_16x16x32_bf16 v[50:53], v[142:145], v[190:193], v[50:53]
	v_mfma_f32_16x16x32_bf16 v[42:45], v[150:153], v[190:193], v[42:45]
	v_mfma_f32_16x16x32_bf16 v[34:37], v[142:145], v[198:201], v[34:37]
	v_mfma_f32_16x16x32_bf16 v[26:29], v[150:153], v[198:201], v[26:29]
	v_mfma_f32_16x16x32_bf16 v[18:21], v[142:145], v[206:209], v[18:21]
	v_mfma_f32_16x16x32_bf16 v[10:13], v[150:153], v[206:209], v[10:13]
	v_mfma_f32_16x16x32_bf16 v[62:65], v[146:149], v[186:189], v[62:65]
	v_mfma_f32_16x16x32_bf16 v[58:61], v[158:161], v[186:189], v[58:61]
	v_mfma_f32_16x16x32_bf16 v[50:53], v[146:149], v[194:197], v[50:53]
	v_mfma_f32_16x16x32_bf16 v[42:45], v[158:161], v[194:197], v[42:45]
	v_mfma_f32_16x16x32_bf16 v[34:37], v[146:149], v[202:205], v[34:37]
	v_mfma_f32_16x16x32_bf16 v[26:29], v[158:161], v[202:205], v[26:29]
	v_mfma_f32_16x16x32_bf16 v[18:21], v[146:149], v[210:213], v[18:21]
	v_mfma_f32_16x16x32_bf16 v[10:13], v[158:161], v[210:213], v[10:13]
	v_mfma_f32_16x16x32_bf16 v[54:57], v[162:165], v[180:183], v[54:57]
	v_mfma_f32_16x16x32_bf16 v[46:49], v[170:173], v[180:183], v[46:49]
	v_mfma_f32_16x16x32_bf16 v[38:41], v[162:165], v[190:193], v[38:41]
	v_mfma_f32_16x16x32_bf16 v[30:33], v[170:173], v[190:193], v[30:33]
	v_mfma_f32_16x16x32_bf16 v[22:25], v[162:165], v[198:201], v[22:25]
	v_mfma_f32_16x16x32_bf16 v[14:17], v[170:173], v[198:201], v[14:17]
	v_mfma_f32_16x16x32_bf16 v[6:9], v[162:165], v[206:209], v[6:9]
	v_mfma_f32_16x16x32_bf16 v[2:5], v[170:173], v[206:209], v[2:5]
	v_mfma_f32_16x16x32_bf16 v[54:57], v[166:169], v[186:189], v[54:57]
	v_mfma_f32_16x16x32_bf16 v[46:49], v[174:177], v[186:189], v[46:49]
	v_mfma_f32_16x16x32_bf16 v[38:41], v[166:169], v[194:197], v[38:41]
	v_mfma_f32_16x16x32_bf16 v[30:33], v[174:177], v[194:197], v[30:33]
	v_mfma_f32_16x16x32_bf16 v[22:25], v[166:169], v[202:205], v[22:25]
	v_mfma_f32_16x16x32_bf16 v[14:17], v[174:177], v[202:205], v[14:17]
	v_mfma_f32_16x16x32_bf16 v[6:9], v[166:169], v[210:213], v[6:9]
	v_mfma_f32_16x16x32_bf16 v[2:5], v[174:177], v[210:213], v[2:5]
	s_barrier
; #define PG8_STAGE(bufoff, gbase, voff) do { _Pragma("unroll") for (int _i = 0; _i < 2; ++_i) \
;         __builtin_amdgcn_global_load_lds((const unsigned*)((const char*)(gbase) + (voff)[_i]), (PG8_LAS unsigned*)(lds + (bufoff) + ldsw + _i * 8192), 16, 0, 0); } while (0)
; #define PG8_LDA(dst, b, h) do { _Pragma("unroll") for (int m = 0; m < 4; ++m) _Pragma("unroll") for (int k = 0; k < 2; ++k) dst[m][k] = *(const PG8_LAS bf16x8*)(lds + PG8_SA(b, h) + aoff + m * 2048 + k * 1024); } while (0)
; #define PG8_LDB(dst, b, h) do { _Pragma("unroll") for (int n = 0; n < 2; ++n) _Pragma("unroll") for (int k = 0; k < 2; ++k) dst[n][k] = *(const PG8_LAS bf16x8*)(lds + PG8_SB(b, h) + boff + n * 2048 + k * 1024); } while (0)
; #define PG8_MMA(ai, bj, At, Bt) do { __builtin_amdgcn_s_setprio(1); _Pragma("unroll") for (int m = 0; m < 4; ++m) _Pragma("unroll") for (int n = 0; n < 2; ++n) _Pragma("unroll") for (int k = 0; k < 2; ++k) \
;         acc[ai][bj][m][n] = __builtin_amdgcn_mfma_f32_16x16x32_bf16(Bt[n][k], At[m][k], acc[ai][bj][m][n], 0, 0, 0); __builtin_amdgcn_s_setprio(0); } while (0)
; #define PG8_WAIT_V(n) asm volatile("s_waitcnt vmcnt(" #n ")" ::: "memory")
; #define PG8_WAIT_L(n) asm volatile("s_waitcnt lgkmcnt(" #n ")" ::: "memory")
; #define PG8_BAR __builtin_amdgcn_s_barrier()
; #define PG8_SCHED __builtin_amdgcn_sched_barrier(0)
; template <class Epi, class Sched, bool ALIGN_EPI = false, bool SP2 = false>
; __device__ __forceinline__ void gemm_phase(PG8_LAS unsigned char* lds, const Gemm g, const Sched& S, const Epi& E) {
;     ...
;             PG8_LDB(B0, 1, 0); PG8_LDB(B1, 1, 1); PG8_SCHED; PG8_LDA(At, 1, 0); PG8_STAGE(PG8_SA(0, 1), a2 + hstep, voffA);
;             PG8_WAIT_V(8); PG8_WAIT_L(0); PG8_BAR; PG8_MMA(0, 0, At, B0); PG8_MMA(0, 1, At, B1); PG8_BAR; PG8_SCHED;
;             PG8_LDA(At, 1, 1); PG8_STAGE(PG8_SB(1, 0), b3, voffB); PG8_STAGE(PG8_SB(1, 1), b3 + hstep, voffB); PG8_STAGE(PG8_SA(1, 0), a3, voffA);
;             PG8_WAIT_V(8); PG8_WAIT_L(0); PG8_BAR; PG8_MMA(1, 0, At, B0); PG8_MMA(1, 1, At, B1); PG8_BAR; PG8_SCHED;
;     ...
;         if constexpr (ALIGN_EPI) { if (wr == 0) PG8_BAR; }
	s_add_i32 s52, 0, 0x18000
	v_add_u32_e32 v157, s52, v154
	s_add_i32 s53, 0, 0x1c000
	ds_read_b128 v[142:145], v157
	ds_read_b128 v[146:149], v157 offset:1024
	ds_read_b128 v[150:153], v157 offset:2048
	ds_read_b128 v[158:161], v157 offset:3072
	v_add_u32_e32 v157, s53, v154
	ds_read_b128 v[162:165], v157
	ds_read_b128 v[166:169], v157 offset:1024
	ds_read_b128 v[170:173], v157 offset:2048
	ds_read_b128 v[174:177], v157 offset:3072
	s_add_u32 s20, s26, 0xb0000
	s_addc_u32 s21, s27, 0
	s_mov_b32 m0, s39
	v_lshl_add_u64 v[222:223], s[20:21], 0, v[130:131]
	ds_read_b128 v[180:183], v156 offset:32768
	ds_read_b128 v[186:189], v156 offset:33792
	ds_read_b128 v[190:193], v156 offset:34816
	ds_read_b128 v[194:197], v156 offset:35840
	ds_read_b128 v[198:201], v156 offset:36864
	ds_read_b128 v[202:205], v156 offset:37888
	ds_read_b128 v[206:209], v156 offset:38912
	ds_read_b128 v[210:213], v156 offset:39936
	global_load_lds_dwordx4 v[222:223], off
	v_lshl_add_u64 v[222:223], s[20:21], 0, v[134:135]
	s_mov_b32 m0, s40
	s_nop 0
	global_load_lds_dwordx4 v[222:223], off
	s_waitcnt vmcnt(8) lgkmcnt(0)
	s_barrier
	v_mfma_f32_16x16x32_bf16 v[126:129], v[142:145], v[180:183], v[126:129]
	v_mfma_f32_16x16x32_bf16 v[122:125], v[150:153], v[180:183], v[122:125]
	v_mfma_f32_16x16x32_bf16 v[114:117], v[142:145], v[190:193], v[114:117]
	v_mfma_f32_16x16x32_bf16 v[106:109], v[150:153], v[190:193], v[106:109]
	v_mfma_f32_16x16x32_bf16 v[98:101], v[142:145], v[198:201], v[98:101]
	v_mfma_f32_16x16x32_bf16 v[90:93], v[150:153], v[198:201], v[90:93]
	v_mfma_f32_16x16x32_bf16 v[82:85], v[142:145], v[206:209], v[82:85]
	v_mfma_f32_16x16x32_bf16 v[74:77], v[150:153], v[206:209], v[74:77]
	v_mfma_f32_16x16x32_bf16 v[126:129], v[146:149], v[186:189], v[126:129]
	v_mfma_f32_16x16x32_bf16 v[122:125], v[158:161], v[186:189], v[122:125]
	v_mfma_f32_16x16x32_bf16 v[114:117], v[146:149], v[194:197], v[114:117]
	v_mfma_f32_16x16x32_bf16 v[106:109], v[158:161], v[194:197], v[106:109]
	v_mfma_f32_16x16x32_bf16 v[98:101], v[146:149], v[202:205], v[98:101]
	v_mfma_f32_16x16x32_bf16 v[90:93], v[158:161], v[202:205], v[90:93]
	v_mfma_f32_16x16x32_bf16 v[82:85], v[146:149], v[210:213], v[82:85]
	v_mfma_f32_16x16x32_bf16 v[74:77], v[158:161], v[210:213], v[74:77]
	v_mfma_f32_16x16x32_bf16 v[118:121], v[162:165], v[180:183], v[118:121]
	v_mfma_f32_16x16x32_bf16 v[110:113], v[170:173], v[180:183], v[110:113]
	v_mfma_f32_16x16x32_bf16 v[102:105], v[162:165], v[190:193], v[102:105]
	v_mfma_f32_16x16x32_bf16 v[94:97], v[170:173], v[190:193], v[94:97]
	v_mfma_f32_16x16x32_bf16 v[86:89], v[162:165], v[198:201], v[86:89]
	v_mfma_f32_16x16x32_bf16 v[78:81], v[170:173], v[198:201], v[78:81]
	v_mfma_f32_16x16x32_bf16 v[70:73], v[162:165], v[206:209], v[70:73]
	v_mfma_f32_16x16x32_bf16 v[66:69], v[170:173], v[206:209], v[66:69]
	v_mfma_f32_16x16x32_bf16 v[118:121], v[166:169], v[186:189], v[118:121]
	v_mfma_f32_16x16x32_bf16 v[110:113], v[174:177], v[186:189], v[110:113]
	v_mfma_f32_16x16x32_bf16 v[102:105], v[166:169], v[194:197], v[102:105]
	v_mfma_f32_16x16x32_bf16 v[94:97], v[174:177], v[194:197], v[94:97]
	v_mfma_f32_16x16x32_bf16 v[86:89], v[166:169], v[202:205], v[86:89]
	v_mfma_f32_16x16x32_bf16 v[78:81], v[174:177], v[202:205], v[78:81]
	v_mfma_f32_16x16x32_bf16 v[70:73], v[166:169], v[210:213], v[70:73]
	v_mfma_f32_16x16x32_bf16 v[66:69], v[174:177], v[210:213], v[66:69]
	s_barrier
	s_add_i32 s20, s52, s36
	v_lshl_add_u64 v[214:215], v[214:215], 0, s[80:81]
	s_mov_b32 m0, s20
	ds_read_b128 v[180:183], v156 offset:49152
	ds_read_b128 v[186:189], v156 offset:50176
	ds_read_b128 v[190:193], v156 offset:51200
	ds_read_b128 v[194:197], v156 offset:52224
	ds_read_b128 v[198:201], v156 offset:53248
	ds_read_b128 v[202:205], v156 offset:54272
	ds_read_b128 v[206:209], v156 offset:55296
	ds_read_b128 v[210:213], v156 offset:56320
	global_load_lds_dwordx4 v[214:215], off
	s_add_i32 m0, s20, 0x2000
	s_add_u32 s20, s24, 0xb0080
	v_lshl_add_u64 v[214:215], v[216:217], 0, s[80:81]
	s_addc_u32 s21, s25, 0
	s_add_i32 s24, s53, s36
	global_load_lds_dwordx4 v[214:215], off
	v_lshl_add_u64 v[214:215], s[20:21], 0, v[132:133]
	s_mov_b32 m0, s24
	s_nop 0
	global_load_lds_dwordx4 v[214:215], off
	v_lshl_add_u64 v[214:215], s[20:21], 0, v[136:137]
	s_add_i32 m0, s24, 0x2000
	s_nop 0
	global_load_lds_dwordx4 v[214:215], off
	v_lshl_add_u64 v[214:215], v[218:219], 0, s[80:81]
	s_mov_b32 m0, s41
	s_nop 0
	global_load_lds_dwordx4 v[214:215], off
	v_lshl_add_u64 v[214:215], v[220:221], 0, s[80:81]
	s_mov_b32 m0, s42
	s_nop 0
	global_load_lds_dwordx4 v[214:215], off
	s_waitcnt vmcnt(8) lgkmcnt(0)
	s_barrier
	v_mfma_f32_16x16x32_bf16 v[62:65], v[142:145], v[180:183], v[62:65]
	v_mfma_f32_16x16x32_bf16 v[58:61], v[150:153], v[180:183], v[58:61]
	v_mfma_f32_16x16x32_bf16 v[50:53], v[142:145], v[190:193], v[50:53]
	v_mfma_f32_16x16x32_bf16 v[42:45], v[150:153], v[190:193], v[42:45]
	v_mfma_f32_16x16x32_bf16 v[34:37], v[142:145], v[198:201], v[34:37]
	v_mfma_f32_16x16x32_bf16 v[26:29], v[150:153], v[198:201], v[26:29]
	v_mfma_f32_16x16x32_bf16 v[18:21], v[142:145], v[206:209], v[18:21]
	v_mfma_f32_16x16x32_bf16 v[10:13], v[150:153], v[206:209], v[10:13]
	v_mfma_f32_16x16x32_bf16 v[62:65], v[146:149], v[186:189], v[62:65]
	v_mfma_f32_16x16x32_bf16 v[58:61], v[158:161], v[186:189], v[58:61]
	v_mfma_f32_16x16x32_bf16 v[50:53], v[146:149], v[194:197], v[50:53]
	v_mfma_f32_16x16x32_bf16 v[42:45], v[158:161], v[194:197], v[42:45]
	v_mfma_f32_16x16x32_bf16 v[34:37], v[146:149], v[202:205], v[34:37]
	v_mfma_f32_16x16x32_bf16 v[26:29], v[158:161], v[202:205], v[26:29]
	v_mfma_f32_16x16x32_bf16 v[18:21], v[146:149], v[210:213], v[18:21]
	v_mfma_f32_16x16x32_bf16 v[10:13], v[158:161], v[210:213], v[10:13]
	v_mfma_f32_16x16x32_bf16 v[54:57], v[162:165], v[180:183], v[54:57]
	v_mfma_f32_16x16x32_bf16 v[46:49], v[170:173], v[180:183], v[46:49]
	v_mfma_f32_16x16x32_bf16 v[38:41], v[162:165], v[190:193], v[38:41]
	v_mfma_f32_16x16x32_bf16 v[30:33], v[170:173], v[190:193], v[30:33]
	v_mfma_f32_16x16x32_bf16 v[22:25], v[162:165], v[198:201], v[22:25]
	v_mfma_f32_16x16x32_bf16 v[14:17], v[170:173], v[198:201], v[14:17]
	v_mfma_f32_16x16x32_bf16 v[6:9], v[162:165], v[206:209], v[6:9]
	v_mfma_f32_16x16x32_bf16 v[2:5], v[170:173], v[206:209], v[2:5]
	v_mfma_f32_16x16x32_bf16 v[54:57], v[166:169], v[186:189], v[54:57]
	v_mfma_f32_16x16x32_bf16 v[46:49], v[174:177], v[186:189], v[46:49]
	v_mfma_f32_16x16x32_bf16 v[38:41], v[166:169], v[194:197], v[38:41]
	v_mfma_f32_16x16x32_bf16 v[30:33], v[174:177], v[194:197], v[30:33]
	v_mfma_f32_16x16x32_bf16 v[22:25], v[166:169], v[202:205], v[22:25]
	v_mfma_f32_16x16x32_bf16 v[14:17], v[174:177], v[202:205], v[14:17]
	v_mfma_f32_16x16x32_bf16 v[6:9], v[166:169], v[210:213], v[6:9]
	v_mfma_f32_16x16x32_bf16 v[2:5], v[174:177], v[210:213], v[2:5]
	s_barrier
	s_add_i32 s51, s51, 2
	s_add_u32 s49, s49, 0x100
	s_addc_u32 s50, s50, 0
	s_cmp_gt_u32 s51, 41
	s_mov_b64 s[20:21], s[22:23]
	s_cbranch_scc0 .LBB0_1330
	s_and_b64 vcc, exec, s[16:17]
	s_cbranch_vccz .LBB0_1333
	s_barrier

; #define PG8_STAGE(bufoff, gbase, voff) do { _Pragma("unroll") for (int _i = 0; _i < 2; ++_i) \
;         __builtin_amdgcn_global_load_lds((const unsigned*)((const char*)(gbase) + (voff)[_i]), (PG8_LAS unsigned*)(lds + (bufoff) + ldsw + _i * 8192), 16, 0, 0); } while (0)
; #define PG8_LDA(dst, b, h) do { _Pragma("unroll") for (int m = 0; m < 4; ++m) _Pragma("unroll") for (int k = 0; k < 2; ++k) dst[m][k] = *(const PG8_LAS bf16x8*)(lds + PG8_SA(b, h) + aoff + m * 2048 + k * 1024); } while (0)
; #define PG8_LDB(dst, b, h) do { _Pragma("unroll") for (int n = 0; n < 2; ++n) _Pragma("unroll") for (int k = 0; k < 2; ++k) dst[n][k] = *(const PG8_LAS bf16x8*)(lds + PG8_SB(b, h) + boff + n * 2048 + k * 1024); } while (0)
; #define PG8_WAIT_V(n) asm volatile("s_waitcnt vmcnt(" #n ")" ::: "memory")
; #define PG8_WAIT_L(n) asm volatile("s_waitcnt lgkmcnt(" #n ")" ::: "memory")
; #define PG8_BAR __builtin_amdgcn_s_barrier()
; #define PG8_SCHED __builtin_amdgcn_sched_barrier(0)
; template <class Epi, class Sched, bool ALIGN_EPI = false, bool SP2 = false>
; __device__ __forceinline__ void gemm_phase(PG8_LAS unsigned char* lds, const Gemm g, const Sched& S, const Epi& E) {
;     ...
;     for (;;) {
;         const bool has_next = S.next(ui + 1, nxt);
;         const char* nA = has_next ? (const char*)g.A + (size_t)nxt.pm * tstep : cA; const char* nB = has_next ? (const char*)g.Bt + (size_t)nxt.pn * tstep : cB;
;         for (int t = 0; t < nt; t += 2) {
;             const bool last = (t == nt - 2);
;             const char* a1 = cA + (size_t)(t + 1) * kstep;
;             const char* a2 = last ? nA : cA + (size_t)(t + 2) * kstep; const char* b2 = last ? nB : cB + (size_t)(t + 2) * kstep;
;             const char* a3 = a2 + kstep; const char* b3 = b2 + kstep;
;             if (last && has_next) S.a_ready(nxt);
;             if constexpr (SP2) {
;             PG8_LDB(B0, 0, 0); PG8_LDB(B1, 0, 1); PG8_SCHED; PG8_LDA(At, 0, 0); PG8_STAGE(PG8_SA(1, 1), a1 + hstep, voffA);
;             PG8_WAIT_V(8); PG8_WAIT_L(0); PG8_BAR; PG8_MMA(0, 0, At, B0); PG8_MMA(0, 1, At, B1); PG8_BAR; PG8_SCHED;
;             PG8_LDA(At, 0, 1); PG8_STAGE(PG8_SB(0, 0), b2, voffB); PG8_STAGE(PG8_SB(0, 1), b2 + hstep, voffB); PG8_STAGE(PG8_SA(0, 0), a2, voffA);
;             PG8_WAIT_V(8); PG8_WAIT_L(0); PG8_BAR; PG8_MMA(1, 0, At, B0); PG8_MMA(1, 1, At, B1); PG8_BAR; PG8_SCHED;
.LBB0_1359:
	s_add_u32 s47, s20, 0x100
	s_addc_u32 s48, s21, 0
	s_mov_b32 s49, -2
	s_add_u32 s20, s18, 0x100
	s_addc_u32 s21, s19, 0
	s_add_i32 s50, 0, 0x10000
	s_cmp_eq_u32 s49, 40
	s_cselect_b32 s25, s7, s21
	s_cselect_b32 s24, s6, s20
	v_add_u32_e32 v146, s50, v148
	s_cselect_b32 s23, s17, s48
	s_cselect_b32 s22, s16, s47
	s_add_i32 s51, 0, 0x14000
	ds_read_b128 v[142:145], v146
	ds_read_b128 v[152:155], v146 offset:1024
	ds_read_b128 v[156:159], v146 offset:2048
	ds_read_b128 v[160:163], v146 offset:3072
	v_add_u32_e32 v146, s51, v148
	ds_read_b128 v[164:167], v146
	ds_read_b128 v[168:171], v146 offset:1024
	ds_read_b128 v[172:175], v146 offset:2048
	ds_read_b128 v[180:183], v146 offset:3072
	v_lshl_add_u64 v[146:147], s[18:19], 0, v[138:139]
	s_add_i32 m0, s33, 0xc000
	ds_read_b128 v[186:189], v150
	ds_read_b128 v[190:193], v150 offset:1024
	ds_read_b128 v[194:197], v150 offset:2048
	ds_read_b128 v[198:201], v150 offset:3072
	ds_read_b128 v[202:205], v150 offset:4096
	ds_read_b128 v[206:209], v150 offset:5120
	ds_read_b128 v[210:213], v150 offset:6144
	ds_read_b128 v[214:217], v150 offset:7168
	global_load_lds_dwordx4 v[146:147], off
	v_lshl_add_u64 v[146:147], s[18:19], 0, v[140:141]
	s_add_i32 m0, s33, 0xe000
	s_nop 0
	global_load_lds_dwordx4 v[146:147], off
	s_waitcnt vmcnt(8) lgkmcnt(0)
	s_barrier
	v_mfma_f32_16x16x32_bf16 v[126:129], v[142:145], v[186:189], 0
	v_mfma_f32_16x16x32_bf16 v[122:125], v[156:159], v[186:189], 0
	v_mfma_f32_16x16x32_bf16 v[114:117], v[142:145], v[194:197], 0
	v_mfma_f32_16x16x32_bf16 v[106:109], v[156:159], v[194:197], 0
	v_mfma_f32_16x16x32_bf16 v[98:101], v[142:145], v[202:205], 0
	v_mfma_f32_16x16x32_bf16 v[90:93], v[156:159], v[202:205], 0
	v_mfma_f32_16x16x32_bf16 v[82:85], v[142:145], v[210:213], 0
	v_mfma_f32_16x16x32_bf16 v[74:77], v[156:159], v[210:213], 0
	v_mfma_f32_16x16x32_bf16 v[126:129], v[152:155], v[190:193], v[126:129]
	v_mfma_f32_16x16x32_bf16 v[122:125], v[160:163], v[190:193], v[122:125]
	v_mfma_f32_16x16x32_bf16 v[114:117], v[152:155], v[198:201], v[114:117]
	v_mfma_f32_16x16x32_bf16 v[106:109], v[160:163], v[198:201], v[106:109]
	v_mfma_f32_16x16x32_bf16 v[98:101], v[152:155], v[206:209], v[98:101]
	v_mfma_f32_16x16x32_bf16 v[90:93], v[160:163], v[206:209], v[90:93]
	v_mfma_f32_16x16x32_bf16 v[82:85], v[152:155], v[214:217], v[82:85]
	v_mfma_f32_16x16x32_bf16 v[74:77], v[160:163], v[214:217], v[74:77]
	v_mfma_f32_16x16x32_bf16 v[118:121], v[164:167], v[186:189], 0
	v_mfma_f32_16x16x32_bf16 v[110:113], v[172:175], v[186:189], 0
	v_mfma_f32_16x16x32_bf16 v[102:105], v[164:167], v[194:197], 0
	v_mfma_f32_16x16x32_bf16 v[94:97], v[172:175], v[194:197], 0
	v_mfma_f32_16x16x32_bf16 v[86:89], v[164:167], v[202:205], 0
	v_mfma_f32_16x16x32_bf16 v[78:81], v[172:175], v[202:205], 0
	v_mfma_f32_16x16x32_bf16 v[70:73], v[164:167], v[210:213], 0
	v_mfma_f32_16x16x32_bf16 v[66:69], v[172:175], v[210:213], 0
	v_mfma_f32_16x16x32_bf16 v[118:121], v[168:171], v[190:193], v[118:121]
	v_mfma_f32_16x16x32_bf16 v[110:113], v[180:183], v[190:193], v[110:113]
	v_mfma_f32_16x16x32_bf16 v[102:105], v[168:171], v[198:201], v[102:105]
	v_mfma_f32_16x16x32_bf16 v[94:97], v[180:183], v[198:201], v[94:97]
	v_mfma_f32_16x16x32_bf16 v[86:89], v[168:171], v[206:209], v[86:89]
	v_mfma_f32_16x16x32_bf16 v[78:81], v[180:183], v[206:209], v[78:81]
	v_mfma_f32_16x16x32_bf16 v[70:73], v[168:171], v[214:217], v[70:73]
	v_mfma_f32_16x16x32_bf16 v[66:69], v[180:183], v[214:217], v[66:69]
	s_barrier
	s_add_i32 s18, s50, s27
	v_lshl_add_u64 v[146:147], s[22:23], 0, v[132:133]
	s_mov_b32 m0, s18
	ds_read_b128 v[186:189], v150 offset:16384
	ds_read_b128 v[190:193], v150 offset:17408
	ds_read_b128 v[194:197], v150 offset:18432
	ds_read_b128 v[198:201], v150 offset:19456
	ds_read_b128 v[202:205], v150 offset:20480
	ds_read_b128 v[206:209], v150 offset:21504
	ds_read_b128 v[210:213], v150 offset:22528
	ds_read_b128 v[214:217], v150 offset:23552
	global_load_lds_dwordx4 v[146:147], off
	s_add_i32 m0, s18, 0x2000
	s_add_u32 s18, s22, 0xb0000
	v_lshl_add_u64 v[176:177], s[22:23], 0, v[136:137]
	s_addc_u32 s19, s23, 0
	s_add_i32 s50, s51, s27
	global_load_lds_dwordx4 v[176:177], off
	v_lshl_add_u64 v[218:219], s[18:19], 0, v[132:133]
	s_mov_b32 m0, s50
	v_lshl_add_u64 v[220:221], s[24:25], 0, v[134:135]
	global_load_lds_dwordx4 v[218:219], off
	v_lshl_add_u64 v[218:219], s[18:19], 0, v[136:137]
	s_add_i32 m0, s50, 0x2000
	s_nop 0
	global_load_lds_dwordx4 v[218:219], off
	v_lshl_add_u64 v[218:219], s[24:25], 0, v[130:131]
	s_mov_b32 m0, s33
	s_nop 0
	global_load_lds_dwordx4 v[218:219], off
	s_mov_b32 m0, s36
	s_nop 0
	global_load_lds_dwordx4 v[220:221], off
	s_waitcnt vmcnt(8) lgkmcnt(0)
	s_barrier
; #define PG8_STAGE(bufoff, gbase, voff) do { _Pragma("unroll") for (int _i = 0; _i < 2; ++_i) \
;         __builtin_amdgcn_global_load_lds((const unsigned*)((const char*)(gbase) + (voff)[_i]), (PG8_LAS unsigned*)(lds + (bufoff) + ldsw + _i * 8192), 16, 0, 0); } while (0)
; #define PG8_LDA(dst, b, h) do { _Pragma("unroll") for (int m = 0; m < 4; ++m) _Pragma("unroll") for (int k = 0; k < 2; ++k) dst[m][k] = *(const PG8_LAS bf16x8*)(lds + PG8_SA(b, h) + aoff + m * 2048 + k * 1024); } while (0)
; #define PG8_LDB(dst, b, h) do { _Pragma("unroll") for (int n = 0; n < 2; ++n) _Pragma("unroll") for (int k = 0; k < 2; ++k) dst[n][k] = *(const PG8_LAS bf16x8*)(lds + PG8_SB(b, h) + boff + n * 2048 + k * 1024); } while (0)
; #define PG8_MMA(ai, bj, At, Bt) do { __builtin_amdgcn_s_setprio(1); _Pragma("unroll") for (int m = 0; m < 4; ++m) _Pragma("unroll") for (int n = 0; n < 2; ++n) _Pragma("unroll") for (int k = 0; k < 2; ++k) \
;         acc[ai][bj][m][n] = __builtin_amdgcn_mfma_f32_16x16x32_bf16(Bt[n][k], At[m][k], acc[ai][bj][m][n], 0, 0, 0); __builtin_amdgcn_s_setprio(0); } while (0)
; #define PG8_WAIT_V(n) asm volatile("s_waitcnt vmcnt(" #n ")" ::: "memory")
; #define PG8_WAIT_L(n) asm volatile("s_waitcnt lgkmcnt(" #n ")" ::: "memory")
; #define PG8_BAR __builtin_amdgcn_s_barrier()
; #define PG8_SCHED __builtin_amdgcn_sched_barrier(0)
; template <class Epi, class Sched, bool ALIGN_EPI = false, bool SP2 = false>
; __device__ __forceinline__ void gemm_phase(PG8_LAS unsigned char* lds, const Gemm g, const Sched& S, const Epi& E) {
;     ...
;             PG8_LDA(At, 0, 1); PG8_STAGE(PG8_SB(0, 0), b2, voffB); PG8_STAGE(PG8_SB(0, 1), b2 + hstep, voffB); PG8_STAGE(PG8_SA(0, 0), a2, voffA);
;             PG8_WAIT_V(8); PG8_WAIT_L(0); PG8_BAR; PG8_MMA(1, 0, At, B0); PG8_MMA(1, 1, At, B1); PG8_BAR; PG8_SCHED;
;             PG8_LDB(B0, 1, 0); PG8_LDB(B1, 1, 1); PG8_SCHED; PG8_LDA(At, 1, 0); PG8_STAGE(PG8_SA(0, 1), a2 + hstep, voffA);
;             PG8_WAIT_V(8); PG8_WAIT_L(0); PG8_BAR; PG8_MMA(0, 0, At, B0); PG8_MMA(0, 1, At, B1); PG8_BAR; PG8_SCHED;
	v_mfma_f32_16x16x32_bf16 v[62:65], v[142:145], v[186:189], 0
	v_mfma_f32_16x16x32_bf16 v[58:61], v[156:159], v[186:189], 0
	v_mfma_f32_16x16x32_bf16 v[50:53], v[142:145], v[194:197], 0
	v_mfma_f32_16x16x32_bf16 v[42:45], v[156:159], v[194:197], 0
	v_mfma_f32_16x16x32_bf16 v[34:37], v[142:145], v[202:205], 0
	v_mfma_f32_16x16x32_bf16 v[26:29], v[156:159], v[202:205], 0
	v_mfma_f32_16x16x32_bf16 v[18:21], v[142:145], v[210:213], 0
	v_mfma_f32_16x16x32_bf16 v[10:13], v[156:159], v[210:213], 0
	v_mfma_f32_16x16x32_bf16 v[62:65], v[152:155], v[190:193], v[62:65]
	v_mfma_f32_16x16x32_bf16 v[58:61], v[160:163], v[190:193], v[58:61]
	v_mfma_f32_16x16x32_bf16 v[50:53], v[152:155], v[198:201], v[50:53]
	v_mfma_f32_16x16x32_bf16 v[42:45], v[160:163], v[198:201], v[42:45]
	v_mfma_f32_16x16x32_bf16 v[34:37], v[152:155], v[206:209], v[34:37]
	v_mfma_f32_16x16x32_bf16 v[26:29], v[160:163], v[206:209], v[26:29]
	v_mfma_f32_16x16x32_bf16 v[18:21], v[152:155], v[214:217], v[18:21]
	v_mfma_f32_16x16x32_bf16 v[10:13], v[160:163], v[214:217], v[10:13]
	v_mfma_f32_16x16x32_bf16 v[54:57], v[164:167], v[186:189], 0
	v_mfma_f32_16x16x32_bf16 v[46:49], v[172:175], v[186:189], 0
	v_mfma_f32_16x16x32_bf16 v[38:41], v[164:167], v[194:197], 0
	v_mfma_f32_16x16x32_bf16 v[30:33], v[172:175], v[194:197], 0
	v_mfma_f32_16x16x32_bf16 v[22:25], v[164:167], v[202:205], 0
	v_mfma_f32_16x16x32_bf16 v[14:17], v[172:175], v[202:205], 0
	v_mfma_f32_16x16x32_bf16 v[6:9], v[164:167], v[210:213], 0
	v_mfma_f32_16x16x32_bf16 v[2:5], v[172:175], v[210:213], 0
	v_mfma_f32_16x16x32_bf16 v[54:57], v[168:171], v[190:193], v[54:57]
	v_mfma_f32_16x16x32_bf16 v[46:49], v[180:183], v[190:193], v[46:49]
	v_mfma_f32_16x16x32_bf16 v[38:41], v[168:171], v[198:201], v[38:41]
	v_mfma_f32_16x16x32_bf16 v[30:33], v[180:183], v[198:201], v[30:33]
	v_mfma_f32_16x16x32_bf16 v[22:25], v[168:171], v[206:209], v[22:25]
	v_mfma_f32_16x16x32_bf16 v[14:17], v[180:183], v[206:209], v[14:17]
	v_mfma_f32_16x16x32_bf16 v[6:9], v[168:171], v[214:217], v[6:9]
	v_mfma_f32_16x16x32_bf16 v[2:5], v[180:183], v[214:217], v[2:5]
	s_barrier
	s_add_i32 s50, 0, 0x18000
	v_add_u32_e32 v151, s50, v148
	s_add_i32 s51, 0, 0x1c000
	ds_read_b128 v[142:145], v151
	ds_read_b128 v[152:155], v151 offset:1024
	ds_read_b128 v[156:159], v151 offset:2048
	ds_read_b128 v[160:163], v151 offset:3072
	v_add_u32_e32 v151, s51, v148
	ds_read_b128 v[164:167], v151
	ds_read_b128 v[168:171], v151 offset:1024
	ds_read_b128 v[172:175], v151 offset:2048
	ds_read_b128 v[180:183], v151 offset:3072
	s_add_u32 s18, s24, 0xb0000
	s_addc_u32 s19, s25, 0
	s_mov_b32 m0, s37
	v_lshl_add_u64 v[222:223], s[18:19], 0, v[130:131]
	ds_read_b128 v[186:189], v150 offset:32768
	ds_read_b128 v[190:193], v150 offset:33792
	ds_read_b128 v[194:197], v150 offset:34816
	ds_read_b128 v[198:201], v150 offset:35840
	ds_read_b128 v[202:205], v150 offset:36864
	ds_read_b128 v[206:209], v150 offset:37888
	ds_read_b128 v[210:213], v150 offset:38912
	ds_read_b128 v[214:217], v150 offset:39936
	global_load_lds_dwordx4 v[222:223], off
	v_lshl_add_u64 v[222:223], s[18:19], 0, v[134:135]
	s_mov_b32 m0, s38
	s_nop 0
	global_load_lds_dwordx4 v[222:223], off
	s_waitcnt vmcnt(8) lgkmcnt(0)
	s_barrier
	v_mfma_f32_16x16x32_bf16 v[126:129], v[142:145], v[186:189], v[126:129]
	v_mfma_f32_16x16x32_bf16 v[122:125], v[156:159], v[186:189], v[122:125]
	v_mfma_f32_16x16x32_bf16 v[114:117], v[142:145], v[194:197], v[114:117]
	v_mfma_f32_16x16x32_bf16 v[106:109], v[156:159], v[194:197], v[106:109]
	v_mfma_f32_16x16x32_bf16 v[98:101], v[142:145], v[202:205], v[98:101]
	v_mfma_f32_16x16x32_bf16 v[90:93], v[156:159], v[202:205], v[90:93]
	v_mfma_f32_16x16x32_bf16 v[82:85], v[142:145], v[210:213], v[82:85]
	v_mfma_f32_16x16x32_bf16 v[74:77], v[156:159], v[210:213], v[74:77]
	v_mfma_f32_16x16x32_bf16 v[126:129], v[152:155], v[190:193], v[126:129]
	v_mfma_f32_16x16x32_bf16 v[122:125], v[160:163], v[190:193], v[122:125]
	v_mfma_f32_16x16x32_bf16 v[114:117], v[152:155], v[198:201], v[114:117]
	v_mfma_f32_16x16x32_bf16 v[106:109], v[160:163], v[198:201], v[106:109]
	v_mfma_f32_16x16x32_bf16 v[98:101], v[152:155], v[206:209], v[98:101]
	v_mfma_f32_16x16x32_bf16 v[90:93], v[160:163], v[206:209], v[90:93]
	v_mfma_f32_16x16x32_bf16 v[82:85], v[152:155], v[214:217], v[82:85]
	v_mfma_f32_16x16x32_bf16 v[74:77], v[160:163], v[214:217], v[74:77]
	v_mfma_f32_16x16x32_bf16 v[118:121], v[164:167], v[186:189], v[118:121]
	v_mfma_f32_16x16x32_bf16 v[110:113], v[172:175], v[186:189], v[110:113]
	v_mfma_f32_16x16x32_bf16 v[102:105], v[164:167], v[194:197], v[102:105]
	v_mfma_f32_16x16x32_bf16 v[94:97], v[172:175], v[194:197], v[94:97]
	v_mfma_f32_16x16x32_bf16 v[86:89], v[164:167], v[202:205], v[86:89]
	v_mfma_f32_16x16x32_bf16 v[78:81], v[172:175], v[202:205], v[78:81]
	v_mfma_f32_16x16x32_bf16 v[70:73], v[164:167], v[210:213], v[70:73]
	v_mfma_f32_16x16x32_bf16 v[66:69], v[172:175], v[210:213], v[66:69]
	v_mfma_f32_16x16x32_bf16 v[118:121], v[168:171], v[190:193], v[118:121]
	v_mfma_f32_16x16x32_bf16 v[110:113], v[180:183], v[190:193], v[110:113]
	v_mfma_f32_16x16x32_bf16 v[102:105], v[168:171], v[198:201], v[102:105]
	v_mfma_f32_16x16x32_bf16 v[94:97], v[180:183], v[198:201], v[94:97]
	v_mfma_f32_16x16x32_bf16 v[86:89], v[168:171], v[206:209], v[86:89]
	v_mfma_f32_16x16x32_bf16 v[78:81], v[180:183], v[206:209], v[78:81]
	v_mfma_f32_16x16x32_bf16 v[70:73], v[168:171], v[214:217], v[70:73]
	v_mfma_f32_16x16x32_bf16 v[66:69], v[180:183], v[214:217], v[66:69]
	s_barrier
; #define PG8_STAGE(bufoff, gbase, voff) do { _Pragma("unroll") for (int _i = 0; _i < 2; ++_i) \
;         __builtin_amdgcn_global_load_lds((const unsigned*)((const char*)(gbase) + (voff)[_i]), (PG8_LAS unsigned*)(lds + (bufoff) + ldsw + _i * 8192), 16, 0, 0); } while (0)
; #define PG8_LDA(dst, b, h) do { _Pragma("unroll") for (int m = 0; m < 4; ++m) _Pragma("unroll") for (int k = 0; k < 2; ++k) dst[m][k] = *(const PG8_LAS bf16x8*)(lds + PG8_SA(b, h) + aoff + m * 2048 + k * 1024); } while (0)
; #define PG8_LDB(dst, b, h) do { _Pragma("unroll") for (int n = 0; n < 2; ++n) _Pragma("unroll") for (int k = 0; k < 2; ++k) dst[n][k] = *(const PG8_LAS bf16x8*)(lds + PG8_SB(b, h) + boff + n * 2048 + k * 1024); } while (0)
; template <class Epi, class Sched, bool ALIGN_EPI = false, bool SP2 = false>
; __device__ __forceinline__ void gemm_phase(PG8_LAS unsigned char* lds, const Gemm g, const Sched& S, const Epi& E) {
;     ...
;         for (int t = 0; t < nt; t += 2) {
;             const bool last = (t == nt - 2);
;             const char* a1 = cA + (size_t)(t + 1) * kstep;
;             const char* a2 = last ? nA : cA + (size_t)(t + 2) * kstep; const char* b2 = last ? nB : cB + (size_t)(t + 2) * kstep;
;             const char* a3 = a2 + kstep; const char* b3 = b2 + kstep;
;             if (last && has_next) S.a_ready(nxt);
;             if constexpr (SP2) {
;             PG8_LDB(B0, 0, 0); PG8_LDB(B1, 0, 1); PG8_SCHED; PG8_LDA(At, 0, 0); PG8_STAGE(PG8_SA(1, 1), a1 + hstep, voffA);
;             PG8_WAIT_V(8); PG8_WAIT_L(0); PG8_BAR; PG8_MMA(0, 0, At, B0); PG8_MMA(0, 1, At, B1); PG8_BAR; PG8_SCHED;
;             PG8_LDA(At, 0, 1); PG8_STAGE(PG8_SB(0, 0), b2, voffB); PG8_STAGE(PG8_SB(0, 1), b2 + hstep, voffB); PG8_STAGE(PG8_SA(0, 0), a2, voffA);
;             PG8_WAIT_V(8); PG8_WAIT_L(0); PG8_BAR; PG8_MMA(1, 0, At, B0); PG8_MMA(1, 1, At, B1); PG8_BAR; PG8_SCHED;
;             PG8_LDB(B0, 1, 0); PG8_LDB(B1, 1, 1); PG8_SCHED; PG8_LDA(At, 1, 0); PG8_STAGE(PG8_SA(0, 1), a2 + hstep, voffA);
;             PG8_WAIT_V(8); PG8_WAIT_L(0); PG8_BAR; PG8_MMA(0, 0, At, B0); PG8_MMA(0, 1, At, B1); PG8_BAR; PG8_SCHED;
;             PG8_LDA(At, 1, 1); PG8_STAGE(PG8_SB(1, 0), b3, voffB); PG8_STAGE(PG8_SB(1, 1), b3 + hstep, voffB); PG8_STAGE(PG8_SA(1, 0), a3, voffA);
;             PG8_WAIT_V(8); PG8_WAIT_L(0); PG8_BAR; PG8_MMA(1, 0, At, B0); PG8_MMA(1, 1, At, B1); PG8_BAR; PG8_SCHED;
	s_add_i32 s18, s50, s27
	v_lshl_add_u64 v[146:147], v[146:147], 0, s[80:81]
	s_mov_b32 m0, s18
	ds_read_b128 v[186:189], v150 offset:49152
	ds_read_b128 v[190:193], v150 offset:50176
	ds_read_b128 v[194:197], v150 offset:51200
	ds_read_b128 v[198:201], v150 offset:52224
	ds_read_b128 v[202:205], v150 offset:53248
	ds_read_b128 v[206:209], v150 offset:54272
	ds_read_b128 v[210:213], v150 offset:55296
	ds_read_b128 v[214:217], v150 offset:56320
	global_load_lds_dwordx4 v[146:147], off
	s_add_i32 m0, s18, 0x2000
	s_add_u32 s18, s22, 0xb0080
	v_lshl_add_u64 v[146:147], v[176:177], 0, s[80:81]
	s_addc_u32 s19, s23, 0
	s_add_i32 s22, s51, s27
	global_load_lds_dwordx4 v[146:147], off
	v_lshl_add_u64 v[146:147], s[18:19], 0, v[132:133]
	s_mov_b32 m0, s22
	s_nop 0
	global_load_lds_dwordx4 v[146:147], off
	v_lshl_add_u64 v[146:147], s[18:19], 0, v[136:137]
	s_add_i32 m0, s22, 0x2000
	s_nop 0
	global_load_lds_dwordx4 v[146:147], off
	v_lshl_add_u64 v[146:147], v[218:219], 0, s[80:81]
	s_mov_b32 m0, s39
	s_nop 0
	global_load_lds_dwordx4 v[146:147], off
	v_lshl_add_u64 v[146:147], v[220:221], 0, s[80:81]
	s_mov_b32 m0, s40
	s_nop 0
	global_load_lds_dwordx4 v[146:147], off
	s_waitcnt vmcnt(8) lgkmcnt(0)
	s_barrier
	v_mfma_f32_16x16x32_bf16 v[62:65], v[142:145], v[186:189], v[62:65]
	v_mfma_f32_16x16x32_bf16 v[58:61], v[156:159], v[186:189], v[58:61]
	v_mfma_f32_16x16x32_bf16 v[50:53], v[142:145], v[194:197], v[50:53]
	v_mfma_f32_16x16x32_bf16 v[42:45], v[156:159], v[194:197], v[42:45]
	v_mfma_f32_16x16x32_bf16 v[34:37], v[142:145], v[202:205], v[34:37]
	v_mfma_f32_16x16x32_bf16 v[26:29], v[156:159], v[202:205], v[26:29]
	v_mfma_f32_16x16x32_bf16 v[18:21], v[142:145], v[210:213], v[18:21]
	v_mfma_f32_16x16x32_bf16 v[10:13], v[156:159], v[210:213], v[10:13]
	v_mfma_f32_16x16x32_bf16 v[62:65], v[152:155], v[190:193], v[62:65]
	v_mfma_f32_16x16x32_bf16 v[58:61], v[160:163], v[190:193], v[58:61]
	v_mfma_f32_16x16x32_bf16 v[50:53], v[152:155], v[198:201], v[50:53]
	v_mfma_f32_16x16x32_bf16 v[42:45], v[160:163], v[198:201], v[42:45]
	v_mfma_f32_16x16x32_bf16 v[34:37], v[152:155], v[206:209], v[34:37]
	v_mfma_f32_16x16x32_bf16 v[26:29], v[160:163], v[206:209], v[26:29]
	v_mfma_f32_16x16x32_bf16 v[18:21], v[152:155], v[214:217], v[18:21]
	v_mfma_f32_16x16x32_bf16 v[10:13], v[160:163], v[214:217], v[10:13]
	v_mfma_f32_16x16x32_bf16 v[54:57], v[164:167], v[186:189], v[54:57]
	v_mfma_f32_16x16x32_bf16 v[46:49], v[172:175], v[186:189], v[46:49]
	v_mfma_f32_16x16x32_bf16 v[38:41], v[164:167], v[194:197], v[38:41]
	v_mfma_f32_16x16x32_bf16 v[30:33], v[172:175], v[194:197], v[30:33]
	v_mfma_f32_16x16x32_bf16 v[22:25], v[164:167], v[202:205], v[22:25]
	v_mfma_f32_16x16x32_bf16 v[14:17], v[172:175], v[202:205], v[14:17]
	v_mfma_f32_16x16x32_bf16 v[6:9], v[164:167], v[210:213], v[6:9]
	v_mfma_f32_16x16x32_bf16 v[2:5], v[172:175], v[210:213], v[2:5]
	v_mfma_f32_16x16x32_bf16 v[54:57], v[168:171], v[190:193], v[54:57]
	v_mfma_f32_16x16x32_bf16 v[46:49], v[180:183], v[190:193], v[46:49]
	v_mfma_f32_16x16x32_bf16 v[38:41], v[168:171], v[198:201], v[38:41]
	v_mfma_f32_16x16x32_bf16 v[30:33], v[180:183], v[198:201], v[30:33]
	v_mfma_f32_16x16x32_bf16 v[22:25], v[168:171], v[206:209], v[22:25]
	v_mfma_f32_16x16x32_bf16 v[14:17], v[180:183], v[206:209], v[14:17]
	v_mfma_f32_16x16x32_bf16 v[6:9], v[168:171], v[214:217], v[6:9]
	v_mfma_f32_16x16x32_bf16 v[2:5], v[180:183], v[214:217], v[2:5]
	s_barrier
	s_add_i32 s49, s49, 2
	s_add_u32 s47, s47, 0x100
	s_addc_u32 s48, s48, 0
	s_cmp_gt_u32 s49, 41
	s_mov_b64 s[18:19], s[20:21]
	s_branch .LBB0_1360
.LBB0_1360:
	s_add_u32 s20, s18, 0x100
	s_addc_u32 s21, s19, 0
	s_add_i32 s50, 0, 0x10000
	s_cmp_eq_u32 s49, 40
	s_cselect_b32 s25, s7, s21
	s_cselect_b32 s24, s6, s20
	v_add_u32_e32 v146, s50, v148
	s_cselect_b32 s23, s17, s48
	s_cselect_b32 s22, s16, s47
	s_add_i32 s51, 0, 0x14000
	ds_read_b128 v[142:145], v146
	ds_read_b128 v[152:155], v146 offset:1024
	ds_read_b128 v[156:159], v146 offset:2048
	ds_read_b128 v[160:163], v146 offset:3072
	v_add_u32_e32 v146, s51, v148
	ds_read_b128 v[164:167], v146
	ds_read_b128 v[168:171], v146 offset:1024
	ds_read_b128 v[172:175], v146 offset:2048
	ds_read_b128 v[180:183], v146 offset:3072
	v_lshl_add_u64 v[146:147], s[18:19], 0, v[138:139]
	s_add_i32 m0, s33, 0xc000
	ds_read_b128 v[186:189], v150
	ds_read_b128 v[190:193], v150 offset:1024
	ds_read_b128 v[194:197], v150 offset:2048
	ds_read_b128 v[198:201], v150 offset:3072
	ds_read_b128 v[202:205], v150 offset:4096
	ds_read_b128 v[206:209], v150 offset:5120
	ds_read_b128 v[210:213], v150 offset:6144
	ds_read_b128 v[214:217], v150 offset:7168
	global_load_lds_dwordx4 v[146:147], off
	v_lshl_add_u64 v[146:147], s[18:19], 0, v[140:141]
	s_add_i32 m0, s33, 0xe000
	s_nop 0
	global_load_lds_dwordx4 v[146:147], off
	s_waitcnt vmcnt(8) lgkmcnt(0)
	s_barrier
; #define PG8_STAGE(bufoff, gbase, voff) do { _Pragma("unroll") for (int _i = 0; _i < 2; ++_i) \
;         __builtin_amdgcn_global_load_lds((const unsigned*)((const char*)(gbase) + (voff)[_i]), (PG8_LAS unsigned*)(lds + (bufoff) + ldsw + _i * 8192), 16, 0, 0); } while (0)
; #define PG8_LDA(dst, b, h) do { _Pragma("unroll") for (int m = 0; m < 4; ++m) _Pragma("unroll") for (int k = 0; k < 2; ++k) dst[m][k] = *(const PG8_LAS bf16x8*)(lds + PG8_SA(b, h) + aoff + m * 2048 + k * 1024); } while (0)
; #define PG8_LDB(dst, b, h) do { _Pragma("unroll") for (int n = 0; n < 2; ++n) _Pragma("unroll") for (int k = 0; k < 2; ++k) dst[n][k] = *(const PG8_LAS bf16x8*)(lds + PG8_SB(b, h) + boff + n * 2048 + k * 1024); } while (0)
; #define PG8_MMA(ai, bj, At, Bt) do { __builtin_amdgcn_s_setprio(1); _Pragma("unroll") for (int m = 0; m < 4; ++m) _Pragma("unroll") for (int n = 0; n < 2; ++n) _Pragma("unroll") for (int k = 0; k < 2; ++k) \
;         acc[ai][bj][m][n] = __builtin_amdgcn_mfma_f32_16x16x32_bf16(Bt[n][k], At[m][k], acc[ai][bj][m][n], 0, 0, 0); __builtin_amdgcn_s_setprio(0); } while (0)
; #define PG8_WAIT_V(n) asm volatile("s_waitcnt vmcnt(" #n ")" ::: "memory")
; template <class Epi, class Sched, bool ALIGN_EPI = false, bool SP2 = false>
; __device__ __forceinline__ void gemm_phase(PG8_LAS unsigned char* lds, const Gemm g, const Sched& S, const Epi& E) {
;     ...
;             PG8_LDB(B0, 0, 0); PG8_LDB(B1, 0, 1); PG8_SCHED; PG8_LDA(At, 0, 0); PG8_STAGE(PG8_SA(1, 1), a1 + hstep, voffA);
;             PG8_WAIT_V(8); PG8_WAIT_L(0); PG8_BAR; PG8_MMA(0, 0, At, B0); PG8_MMA(0, 1, At, B1); PG8_BAR; PG8_SCHED;
;             PG8_LDA(At, 0, 1); PG8_STAGE(PG8_SB(0, 0), b2, voffB); PG8_STAGE(PG8_SB(0, 1), b2 + hstep, voffB); PG8_STAGE(PG8_SA(0, 0), a2, voffA);
;             PG8_WAIT_V(8); PG8_WAIT_L(0); PG8_BAR; PG8_MMA(1, 0, At, B0); PG8_MMA(1, 1, At, B1); PG8_BAR; PG8_SCHED;
;             PG8_LDB(B0, 1, 0); PG8_LDB(B1, 1, 1); PG8_SCHED; PG8_LDA(At, 1, 0); PG8_STAGE(PG8_SA(0, 1), a2 + hstep, voffA);
;             PG8_WAIT_V(8); PG8_WAIT_L(0); PG8_BAR; PG8_MMA(0, 0, At, B0); PG8_MMA(0, 1, At, B1); PG8_BAR; PG8_SCHED;
;             PG8_LDA(At, 1, 1); PG8_STAGE(PG8_SB(1, 0), b3, voffB); PG8_STAGE(PG8_SB(1, 1), b3 + hstep, voffB); PG8_STAGE(PG8_SA(1, 0), a3, voffA);
;             PG8_WAIT_V(8); PG8_WAIT_L(0); PG8_BAR; PG8_MMA(1, 0, At, B0); PG8_MMA(1, 1, At, B1); PG8_BAR; PG8_SCHED;
	v_mfma_f32_16x16x32_bf16 v[126:129], v[142:145], v[186:189], v[126:129]
	v_mfma_f32_16x16x32_bf16 v[122:125], v[156:159], v[186:189], v[122:125]
	v_mfma_f32_16x16x32_bf16 v[114:117], v[142:145], v[194:197], v[114:117]
	v_mfma_f32_16x16x32_bf16 v[106:109], v[156:159], v[194:197], v[106:109]
	v_mfma_f32_16x16x32_bf16 v[98:101], v[142:145], v[202:205], v[98:101]
	v_mfma_f32_16x16x32_bf16 v[90:93], v[156:159], v[202:205], v[90:93]
	v_mfma_f32_16x16x32_bf16 v[82:85], v[142:145], v[210:213], v[82:85]
	v_mfma_f32_16x16x32_bf16 v[74:77], v[156:159], v[210:213], v[74:77]
	v_mfma_f32_16x16x32_bf16 v[126:129], v[152:155], v[190:193], v[126:129]
	v_mfma_f32_16x16x32_bf16 v[122:125], v[160:163], v[190:193], v[122:125]
	v_mfma_f32_16x16x32_bf16 v[114:117], v[152:155], v[198:201], v[114:117]
	v_mfma_f32_16x16x32_bf16 v[106:109], v[160:163], v[198:201], v[106:109]
	v_mfma_f32_16x16x32_bf16 v[98:101], v[152:155], v[206:209], v[98:101]
	v_mfma_f32_16x16x32_bf16 v[90:93], v[160:163], v[206:209], v[90:93]
	v_mfma_f32_16x16x32_bf16 v[82:85], v[152:155], v[214:217], v[82:85]
	v_mfma_f32_16x16x32_bf16 v[74:77], v[160:163], v[214:217], v[74:77]
	v_mfma_f32_16x16x32_bf16 v[118:121], v[164:167], v[186:189], v[118:121]
	v_mfma_f32_16x16x32_bf16 v[110:113], v[172:175], v[186:189], v[110:113]
	v_mfma_f32_16x16x32_bf16 v[102:105], v[164:167], v[194:197], v[102:105]
	v_mfma_f32_16x16x32_bf16 v[94:97], v[172:175], v[194:197], v[94:97]
	v_mfma_f32_16x16x32_bf16 v[86:89], v[164:167], v[202:205], v[86:89]
	v_mfma_f32_16x16x32_bf16 v[78:81], v[172:175], v[202:205], v[78:81]
	v_mfma_f32_16x16x32_bf16 v[70:73], v[164:167], v[210:213], v[70:73]
	v_mfma_f32_16x16x32_bf16 v[66:69], v[172:175], v[210:213], v[66:69]
	v_mfma_f32_16x16x32_bf16 v[118:121], v[168:171], v[190:193], v[118:121]
	v_mfma_f32_16x16x32_bf16 v[110:113], v[180:183], v[190:193], v[110:113]
	v_mfma_f32_16x16x32_bf16 v[102:105], v[168:171], v[198:201], v[102:105]
	v_mfma_f32_16x16x32_bf16 v[94:97], v[180:183], v[198:201], v[94:97]
	v_mfma_f32_16x16x32_bf16 v[86:89], v[168:171], v[206:209], v[86:89]
	v_mfma_f32_16x16x32_bf16 v[78:81], v[180:183], v[206:209], v[78:81]
	v_mfma_f32_16x16x32_bf16 v[70:73], v[168:171], v[214:217], v[70:73]
	v_mfma_f32_16x16x32_bf16 v[66:69], v[180:183], v[214:217], v[66:69]
	s_barrier
	s_add_i32 s18, s50, s27
	v_lshl_add_u64 v[146:147], s[22:23], 0, v[132:133]
	s_mov_b32 m0, s18
	ds_read_b128 v[186:189], v150 offset:16384
	ds_read_b128 v[190:193], v150 offset:17408
	ds_read_b128 v[194:197], v150 offset:18432
	ds_read_b128 v[198:201], v150 offset:19456
	ds_read_b128 v[202:205], v150 offset:20480
	ds_read_b128 v[206:209], v150 offset:21504
	ds_read_b128 v[210:213], v150 offset:22528
	ds_read_b128 v[214:217], v150 offset:23552
	global_load_lds_dwordx4 v[146:147], off
	s_add_i32 m0, s18, 0x2000
	s_add_u32 s18, s22, 0xb0000
	v_lshl_add_u64 v[176:177], s[22:23], 0, v[136:137]
	s_addc_u32 s19, s23, 0
	s_add_i32 s50, s51, s27
	global_load_lds_dwordx4 v[176:177], off
	v_lshl_add_u64 v[218:219], s[18:19], 0, v[132:133]
	s_mov_b32 m0, s50
	v_lshl_add_u64 v[220:221], s[24:25], 0, v[134:135]
	global_load_lds_dwordx4 v[218:219], off
	v_lshl_add_u64 v[218:219], s[18:19], 0, v[136:137]
	s_add_i32 m0, s50, 0x2000
	s_nop 0
	global_load_lds_dwordx4 v[218:219], off
	v_lshl_add_u64 v[218:219], s[24:25], 0, v[130:131]
	s_mov_b32 m0, s33
	s_nop 0
	global_load_lds_dwordx4 v[218:219], off
	s_mov_b32 m0, s36
	s_nop 0
	global_load_lds_dwordx4 v[220:221], off
	s_waitcnt vmcnt(8) lgkmcnt(0)
	s_barrier
	v_mfma_f32_16x16x32_bf16 v[62:65], v[142:145], v[186:189], v[62:65]
	v_mfma_f32_16x16x32_bf16 v[58:61], v[156:159], v[186:189], v[58:61]
	v_mfma_f32_16x16x32_bf16 v[50:53], v[142:145], v[194:197], v[50:53]
	v_mfma_f32_16x16x32_bf16 v[42:45], v[156:159], v[194:197], v[42:45]
	v_mfma_f32_16x16x32_bf16 v[34:37], v[142:145], v[202:205], v[34:37]
	v_mfma_f32_16x16x32_bf16 v[26:29], v[156:159], v[202:205], v[26:29]
	v_mfma_f32_16x16x32_bf16 v[18:21], v[142:145], v[210:213], v[18:21]
	v_mfma_f32_16x16x32_bf16 v[10:13], v[156:159], v[210:213], v[10:13]
	v_mfma_f32_16x16x32_bf16 v[62:65], v[152:155], v[190:193], v[62:65]
	v_mfma_f32_16x16x32_bf16 v[58:61], v[160:163], v[190:193], v[58:61]
	v_mfma_f32_16x16x32_bf16 v[50:53], v[152:155], v[198:201], v[50:53]
	v_mfma_f32_16x16x32_bf16 v[42:45], v[160:163], v[198:201], v[42:45]
	v_mfma_f32_16x16x32_bf16 v[34:37], v[152:155], v[206:209], v[34:37]
	v_mfma_f32_16x16x32_bf16 v[26:29], v[160:163], v[206:209], v[26:29]
	v_mfma_f32_16x16x32_bf16 v[18:21], v[152:155], v[214:217], v[18:21]
	v_mfma_f32_16x16x32_bf16 v[10:13], v[160:163], v[214:217], v[10:13]
	v_mfma_f32_16x16x32_bf16 v[54:57], v[164:167], v[186:189], v[54:57]
	v_mfma_f32_16x16x32_bf16 v[46:49], v[172:175], v[186:189], v[46:49]
	v_mfma_f32_16x16x32_bf16 v[38:41], v[164:167], v[194:197], v[38:41]
	v_mfma_f32_16x16x32_bf16 v[30:33], v[172:175], v[194:197], v[30:33]
	v_mfma_f32_16x16x32_bf16 v[22:25], v[164:167], v[202:205], v[22:25]
	v_mfma_f32_16x16x32_bf16 v[14:17], v[172:175], v[202:205], v[14:17]
	v_mfma_f32_16x16x32_bf16 v[6:9], v[164:167], v[210:213], v[6:9]
	v_mfma_f32_16x16x32_bf16 v[2:5], v[172:175], v[210:213], v[2:5]
	v_mfma_f32_16x16x32_bf16 v[54:57], v[168:171], v[190:193], v[54:57]
	v_mfma_f32_16x16x32_bf16 v[46:49], v[180:183], v[190:193], v[46:49]
	v_mfma_f32_16x16x32_bf16 v[38:41], v[168:171], v[198:201], v[38:41]
	v_mfma_f32_16x16x32_bf16 v[30:33], v[180:183], v[198:201], v[30:33]
	v_mfma_f32_16x16x32_bf16 v[22:25], v[168:171], v[206:209], v[22:25]
	v_mfma_f32_16x16x32_bf16 v[14:17], v[180:183], v[206:209], v[14:17]
	v_mfma_f32_16x16x32_bf16 v[6:9], v[168:171], v[214:217], v[6:9]
	v_mfma_f32_16x16x32_bf16 v[2:5], v[180:183], v[214:217], v[2:5]
	s_barrier
; #define PG8_STAGE(bufoff, gbase, voff) do { _Pragma("unroll") for (int _i = 0; _i < 2; ++_i) \
;         __builtin_amdgcn_global_load_lds((const unsigned*)((const char*)(gbase) + (voff)[_i]), (PG8_LAS unsigned*)(lds + (bufoff) + ldsw + _i * 8192), 16, 0, 0); } while (0)
; #define PG8_LDA(dst, b, h) do { _Pragma("unroll") for (int m = 0; m < 4; ++m) _Pragma("unroll") for (int k = 0; k < 2; ++k) dst[m][k] = *(const PG8_LAS bf16x8*)(lds + PG8_SA(b, h) + aoff + m * 2048 + k * 1024); } while (0)
; #define PG8_LDB(dst, b, h) do { _Pragma("unroll") for (int n = 0; n < 2; ++n) _Pragma("unroll") for (int k = 0; k < 2; ++k) dst[n][k] = *(const PG8_LAS bf16x8*)(lds + PG8_SB(b, h) + boff + n * 2048 + k * 1024); } while (0)
; #define PG8_MMA(ai, bj, At, Bt) do { __builtin_amdgcn_s_setprio(1); _Pragma("unroll") for (int m = 0; m < 4; ++m) _Pragma("unroll") for (int n = 0; n < 2; ++n) _Pragma("unroll") for (int k = 0; k < 2; ++k) \
;         acc[ai][bj][m][n] = __builtin_amdgcn_mfma_f32_16x16x32_bf16(Bt[n][k], At[m][k], acc[ai][bj][m][n], 0, 0, 0); __builtin_amdgcn_s_setprio(0); } while (0)
; #define PG8_WAIT_V(n) asm volatile("s_waitcnt vmcnt(" #n ")" ::: "memory")
; #define PG8_WAIT_L(n) asm volatile("s_waitcnt lgkmcnt(" #n ")" ::: "memory")
; #define PG8_BAR __builtin_amdgcn_s_barrier()
; #define PG8_SCHED __builtin_amdgcn_sched_barrier(0)
; template <class Epi, class Sched, bool ALIGN_EPI = false, bool SP2 = false>
; __device__ __forceinline__ void gemm_phase(PG8_LAS unsigned char* lds, const Gemm g, const Sched& S, const Epi& E) {
;     ...
;             PG8_LDB(B0, 1, 0); PG8_LDB(B1, 1, 1); PG8_SCHED; PG8_LDA(At, 1, 0); PG8_STAGE(PG8_SA(0, 1), a2 + hstep, voffA);
;             PG8_WAIT_V(8); PG8_WAIT_L(0); PG8_BAR; PG8_MMA(0, 0, At, B0); PG8_MMA(0, 1, At, B1); PG8_BAR; PG8_SCHED;
;             PG8_LDA(At, 1, 1); PG8_STAGE(PG8_SB(1, 0), b3, voffB); PG8_STAGE(PG8_SB(1, 1), b3 + hstep, voffB); PG8_STAGE(PG8_SA(1, 0), a3, voffA);
;             PG8_WAIT_V(8); PG8_WAIT_L(0); PG8_BAR; PG8_MMA(1, 0, At, B0); PG8_MMA(1, 1, At, B1); PG8_BAR; PG8_SCHED;
;     ...
;         if constexpr (ALIGN_EPI) { if (wr == 0) PG8_BAR; }
	s_add_i32 s50, 0, 0x18000
	v_add_u32_e32 v151, s50, v148
	s_add_i32 s51, 0, 0x1c000
	ds_read_b128 v[142:145], v151
	ds_read_b128 v[152:155], v151 offset:1024
	ds_read_b128 v[156:159], v151 offset:2048
	ds_read_b128 v[160:163], v151 offset:3072
	v_add_u32_e32 v151, s51, v148
	ds_read_b128 v[164:167], v151
	ds_read_b128 v[168:171], v151 offset:1024
	ds_read_b128 v[172:175], v151 offset:2048
	ds_read_b128 v[180:183], v151 offset:3072
	s_add_u32 s18, s24, 0xb0000
	s_addc_u32 s19, s25, 0
	s_mov_b32 m0, s37
	v_lshl_add_u64 v[222:223], s[18:19], 0, v[130:131]
	ds_read_b128 v[186:189], v150 offset:32768
	ds_read_b128 v[190:193], v150 offset:33792
	ds_read_b128 v[194:197], v150 offset:34816
	ds_read_b128 v[198:201], v150 offset:35840
	ds_read_b128 v[202:205], v150 offset:36864
	ds_read_b128 v[206:209], v150 offset:37888
	ds_read_b128 v[210:213], v150 offset:38912
	ds_read_b128 v[214:217], v150 offset:39936
	global_load_lds_dwordx4 v[222:223], off
	v_lshl_add_u64 v[222:223], s[18:19], 0, v[134:135]
	s_mov_b32 m0, s38
	s_nop 0
	global_load_lds_dwordx4 v[222:223], off
	s_waitcnt vmcnt(8) lgkmcnt(0)
	s_barrier
	v_mfma_f32_16x16x32_bf16 v[126:129], v[142:145], v[186:189], v[126:129]
	v_mfma_f32_16x16x32_bf16 v[122:125], v[156:159], v[186:189], v[122:125]
	v_mfma_f32_16x16x32_bf16 v[114:117], v[142:145], v[194:197], v[114:117]
	v_mfma_f32_16x16x32_bf16 v[106:109], v[156:159], v[194:197], v[106:109]
	v_mfma_f32_16x16x32_bf16 v[98:101], v[142:145], v[202:205], v[98:101]
	v_mfma_f32_16x16x32_bf16 v[90:93], v[156:159], v[202:205], v[90:93]
	v_mfma_f32_16x16x32_bf16 v[82:85], v[142:145], v[210:213], v[82:85]
	v_mfma_f32_16x16x32_bf16 v[74:77], v[156:159], v[210:213], v[74:77]
	v_mfma_f32_16x16x32_bf16 v[126:129], v[152:155], v[190:193], v[126:129]
	v_mfma_f32_16x16x32_bf16 v[122:125], v[160:163], v[190:193], v[122:125]
	v_mfma_f32_16x16x32_bf16 v[114:117], v[152:155], v[198:201], v[114:117]
	v_mfma_f32_16x16x32_bf16 v[106:109], v[160:163], v[198:201], v[106:109]
	v_mfma_f32_16x16x32_bf16 v[98:101], v[152:155], v[206:209], v[98:101]
	v_mfma_f32_16x16x32_bf16 v[90:93], v[160:163], v[206:209], v[90:93]
	v_mfma_f32_16x16x32_bf16 v[82:85], v[152:155], v[214:217], v[82:85]
	v_mfma_f32_16x16x32_bf16 v[74:77], v[160:163], v[214:217], v[74:77]
	v_mfma_f32_16x16x32_bf16 v[118:121], v[164:167], v[186:189], v[118:121]
	v_mfma_f32_16x16x32_bf16 v[110:113], v[172:175], v[186:189], v[110:113]
	v_mfma_f32_16x16x32_bf16 v[102:105], v[164:167], v[194:197], v[102:105]
	v_mfma_f32_16x16x32_bf16 v[94:97], v[172:175], v[194:197], v[94:97]
	v_mfma_f32_16x16x32_bf16 v[86:89], v[164:167], v[202:205], v[86:89]
	v_mfma_f32_16x16x32_bf16 v[78:81], v[172:175], v[202:205], v[78:81]
	v_mfma_f32_16x16x32_bf16 v[70:73], v[164:167], v[210:213], v[70:73]
	v_mfma_f32_16x16x32_bf16 v[66:69], v[172:175], v[210:213], v[66:69]
	v_mfma_f32_16x16x32_bf16 v[118:121], v[168:171], v[190:193], v[118:121]
	v_mfma_f32_16x16x32_bf16 v[110:113], v[180:183], v[190:193], v[110:113]
	v_mfma_f32_16x16x32_bf16 v[102:105], v[168:171], v[198:201], v[102:105]
	v_mfma_f32_16x16x32_bf16 v[94:97], v[180:183], v[198:201], v[94:97]
	v_mfma_f32_16x16x32_bf16 v[86:89], v[168:171], v[206:209], v[86:89]
	v_mfma_f32_16x16x32_bf16 v[78:81], v[180:183], v[206:209], v[78:81]
	v_mfma_f32_16x16x32_bf16 v[70:73], v[168:171], v[214:217], v[70:73]
	v_mfma_f32_16x16x32_bf16 v[66:69], v[180:183], v[214:217], v[66:69]
	s_barrier
	s_add_i32 s18, s50, s27
	v_lshl_add_u64 v[146:147], v[146:147], 0, s[80:81]
	s_mov_b32 m0, s18
	ds_read_b128 v[186:189], v150 offset:49152
	ds_read_b128 v[190:193], v150 offset:50176
	ds_read_b128 v[194:197], v150 offset:51200
	ds_read_b128 v[198:201], v150 offset:52224
	ds_read_b128 v[202:205], v150 offset:53248
	ds_read_b128 v[206:209], v150 offset:54272
	ds_read_b128 v[210:213], v150 offset:55296
	ds_read_b128 v[214:217], v150 offset:56320
	global_load_lds_dwordx4 v[146:147], off
	s_add_i32 m0, s18, 0x2000
	s_add_u32 s18, s22, 0xb0080
	v_lshl_add_u64 v[146:147], v[176:177], 0, s[80:81]
	s_addc_u32 s19, s23, 0
	s_add_i32 s22, s51, s27
	global_load_lds_dwordx4 v[146:147], off
	v_lshl_add_u64 v[146:147], s[18:19], 0, v[132:133]
	s_mov_b32 m0, s22
	s_nop 0
	global_load_lds_dwordx4 v[146:147], off
	v_lshl_add_u64 v[146:147], s[18:19], 0, v[136:137]
	s_add_i32 m0, s22, 0x2000
	s_nop 0
	global_load_lds_dwordx4 v[146:147], off
	v_lshl_add_u64 v[146:147], v[218:219], 0, s[80:81]
	s_mov_b32 m0, s39
	s_nop 0
	global_load_lds_dwordx4 v[146:147], off
	v_lshl_add_u64 v[146:147], v[220:221], 0, s[80:81]
	s_mov_b32 m0, s40
	s_nop 0
	global_load_lds_dwordx4 v[146:147], off
	s_waitcnt vmcnt(8) lgkmcnt(0)
	s_barrier
	v_mfma_f32_16x16x32_bf16 v[62:65], v[142:145], v[186:189], v[62:65]
	v_mfma_f32_16x16x32_bf16 v[58:61], v[156:159], v[186:189], v[58:61]
	v_mfma_f32_16x16x32_bf16 v[50:53], v[142:145], v[194:197], v[50:53]
	v_mfma_f32_16x16x32_bf16 v[42:45], v[156:159], v[194:197], v[42:45]
	v_mfma_f32_16x16x32_bf16 v[34:37], v[142:145], v[202:205], v[34:37]
	v_mfma_f32_16x16x32_bf16 v[26:29], v[156:159], v[202:205], v[26:29]
	v_mfma_f32_16x16x32_bf16 v[18:21], v[142:145], v[210:213], v[18:21]
	v_mfma_f32_16x16x32_bf16 v[10:13], v[156:159], v[210:213], v[10:13]
	v_mfma_f32_16x16x32_bf16 v[62:65], v[152:155], v[190:193], v[62:65]
	v_mfma_f32_16x16x32_bf16 v[58:61], v[160:163], v[190:193], v[58:61]
	v_mfma_f32_16x16x32_bf16 v[50:53], v[152:155], v[198:201], v[50:53]
	v_mfma_f32_16x16x32_bf16 v[42:45], v[160:163], v[198:201], v[42:45]
	v_mfma_f32_16x16x32_bf16 v[34:37], v[152:155], v[206:209], v[34:37]
	v_mfma_f32_16x16x32_bf16 v[26:29], v[160:163], v[206:209], v[26:29]
	v_mfma_f32_16x16x32_bf16 v[18:21], v[152:155], v[214:217], v[18:21]
	v_mfma_f32_16x16x32_bf16 v[10:13], v[160:163], v[214:217], v[10:13]
	v_mfma_f32_16x16x32_bf16 v[54:57], v[164:167], v[186:189], v[54:57]
	v_mfma_f32_16x16x32_bf16 v[46:49], v[172:175], v[186:189], v[46:49]
	v_mfma_f32_16x16x32_bf16 v[38:41], v[164:167], v[194:197], v[38:41]
	v_mfma_f32_16x16x32_bf16 v[30:33], v[172:175], v[194:197], v[30:33]
	v_mfma_f32_16x16x32_bf16 v[22:25], v[164:167], v[202:205], v[22:25]
	v_mfma_f32_16x16x32_bf16 v[14:17], v[172:175], v[202:205], v[14:17]
	v_mfma_f32_16x16x32_bf16 v[6:9], v[164:167], v[210:213], v[6:9]
	v_mfma_f32_16x16x32_bf16 v[2:5], v[172:175], v[210:213], v[2:5]
	v_mfma_f32_16x16x32_bf16 v[54:57], v[168:171], v[190:193], v[54:57]
	v_mfma_f32_16x16x32_bf16 v[46:49], v[180:183], v[190:193], v[46:49]
	v_mfma_f32_16x16x32_bf16 v[38:41], v[168:171], v[198:201], v[38:41]
	v_mfma_f32_16x16x32_bf16 v[30:33], v[180:183], v[198:201], v[30:33]
	v_mfma_f32_16x16x32_bf16 v[22:25], v[168:171], v[206:209], v[22:25]
	v_mfma_f32_16x16x32_bf16 v[14:17], v[180:183], v[206:209], v[14:17]
	v_mfma_f32_16x16x32_bf16 v[6:9], v[168:171], v[214:217], v[6:9]
	v_mfma_f32_16x16x32_bf16 v[2:5], v[180:183], v[214:217], v[2:5]
	s_barrier
	s_add_i32 s49, s49, 2
	s_add_u32 s47, s47, 0x100
	s_addc_u32 s48, s48, 0
	s_cmp_gt_u32 s49, 41
	s_mov_b64 s[18:19], s[20:21]
	s_cbranch_scc0 .LBB0_1360
	s_and_b64 vcc, exec, s[14:15]
	s_cbranch_vccz .LBB0_1363
	s_barrier
